# speedup vs baseline: 1.0140x; 1.0140x over previous
; #define PG8_STAGE(bufoff, gbase, voff) do { _Pragma("unroll") for (int _i = 0; _i < 2; ++_i) \
;         __builtin_amdgcn_global_load_lds((const unsigned*)((const char*)(gbase) + (voff)[_i]), (LAS unsigned*)(lds + (bufoff) + ldsw + _i * 8192), 16, 0, 0); } while (0)
; #define PG8_LDA(dst, b, h) do { _Pragma("unroll") for (int m = 0; m < 4; ++m) _Pragma("unroll") for (int k = 0; k < 2; ++k) dst[m][k] = *(const LAS bf16x8*)(lds + PG8_SA(b, h) + aoff + m * 2048 + k * 1024); } while (0)
; #define PG8_LDB(dst, b, h) do { _Pragma("unroll") for (int n = 0; n < 2; ++n) _Pragma("unroll") for (int k = 0; k < 2; ++k) dst[n][k] = *(const LAS bf16x8*)(lds + PG8_SB(b, h) + boff + n * 2048 + k * 1024); } while (0)
; #define PG8_WAIT_V(n) asm volatile("s_waitcnt vmcnt(" #n ")" ::: "memory")
; #define PG8_WAIT_L(n) asm volatile("s_waitcnt lgkmcnt(" #n ")" ::: "memory")
; #define PG8_BAR __builtin_amdgcn_s_barrier()
; template <class Epi, class Sched>
; DI void gemm_phase(LAS unsigned char* lds, const Gemm g, const Sched& S, const Epi& E) {
;     ...
;         for (int t = 0; t < nt; t += 2) {
;             if constexpr (Epi::HAS_MID) { if (t == E.mid_t(nt)) { int fr3 = fr, fq3 = fq; asm volatile("" : "+v"(fr3), "+v"(fq3)); E.mid(acc, cur, wr, wc, fr3, fq3); } }
;             const bool last = (t == nt - 2);
;             const char* a1 = cA + (size_t)(t + 1) * kstep;
;             const char* a2 = last ? nA : cA + (size_t)(t + 2) * kstep; const char* b2 = last ? nB : cB + (size_t)(t + 2) * kstep;
;             const char* a3 = a2 + kstep; const char* b3 = b2 + kstep;
;             PG8_LDB(B0, 0, 0); PG8_SCHED; PG8_LDA(At, 0, 0); PG8_STAGE(PG8_SA(1, 1), a1 + hstep, voffA);
;             PG8_WAIT_L(8); PG8_BAR; PG8_WAIT_L(0); PG8_MMA(0, 0, At, B0); PG8_BAR; PG8_SCHED;
;             PG8_LDB(B1, 0, 1); PG8_STAGE(PG8_SB(0, 0), b2, voffB);
;             PG8_BAR; PG8_WAIT_L(0); PG8_MMA(0, 1, At, B1); PG8_BAR;
;             PG8_LDA(At, 0, 1); PG8_STAGE(PG8_SA(0, 0), a2, voffA);
;             PG8_BAR; PG8_WAIT_L(0); PG8_MMA(1, 0, At, B0); PG8_BAR; PG8_SCHED;
;             PG8_STAGE(PG8_SB(0, 1), b2 + hstep, voffB);
;             PG8_WAIT_V(6); PG8_BAR; PG8_MMA(1, 1, At, B1); PG8_BAR;
;             PG8_LDB(B0, 1, 0); PG8_SCHED; PG8_LDA(At, 1, 0); PG8_STAGE(PG8_SA(0, 1), a2 + hstep, voffA);
;             PG8_WAIT_L(8); PG8_BAR; PG8_WAIT_L(0); PG8_MMA(0, 0, At, B0); PG8_BAR; PG8_SCHED;
.LBB0_297:
	ds_read_b128 v[144:147], v158
	ds_read_b128 v[164:167], v158 offset:1024
	ds_read_b128 v[168:171], v158 offset:2048
	ds_read_b128 v[172:175], v158 offset:3072
	s_add_u32 s0, s40, 0xffea0080
	s_addc_u32 s1, s41, -1
	s_cmpk_eq_i32 s69, 0x54
	s_cselect_b32 s45, s9, s1
	s_cselect_b32 s44, s8, s0
	s_cselect_b32 s43, s11, s68
	s_cselect_b32 s42, s10, s35
	v_lshl_add_u64 v[214:215], s[40:41], 0, v[136:137]
	s_add_i32 m0, s54, 0xc000
	ds_read_b128 v[176:179], v159
	ds_read_b128 v[180:183], v159 offset:1024
	ds_read_b128 v[188:191], v159 offset:2048
	ds_read_b128 v[194:197], v159 offset:3072
	ds_read_b128 v[198:201], v159 offset:4096
	ds_read_b128 v[202:205], v159 offset:5120
	ds_read_b128 v[206:209], v159 offset:6144
	ds_read_b128 v[210:213], v159 offset:7168
	global_load_lds_dwordx4 v[214:215], off
	v_lshl_add_u64 v[214:215], s[40:41], 0, v[138:139]
	s_add_i32 m0, s54, 0xe000
	s_nop 0
	global_load_lds_dwordx4 v[214:215], off
	s_waitcnt lgkmcnt(8)
	s_barrier
	s_waitcnt lgkmcnt(0)
	s_setprio 1
	s_waitcnt lgkmcnt(0)
	v_mfma_f32_16x16x32_bf16 v[124:127], v[144:147], v[176:179], v[124:127]
	v_mfma_f32_16x16x32_bf16 v[120:123], v[168:171], v[176:179], v[120:123]
	v_mfma_f32_16x16x32_bf16 v[108:111], v[144:147], v[188:191], v[108:111]
	v_mfma_f32_16x16x32_bf16 v[104:107], v[168:171], v[188:191], v[104:107]
	v_mfma_f32_16x16x32_bf16 v[92:95], v[144:147], v[198:201], v[92:95]
	v_mfma_f32_16x16x32_bf16 v[88:91], v[168:171], v[198:201], v[88:91]
	v_mfma_f32_16x16x32_bf16 v[76:79], v[144:147], v[206:209], v[76:79]
	v_mfma_f32_16x16x32_bf16 v[72:75], v[168:171], v[206:209], v[72:75]
	v_mfma_f32_16x16x32_bf16 v[124:127], v[164:167], v[180:183], v[124:127]
	v_mfma_f32_16x16x32_bf16 v[120:123], v[172:175], v[180:183], v[120:123]
	v_mfma_f32_16x16x32_bf16 v[108:111], v[164:167], v[194:197], v[108:111]
	v_mfma_f32_16x16x32_bf16 v[104:107], v[172:175], v[194:197], v[104:107]
	v_mfma_f32_16x16x32_bf16 v[92:95], v[164:167], v[202:205], v[92:95]
	v_mfma_f32_16x16x32_bf16 v[88:91], v[172:175], v[202:205], v[88:91]
	v_mfma_f32_16x16x32_bf16 v[76:79], v[164:167], v[210:213], v[76:79]
	v_mfma_f32_16x16x32_bf16 v[72:75], v[172:175], v[210:213], v[72:75]
	s_setprio 0
	s_barrier
	s_add_i32 s0, s63, s53
	v_lshl_add_u64 v[230:231], s[42:43], 0, v[130:131]
	s_mov_b32 m0, s0
	ds_read_b128 v[214:217], v161
	ds_read_b128 v[218:221], v161 offset:1024
	ds_read_b128 v[222:225], v161 offset:2048
	ds_read_b128 v[226:229], v161 offset:3072
	global_load_lds_dwordx4 v[230:231], off
	v_lshl_add_u64 v[232:233], s[42:43], 0, v[134:135]
	s_add_i32 m0, s0, 0x2000
	s_nop 0
	global_load_lds_dwordx4 v[232:233], off
	s_barrier
	s_waitcnt lgkmcnt(0)
	s_setprio 1
	s_waitcnt lgkmcnt(0)
	v_mfma_f32_16x16x32_bf16 v[116:119], v[214:217], v[176:179], v[116:119]
	v_mfma_f32_16x16x32_bf16 v[112:115], v[222:225], v[176:179], v[112:115]
	v_mfma_f32_16x16x32_bf16 v[100:103], v[214:217], v[188:191], v[100:103]
	v_mfma_f32_16x16x32_bf16 v[96:99], v[222:225], v[188:191], v[96:99]
	v_mfma_f32_16x16x32_bf16 v[84:87], v[214:217], v[198:201], v[84:87]
	v_mfma_f32_16x16x32_bf16 v[80:83], v[222:225], v[198:201], v[80:83]
	v_mfma_f32_16x16x32_bf16 v[68:71], v[214:217], v[206:209], v[68:71]
	v_mfma_f32_16x16x32_bf16 v[64:67], v[222:225], v[206:209], v[64:67]
	v_mfma_f32_16x16x32_bf16 v[116:119], v[218:221], v[180:183], v[116:119]
	v_mfma_f32_16x16x32_bf16 v[112:115], v[226:229], v[180:183], v[112:115]
	v_mfma_f32_16x16x32_bf16 v[100:103], v[218:221], v[194:197], v[100:103]
	v_mfma_f32_16x16x32_bf16 v[96:99], v[226:229], v[194:197], v[96:99]
	v_mfma_f32_16x16x32_bf16 v[84:87], v[218:221], v[202:205], v[84:87]
	v_mfma_f32_16x16x32_bf16 v[80:83], v[226:229], v[202:205], v[80:83]
	v_mfma_f32_16x16x32_bf16 v[68:71], v[218:221], v[210:213], v[68:71]
	v_mfma_f32_16x16x32_bf16 v[64:67], v[226:229], v[210:213], v[64:67]
	s_setprio 0
	s_mov_b32 m0, s54
	v_lshl_add_u64 v[234:235], s[44:45], 0, v[128:129]
	s_barrier
	ds_read_b128 v[176:179], v159 offset:16384
	ds_read_b128 v[180:183], v159 offset:17408
	ds_read_b128 v[188:191], v159 offset:18432
	ds_read_b128 v[194:197], v159 offset:19456
	ds_read_b128 v[198:201], v159 offset:20480
	ds_read_b128 v[202:205], v159 offset:21504
	ds_read_b128 v[206:209], v159 offset:22528
	ds_read_b128 v[210:213], v159 offset:23552
	global_load_lds_dwordx4 v[234:235], off
	v_lshl_add_u64 v[236:237], s[44:45], 0, v[132:133]
	s_mov_b32 m0, s55
	s_nop 0
	global_load_lds_dwordx4 v[236:237], off
	s_barrier
	s_waitcnt lgkmcnt(0)
	s_setprio 1
	s_waitcnt lgkmcnt(0)
	v_mfma_f32_16x16x32_bf16 v[60:63], v[144:147], v[176:179], v[60:63]
	v_mfma_f32_16x16x32_bf16 v[56:59], v[168:171], v[176:179], v[56:59]
	v_mfma_f32_16x16x32_bf16 v[44:47], v[144:147], v[188:191], v[44:47]
	v_mfma_f32_16x16x32_bf16 v[40:43], v[168:171], v[188:191], v[40:43]
	v_mfma_f32_16x16x32_bf16 v[28:31], v[144:147], v[198:201], v[28:31]
	v_mfma_f32_16x16x32_bf16 v[24:27], v[168:171], v[198:201], v[24:27]
	v_mfma_f32_16x16x32_bf16 v[12:15], v[144:147], v[206:209], v[12:15]
	v_mfma_f32_16x16x32_bf16 v[8:11], v[168:171], v[206:209], v[8:11]
	v_mfma_f32_16x16x32_bf16 v[60:63], v[164:167], v[180:183], v[60:63]
	v_mfma_f32_16x16x32_bf16 v[56:59], v[172:175], v[180:183], v[56:59]
	v_mfma_f32_16x16x32_bf16 v[44:47], v[164:167], v[194:197], v[44:47]
	v_mfma_f32_16x16x32_bf16 v[40:43], v[172:175], v[194:197], v[40:43]
	v_mfma_f32_16x16x32_bf16 v[28:31], v[164:167], v[202:205], v[28:31]
	v_mfma_f32_16x16x32_bf16 v[24:27], v[172:175], v[202:205], v[24:27]
	v_mfma_f32_16x16x32_bf16 v[12:15], v[164:167], v[210:213], v[12:15]
	v_mfma_f32_16x16x32_bf16 v[8:11], v[172:175], v[210:213], v[8:11]
	s_setprio 0
	s_barrier
; #define PG8_STAGE(bufoff, gbase, voff) do { _Pragma("unroll") for (int _i = 0; _i < 2; ++_i) \
;         __builtin_amdgcn_global_load_lds((const unsigned*)((const char*)(gbase) + (voff)[_i]), (LAS unsigned*)(lds + (bufoff) + ldsw + _i * 8192), 16, 0, 0); } while (0)
; #define PG8_LDA(dst, b, h) do { _Pragma("unroll") for (int m = 0; m < 4; ++m) _Pragma("unroll") for (int k = 0; k < 2; ++k) dst[m][k] = *(const LAS bf16x8*)(lds + PG8_SA(b, h) + aoff + m * 2048 + k * 1024); } while (0)
; #define PG8_LDB(dst, b, h) do { _Pragma("unroll") for (int n = 0; n < 2; ++n) _Pragma("unroll") for (int k = 0; k < 2; ++k) dst[n][k] = *(const LAS bf16x8*)(lds + PG8_SB(b, h) + boff + n * 2048 + k * 1024); } while (0)
; #define PG8_MMA(ai, bj, At, Bt) do { __builtin_amdgcn_s_setprio(1); _Pragma("unroll") for (int m = 0; m < 4; ++m) _Pragma("unroll") for (int n = 0; n < 2; ++n) _Pragma("unroll") for (int k = 0; k < 2; ++k) \
;         acc[ai][bj][m][n] = __builtin_amdgcn_mfma_f32_16x16x32_bf16(Bt[n][k], At[m][k], acc[ai][bj][m][n], 0, 0, 0); __builtin_amdgcn_s_setprio(0); } while (0)
; #define PG8_WAIT_V(n) asm volatile("s_waitcnt vmcnt(" #n ")" ::: "memory")
; #define PG8_WAIT_L(n) asm volatile("s_waitcnt lgkmcnt(" #n ")" ::: "memory")
; #define PG8_BAR __builtin_amdgcn_s_barrier()
; #define PG8_SCHED __builtin_amdgcn_sched_barrier(0)
; template <class Epi, class Sched>
; DI void gemm_phase(LAS unsigned char* lds, const Gemm g, const Sched& S, const Epi& E) {
;     ...
;             PG8_STAGE(PG8_SB(0, 1), b2 + hstep, voffB);
;             PG8_WAIT_V(6); PG8_BAR; PG8_MMA(1, 1, At, B1); PG8_BAR;
;             PG8_LDB(B0, 1, 0); PG8_SCHED; PG8_LDA(At, 1, 0); PG8_STAGE(PG8_SA(0, 1), a2 + hstep, voffA);
;             PG8_WAIT_L(8); PG8_BAR; PG8_WAIT_L(0); PG8_MMA(0, 0, At, B0); PG8_BAR; PG8_SCHED;
;             PG8_LDB(B1, 1, 1); PG8_STAGE(PG8_SB(1, 0), b3, voffB);
;             PG8_BAR; PG8_WAIT_L(0); PG8_MMA(0, 1, At, B1); PG8_BAR;
;             PG8_LDA(At, 1, 1); PG8_STAGE(PG8_SA(1, 0), a3, voffA);
;             PG8_BAR; PG8_WAIT_L(0); PG8_MMA(1, 0, At, B0); PG8_BAR; PG8_SCHED;
;             PG8_STAGE(PG8_SB(1, 1), b3 + hstep, voffB);
;             PG8_WAIT_V(6); PG8_BAR; PG8_MMA(1, 1, At, B1); PG8_BAR;
	s_add_u32 s0, s42, 0x160000
	s_addc_u32 s1, s43, 0
	s_add_i32 s4, s64, s53
	v_lshl_add_u64 v[144:145], s[0:1], 0, v[130:131]
	s_mov_b32 m0, s4
	s_nop 0
	global_load_lds_dwordx4 v[144:145], off
	v_lshl_add_u64 v[144:145], s[0:1], 0, v[134:135]
	s_add_i32 m0, s4, 0x2000
	s_nop 0
	global_load_lds_dwordx4 v[144:145], off
	s_waitcnt vmcnt(6)
	s_barrier
	s_setprio 1
	v_mfma_f32_16x16x32_bf16 v[52:55], v[214:217], v[176:179], v[52:55]
	v_mfma_f32_16x16x32_bf16 v[48:51], v[222:225], v[176:179], v[48:51]
	v_mfma_f32_16x16x32_bf16 v[36:39], v[214:217], v[188:191], v[36:39]
	v_mfma_f32_16x16x32_bf16 v[32:35], v[222:225], v[188:191], v[32:35]
	v_mfma_f32_16x16x32_bf16 v[20:23], v[214:217], v[198:201], v[20:23]
	v_mfma_f32_16x16x32_bf16 v[16:19], v[222:225], v[198:201], v[16:19]
	v_mfma_f32_16x16x32_bf16 v[4:7], v[214:217], v[206:209], v[4:7]
	v_mfma_f32_16x16x32_bf16 v[0:3], v[222:225], v[206:209], v[0:3]
	v_mfma_f32_16x16x32_bf16 v[52:55], v[218:221], v[180:183], v[52:55]
	v_mfma_f32_16x16x32_bf16 v[48:51], v[226:229], v[180:183], v[48:51]
	v_mfma_f32_16x16x32_bf16 v[36:39], v[218:221], v[194:197], v[36:39]
	v_mfma_f32_16x16x32_bf16 v[32:35], v[226:229], v[194:197], v[32:35]
	v_mfma_f32_16x16x32_bf16 v[20:23], v[218:221], v[202:205], v[20:23]
	v_mfma_f32_16x16x32_bf16 v[16:19], v[226:229], v[202:205], v[16:19]
	v_mfma_f32_16x16x32_bf16 v[4:7], v[218:221], v[210:213], v[4:7]
	v_mfma_f32_16x16x32_bf16 v[0:3], v[226:229], v[210:213], v[0:3]
	s_setprio 0
	s_add_i32 s4, 0, 0x18000
	v_add_u32_e32 v163, s4, v157
	s_barrier
	ds_read_b128 v[144:147], v163
	ds_read_b128 v[164:167], v163 offset:1024
	ds_read_b128 v[168:171], v163 offset:2048
	ds_read_b128 v[172:175], v163 offset:3072
	s_add_u32 s0, s44, 0x160000
	s_addc_u32 s1, s45, 0
	s_mov_b32 m0, s56
	v_lshl_add_u64 v[214:215], s[0:1], 0, v[128:129]
	ds_read_b128 v[176:179], v159 offset:32768
	ds_read_b128 v[180:183], v159 offset:33792
	ds_read_b128 v[188:191], v159 offset:34816
	ds_read_b128 v[194:197], v159 offset:35840
	ds_read_b128 v[198:201], v159 offset:36864
	ds_read_b128 v[202:205], v159 offset:37888
	ds_read_b128 v[206:209], v159 offset:38912
	ds_read_b128 v[210:213], v159 offset:39936
	global_load_lds_dwordx4 v[214:215], off
	v_lshl_add_u64 v[214:215], s[0:1], 0, v[132:133]
	s_mov_b32 m0, s57
	s_nop 0
	global_load_lds_dwordx4 v[214:215], off
	s_waitcnt lgkmcnt(8)
	s_barrier
	s_waitcnt lgkmcnt(0)
	s_setprio 1
	s_waitcnt lgkmcnt(0)
	v_mfma_f32_16x16x32_bf16 v[124:127], v[144:147], v[176:179], v[124:127]
	v_mfma_f32_16x16x32_bf16 v[120:123], v[168:171], v[176:179], v[120:123]
	v_mfma_f32_16x16x32_bf16 v[108:111], v[144:147], v[188:191], v[108:111]
	v_mfma_f32_16x16x32_bf16 v[104:107], v[168:171], v[188:191], v[104:107]
	v_mfma_f32_16x16x32_bf16 v[92:95], v[144:147], v[198:201], v[92:95]
	v_mfma_f32_16x16x32_bf16 v[88:91], v[168:171], v[198:201], v[88:91]
	v_mfma_f32_16x16x32_bf16 v[76:79], v[144:147], v[206:209], v[76:79]
	v_mfma_f32_16x16x32_bf16 v[72:75], v[168:171], v[206:209], v[72:75]
	v_mfma_f32_16x16x32_bf16 v[124:127], v[164:167], v[180:183], v[124:127]
	v_mfma_f32_16x16x32_bf16 v[120:123], v[172:175], v[180:183], v[120:123]
	v_mfma_f32_16x16x32_bf16 v[108:111], v[164:167], v[194:197], v[108:111]
	v_mfma_f32_16x16x32_bf16 v[104:107], v[172:175], v[194:197], v[104:107]
	v_mfma_f32_16x16x32_bf16 v[92:95], v[164:167], v[202:205], v[92:95]
	v_mfma_f32_16x16x32_bf16 v[88:91], v[172:175], v[202:205], v[88:91]
	v_mfma_f32_16x16x32_bf16 v[76:79], v[164:167], v[210:213], v[76:79]
	v_mfma_f32_16x16x32_bf16 v[72:75], v[172:175], v[210:213], v[72:75]
	s_setprio 0
	s_barrier
	s_add_i32 s5, 0, 0x1c000
	s_add_i32 s0, s4, s53
	v_add_u32_e32 v163, s5, v157
	v_lshl_add_u64 v[230:231], v[230:231], 0, s[38:39]
	s_mov_b32 m0, s0
	ds_read_b128 v[214:217], v163
	ds_read_b128 v[218:221], v163 offset:1024
	ds_read_b128 v[222:225], v163 offset:2048
	ds_read_b128 v[226:229], v163 offset:3072
	global_load_lds_dwordx4 v[230:231], off
	v_lshl_add_u64 v[230:231], v[232:233], 0, s[38:39]
	s_add_i32 m0, s0, 0x2000
	s_nop 0
	global_load_lds_dwordx4 v[230:231], off
	s_barrier
	s_waitcnt lgkmcnt(0)
	s_setprio 1
	s_waitcnt lgkmcnt(0)
	v_mfma_f32_16x16x32_bf16 v[116:119], v[214:217], v[176:179], v[116:119]
	v_mfma_f32_16x16x32_bf16 v[112:115], v[222:225], v[176:179], v[112:115]
	v_mfma_f32_16x16x32_bf16 v[100:103], v[214:217], v[188:191], v[100:103]
	v_mfma_f32_16x16x32_bf16 v[96:99], v[222:225], v[188:191], v[96:99]
	v_mfma_f32_16x16x32_bf16 v[84:87], v[214:217], v[198:201], v[84:87]
	v_mfma_f32_16x16x32_bf16 v[80:83], v[222:225], v[198:201], v[80:83]
	v_mfma_f32_16x16x32_bf16 v[68:71], v[214:217], v[206:209], v[68:71]
	v_mfma_f32_16x16x32_bf16 v[64:67], v[222:225], v[206:209], v[64:67]
	v_mfma_f32_16x16x32_bf16 v[116:119], v[218:221], v[180:183], v[116:119]
	v_mfma_f32_16x16x32_bf16 v[112:115], v[226:229], v[180:183], v[112:115]
	v_mfma_f32_16x16x32_bf16 v[100:103], v[218:221], v[194:197], v[100:103]
	v_mfma_f32_16x16x32_bf16 v[96:99], v[226:229], v[194:197], v[96:99]
	v_mfma_f32_16x16x32_bf16 v[84:87], v[218:221], v[202:205], v[84:87]
	v_mfma_f32_16x16x32_bf16 v[80:83], v[226:229], v[202:205], v[80:83]
	v_mfma_f32_16x16x32_bf16 v[68:71], v[218:221], v[210:213], v[68:71]
	v_mfma_f32_16x16x32_bf16 v[64:67], v[226:229], v[210:213], v[64:67]
	s_setprio 0
	s_mov_b32 m0, s61
	v_lshl_add_u64 v[230:231], v[234:235], 0, s[38:39]
	s_barrier
	ds_read_b128 v[176:179], v159 offset:49152
	ds_read_b128 v[180:183], v159 offset:50176
	ds_read_b128 v[188:191], v159 offset:51200
	ds_read_b128 v[194:197], v159 offset:52224
	ds_read_b128 v[198:201], v159 offset:53248
	ds_read_b128 v[202:205], v159 offset:54272
	ds_read_b128 v[206:209], v159 offset:55296
	ds_read_b128 v[210:213], v159 offset:56320
	global_load_lds_dwordx4 v[230:231], off
	v_lshl_add_u64 v[230:231], v[236:237], 0, s[38:39]
	s_mov_b32 m0, s62
	s_nop 0
	global_load_lds_dwordx4 v[230:231], off
	s_barrier
; DI float bf_lo(unsigned u) { return __uint_as_float(u << 16); }
; DI float bf_hi(unsigned u) { return __uint_as_float(u & 0xffff0000u); }
; DI u32x4 pack8(f32x4 a, f32x4 b) { u32x4 w; w.x = cvt_pk_bf16(a[0], a[1]); w.y = cvt_pk_bf16(a[2], a[3]); w.z = cvt_pk_bf16(b[0], b[1]); w.w = cvt_pk_bf16(b[2], b[3]); return w; }
; #define PG8_LDA(dst, b, h) do { _Pragma("unroll") for (int m = 0; m < 4; ++m) _Pragma("unroll") for (int k = 0; k < 2; ++k) dst[m][k] = *(const LAS bf16x8*)(lds + PG8_SA(b, h) + aoff + m * 2048 + k * 1024); } while (0)
; template <class Epi, class Sched>
; DI void gemm_phase(LAS unsigned char* lds, const Gemm g, const Sched& S, const Epi& E) {
;     ...
;             PG8_WAIT_V(6); PG8_BAR; PG8_MMA(1, 1, At, B1); PG8_BAR;
;             PG8_LDB(B0, 1, 0); PG8_SCHED; PG8_LDA(At, 1, 0); PG8_STAGE(PG8_SA(0, 1), a2 + hstep, voffA);
;             PG8_WAIT_L(8); PG8_BAR; PG8_WAIT_L(0); PG8_MMA(0, 0, At, B0); PG8_BAR; PG8_SCHED;
;             PG8_LDB(B1, 1, 1); PG8_STAGE(PG8_SB(1, 0), b3, voffB);
;             PG8_BAR; PG8_WAIT_L(0); PG8_MMA(0, 1, At, B1); PG8_BAR;
;             PG8_LDA(At, 1, 1); PG8_STAGE(PG8_SA(1, 0), a3, voffA);
;             PG8_BAR; PG8_WAIT_L(0); PG8_MMA(1, 0, At, B0); PG8_BAR; PG8_SCHED;
;             PG8_STAGE(PG8_SB(1, 1), b3 + hstep, voffB);
;             PG8_WAIT_V(6); PG8_BAR; PG8_MMA(1, 1, At, B1); PG8_BAR;
;         }
;         { int fr2 = fr, fq2 = fq; asm volatile("" : "+v"(fr2), "+v"(fq2)); E(acc, cur, wr, wc, fr2, fq2); }
;     DI void operator()(AccRef acc, const Unit& u, int wr, int wc, int fr, int fq) const {
;     ...
;             for (int m = 0; m < 4; ++m) { const int row = u.pm * 256 + ai * 128 + wr * 64 + m * 16 + fr; const size_t off = (size_t)row * DM + col0; float q = 0.f;
; #pragma unroll
;                 for (int bj = 0; bj < 2; ++bj) {
;                     f32x4 b0, b1;
;                     if (F32BASE) { b0 = *(const f32x4*)(bp + off + bj * 128); b1 = *(const f32x4*)(bp + off + bj * 128 + 4); }
;                     else { const u32x4 uv = *(const u32x4*)(Ui + off + bj * 128); b0 = (f32x4){bf_lo(uv.x), bf_hi(uv.x), bf_lo(uv.y), bf_hi(uv.y)}; b1 = (f32x4){bf_lo(uv.z), bf_hi(uv.z), bf_lo(uv.w), bf_hi(uv.w)}; }
;                     const u32x4 w = pack8(b0 + acc[ai][bj][m][0] * (0.5f * S2), b1 + acc[ai][bj][m][1] * (0.5f * S2));
;                     *(u32x4*)(Uo + (size_t)row * ldo + col0 + bj * 128) = w;
	s_waitcnt lgkmcnt(0)
	s_setprio 1
	s_waitcnt lgkmcnt(0)
	v_mfma_f32_16x16x32_bf16 v[60:63], v[144:147], v[176:179], v[60:63]
	v_mfma_f32_16x16x32_bf16 v[56:59], v[168:171], v[176:179], v[56:59]
	v_mfma_f32_16x16x32_bf16 v[44:47], v[144:147], v[188:191], v[44:47]
	v_mfma_f32_16x16x32_bf16 v[40:43], v[168:171], v[188:191], v[40:43]
	v_mfma_f32_16x16x32_bf16 v[28:31], v[144:147], v[198:201], v[28:31]
	v_mfma_f32_16x16x32_bf16 v[24:27], v[168:171], v[198:201], v[24:27]
	v_mfma_f32_16x16x32_bf16 v[12:15], v[144:147], v[206:209], v[12:15]
	v_mfma_f32_16x16x32_bf16 v[8:11], v[168:171], v[206:209], v[8:11]
	v_mfma_f32_16x16x32_bf16 v[60:63], v[164:167], v[180:183], v[60:63]
	v_mfma_f32_16x16x32_bf16 v[56:59], v[172:175], v[180:183], v[56:59]
	v_mfma_f32_16x16x32_bf16 v[44:47], v[164:167], v[194:197], v[44:47]
	v_mfma_f32_16x16x32_bf16 v[40:43], v[172:175], v[194:197], v[40:43]
	v_mfma_f32_16x16x32_bf16 v[28:31], v[164:167], v[202:205], v[28:31]
	v_mfma_f32_16x16x32_bf16 v[24:27], v[172:175], v[202:205], v[24:27]
	v_mfma_f32_16x16x32_bf16 v[12:15], v[164:167], v[210:213], v[12:15]
	v_mfma_f32_16x16x32_bf16 v[8:11], v[172:175], v[210:213], v[8:11]
	s_setprio 0
	s_barrier
	s_add_u32 s0, s42, 0x160080
	s_addc_u32 s1, s43, 0
	s_add_i32 s4, s5, s53
	v_lshl_add_u64 v[144:145], s[0:1], 0, v[130:131]
	s_mov_b32 m0, s4
	s_nop 0
	global_load_lds_dwordx4 v[144:145], off
	v_lshl_add_u64 v[144:145], s[0:1], 0, v[134:135]
	s_add_i32 m0, s4, 0x2000
	s_nop 0
	global_load_lds_dwordx4 v[144:145], off
	s_waitcnt vmcnt(6)
	s_barrier
	s_setprio 1
	v_mfma_f32_16x16x32_bf16 v[52:55], v[214:217], v[176:179], v[52:55]
	v_mfma_f32_16x16x32_bf16 v[48:51], v[222:225], v[176:179], v[48:51]
	v_mfma_f32_16x16x32_bf16 v[36:39], v[214:217], v[188:191], v[36:39]
	v_mfma_f32_16x16x32_bf16 v[32:35], v[222:225], v[188:191], v[32:35]
	v_mfma_f32_16x16x32_bf16 v[20:23], v[214:217], v[198:201], v[20:23]
	v_mfma_f32_16x16x32_bf16 v[16:19], v[222:225], v[198:201], v[16:19]
	v_mfma_f32_16x16x32_bf16 v[4:7], v[214:217], v[206:209], v[4:7]
	v_mfma_f32_16x16x32_bf16 v[0:3], v[222:225], v[206:209], v[0:3]
	v_mfma_f32_16x16x32_bf16 v[52:55], v[218:221], v[180:183], v[52:55]
	v_mfma_f32_16x16x32_bf16 v[48:51], v[226:229], v[180:183], v[48:51]
	v_mfma_f32_16x16x32_bf16 v[36:39], v[218:221], v[194:197], v[36:39]
	v_mfma_f32_16x16x32_bf16 v[32:35], v[226:229], v[194:197], v[32:35]
	v_mfma_f32_16x16x32_bf16 v[20:23], v[218:221], v[202:205], v[20:23]
	v_mfma_f32_16x16x32_bf16 v[16:19], v[226:229], v[202:205], v[16:19]
	v_mfma_f32_16x16x32_bf16 v[4:7], v[218:221], v[210:213], v[4:7]
	v_mfma_f32_16x16x32_bf16 v[0:3], v[226:229], v[210:213], v[0:3]
	s_setprio 0
	s_add_i32 s69, s69, 2
	s_add_u32 s40, s40, 0x100
	s_addc_u32 s41, s41, 0
	s_add_u32 s35, s35, 0x100
	s_addc_u32 s68, s68, 0
	s_cmpk_gt_u32 s69, 0x55
	s_barrier
	s_cbranch_scc0 .LBB0_297
	s_lshl_b32 s0, s16, 8
	v_mov_b32_e32 v145, v148
	v_mov_b32_e32 v163, v149
	s_or_b32 s0, s0, s60
	s_lshl_b32 s40, s16, 2
	v_lshl_add_u32 v144, v163, 3, s0
	s_lshl_b32 s0, s34, 8
	s_add_i32 s0, s0, s59
	v_add_u32_e32 v146, s0, v145
	v_ashrrev_i32_e32 v147, 31, v146
	v_lshlrev_b64 v[164:165], 13, v[146:147]
	v_ashrrev_i32_e32 v145, 31, v144
	v_lshl_add_u64 v[164:165], s[28:29], 0, v[164:165]
	v_lshl_add_u64 v[172:173], v[144:145], 2, v[164:165]
	v_mov_b64_e32 v[240:241], v[172:173]
	s_mov_b32 s75, 0
	global_load_dwordx4 v[208:211], v[240:241], off
	global_load_dwordx4 v[212:215], v[240:241], off offset:16
	global_load_dwordx4 v[216:219], v[240:241], off offset:512
	global_load_dwordx4 v[220:223], v[240:241], off offset:528
	s_mov_b32 s74, 0x20000
	v_lshl_add_u64 v[240:241], v[240:241], 0, s[74:75]
	global_load_dwordx4 v[224:227], v[240:241], off
	global_load_dwordx4 v[228:231], v[240:241], off offset:16
	global_load_dwordx4 v[232:235], v[240:241], off offset:512
	global_load_dwordx4 v[236:239], v[240:241], off offset:528
	v_mov_b64_e32 v[242:243], v[240:241]
	s_mov_b32 s74, 0x20000
	v_lshl_add_u64 v[242:243], v[242:243], 0, s[74:75]
	global_load_dword v186, v[242:243], off
	global_load_dword v186, v[242:243], off offset:512
	s_mov_b32 s74, 0x20000
	v_lshl_add_u64 v[242:243], v[242:243], 0, s[74:75]
	global_load_dword v186, v[242:243], off
	global_load_dword v186, v[242:243], off offset:512
	s_mov_b32 s74, 0xa0000
	v_lshl_add_u64 v[242:243], v[242:243], 0, s[74:75]
	global_load_dword v186, v[242:243], off
	global_load_dword v186, v[242:243], off offset:512
	s_mov_b32 s74, 0x20000
	v_lshl_add_u64 v[242:243], v[242:243], 0, s[74:75]
	global_load_dword v186, v[242:243], off
	global_load_dword v186, v[242:243], off offset:512
	s_mov_b32 s74, 0x20000
	v_lshl_add_u64 v[242:243], v[242:243], 0, s[74:75]
	global_load_dword v186, v[242:243], off
	global_load_dword v186, v[242:243], off offset:512
	s_mov_b32 s74, 0x20000
	v_lshl_add_u64 v[242:243], v[242:243], 0, s[74:75]
	global_load_dword v186, v[242:243], off
	global_load_dword v186, v[242:243], off offset:512
	s_waitcnt vmcnt(19)
	v_mov_b64_e32 v[164:165], v[208:209]
	v_mov_b64_e32 v[166:167], v[210:211]
	s_mov_b32 s74, 0x20000
	v_lshl_add_u64 v[240:241], v[240:241], 0, s[74:75]
	global_load_dwordx4 v[208:211], v[240:241], off
	s_waitcnt vmcnt(19)
	v_mov_b64_e32 v[168:169], v[212:213]
	v_mov_b64_e32 v[170:171], v[214:215]
	global_load_dwordx4 v[212:215], v[240:241], off offset:16
	v_lshlrev_b64 v[174:175], 12, v[146:147]
	v_lshl_add_u64 v[174:175], s[18:19], 0, v[174:175]
	v_lshl_add_u64 v[174:175], v[144:145], 1, v[174:175]
	s_ashr_i32 s41, s40, 31
	v_pk_fma_f32 v[124:125], v[124:125], 0.5, v[164:165] op_sel_hi:[1,0,1]
	v_pk_fma_f32 v[126:127], v[126:127], 0.5, v[166:167] op_sel_hi:[1,0,1]
	v_pk_fma_f32 v[164:165], v[122:123], 0.5, v[170:171] op_sel_hi:[1,0,1]
	v_pk_fma_f32 v[120:121], v[120:121], 0.5, v[168:169] op_sel_hi:[1,0,1]
	v_cvt_pk_bf16_f32 v122, v124, v125
	v_cvt_pk_bf16_f32 v123, v126, v127
	s_nop 0
	v_cvt_pk_bf16_f32 v124, v120, v121
	v_cvt_pk_bf16_f32 v125, v164, v165
	global_store_dwordx4 v[174:175], v[122:125], off
	s_waitcnt vmcnt(20)
; DI float bf_lo(unsigned u) { return __uint_as_float(u << 16); }
; DI float bf_hi(unsigned u) { return __uint_as_float(u & 0xffff0000u); }
; DI u32x4 pack8(f32x4 a, f32x4 b) { u32x4 w; w.x = cvt_pk_bf16(a[0], a[1]); w.y = cvt_pk_bf16(a[2], a[3]); w.z = cvt_pk_bf16(b[0], b[1]); w.w = cvt_pk_bf16(b[2], b[3]); return w; }
;     DI void operator()(AccRef acc, const Unit& u, int wr, int wc, int fr, int fq) const {
;     ...
;             for (int m = 0; m < 4; ++m) { const int row = u.pm * 256 + ai * 128 + wr * 64 + m * 16 + fr; const size_t off = (size_t)row * DM + col0; float q = 0.f;
; #pragma unroll
;                 for (int bj = 0; bj < 2; ++bj) {
;                     f32x4 b0, b1;
;                     if (F32BASE) { b0 = *(const f32x4*)(bp + off + bj * 128); b1 = *(const f32x4*)(bp + off + bj * 128 + 4); }
;                     else { const u32x4 uv = *(const u32x4*)(Ui + off + bj * 128); b0 = (f32x4){bf_lo(uv.x), bf_hi(uv.x), bf_lo(uv.y), bf_hi(uv.y)}; b1 = (f32x4){bf_lo(uv.z), bf_hi(uv.z), bf_lo(uv.w), bf_hi(uv.w)}; }
;                     const u32x4 w = pack8(b0 + acc[ai][bj][m][0] * (0.5f * S2), b1 + acc[ai][bj][m][1] * (0.5f * S2));
;                     *(u32x4*)(Uo + (size_t)row * ldo + col0 + bj * 128) = w;
;                     const float r0 = bf_lo(w.x), r1 = bf_hi(w.x), r2 = bf_lo(w.y), r3 = bf_hi(w.y), r4 = bf_lo(w.z), r5 = bf_hi(w.z), r6 = bf_lo(w.w), r7 = bf_hi(w.w);
;                     q += (r0 * r0 + r1 * r1) + (r2 * r2 + r3 * r3) + (r4 * r4 + r5 * r5) + (r6 * r6 + r7 * r7); }
;                 q += __shfl_xor(q, 16); q += __shfl_xor(q, 32); if (fq == 0) ssp[(size_t)row * 32 + u.pn * 4 + wc] = q; }
	v_mov_b64_e32 v[164:165], v[216:217]
	v_mov_b64_e32 v[166:167], v[218:219]
	global_load_dwordx4 v[216:219], v[240:241], off offset:512
	s_waitcnt vmcnt(20)
	v_mov_b64_e32 v[168:169], v[220:221]
	v_mov_b64_e32 v[170:171], v[222:223]
	global_load_dwordx4 v[220:223], v[240:241], off offset:528
	v_lshlrev_b32_e32 v126, 16, v122
	v_and_b32_e32 v122, 0xffff0000, v122
	v_lshlrev_b32_e32 v127, 16, v123
	v_and_b32_e32 v123, 0xffff0000, v123
	v_lshlrev_b32_e32 v172, 16, v124
	v_and_b32_e32 v124, 0xffff0000, v124
	v_mul_f32_e32 v122, v122, v122
	v_mul_f32_e32 v123, v123, v123
	v_mul_f32_e32 v124, v124, v124
	v_fmac_f32_e32 v122, v126, v126
	v_fmac_f32_e32 v123, v127, v127
	v_lshlrev_b32_e32 v173, 16, v125
	v_and_b32_e32 v125, 0xffff0000, v125
	v_fmac_f32_e32 v124, v172, v172
	v_add_f32_e32 v122, v122, v123
	v_mul_f32_e32 v125, v125, v125
	v_add_f32_e32 v122, v122, v124
	v_and_b32_e32 v121, 64, v162
	v_fmac_f32_e32 v125, v173, v173
	v_xor_b32_e32 v120, 16, v162
	v_add_u32_e32 v121, 64, v121
	v_add_f32_e32 v122, v122, v125
	v_cmp_lt_i32_e32 vcc, v120, v121
	v_pk_fma_f32 v[118:119], v[118:119], 0.5, v[166:167] op_sel_hi:[1,0,1]
	v_pk_fma_f32 v[116:117], v[116:117], 0.5, v[164:165] op_sel_hi:[1,0,1]
	v_pk_fma_f32 v[114:115], v[114:115], 0.5, v[170:171] op_sel_hi:[1,0,1]
	v_pk_fma_f32 v[112:113], v[112:113], 0.5, v[168:169] op_sel_hi:[1,0,1]
	v_cvt_pk_bf16_f32 v116, v116, v117
	v_cvt_pk_bf16_f32 v117, v118, v119
	v_cndmask_b32_e32 v120, v162, v120, vcc
	v_cvt_pk_bf16_f32 v118, v112, v113
	v_cvt_pk_bf16_f32 v119, v114, v115
	v_and_b32_e32 v113, 0xffff0000, v116
	v_and_b32_e32 v115, 0xffff0000, v117
	v_lshlrev_b32_e32 v112, 16, v116
	v_lshlrev_b32_e32 v114, 16, v117
	v_and_b32_e32 v124, 0xffff0000, v118
	v_mul_f32_e32 v113, v113, v113
	v_mul_f32_e32 v115, v115, v115
	v_lshlrev_b32_e32 v123, 16, v118
	v_and_b32_e32 v126, 0xffff0000, v119
	v_mul_f32_e32 v124, v124, v124
	v_fmac_f32_e32 v113, v112, v112
	v_fmac_f32_e32 v115, v114, v114
	v_lshlrev_b32_e32 v125, 16, v119
	v_mul_f32_e32 v126, v126, v126
	v_fmac_f32_e32 v124, v123, v123
	v_add_f32_e32 v112, v113, v115
	v_fmac_f32_e32 v126, v125, v125
	v_add_f32_e32 v112, v112, v124
	v_add_f32_e32 v112, v112, v126
	v_lshlrev_b32_e32 v120, 2, v120
	v_add_f32_e32 v112, v122, v112
	ds_bpermute_b32 v113, v120, v112
	v_xor_b32_e32 v114, 32, v162
	v_cmp_lt_i32_e32 vcc, v114, v121
	global_store_dwordx4 v[174:175], v[116:119], off offset:256
	s_waitcnt lgkmcnt(0)
	v_add_f32_e32 v112, v112, v113
	v_cndmask_b32_e32 v114, v162, v114, vcc
	v_lshlrev_b32_e32 v114, 2, v114
	ds_bpermute_b32 v113, v114, v112
	v_cmp_eq_u32_e32 vcc, 0, v163
	s_and_saveexec_b64 s[42:43], vcc
	s_cbranch_execz .LBB0_300
	v_lshlrev_b64 v[116:117], 7, v[146:147]
	v_lshl_add_u64 v[116:117], s[36:37], 0, v[116:117]
	v_lshl_add_u64 v[116:117], s[40:41], 2, v[116:117]
	s_lshl_b32 s16, s58, 2
	v_lshl_add_u64 v[116:117], v[116:117], 0, s[16:17]
	s_waitcnt lgkmcnt(0)
	v_add_f32_e32 v112, v112, v113
	global_store_dword v[116:117], v112, off
.LBB0_300:
	s_or_b64 exec, exec, s[42:43]
	v_add_u32_e32 v112, 16, v146
	s_waitcnt lgkmcnt(0)
	v_ashrrev_i32_e32 v113, 31, v112
	v_lshlrev_b64 v[116:117], 13, v[112:113]
	v_lshl_add_u64 v[116:117], s[28:29], 0, v[116:117]
	v_lshl_add_u64 v[126:127], v[144:145], 2, v[116:117]
	s_waitcnt vmcnt(21)
	v_mov_b64_e32 v[116:117], v[224:225]
	v_mov_b64_e32 v[118:119], v[226:227]
	s_mov_b32 s74, 0x20000
	v_lshl_add_u64 v[240:241], v[240:241], 0, s[74:75]
	global_load_dwordx4 v[224:227], v[240:241], off
	s_waitcnt vmcnt(21)
	v_mov_b64_e32 v[122:123], v[228:229]
	v_mov_b64_e32 v[124:125], v[230:231]
	global_load_dwordx4 v[228:231], v[240:241], off offset:16
	v_lshlrev_b64 v[164:165], 12, v[112:113]
	v_lshl_add_u64 v[164:165], s[18:19], 0, v[164:165]
	v_lshl_add_u64 v[164:165], v[144:145], 1, v[164:165]
	v_pk_fma_f32 v[108:109], v[108:109], 0.5, v[116:117] op_sel_hi:[1,0,1]
	v_pk_fma_f32 v[116:117], v[106:107], 0.5, v[124:125] op_sel_hi:[1,0,1]
	v_pk_fma_f32 v[106:107], v[104:105], 0.5, v[122:123] op_sel_hi:[1,0,1]
	v_pk_fma_f32 v[110:111], v[110:111], 0.5, v[118:119] op_sel_hi:[1,0,1]
	v_cvt_pk_bf16_f32 v104, v108, v109
	s_nop 0
	v_cvt_pk_bf16_f32 v105, v110, v111
	v_cvt_pk_bf16_f32 v106, v106, v107
	v_cvt_pk_bf16_f32 v107, v116, v117
	global_store_dwordx4 v[164:165], v[104:107], off
	s_waitcnt vmcnt(22)
	v_mov_b64_e32 v[108:109], v[232:233]
	v_mov_b64_e32 v[110:111], v[234:235]
	global_load_dwordx4 v[232:235], v[240:241], off offset:512
	s_waitcnt vmcnt(22)
	v_mov_b64_e32 v[116:117], v[236:237]
	v_mov_b64_e32 v[118:119], v[238:239]
	global_load_dwordx4 v[236:239], v[240:241], off offset:528
	v_lshlrev_b32_e32 v115, 16, v104
	v_and_b32_e32 v104, 0xffff0000, v104
	v_lshlrev_b32_e32 v121, 16, v105
	v_and_b32_e32 v105, 0xffff0000, v105
	v_lshlrev_b32_e32 v122, 16, v106
	v_and_b32_e32 v106, 0xffff0000, v106
	v_mul_f32_e32 v104, v104, v104
	v_mul_f32_e32 v105, v105, v105
	v_lshlrev_b32_e32 v123, 16, v107
	v_and_b32_e32 v107, 0xffff0000, v107
	v_mul_f32_e32 v106, v106, v106
	v_fmac_f32_e32 v104, v115, v115
	v_fmac_f32_e32 v105, v121, v121
	v_mul_f32_e32 v107, v107, v107
	v_fmac_f32_e32 v106, v122, v122
	v_add_f32_e32 v104, v104, v105
	v_fmac_f32_e32 v107, v123, v123
	v_add_f32_e32 v104, v104, v106
	v_add_f32_e32 v106, v104, v107
	v_pk_fma_f32 v[102:103], v[102:103], 0.5, v[110:111] op_sel_hi:[1,0,1]
	v_pk_fma_f32 v[100:101], v[100:101], 0.5, v[108:109] op_sel_hi:[1,0,1]
	v_pk_fma_f32 v[96:97], v[96:97], 0.5, v[116:117] op_sel_hi:[1,0,1]
	v_pk_fma_f32 v[104:105], v[98:99], 0.5, v[118:119] op_sel_hi:[1,0,1]
	v_cvt_pk_bf16_f32 v98, v100, v101
	v_cvt_pk_bf16_f32 v99, v102, v103
	v_cvt_pk_bf16_f32 v100, v96, v97
	s_nop 0
	v_and_b32_e32 v97, 0xffff0000, v98
	v_and_b32_e32 v103, 0xffff0000, v99
	v_cvt_pk_bf16_f32 v101, v104, v105
	v_lshlrev_b32_e32 v96, 16, v98
	v_lshlrev_b32_e32 v102, 16, v99
	v_and_b32_e32 v105, 0xffff0000, v100
	v_mul_f32_e32 v97, v97, v97
	v_mul_f32_e32 v103, v103, v103
	v_lshlrev_b32_e32 v104, 16, v100
	v_and_b32_e32 v108, 0xffff0000, v101
	v_mul_f32_e32 v105, v105, v105
	v_fmac_f32_e32 v97, v96, v96
	v_fmac_f32_e32 v103, v102, v102
	v_lshlrev_b32_e32 v107, 16, v101
	v_mul_f32_e32 v108, v108, v108
	v_fmac_f32_e32 v105, v104, v104
	v_add_f32_e32 v96, v97, v103
	v_add_f32_e32 v96, v96, v105
	v_fmac_f32_e32 v108, v107, v107
	v_add_f32_e32 v96, v96, v108
	v_add_f32_e32 v96, v106, v96
	ds_bpermute_b32 v97, v120, v96
	global_store_dwordx4 v[164:165], v[98:101], off offset:256
	s_waitcnt lgkmcnt(0)
	v_add_f32_e32 v96, v96, v97
	ds_bpermute_b32 v97, v114, v96
	s_and_saveexec_b64 s[42:43], vcc
	s_cbranch_execz .LBB0_302
	v_lshlrev_b64 v[98:99], 7, v[112:113]
	v_lshl_add_u64 v[98:99], s[36:37], 0, v[98:99]
	v_lshl_add_u64 v[98:99], s[40:41], 2, v[98:99]
	s_lshl_b32 s16, s58, 2
	v_lshl_add_u64 v[98:99], v[98:99], 0, s[16:17]
	s_waitcnt lgkmcnt(0)
	v_add_f32_e32 v96, v96, v97
	global_store_dword v[98:99], v96, off

; #define PG8_STAGE(bufoff, gbase, voff) do { _Pragma("unroll") for (int _i = 0; _i < 2; ++_i) \
;         __builtin_amdgcn_global_load_lds((const unsigned*)((const char*)(gbase) + (voff)[_i]), (LAS unsigned*)(lds + (bufoff) + ldsw + _i * 8192), 16, 0, 0); } while (0)
; #define PG8_LDA(dst, b, h) do { _Pragma("unroll") for (int m = 0; m < 4; ++m) _Pragma("unroll") for (int k = 0; k < 2; ++k) dst[m][k] = *(const LAS bf16x8*)(lds + PG8_SA(b, h) + aoff + m * 2048 + k * 1024); } while (0)
; #define PG8_LDB(dst, b, h) do { _Pragma("unroll") for (int n = 0; n < 2; ++n) _Pragma("unroll") for (int k = 0; k < 2; ++k) dst[n][k] = *(const LAS bf16x8*)(lds + PG8_SB(b, h) + boff + n * 2048 + k * 1024); } while (0)
; #define PG8_MMA(ai, bj, At, Bt) do { __builtin_amdgcn_s_setprio(1); _Pragma("unroll") for (int m = 0; m < 4; ++m) _Pragma("unroll") for (int n = 0; n < 2; ++n) _Pragma("unroll") for (int k = 0; k < 2; ++k) \
;         acc[ai][bj][m][n] = __builtin_amdgcn_mfma_f32_16x16x32_bf16(Bt[n][k], At[m][k], acc[ai][bj][m][n], 0, 0, 0); __builtin_amdgcn_s_setprio(0); } while (0)
; template <class Epi, class Sched>
; DI void gemm_phase(LAS unsigned char* lds, const Gemm g, const Sched& S, const Epi& E) {
;     ...
;         for (int t = 0; t < nt; t += 2) {
;             if constexpr (Epi::HAS_MID) { if (t == E.mid_t(nt)) { int fr3 = fr, fq3 = fq; asm volatile("" : "+v"(fr3), "+v"(fq3)); E.mid(acc, cur, wr, wc, fr3, fq3); } }
;             const bool last = (t == nt - 2);
;             const char* a1 = cA + (size_t)(t + 1) * kstep;
;             const char* a2 = last ? nA : cA + (size_t)(t + 2) * kstep; const char* b2 = last ? nB : cB + (size_t)(t + 2) * kstep;
;             const char* a3 = a2 + kstep; const char* b3 = b2 + kstep;
;             PG8_LDB(B0, 0, 0); PG8_SCHED; PG8_LDA(At, 0, 0); PG8_STAGE(PG8_SA(1, 1), a1 + hstep, voffA);
;             PG8_WAIT_L(8); PG8_BAR; PG8_WAIT_L(0); PG8_MMA(0, 0, At, B0); PG8_BAR; PG8_SCHED;
;             PG8_LDB(B1, 0, 1); PG8_STAGE(PG8_SB(0, 0), b2, voffB);
;             PG8_BAR; PG8_WAIT_L(0); PG8_MMA(0, 1, At, B1); PG8_BAR;
;             PG8_LDA(At, 0, 1); PG8_STAGE(PG8_SA(0, 0), a2, voffA);
;             PG8_BAR; PG8_WAIT_L(0); PG8_MMA(1, 0, At, B0); PG8_BAR; PG8_SCHED;
;             PG8_STAGE(PG8_SB(0, 1), b2 + hstep, voffB);
;             PG8_WAIT_V(6); PG8_BAR; PG8_MMA(1, 1, At, B1); PG8_BAR;
.LBB0_527:
	ds_read_b128 v[146:149], v164
	ds_read_b128 v[150:153], v164 offset:1024
	ds_read_b128 v[154:157], v164 offset:2048
	ds_read_b128 v[170:173], v164 offset:3072
	s_add_u32 s0, s8, 0xfff80080
	s_addc_u32 s1, s9, -1
	s_cmp_eq_u32 s35, 28
	s_cselect_b32 s13, s14, s1
	s_cselect_b32 s12, s15, s0
	s_cselect_b32 s11, s16, s34
	s_cselect_b32 s10, s17, s28
	v_lshl_add_u64 v[158:159], s[8:9], 0, v[138:139]
	s_add_i32 m0, s59, 0xc000
	ds_read_b128 v[174:177], v165
	ds_read_b128 v[178:181], v165 offset:1024
	ds_read_b128 v[188:191], v165 offset:2048
	ds_read_b128 v[194:197], v165 offset:3072
	ds_read_b128 v[198:201], v165 offset:4096
	ds_read_b128 v[202:205], v165 offset:5120
	ds_read_b128 v[206:209], v165 offset:6144
	ds_read_b128 v[210:213], v165 offset:7168
	global_load_lds_dwordx4 v[158:159], off
	v_lshl_add_u64 v[158:159], s[8:9], 0, v[140:141]
	s_add_i32 m0, s59, 0xe000
	s_nop 0
	global_load_lds_dwordx4 v[158:159], off
	s_waitcnt lgkmcnt(8)
	s_barrier
	s_waitcnt lgkmcnt(0)
	s_setprio 1
	s_waitcnt lgkmcnt(0)
	v_mfma_f32_16x16x32_bf16 v[124:127], v[146:149], v[174:177], v[124:127]
	v_mfma_f32_16x16x32_bf16 v[120:123], v[154:157], v[174:177], v[120:123]
	v_mfma_f32_16x16x32_bf16 v[108:111], v[146:149], v[188:191], v[108:111]
	v_mfma_f32_16x16x32_bf16 v[104:107], v[154:157], v[188:191], v[104:107]
	v_mfma_f32_16x16x32_bf16 v[92:95], v[146:149], v[198:201], v[92:95]
	v_mfma_f32_16x16x32_bf16 v[88:91], v[154:157], v[198:201], v[88:91]
	v_mfma_f32_16x16x32_bf16 v[76:79], v[146:149], v[206:209], v[76:79]
	v_mfma_f32_16x16x32_bf16 v[72:75], v[154:157], v[206:209], v[72:75]
	v_mfma_f32_16x16x32_bf16 v[124:127], v[150:153], v[178:181], v[124:127]
	v_mfma_f32_16x16x32_bf16 v[120:123], v[170:173], v[178:181], v[120:123]
	v_mfma_f32_16x16x32_bf16 v[108:111], v[150:153], v[194:197], v[108:111]
	v_mfma_f32_16x16x32_bf16 v[104:107], v[170:173], v[194:197], v[104:107]
	v_mfma_f32_16x16x32_bf16 v[92:95], v[150:153], v[202:205], v[92:95]
	v_mfma_f32_16x16x32_bf16 v[88:91], v[170:173], v[202:205], v[88:91]
	v_mfma_f32_16x16x32_bf16 v[76:79], v[150:153], v[210:213], v[76:79]
	v_mfma_f32_16x16x32_bf16 v[72:75], v[170:173], v[210:213], v[72:75]
	s_setprio 0
	s_barrier
	s_add_i32 s0, s47, s74
	v_lshl_add_u64 v[158:159], s[10:11], 0, v[130:131]
	s_mov_b32 m0, s0
	ds_read_b128 v[214:217], v166
	ds_read_b128 v[218:221], v166 offset:1024
	ds_read_b128 v[222:225], v166 offset:2048
	ds_read_b128 v[226:229], v166 offset:3072
	global_load_lds_dwordx4 v[158:159], off
	v_lshl_add_u64 v[182:183], s[10:11], 0, v[134:135]
	s_add_i32 m0, s0, 0x2000
	s_nop 0
	global_load_lds_dwordx4 v[182:183], off
	s_barrier
	s_waitcnt lgkmcnt(0)
	s_setprio 1
	s_waitcnt lgkmcnt(0)
	v_mfma_f32_16x16x32_bf16 v[116:119], v[214:217], v[174:177], v[116:119]
	v_mfma_f32_16x16x32_bf16 v[112:115], v[222:225], v[174:177], v[112:115]
	v_mfma_f32_16x16x32_bf16 v[100:103], v[214:217], v[188:191], v[100:103]
	v_mfma_f32_16x16x32_bf16 v[96:99], v[222:225], v[188:191], v[96:99]
	v_mfma_f32_16x16x32_bf16 v[84:87], v[214:217], v[198:201], v[84:87]
	v_mfma_f32_16x16x32_bf16 v[80:83], v[222:225], v[198:201], v[80:83]
	v_mfma_f32_16x16x32_bf16 v[68:71], v[214:217], v[206:209], v[68:71]
	v_mfma_f32_16x16x32_bf16 v[64:67], v[222:225], v[206:209], v[64:67]
	v_mfma_f32_16x16x32_bf16 v[116:119], v[218:221], v[178:181], v[116:119]
	v_mfma_f32_16x16x32_bf16 v[112:115], v[226:229], v[178:181], v[112:115]
	v_mfma_f32_16x16x32_bf16 v[100:103], v[218:221], v[194:197], v[100:103]
	v_mfma_f32_16x16x32_bf16 v[96:99], v[226:229], v[194:197], v[96:99]
	v_mfma_f32_16x16x32_bf16 v[84:87], v[218:221], v[202:205], v[84:87]
	v_mfma_f32_16x16x32_bf16 v[80:83], v[226:229], v[202:205], v[80:83]
	v_mfma_f32_16x16x32_bf16 v[68:71], v[218:221], v[210:213], v[68:71]
	v_mfma_f32_16x16x32_bf16 v[64:67], v[226:229], v[210:213], v[64:67]
	s_setprio 0
	s_mov_b32 m0, s59
	v_lshl_add_u64 v[230:231], s[12:13], 0, v[128:129]
	s_barrier
	ds_read_b128 v[174:177], v165 offset:16384
	ds_read_b128 v[178:181], v165 offset:17408
	ds_read_b128 v[188:191], v165 offset:18432
	ds_read_b128 v[194:197], v165 offset:19456
	ds_read_b128 v[198:201], v165 offset:20480
	ds_read_b128 v[202:205], v165 offset:21504
	ds_read_b128 v[206:209], v165 offset:22528
	ds_read_b128 v[210:213], v165 offset:23552
	global_load_lds_dwordx4 v[230:231], off
	v_lshl_add_u64 v[232:233], s[12:13], 0, v[132:133]
	s_mov_b32 m0, s75
	s_nop 0
	global_load_lds_dwordx4 v[232:233], off
	s_barrier
	s_waitcnt lgkmcnt(0)
	s_setprio 1
	s_waitcnt lgkmcnt(0)
	v_mfma_f32_16x16x32_bf16 v[60:63], v[146:149], v[174:177], v[60:63]
	v_mfma_f32_16x16x32_bf16 v[56:59], v[154:157], v[174:177], v[56:59]
	v_mfma_f32_16x16x32_bf16 v[44:47], v[146:149], v[188:191], v[44:47]
	v_mfma_f32_16x16x32_bf16 v[40:43], v[154:157], v[188:191], v[40:43]
	v_mfma_f32_16x16x32_bf16 v[28:31], v[146:149], v[198:201], v[28:31]
	v_mfma_f32_16x16x32_bf16 v[24:27], v[154:157], v[198:201], v[24:27]
	v_mfma_f32_16x16x32_bf16 v[12:15], v[146:149], v[206:209], v[12:15]
	v_mfma_f32_16x16x32_bf16 v[8:11], v[154:157], v[206:209], v[8:11]
	v_mfma_f32_16x16x32_bf16 v[60:63], v[150:153], v[178:181], v[60:63]
	v_mfma_f32_16x16x32_bf16 v[56:59], v[170:173], v[178:181], v[56:59]
	v_mfma_f32_16x16x32_bf16 v[44:47], v[150:153], v[194:197], v[44:47]
	v_mfma_f32_16x16x32_bf16 v[40:43], v[170:173], v[194:197], v[40:43]
	v_mfma_f32_16x16x32_bf16 v[28:31], v[150:153], v[202:205], v[28:31]
	v_mfma_f32_16x16x32_bf16 v[24:27], v[170:173], v[202:205], v[24:27]
	v_mfma_f32_16x16x32_bf16 v[12:15], v[150:153], v[210:213], v[12:15]
	v_mfma_f32_16x16x32_bf16 v[8:11], v[170:173], v[210:213], v[8:11]
	s_setprio 0
	s_barrier
; #define PG8_STAGE(bufoff, gbase, voff) do { _Pragma("unroll") for (int _i = 0; _i < 2; ++_i) \
;         __builtin_amdgcn_global_load_lds((const unsigned*)((const char*)(gbase) + (voff)[_i]), (LAS unsigned*)(lds + (bufoff) + ldsw + _i * 8192), 16, 0, 0); } while (0)
; #define PG8_LDA(dst, b, h) do { _Pragma("unroll") for (int m = 0; m < 4; ++m) _Pragma("unroll") for (int k = 0; k < 2; ++k) dst[m][k] = *(const LAS bf16x8*)(lds + PG8_SA(b, h) + aoff + m * 2048 + k * 1024); } while (0)
; #define PG8_LDB(dst, b, h) do { _Pragma("unroll") for (int n = 0; n < 2; ++n) _Pragma("unroll") for (int k = 0; k < 2; ++k) dst[n][k] = *(const LAS bf16x8*)(lds + PG8_SB(b, h) + boff + n * 2048 + k * 1024); } while (0)
; #define PG8_MMA(ai, bj, At, Bt) do { __builtin_amdgcn_s_setprio(1); _Pragma("unroll") for (int m = 0; m < 4; ++m) _Pragma("unroll") for (int n = 0; n < 2; ++n) _Pragma("unroll") for (int k = 0; k < 2; ++k) \
;         acc[ai][bj][m][n] = __builtin_amdgcn_mfma_f32_16x16x32_bf16(Bt[n][k], At[m][k], acc[ai][bj][m][n], 0, 0, 0); __builtin_amdgcn_s_setprio(0); } while (0)
; #define PG8_WAIT_V(n) asm volatile("s_waitcnt vmcnt(" #n ")" ::: "memory")
; #define PG8_WAIT_L(n) asm volatile("s_waitcnt lgkmcnt(" #n ")" ::: "memory")
; #define PG8_BAR __builtin_amdgcn_s_barrier()
; #define PG8_SCHED __builtin_amdgcn_sched_barrier(0)
; template <class Epi, class Sched>
; DI void gemm_phase(LAS unsigned char* lds, const Gemm g, const Sched& S, const Epi& E) {
;     ...
;             PG8_STAGE(PG8_SB(0, 1), b2 + hstep, voffB);
;             PG8_WAIT_V(6); PG8_BAR; PG8_MMA(1, 1, At, B1); PG8_BAR;
;             PG8_LDB(B0, 1, 0); PG8_SCHED; PG8_LDA(At, 1, 0); PG8_STAGE(PG8_SA(0, 1), a2 + hstep, voffA);
;             PG8_WAIT_L(8); PG8_BAR; PG8_WAIT_L(0); PG8_MMA(0, 0, At, B0); PG8_BAR; PG8_SCHED;
;             PG8_LDB(B1, 1, 1); PG8_STAGE(PG8_SB(1, 0), b3, voffB);
;             PG8_BAR; PG8_WAIT_L(0); PG8_MMA(0, 1, At, B1); PG8_BAR;
;             PG8_LDA(At, 1, 1); PG8_STAGE(PG8_SA(1, 0), a3, voffA);
;             PG8_BAR; PG8_WAIT_L(0); PG8_MMA(1, 0, At, B0); PG8_BAR; PG8_SCHED;
;             PG8_STAGE(PG8_SB(1, 1), b3 + hstep, voffB);
;             PG8_WAIT_V(6); PG8_BAR; PG8_MMA(1, 1, At, B1); PG8_BAR;
	s_add_u32 s0, s10, 0x80000
	s_addc_u32 s1, s11, 0
	s_add_i32 s4, s87, s74
	v_lshl_add_u64 v[146:147], s[0:1], 0, v[130:131]
	s_mov_b32 m0, s4
	s_nop 0
	global_load_lds_dwordx4 v[146:147], off
	v_lshl_add_u64 v[146:147], s[0:1], 0, v[134:135]
	s_add_i32 m0, s4, 0x2000
	s_nop 0
	global_load_lds_dwordx4 v[146:147], off
	s_waitcnt vmcnt(6)
	s_barrier
	s_setprio 1
	v_mfma_f32_16x16x32_bf16 v[52:55], v[214:217], v[174:177], v[52:55]
	v_mfma_f32_16x16x32_bf16 v[48:51], v[222:225], v[174:177], v[48:51]
	v_mfma_f32_16x16x32_bf16 v[36:39], v[214:217], v[188:191], v[36:39]
	v_mfma_f32_16x16x32_bf16 v[32:35], v[222:225], v[188:191], v[32:35]
	v_mfma_f32_16x16x32_bf16 v[20:23], v[214:217], v[198:201], v[20:23]
	v_mfma_f32_16x16x32_bf16 v[16:19], v[222:225], v[198:201], v[16:19]
	v_mfma_f32_16x16x32_bf16 v[4:7], v[214:217], v[206:209], v[4:7]
	v_mfma_f32_16x16x32_bf16 v[0:3], v[222:225], v[206:209], v[0:3]
	v_mfma_f32_16x16x32_bf16 v[52:55], v[218:221], v[178:181], v[52:55]
	v_mfma_f32_16x16x32_bf16 v[48:51], v[226:229], v[178:181], v[48:51]
	v_mfma_f32_16x16x32_bf16 v[36:39], v[218:221], v[194:197], v[36:39]
	v_mfma_f32_16x16x32_bf16 v[32:35], v[226:229], v[194:197], v[32:35]
	v_mfma_f32_16x16x32_bf16 v[20:23], v[218:221], v[202:205], v[20:23]
	v_mfma_f32_16x16x32_bf16 v[16:19], v[226:229], v[202:205], v[16:19]
	v_mfma_f32_16x16x32_bf16 v[4:7], v[218:221], v[210:213], v[4:7]
	v_mfma_f32_16x16x32_bf16 v[0:3], v[226:229], v[210:213], v[0:3]
	s_setprio 0
	s_add_i32 s4, 0, 0x18000
	v_add_u32_e32 v137, s4, v163
	s_barrier
	ds_read_b128 v[146:149], v137
	ds_read_b128 v[150:153], v137 offset:1024
	ds_read_b128 v[154:157], v137 offset:2048
	ds_read_b128 v[170:173], v137 offset:3072
	s_add_u32 s0, s12, 0x80000
	s_addc_u32 s1, s13, 0
	s_mov_b32 m0, s76
	v_lshl_add_u64 v[214:215], s[0:1], 0, v[128:129]
	ds_read_b128 v[174:177], v165 offset:32768
	ds_read_b128 v[178:181], v165 offset:33792
	ds_read_b128 v[188:191], v165 offset:34816
	ds_read_b128 v[194:197], v165 offset:35840
	ds_read_b128 v[198:201], v165 offset:36864
	ds_read_b128 v[202:205], v165 offset:37888
	ds_read_b128 v[206:209], v165 offset:38912
	ds_read_b128 v[210:213], v165 offset:39936
	global_load_lds_dwordx4 v[214:215], off
	v_lshl_add_u64 v[214:215], s[0:1], 0, v[132:133]
	s_mov_b32 m0, s77
	s_nop 0
	global_load_lds_dwordx4 v[214:215], off
	s_waitcnt lgkmcnt(8)
	s_barrier
	s_waitcnt lgkmcnt(0)
	s_setprio 1
	s_waitcnt lgkmcnt(0)
	v_mfma_f32_16x16x32_bf16 v[124:127], v[146:149], v[174:177], v[124:127]
	v_mfma_f32_16x16x32_bf16 v[120:123], v[154:157], v[174:177], v[120:123]
	v_mfma_f32_16x16x32_bf16 v[108:111], v[146:149], v[188:191], v[108:111]
	v_mfma_f32_16x16x32_bf16 v[104:107], v[154:157], v[188:191], v[104:107]
	v_mfma_f32_16x16x32_bf16 v[92:95], v[146:149], v[198:201], v[92:95]
	v_mfma_f32_16x16x32_bf16 v[88:91], v[154:157], v[198:201], v[88:91]
	v_mfma_f32_16x16x32_bf16 v[76:79], v[146:149], v[206:209], v[76:79]
	v_mfma_f32_16x16x32_bf16 v[72:75], v[154:157], v[206:209], v[72:75]
	v_mfma_f32_16x16x32_bf16 v[124:127], v[150:153], v[178:181], v[124:127]
	v_mfma_f32_16x16x32_bf16 v[120:123], v[170:173], v[178:181], v[120:123]
	v_mfma_f32_16x16x32_bf16 v[108:111], v[150:153], v[194:197], v[108:111]
	v_mfma_f32_16x16x32_bf16 v[104:107], v[170:173], v[194:197], v[104:107]
	v_mfma_f32_16x16x32_bf16 v[92:95], v[150:153], v[202:205], v[92:95]
	v_mfma_f32_16x16x32_bf16 v[88:91], v[170:173], v[202:205], v[88:91]
	v_mfma_f32_16x16x32_bf16 v[76:79], v[150:153], v[210:213], v[76:79]
	v_mfma_f32_16x16x32_bf16 v[72:75], v[170:173], v[210:213], v[72:75]
	s_setprio 0
	s_barrier
	s_add_i32 s5, 0, 0x1c000
	s_add_i32 s0, s4, s74
	v_add_u32_e32 v137, s5, v163
	v_lshl_add_u64 v[158:159], v[158:159], 0, s[40:41]
	s_mov_b32 m0, s0
	ds_read_b128 v[214:217], v137
	ds_read_b128 v[218:221], v137 offset:1024
	ds_read_b128 v[222:225], v137 offset:2048
	ds_read_b128 v[226:229], v137 offset:3072
	global_load_lds_dwordx4 v[158:159], off
	v_lshl_add_u64 v[158:159], v[182:183], 0, s[40:41]
	s_add_i32 m0, s0, 0x2000
	s_nop 0
	global_load_lds_dwordx4 v[158:159], off
	s_barrier
	s_waitcnt lgkmcnt(0)
	s_setprio 1
	s_waitcnt lgkmcnt(0)
	v_mfma_f32_16x16x32_bf16 v[116:119], v[214:217], v[174:177], v[116:119]
	v_mfma_f32_16x16x32_bf16 v[112:115], v[222:225], v[174:177], v[112:115]
	v_mfma_f32_16x16x32_bf16 v[100:103], v[214:217], v[188:191], v[100:103]
	v_mfma_f32_16x16x32_bf16 v[96:99], v[222:225], v[188:191], v[96:99]
	v_mfma_f32_16x16x32_bf16 v[84:87], v[214:217], v[198:201], v[84:87]
	v_mfma_f32_16x16x32_bf16 v[80:83], v[222:225], v[198:201], v[80:83]
	v_mfma_f32_16x16x32_bf16 v[68:71], v[214:217], v[206:209], v[68:71]
	v_mfma_f32_16x16x32_bf16 v[64:67], v[222:225], v[206:209], v[64:67]
	v_mfma_f32_16x16x32_bf16 v[116:119], v[218:221], v[178:181], v[116:119]
	v_mfma_f32_16x16x32_bf16 v[112:115], v[226:229], v[178:181], v[112:115]
	v_mfma_f32_16x16x32_bf16 v[100:103], v[218:221], v[194:197], v[100:103]
	v_mfma_f32_16x16x32_bf16 v[96:99], v[226:229], v[194:197], v[96:99]
	v_mfma_f32_16x16x32_bf16 v[84:87], v[218:221], v[202:205], v[84:87]
	v_mfma_f32_16x16x32_bf16 v[80:83], v[226:229], v[202:205], v[80:83]
	v_mfma_f32_16x16x32_bf16 v[68:71], v[218:221], v[210:213], v[68:71]
	v_mfma_f32_16x16x32_bf16 v[64:67], v[226:229], v[210:213], v[64:67]
	s_setprio 0
	s_mov_b32 m0, s97
	v_lshl_add_u64 v[158:159], v[230:231], 0, s[40:41]
	s_barrier
	ds_read_b128 v[174:177], v165 offset:49152
	ds_read_b128 v[178:181], v165 offset:50176
	ds_read_b128 v[188:191], v165 offset:51200
	ds_read_b128 v[194:197], v165 offset:52224
	ds_read_b128 v[198:201], v165 offset:53248
	ds_read_b128 v[202:205], v165 offset:54272
	ds_read_b128 v[206:209], v165 offset:55296
	ds_read_b128 v[210:213], v165 offset:56320
	global_load_lds_dwordx4 v[158:159], off
	v_lshl_add_u64 v[158:159], v[232:233], 0, s[40:41]
	s_mov_b32 m0, s84
	s_nop 0
	global_load_lds_dwordx4 v[158:159], off
	s_barrier
; DI float rs_of(const float* ss, int row) { return 1.0f / sqrtf(ss[row] * (1.0f / DM) + EPS); }
; #define PG8_STAGE(bufoff, gbase, voff) do { _Pragma("unroll") for (int _i = 0; _i < 2; ++_i) \
;         __builtin_amdgcn_global_load_lds((const unsigned*)((const char*)(gbase) + (voff)[_i]), (LAS unsigned*)(lds + (bufoff) + ldsw + _i * 8192), 16, 0, 0); } while (0)
; #define PG8_MMA(ai, bj, At, Bt) do { __builtin_amdgcn_s_setprio(1); _Pragma("unroll") for (int m = 0; m < 4; ++m) _Pragma("unroll") for (int n = 0; n < 2; ++n) _Pragma("unroll") for (int k = 0; k < 2; ++k) \
;         acc[ai][bj][m][n] = __builtin_amdgcn_mfma_f32_16x16x32_bf16(Bt[n][k], At[m][k], acc[ai][bj][m][n], 0, 0, 0); __builtin_amdgcn_s_setprio(0); } while (0)
; #define PG8_WAIT_V(n) asm volatile("s_waitcnt vmcnt(" #n ")" ::: "memory")
; #define PG8_WAIT_L(n) asm volatile("s_waitcnt lgkmcnt(" #n ")" ::: "memory")
; #define PG8_BAR __builtin_amdgcn_s_barrier()
; #define PG8_SCHED __builtin_amdgcn_sched_barrier(0)
; template <class Epi, class Sched>
; DI void gemm_phase(LAS unsigned char* lds, const Gemm g, const Sched& S, const Epi& E) {
;     ...
;             PG8_BAR; PG8_WAIT_L(0); PG8_MMA(1, 0, At, B0); PG8_BAR; PG8_SCHED;
;             PG8_STAGE(PG8_SB(1, 1), b3 + hstep, voffB);
;             PG8_WAIT_V(6); PG8_BAR; PG8_MMA(1, 1, At, B1); PG8_BAR;
;         }
;         { int fr2 = fr, fq2 = fq; asm volatile("" : "+v"(fr2), "+v"(fq2)); E(acc, cur, wr, wc, fr2, fq2); }
;     DI void operator()(AccRef acc, const Unit& u, int wr, int wc, int fr, int fq) const {
;     ...
;             if (wc < 2) { float* fo = smp ? out + O_KRS : out + O_KRP + (size_t)pm * 256 * 64;
; #pragma unroll
;                 for (int ai = 0; ai < 2; ++ai)
; #pragma unroll
;                     for (int m = 0; m < 4; ++m) { const int rl = rl0 + ai * 128 + m * 16; const float r = rs_of(ss, pm * 256 + rl); float* p = fo + (size_t)rl * 64 + cc0; *(f32x4*)p = (acc[ai][0][m][0] * r); *(f32x4*)(p + 4) = (acc[ai][0][m][1] * r); } }
	s_waitcnt lgkmcnt(0)
	s_setprio 1
	s_waitcnt lgkmcnt(0)
	v_mfma_f32_16x16x32_bf16 v[60:63], v[146:149], v[174:177], v[60:63]
	v_mfma_f32_16x16x32_bf16 v[56:59], v[154:157], v[174:177], v[56:59]
	v_mfma_f32_16x16x32_bf16 v[44:47], v[146:149], v[188:191], v[44:47]
	v_mfma_f32_16x16x32_bf16 v[40:43], v[154:157], v[188:191], v[40:43]
	v_mfma_f32_16x16x32_bf16 v[28:31], v[146:149], v[198:201], v[28:31]
	v_mfma_f32_16x16x32_bf16 v[24:27], v[154:157], v[198:201], v[24:27]
	v_mfma_f32_16x16x32_bf16 v[12:15], v[146:149], v[206:209], v[12:15]
	v_mfma_f32_16x16x32_bf16 v[8:11], v[154:157], v[206:209], v[8:11]
	v_mfma_f32_16x16x32_bf16 v[60:63], v[150:153], v[178:181], v[60:63]
	v_mfma_f32_16x16x32_bf16 v[56:59], v[170:173], v[178:181], v[56:59]
	v_mfma_f32_16x16x32_bf16 v[44:47], v[150:153], v[194:197], v[44:47]
	v_mfma_f32_16x16x32_bf16 v[40:43], v[170:173], v[194:197], v[40:43]
	v_mfma_f32_16x16x32_bf16 v[28:31], v[150:153], v[202:205], v[28:31]
	v_mfma_f32_16x16x32_bf16 v[24:27], v[170:173], v[202:205], v[24:27]
	v_mfma_f32_16x16x32_bf16 v[12:15], v[150:153], v[210:213], v[12:15]
	v_mfma_f32_16x16x32_bf16 v[8:11], v[170:173], v[210:213], v[8:11]
	s_setprio 0
	s_barrier
	s_add_u32 s0, s10, 0x80080
	s_addc_u32 s1, s11, 0
	s_add_i32 s4, s5, s74
	v_lshl_add_u64 v[146:147], s[0:1], 0, v[130:131]
	s_mov_b32 m0, s4
	s_nop 0
	global_load_lds_dwordx4 v[146:147], off
	v_lshl_add_u64 v[146:147], s[0:1], 0, v[134:135]
	s_add_i32 m0, s4, 0x2000
	s_nop 0
	global_load_lds_dwordx4 v[146:147], off
	s_waitcnt vmcnt(6)
	s_barrier
	s_setprio 1
	v_mfma_f32_16x16x32_bf16 v[52:55], v[214:217], v[174:177], v[52:55]
	v_mfma_f32_16x16x32_bf16 v[48:51], v[222:225], v[174:177], v[48:51]
	v_mfma_f32_16x16x32_bf16 v[36:39], v[214:217], v[188:191], v[36:39]
	v_mfma_f32_16x16x32_bf16 v[32:35], v[222:225], v[188:191], v[32:35]
	v_mfma_f32_16x16x32_bf16 v[20:23], v[214:217], v[198:201], v[20:23]
	v_mfma_f32_16x16x32_bf16 v[16:19], v[222:225], v[198:201], v[16:19]
	v_mfma_f32_16x16x32_bf16 v[4:7], v[214:217], v[206:209], v[4:7]
	v_mfma_f32_16x16x32_bf16 v[0:3], v[222:225], v[206:209], v[0:3]
	v_mfma_f32_16x16x32_bf16 v[52:55], v[218:221], v[178:181], v[52:55]
	v_mfma_f32_16x16x32_bf16 v[48:51], v[226:229], v[178:181], v[48:51]
	v_mfma_f32_16x16x32_bf16 v[36:39], v[218:221], v[194:197], v[36:39]
	v_mfma_f32_16x16x32_bf16 v[32:35], v[226:229], v[194:197], v[32:35]
	v_mfma_f32_16x16x32_bf16 v[20:23], v[218:221], v[202:205], v[20:23]
	v_mfma_f32_16x16x32_bf16 v[16:19], v[226:229], v[202:205], v[16:19]
	v_mfma_f32_16x16x32_bf16 v[4:7], v[218:221], v[210:213], v[4:7]
	v_mfma_f32_16x16x32_bf16 v[0:3], v[226:229], v[210:213], v[0:3]
	s_setprio 0
	s_add_i32 s35, s35, 2
	s_add_u32 s8, s8, 0x100
	s_addc_u32 s9, s9, 0
	s_add_u32 s28, s28, 0x100
	s_addc_u32 s34, s34, 0
	s_cmp_gt_u32 s35, 29
	s_barrier
	s_cbranch_scc0 .LBB0_527
	s_cmp_lt_i32 s58, 4
	s_cselect_b64 s[8:9], -1, 0
	s_add_i32 s0, s58, -12
	s_cmp_lt_u32 s0, 3
	v_mov_b32_e32 v146, v162
	v_mov_b32_e32 v137, v161
	s_cselect_b64 s[0:1], -1, 0
	s_or_b64 s[0:1], s[8:9], s[0:1]
	v_add_u32_e32 v148, s95, v137
	v_lshl_add_u32 v146, v146, 3, s96
	s_andn2_b64 vcc, exec, s[0:1]
	s_mov_b64 s[10:11], -1
	s_cbranch_vccz .LBB0_684
	s_cmpk_gt_i32 s56, 0x7f
	s_cselect_b64 s[12:13], -1, 0
	s_cmpk_lt_i32 s56, 0x80
	s_cselect_b64 s[16:17], -1, 0
	s_cmp_gt_u32 s58, 11
	s_cbranch_scc0 .LBB0_537
	s_cmp_gt_u32 s58, 16
	s_cbranch_scc0 .LBB0_534
	s_andn2_b64 vcc, exec, s[42:43]
	s_cbranch_vccnz .LBB0_533
	s_ashr_i32 s57, s56, 31
	s_lshl_b64 s[0:1], s[56:57], 16
	v_readlane_b32 s4, v244, 10
	s_add_u32 s4, s4, s0
	v_readlane_b32 s0, v244, 8
	s_addc_u32 s5, s0, s1
	s_and_b64 s[0:1], s[12:13], exec
	v_readlane_b32 s0, v244, 13
	v_readlane_b32 s1, v244, 9
	s_cselect_b32 s0, s0, s5
	s_cselect_b32 s1, s1, s4
	s_lshl_b32 s14, s56, 8
	v_add_u32_e32 v150, s14, v148
	v_ashrrev_i32_e32 v151, 31, v150
	v_lshl_add_u64 v[150:151], v[150:151], 2, s[38:39]
	v_mov_b64_e32 v[240:241], v[150:151]
	s_mov_b32 s61, 0
	global_load_dword v192, v[240:241], off
	s_mov_b32 s60, 0x40
	v_lshl_add_u64 v[240:241], v[240:241], 0, s[60:61]
	global_load_dword v236, v[240:241], off
	s_mov_b32 s60, 0x40
	v_lshl_add_u64 v[240:241], v[240:241], 0, s[60:61]
	global_load_dword v237, v[240:241], off
	s_mov_b32 s60, 0x40
	v_lshl_add_u64 v[240:241], v[240:241], 0, s[60:61]
	global_load_dword v238, v[240:241], off
	s_mov_b32 s60, 0x140
	v_lshl_add_u64 v[240:241], v[240:241], 0, s[60:61]
	global_load_dword v239, v[240:241], off
	s_mov_b32 s60, 0x40
	v_lshl_add_u64 v[240:241], v[240:241], 0, s[60:61]
	global_load_dword v232, v[240:241], off
	s_mov_b32 s60, 0x40
	v_lshl_add_u64 v[240:241], v[240:241], 0, s[60:61]
	global_load_dword v233, v[240:241], off
	s_mov_b32 s60, 0x40
	v_lshl_add_u64 v[240:241], v[240:241], 0, s[60:61]
	global_load_dword v234, v[240:241], off
	s_waitcnt vmcnt(7)
; DI float rs_of(const float* ss, int row) { return 1.0f / sqrtf(ss[row] * (1.0f / DM) + EPS); }
;     DI void operator()(AccRef acc, const Unit& u, int wr, int wc, int fr, int fq) const {
;     ...
;             if (wc < 2) { float* fo = smp ? out + O_KRS : out + O_KRP + (size_t)pm * 256 * 64;
; #pragma unroll
;                 for (int ai = 0; ai < 2; ++ai)
; #pragma unroll
;                     for (int m = 0; m < 4; ++m) { const int rl = rl0 + ai * 128 + m * 16; const float r = rs_of(ss, pm * 256 + rl); float* p = fo + (size_t)rl * 64 + cc0; *(f32x4*)p = (acc[ai][0][m][0] * r); *(f32x4*)(p + 4) = (acc[ai][0][m][1] * r); } }
	v_mov_b32_e32 v153, v192
	v_ashrrev_i32_e32 v149, 31, v148
	v_lshlrev_b64 v[154:155], 8, v[148:149]
	v_ashrrev_i32_e32 v147, 31, v146
	v_mov_b32_e32 v150, s1
	v_mov_b32_e32 v151, s0
	v_lshl_add_u64 v[150:151], v[146:147], 2, v[150:151]
	v_lshl_add_u64 v[158:159], v[150:151], 0, v[154:155]
	v_add_u32_e32 v152, 16, v148
	v_add_u32_e32 v156, s14, v152
	v_ashrrev_i32_e32 v157, 31, v156
	v_lshl_add_u64 v[174:175], v[156:157], 2, s[38:39]
	v_fmamk_f32 v149, v153, 0x3a000000, v167
	v_mul_f32_e32 v153, 0x4f800000, v149
	v_cmp_gt_f32_e32 vcc, s88, v149
	s_nop 1
	v_cndmask_b32_e32 v149, v149, v153, vcc
	v_sqrt_f32_e32 v153, v149
	s_nop 0
	v_add_u32_e32 v147, -1, v153
	v_add_u32_e32 v154, 1, v153
	v_fma_f32 v155, -v147, v153, v149
	v_fma_f32 v170, -v154, v153, v149
	v_cmp_ge_f32_e64 s[10:11], 0, v155
	s_nop 1
	v_cndmask_b32_e64 v147, v153, v147, s[10:11]
	v_cmp_lt_f32_e64 s[10:11], 0, v170
	s_nop 1
	v_cndmask_b32_e64 v147, v147, v154, s[10:11]
	v_mul_f32_e32 v153, 0x37800000, v147
	v_cndmask_b32_e32 v147, v147, v153, vcc
	v_cmp_class_f32_e32 vcc, v149, v168
	s_nop 1
	v_cndmask_b32_e32 v147, v147, v149, vcc
	v_div_scale_f32 v149, s[0:1], v147, v147, 1.0
	v_rcp_f32_e32 v153, v149
	v_div_scale_f32 v154, vcc, 1.0, v147, 1.0
	v_fma_f32 v155, -v149, v153, 1.0
	v_fmac_f32_e32 v153, v155, v153
	v_mul_f32_e32 v155, v154, v153
	v_fma_f32 v156, -v149, v155, v154
	v_fmac_f32_e32 v155, v156, v153
	v_fma_f32 v149, -v149, v155, v154
	v_div_fmas_f32 v149, v149, v153, v155
	v_div_fixup_f32 v170, v149, v147, 1.0
	v_pk_mul_f32 v[156:157], v[126:127], v[170:171] op_sel_hi:[1,0]
	v_pk_mul_f32 v[154:155], v[124:125], v[170:171] op_sel_hi:[1,0]
	v_pk_mul_f32 v[172:173], v[122:123], v[170:171] op_sel_hi:[1,0]
	v_pk_mul_f32 v[170:171], v[120:121], v[170:171] op_sel_hi:[1,0]
	global_store_dwordx4 v[158:159], v[154:157], off
	global_store_dwordx4 v[158:159], v[170:173], off offset:16
	s_waitcnt vmcnt(8)
	v_mov_b32_e32 v147, v236
	v_add_u32_e32 v154, 32, v148
	v_add_u32_e32 v156, s14, v154
	v_ashrrev_i32_e32 v157, 31, v156
	v_lshl_add_u64 v[174:175], v[156:157], 2, s[38:39]
	v_ashrrev_i32_e32 v153, 31, v152
	v_lshlrev_b64 v[152:153], 8, v[152:153]
	v_lshl_add_u64 v[152:153], v[150:151], 0, v[152:153]
	v_fmamk_f32 v147, v147, 0x3a000000, v167
	v_mul_f32_e32 v149, 0x4f800000, v147
	v_cmp_gt_f32_e32 vcc, s88, v147
	s_nop 1
	v_cndmask_b32_e32 v147, v147, v149, vcc
	v_sqrt_f32_e32 v149, v147
	s_nop 0
	v_add_u32_e32 v155, -1, v149
	v_add_u32_e32 v158, 1, v149
	v_fma_f32 v159, -v155, v149, v147
	v_fma_f32 v170, -v158, v149, v147
	v_cmp_ge_f32_e64 s[10:11], 0, v159
	s_nop 1
	v_cndmask_b32_e64 v149, v149, v155, s[10:11]
	v_cmp_lt_f32_e64 s[10:11], 0, v170
	s_nop 1
	v_cndmask_b32_e64 v149, v149, v158, s[10:11]
	v_mul_f32_e32 v155, 0x37800000, v149
	v_cndmask_b32_e32 v149, v149, v155, vcc
	v_cmp_class_f32_e32 vcc, v147, v168
	s_nop 1
	v_cndmask_b32_e32 v147, v149, v147, vcc
	v_div_scale_f32 v149, s[0:1], v147, v147, 1.0
	v_rcp_f32_e32 v155, v149
	v_div_scale_f32 v156, vcc, 1.0, v147, 1.0
	v_fma_f32 v157, -v149, v155, 1.0
	v_fmac_f32_e32 v155, v157, v155
	v_mul_f32_e32 v157, v156, v155
	v_fma_f32 v158, -v149, v157, v156
	v_fmac_f32_e32 v157, v158, v155
	v_fma_f32 v149, -v149, v157, v156
	v_div_fmas_f32 v149, v149, v155, v157
	v_div_fixup_f32 v170, v149, v147, 1.0
	v_pk_mul_f32 v[158:159], v[110:111], v[170:171] op_sel_hi:[1,0]
	v_pk_mul_f32 v[156:157], v[108:109], v[170:171] op_sel_hi:[1,0]
	v_pk_mul_f32 v[172:173], v[106:107], v[170:171] op_sel_hi:[1,0]
	v_pk_mul_f32 v[170:171], v[104:105], v[170:171] op_sel_hi:[1,0]
	global_store_dwordx4 v[152:153], v[156:159], off
	global_store_dwordx4 v[152:153], v[170:173], off offset:16
	s_waitcnt vmcnt(9)
	v_mov_b32_e32 v147, v237
	v_ashrrev_i32_e32 v155, 31, v154
	v_lshlrev_b64 v[154:155], 8, v[154:155]
	v_lshl_add_u64 v[158:159], v[150:151], 0, v[154:155]
	v_add_u32_e32 v152, 48, v148
	v_add_u32_e32 v156, s14, v152
	v_ashrrev_i32_e32 v157, 31, v156
	v_lshl_add_u64 v[174:175], v[156:157], 2, s[38:39]
	v_fmamk_f32 v147, v147, 0x3a000000, v167
	v_mul_f32_e32 v149, 0x4f800000, v147
	v_cmp_gt_f32_e32 vcc, s88, v147
	s_nop 1
	v_cndmask_b32_e32 v147, v147, v149, vcc
	v_sqrt_f32_e32 v149, v147
	s_nop 0
	v_add_u32_e32 v153, -1, v149
	v_add_u32_e32 v154, 1, v149
	v_fma_f32 v155, -v153, v149, v147
	v_fma_f32 v170, -v154, v149, v147
	v_cmp_ge_f32_e64 s[10:11], 0, v155
	s_nop 1
	v_cndmask_b32_e64 v149, v149, v153, s[10:11]
	v_cmp_lt_f32_e64 s[10:11], 0, v170
	s_nop 1
	v_cndmask_b32_e64 v149, v149, v154, s[10:11]
	v_mul_f32_e32 v153, 0x37800000, v149
	v_cndmask_b32_e32 v149, v149, v153, vcc
	v_cmp_class_f32_e32 vcc, v147, v168
	s_nop 1
	v_cndmask_b32_e32 v147, v149, v147, vcc
	v_div_scale_f32 v149, s[0:1], v147, v147, 1.0
	v_rcp_f32_e32 v153, v149
	v_div_scale_f32 v154, vcc, 1.0, v147, 1.0
	v_fma_f32 v155, -v149, v153, 1.0
	v_fmac_f32_e32 v153, v155, v153
	v_mul_f32_e32 v155, v154, v153
	v_fma_f32 v156, -v149, v155, v154
	v_fmac_f32_e32 v155, v156, v153
	v_fma_f32 v149, -v149, v155, v154
	v_div_fmas_f32 v149, v149, v153, v155
	v_div_fixup_f32 v170, v149, v147, 1.0
	v_pk_mul_f32 v[156:157], v[94:95], v[170:171] op_sel_hi:[1,0]
	v_pk_mul_f32 v[154:155], v[92:93], v[170:171] op_sel_hi:[1,0]
	v_pk_mul_f32 v[172:173], v[90:91], v[170:171] op_sel_hi:[1,0]
	v_pk_mul_f32 v[170:171], v[88:89], v[170:171] op_sel_hi:[1,0]
	global_store_dwordx4 v[158:159], v[154:157], off
	global_store_dwordx4 v[158:159], v[170:173], off offset:16
	s_waitcnt vmcnt(10)
; DI float rs_of(const float* ss, int row) { return 1.0f / sqrtf(ss[row] * (1.0f / DM) + EPS); }
;     DI void operator()(AccRef acc, const Unit& u, int wr, int wc, int fr, int fq) const {
;     ...
;             if (wc < 2) { float* fo = smp ? out + O_KRS : out + O_KRP + (size_t)pm * 256 * 64;
; #pragma unroll
;                 for (int ai = 0; ai < 2; ++ai)
; #pragma unroll
;                     for (int m = 0; m < 4; ++m) { const int rl = rl0 + ai * 128 + m * 16; const float r = rs_of(ss, pm * 256 + rl); float* p = fo + (size_t)rl * 64 + cc0; *(f32x4*)p = (acc[ai][0][m][0] * r); *(f32x4*)(p + 4) = (acc[ai][0][m][1] * r); } }
	v_mov_b32_e32 v147, v238
	v_add_u32_e32 v154, 0x80, v148
	v_add_u32_e32 v156, s14, v154
	v_ashrrev_i32_e32 v157, 31, v156
	v_lshl_add_u64 v[174:175], v[156:157], 2, s[38:39]
	v_ashrrev_i32_e32 v153, 31, v152
	v_lshlrev_b64 v[152:153], 8, v[152:153]
	v_lshl_add_u64 v[152:153], v[150:151], 0, v[152:153]
	v_fmamk_f32 v147, v147, 0x3a000000, v167
	v_mul_f32_e32 v149, 0x4f800000, v147
	v_cmp_gt_f32_e32 vcc, s88, v147
	s_nop 1
	v_cndmask_b32_e32 v147, v147, v149, vcc
	v_sqrt_f32_e32 v149, v147
	s_nop 0
	v_add_u32_e32 v155, -1, v149
	v_add_u32_e32 v158, 1, v149
	v_fma_f32 v159, -v155, v149, v147
	v_fma_f32 v170, -v158, v149, v147
	v_cmp_ge_f32_e64 s[10:11], 0, v159
	s_nop 1
	v_cndmask_b32_e64 v149, v149, v155, s[10:11]
	v_cmp_lt_f32_e64 s[10:11], 0, v170
	s_nop 1
	v_cndmask_b32_e64 v149, v149, v158, s[10:11]
	v_mul_f32_e32 v155, 0x37800000, v149
	v_cndmask_b32_e32 v149, v149, v155, vcc
	v_cmp_class_f32_e32 vcc, v147, v168
	s_nop 1
	v_cndmask_b32_e32 v147, v149, v147, vcc
	v_div_scale_f32 v149, s[0:1], v147, v147, 1.0
	v_rcp_f32_e32 v155, v149
	v_div_scale_f32 v156, vcc, 1.0, v147, 1.0
	v_fma_f32 v157, -v149, v155, 1.0
	v_fmac_f32_e32 v155, v157, v155
	v_mul_f32_e32 v157, v156, v155
	v_fma_f32 v158, -v149, v157, v156
	v_fmac_f32_e32 v157, v158, v155
	v_fma_f32 v149, -v149, v157, v156
	v_div_fmas_f32 v149, v149, v155, v157
	v_div_fixup_f32 v170, v149, v147, 1.0
	v_pk_mul_f32 v[158:159], v[78:79], v[170:171] op_sel_hi:[1,0]
	v_pk_mul_f32 v[156:157], v[76:77], v[170:171] op_sel_hi:[1,0]
	v_pk_mul_f32 v[172:173], v[74:75], v[170:171] op_sel_hi:[1,0]
	v_pk_mul_f32 v[170:171], v[72:73], v[170:171] op_sel_hi:[1,0]
	global_store_dwordx4 v[152:153], v[156:159], off
	global_store_dwordx4 v[152:153], v[170:173], off offset:16
	s_waitcnt vmcnt(11)
	v_mov_b32_e32 v147, v239
	v_ashrrev_i32_e32 v155, 31, v154
	v_lshlrev_b64 v[154:155], 8, v[154:155]
	v_lshl_add_u64 v[158:159], v[150:151], 0, v[154:155]
	v_add_u32_e32 v152, 0x90, v148
	v_add_u32_e32 v156, s14, v152
	v_ashrrev_i32_e32 v157, 31, v156
	v_lshl_add_u64 v[174:175], v[156:157], 2, s[38:39]
	v_fmamk_f32 v147, v147, 0x3a000000, v167
	v_mul_f32_e32 v149, 0x4f800000, v147
	v_cmp_gt_f32_e32 vcc, s88, v147
	s_nop 1
	v_cndmask_b32_e32 v147, v147, v149, vcc
	v_sqrt_f32_e32 v149, v147
	s_nop 0
	v_add_u32_e32 v153, -1, v149
	v_add_u32_e32 v154, 1, v149
	v_fma_f32 v155, -v153, v149, v147
	v_fma_f32 v170, -v154, v149, v147
	v_cmp_ge_f32_e64 s[10:11], 0, v155
	s_nop 1
	v_cndmask_b32_e64 v149, v149, v153, s[10:11]
	v_cmp_lt_f32_e64 s[10:11], 0, v170
	s_nop 1
	v_cndmask_b32_e64 v149, v149, v154, s[10:11]
	v_mul_f32_e32 v153, 0x37800000, v149
	v_cndmask_b32_e32 v149, v149, v153, vcc
	v_cmp_class_f32_e32 vcc, v147, v168
	s_nop 1
	v_cndmask_b32_e32 v147, v149, v147, vcc
	v_div_scale_f32 v149, s[0:1], v147, v147, 1.0
	v_rcp_f32_e32 v153, v149
	v_div_scale_f32 v154, vcc, 1.0, v147, 1.0
	v_fma_f32 v155, -v149, v153, 1.0
	v_fmac_f32_e32 v153, v155, v153
	v_mul_f32_e32 v155, v154, v153
	v_fma_f32 v156, -v149, v155, v154
	v_fmac_f32_e32 v155, v156, v153
	v_fma_f32 v149, -v149, v155, v154
	v_div_fmas_f32 v149, v149, v153, v155
	v_div_fixup_f32 v170, v149, v147, 1.0
	v_pk_mul_f32 v[156:157], v[62:63], v[170:171] op_sel_hi:[1,0]
	v_pk_mul_f32 v[154:155], v[60:61], v[170:171] op_sel_hi:[1,0]
	v_pk_mul_f32 v[172:173], v[58:59], v[170:171] op_sel_hi:[1,0]
	v_pk_mul_f32 v[170:171], v[56:57], v[170:171] op_sel_hi:[1,0]
	global_store_dwordx4 v[158:159], v[154:157], off
	global_store_dwordx4 v[158:159], v[170:173], off offset:16
	s_waitcnt vmcnt(12)
; DI float rs_of(const float* ss, int row) { return 1.0f / sqrtf(ss[row] * (1.0f / DM) + EPS); }
;     DI void operator()(AccRef acc, const Unit& u, int wr, int wc, int fr, int fq) const {
;     ...
;             if (wc < 2) { float* fo = smp ? out + O_KRS : out + O_KRP + (size_t)pm * 256 * 64;
; #pragma unroll
;                 for (int ai = 0; ai < 2; ++ai)
; #pragma unroll
;                     for (int m = 0; m < 4; ++m) { const int rl = rl0 + ai * 128 + m * 16; const float r = rs_of(ss, pm * 256 + rl); float* p = fo + (size_t)rl * 64 + cc0; *(f32x4*)p = (acc[ai][0][m][0] * r); *(f32x4*)(p + 4) = (acc[ai][0][m][1] * r); } }
	v_mov_b32_e32 v147, v232
	v_add_u32_e32 v154, 0xa0, v148
	v_add_u32_e32 v156, s14, v154
	v_ashrrev_i32_e32 v157, 31, v156
	v_lshl_add_u64 v[174:175], v[156:157], 2, s[38:39]
	v_ashrrev_i32_e32 v153, 31, v152
	v_lshlrev_b64 v[152:153], 8, v[152:153]
	v_lshl_add_u64 v[152:153], v[150:151], 0, v[152:153]
	v_fmamk_f32 v147, v147, 0x3a000000, v167
	v_mul_f32_e32 v149, 0x4f800000, v147
	v_cmp_gt_f32_e32 vcc, s88, v147
	s_nop 1
	v_cndmask_b32_e32 v147, v147, v149, vcc
	v_sqrt_f32_e32 v149, v147
	s_nop 0
	v_add_u32_e32 v155, -1, v149
	v_add_u32_e32 v158, 1, v149
	v_fma_f32 v159, -v155, v149, v147
	v_fma_f32 v170, -v158, v149, v147
	v_cmp_ge_f32_e64 s[10:11], 0, v159
	s_nop 1
	v_cndmask_b32_e64 v149, v149, v155, s[10:11]
	v_cmp_lt_f32_e64 s[10:11], 0, v170
	s_nop 1
	v_cndmask_b32_e64 v149, v149, v158, s[10:11]
	v_mul_f32_e32 v155, 0x37800000, v149
	v_cndmask_b32_e32 v149, v149, v155, vcc
	v_cmp_class_f32_e32 vcc, v147, v168
	s_nop 1
	v_cndmask_b32_e32 v147, v149, v147, vcc
	v_div_scale_f32 v149, s[0:1], v147, v147, 1.0
	v_rcp_f32_e32 v155, v149
	v_div_scale_f32 v156, vcc, 1.0, v147, 1.0
	v_fma_f32 v157, -v149, v155, 1.0
	v_fmac_f32_e32 v155, v157, v155
	v_mul_f32_e32 v157, v156, v155
	v_fma_f32 v158, -v149, v157, v156
	v_fmac_f32_e32 v157, v158, v155
	v_fma_f32 v149, -v149, v157, v156
	v_div_fmas_f32 v149, v149, v155, v157
	v_div_fixup_f32 v170, v149, v147, 1.0
	v_pk_mul_f32 v[158:159], v[46:47], v[170:171] op_sel_hi:[1,0]
	v_pk_mul_f32 v[156:157], v[44:45], v[170:171] op_sel_hi:[1,0]
	v_pk_mul_f32 v[172:173], v[42:43], v[170:171] op_sel_hi:[1,0]
	v_pk_mul_f32 v[170:171], v[40:41], v[170:171] op_sel_hi:[1,0]
	global_store_dwordx4 v[152:153], v[156:159], off
	global_store_dwordx4 v[152:153], v[170:173], off offset:16
	s_waitcnt vmcnt(13)
	v_mov_b32_e32 v147, v233
	v_ashrrev_i32_e32 v155, 31, v154
	v_lshlrev_b64 v[154:155], 8, v[154:155]
	v_lshl_add_u64 v[158:159], v[150:151], 0, v[154:155]
	v_add_u32_e32 v152, 0xb0, v148
	v_add_u32_e32 v156, s14, v152
	v_ashrrev_i32_e32 v157, 31, v156
	v_lshl_add_u64 v[174:175], v[156:157], 2, s[38:39]
	v_fmamk_f32 v147, v147, 0x3a000000, v167
	v_mul_f32_e32 v149, 0x4f800000, v147
	v_cmp_gt_f32_e32 vcc, s88, v147
	s_nop 1
	v_cndmask_b32_e32 v147, v147, v149, vcc
	v_sqrt_f32_e32 v149, v147
	s_nop 0
	v_add_u32_e32 v153, -1, v149
	v_add_u32_e32 v154, 1, v149
	v_fma_f32 v155, -v153, v149, v147
	v_fma_f32 v170, -v154, v149, v147
	v_cmp_ge_f32_e64 s[10:11], 0, v155
	s_nop 1
	v_cndmask_b32_e64 v149, v149, v153, s[10:11]
	v_cmp_lt_f32_e64 s[10:11], 0, v170
	s_nop 1
	v_cndmask_b32_e64 v149, v149, v154, s[10:11]
	v_mul_f32_e32 v153, 0x37800000, v149
	v_cndmask_b32_e32 v149, v149, v153, vcc
	v_cmp_class_f32_e32 vcc, v147, v168
	s_nop 1
	v_cndmask_b32_e32 v147, v149, v147, vcc
	v_div_scale_f32 v149, s[0:1], v147, v147, 1.0
	v_rcp_f32_e32 v153, v149
	v_div_scale_f32 v154, vcc, 1.0, v147, 1.0
	v_fma_f32 v155, -v149, v153, 1.0
	v_fmac_f32_e32 v153, v155, v153
	v_mul_f32_e32 v155, v154, v153
	v_fma_f32 v156, -v149, v155, v154
	v_fmac_f32_e32 v155, v156, v153
	v_fma_f32 v149, -v149, v155, v154
	v_div_fmas_f32 v149, v149, v153, v155
	v_div_fixup_f32 v170, v149, v147, 1.0
	v_pk_mul_f32 v[156:157], v[30:31], v[170:171] op_sel_hi:[1,0]
	v_pk_mul_f32 v[154:155], v[28:29], v[170:171] op_sel_hi:[1,0]
	v_pk_mul_f32 v[172:173], v[26:27], v[170:171] op_sel_hi:[1,0]
	v_pk_mul_f32 v[170:171], v[24:25], v[170:171] op_sel_hi:[1,0]
	global_store_dwordx4 v[158:159], v[154:157], off
	global_store_dwordx4 v[158:159], v[170:173], off offset:16
	s_waitcnt vmcnt(14)
	v_mov_b32_e32 v147, v234
	v_ashrrev_i32_e32 v153, 31, v152
	v_lshlrev_b64 v[152:153], 8, v[152:153]
	v_lshl_add_u64 v[158:159], v[150:151], 0, v[152:153]
	v_fmamk_f32 v147, v147, 0x3a000000, v167
	v_mul_f32_e32 v149, 0x4f800000, v147
	v_cmp_gt_f32_e32 vcc, s88, v147
	s_nop 1
	v_cndmask_b32_e32 v147, v147, v149, vcc
	v_sqrt_f32_e32 v149, v147
	s_nop 0
	v_add_u32_e32 v154, -1, v149
	v_add_u32_e32 v155, 1, v149
	v_fma_f32 v156, -v154, v149, v147
	v_fma_f32 v157, -v155, v149, v147
	v_cmp_ge_f32_e64 s[10:11], 0, v156
	s_nop 1
	v_cndmask_b32_e64 v149, v149, v154, s[10:11]
	v_cmp_lt_f32_e64 s[10:11], 0, v157
	s_nop 1
	v_cndmask_b32_e64 v149, v149, v155, s[10:11]
	v_mul_f32_e32 v154, 0x37800000, v149
	v_cndmask_b32_e32 v149, v149, v154, vcc
	v_cmp_class_f32_e32 vcc, v147, v168
	s_nop 1
	v_cndmask_b32_e32 v147, v149, v147, vcc
	v_div_scale_f32 v149, s[0:1], v147, v147, 1.0
	v_rcp_f32_e32 v154, v149
	v_div_scale_f32 v150, vcc, 1.0, v147, 1.0
	v_fma_f32 v151, -v149, v154, 1.0
	v_fmac_f32_e32 v154, v151, v154
	v_mul_f32_e32 v151, v150, v154
	v_fma_f32 v152, -v149, v151, v150
	v_fmac_f32_e32 v151, v152, v154
	v_fma_f32 v149, -v149, v151, v150
	v_div_fmas_f32 v149, v149, v154, v151
	v_div_fixup_f32 v154, v149, v147, 1.0
	v_pk_mul_f32 v[152:153], v[14:15], v[154:155] op_sel_hi:[1,0]
	v_pk_mul_f32 v[150:151], v[12:13], v[154:155] op_sel_hi:[1,0]
	v_pk_mul_f32 v[156:157], v[10:11], v[154:155] op_sel_hi:[1,0]
	v_pk_mul_f32 v[154:155], v[8:9], v[154:155] op_sel_hi:[1,0]
	global_store_dwordx4 v[158:159], v[150:153], off
	global_store_dwordx4 v[158:159], v[154:157], off offset:16

; DI float rs_of(const float* ss, int row) { return 1.0f / sqrtf(ss[row] * (1.0f / DM) + EPS); }
;     DI void operator()(AccRef acc, const Unit& u, int wr, int wc, int fr, int fq) const {
;     ...
;         } else if (pn < 17) {
;             float* fo = smp ? out + O_CKVS : out + O_CKVP + (size_t)pm * 256 * 512; const int c0 = (pn - 15) * 256 + cc0;
; #pragma unroll
;             for (int ai = 0; ai < 2; ++ai)
; #pragma unroll
;                 for (int m = 0; m < 4; ++m) { const int rl = rl0 + ai * 128 + m * 16; const float r = rs_of(ss, pm * 256 + rl);
; #pragma unroll
;                     for (int bj = 0; bj < 2; ++bj) { float* p = fo + (size_t)rl * 512 + c0 + bj * 128; *(f32x4*)p = (acc[ai][bj][m][0] * r); *(f32x4*)(p + 4) = (acc[ai][bj][m][1] * r); } }
.LBB0_534:
	s_andn2_b64 vcc, exec, s[10:11]
	s_cbranch_vccnz .LBB0_536
	s_ashr_i32 s57, s56, 31
	s_lshl_b64 s[0:1], s[56:57], 19
	v_readlane_b32 s4, v244, 11
	s_add_u32 s4, s4, s0
	s_addc_u32 s5, s92, s1
	s_and_b64 s[0:1], s[12:13], exec
	s_cselect_b32 s0, s94, s5
	s_cselect_b32 s1, s93, s4
	s_lshl_b32 s14, s56, 8
	v_add_u32_e32 v150, s14, v148
	v_ashrrev_i32_e32 v151, 31, v150
	v_lshl_add_u64 v[150:151], v[150:151], 2, s[38:39]
	v_mov_b64_e32 v[240:241], v[150:151]
	s_mov_b32 s61, 0
	global_load_dword v192, v[240:241], off
	s_mov_b32 s60, 0x40
	v_lshl_add_u64 v[240:241], v[240:241], 0, s[60:61]
	global_load_dword v236, v[240:241], off
	s_mov_b32 s60, 0x40
	v_lshl_add_u64 v[240:241], v[240:241], 0, s[60:61]
	global_load_dword v237, v[240:241], off
	s_mov_b32 s60, 0x40
	v_lshl_add_u64 v[240:241], v[240:241], 0, s[60:61]
	global_load_dword v238, v[240:241], off
	s_mov_b32 s60, 0x140
	v_lshl_add_u64 v[240:241], v[240:241], 0, s[60:61]
	global_load_dword v239, v[240:241], off
	s_mov_b32 s60, 0x40
	v_lshl_add_u64 v[240:241], v[240:241], 0, s[60:61]
	global_load_dword v232, v[240:241], off
	s_mov_b32 s60, 0x40
	v_lshl_add_u64 v[240:241], v[240:241], 0, s[60:61]
	global_load_dword v233, v[240:241], off
	s_mov_b32 s60, 0x40
	v_lshl_add_u64 v[240:241], v[240:241], 0, s[60:61]
	global_load_dword v234, v[240:241], off
	s_waitcnt vmcnt(7)
	v_mov_b32_e32 v147, v192
	v_ashrrev_i32_e32 v149, 31, v148
	v_lshlrev_b64 v[154:155], 11, v[148:149]
	v_add_u32_e32 v152, 16, v148
	s_lshl_b32 s4, s58, 8
	s_addk_i32 s4, 0xf100
	v_add_u32_e32 v156, s14, v152
	v_add_u32_e32 v158, s4, v146
	v_ashrrev_i32_e32 v157, 31, v156
	v_mov_b32_e32 v150, s1
	v_mov_b32_e32 v151, s0
	v_ashrrev_i32_e32 v159, 31, v158
	v_lshl_add_u64 v[182:183], v[156:157], 2, s[38:39]
	v_lshl_add_u64 v[150:151], v[158:159], 2, v[150:151]
	v_fmamk_f32 v147, v147, 0x3a000000, v167
	v_mul_f32_e32 v149, 0x4f800000, v147
	v_cmp_gt_f32_e32 vcc, s88, v147
	s_nop 1
	v_cndmask_b32_e32 v147, v147, v149, vcc
	v_sqrt_f32_e32 v149, v147
	s_nop 0
	v_add_u32_e32 v153, -1, v149
	v_add_u32_e32 v156, 1, v149
	v_fma_f32 v157, -v153, v149, v147
	v_fma_f32 v158, -v156, v149, v147
	v_cmp_ge_f32_e64 s[10:11], 0, v157
	s_nop 1
	v_cndmask_b32_e64 v149, v149, v153, s[10:11]
	v_cmp_lt_f32_e64 s[10:11], 0, v158
	v_lshl_add_u64 v[158:159], v[150:151], 0, v[154:155]
	s_nop 0
	v_cndmask_b32_e64 v149, v149, v156, s[10:11]
	v_mul_f32_e32 v153, 0x37800000, v149
	v_cndmask_b32_e32 v149, v149, v153, vcc
	v_cmp_class_f32_e32 vcc, v147, v168
	s_nop 1
	v_cndmask_b32_e32 v147, v149, v147, vcc
	v_div_scale_f32 v149, s[0:1], v147, v147, 1.0
	v_rcp_f32_e32 v153, v149
	v_div_scale_f32 v154, vcc, 1.0, v147, 1.0
	v_fma_f32 v155, -v149, v153, 1.0
	v_fmac_f32_e32 v153, v155, v153
	v_mul_f32_e32 v155, v154, v153
	v_fma_f32 v156, -v149, v155, v154
	v_fmac_f32_e32 v155, v156, v153
	v_fma_f32 v149, -v149, v155, v154
	v_div_fmas_f32 v149, v149, v153, v155
	v_div_fixup_f32 v178, v149, v147, 1.0
	v_pk_mul_f32 v[156:157], v[126:127], v[178:179] op_sel_hi:[1,0]
	v_pk_mul_f32 v[154:155], v[124:125], v[178:179] op_sel_hi:[1,0]
	v_pk_mul_f32 v[172:173], v[122:123], v[178:179] op_sel_hi:[1,0]
	v_pk_mul_f32 v[170:171], v[120:121], v[178:179] op_sel_hi:[1,0]
	v_pk_mul_f32 v[176:177], v[118:119], v[178:179] op_sel_hi:[1,0]
	v_pk_mul_f32 v[174:175], v[116:117], v[178:179] op_sel_hi:[1,0]
	v_pk_mul_f32 v[180:181], v[114:115], v[178:179] op_sel_hi:[1,0]
	v_pk_mul_f32 v[178:179], v[112:113], v[178:179] op_sel_hi:[1,0]
	global_store_dwordx4 v[158:159], v[154:157], off
	global_store_dwordx4 v[158:159], v[170:173], off offset:16
	global_store_dwordx4 v[158:159], v[174:177], off offset:512
	global_store_dwordx4 v[158:159], v[178:181], off offset:528
	s_waitcnt vmcnt(10)
	v_mov_b32_e32 v147, v236
	v_add_u32_e32 v154, 32, v148
	v_add_u32_e32 v156, s14, v154
	v_ashrrev_i32_e32 v157, 31, v156
	v_lshl_add_u64 v[182:183], v[156:157], 2, s[38:39]
	v_ashrrev_i32_e32 v153, 31, v152
	v_lshlrev_b64 v[152:153], 11, v[152:153]
	v_lshl_add_u64 v[152:153], v[150:151], 0, v[152:153]
	v_fmamk_f32 v147, v147, 0x3a000000, v167
	v_mul_f32_e32 v149, 0x4f800000, v147
	v_cmp_gt_f32_e32 vcc, s88, v147
	s_nop 1
	v_cndmask_b32_e32 v147, v147, v149, vcc
	v_sqrt_f32_e32 v149, v147
	s_nop 0
	v_add_u32_e32 v155, -1, v149
	v_add_u32_e32 v156, 1, v149
	v_fma_f32 v157, -v155, v149, v147
	v_fma_f32 v158, -v156, v149, v147
	v_cmp_ge_f32_e64 s[10:11], 0, v157
	s_nop 1
	v_cndmask_b32_e64 v149, v149, v155, s[10:11]
	v_cmp_lt_f32_e64 s[10:11], 0, v158
	s_nop 1
	v_cndmask_b32_e64 v149, v149, v156, s[10:11]
	v_mul_f32_e32 v155, 0x37800000, v149
	v_cndmask_b32_e32 v149, v149, v155, vcc
	v_cmp_class_f32_e32 vcc, v147, v168
	s_nop 1
	v_cndmask_b32_e32 v147, v149, v147, vcc
	v_div_scale_f32 v149, s[0:1], v147, v147, 1.0
	v_rcp_f32_e32 v155, v149
	v_div_scale_f32 v156, vcc, 1.0, v147, 1.0
	v_fma_f32 v157, -v149, v155, 1.0
	v_fmac_f32_e32 v155, v157, v155
	v_mul_f32_e32 v157, v156, v155
	v_fma_f32 v158, -v149, v157, v156
	v_fmac_f32_e32 v157, v158, v155
	v_fma_f32 v149, -v149, v157, v156
	v_div_fmas_f32 v149, v149, v155, v157
	v_div_fixup_f32 v178, v149, v147, 1.0
	v_pk_mul_f32 v[158:159], v[110:111], v[178:179] op_sel_hi:[1,0]
	v_pk_mul_f32 v[156:157], v[108:109], v[178:179] op_sel_hi:[1,0]
	v_pk_mul_f32 v[172:173], v[106:107], v[178:179] op_sel_hi:[1,0]
	v_pk_mul_f32 v[170:171], v[104:105], v[178:179] op_sel_hi:[1,0]
	v_pk_mul_f32 v[176:177], v[102:103], v[178:179] op_sel_hi:[1,0]
	v_pk_mul_f32 v[174:175], v[100:101], v[178:179] op_sel_hi:[1,0]
	v_pk_mul_f32 v[180:181], v[98:99], v[178:179] op_sel_hi:[1,0]
	v_pk_mul_f32 v[178:179], v[96:97], v[178:179] op_sel_hi:[1,0]
	global_store_dwordx4 v[152:153], v[156:159], off
	global_store_dwordx4 v[152:153], v[170:173], off offset:16
	global_store_dwordx4 v[152:153], v[174:177], off offset:512
	global_store_dwordx4 v[152:153], v[178:181], off offset:528
	s_waitcnt vmcnt(13)
; DI float rs_of(const float* ss, int row) { return 1.0f / sqrtf(ss[row] * (1.0f / DM) + EPS); }
;     DI void operator()(AccRef acc, const Unit& u, int wr, int wc, int fr, int fq) const {
;     ...
;         } else if (pn < 17) {
;             float* fo = smp ? out + O_CKVS : out + O_CKVP + (size_t)pm * 256 * 512; const int c0 = (pn - 15) * 256 + cc0;
; #pragma unroll
;             for (int ai = 0; ai < 2; ++ai)
; #pragma unroll
;                 for (int m = 0; m < 4; ++m) { const int rl = rl0 + ai * 128 + m * 16; const float r = rs_of(ss, pm * 256 + rl);
; #pragma unroll
;                     for (int bj = 0; bj < 2; ++bj) { float* p = fo + (size_t)rl * 512 + c0 + bj * 128; *(f32x4*)p = (acc[ai][bj][m][0] * r); *(f32x4*)(p + 4) = (acc[ai][bj][m][1] * r); } }
	v_mov_b32_e32 v147, v237
	v_add_u32_e32 v152, 48, v148
	v_add_u32_e32 v156, s14, v152
	v_ashrrev_i32_e32 v157, 31, v156
	v_lshl_add_u64 v[158:159], v[156:157], 2, s[38:39]
	v_ashrrev_i32_e32 v155, 31, v154
	v_lshlrev_b64 v[154:155], 11, v[154:155]
	v_lshl_add_u64 v[182:183], v[150:151], 0, v[154:155]
	v_fmamk_f32 v147, v147, 0x3a000000, v167
	v_mul_f32_e32 v149, 0x4f800000, v147
	v_cmp_gt_f32_e32 vcc, s88, v147
	s_nop 1
	v_cndmask_b32_e32 v147, v147, v149, vcc
	v_sqrt_f32_e32 v149, v147
	s_nop 0
	v_add_u32_e32 v153, -1, v149
	v_add_u32_e32 v156, 1, v149
	v_fma_f32 v157, -v153, v149, v147
	v_fma_f32 v170, -v156, v149, v147
	v_cmp_ge_f32_e64 s[10:11], 0, v157
	s_nop 1
	v_cndmask_b32_e64 v149, v149, v153, s[10:11]
	v_cmp_lt_f32_e64 s[10:11], 0, v170
	s_nop 1
	v_cndmask_b32_e64 v149, v149, v156, s[10:11]
	v_mul_f32_e32 v153, 0x37800000, v149
	v_cndmask_b32_e32 v149, v149, v153, vcc
	v_cmp_class_f32_e32 vcc, v147, v168
	s_nop 1
	v_cndmask_b32_e32 v147, v149, v147, vcc
	v_div_scale_f32 v149, s[0:1], v147, v147, 1.0
	v_rcp_f32_e32 v153, v149
	v_div_scale_f32 v154, vcc, 1.0, v147, 1.0
	v_fma_f32 v155, -v149, v153, 1.0
	v_fmac_f32_e32 v153, v155, v153
	v_mul_f32_e32 v155, v154, v153
	v_fma_f32 v156, -v149, v155, v154
	v_fmac_f32_e32 v155, v156, v153
	v_fma_f32 v149, -v149, v155, v154
	v_div_fmas_f32 v149, v149, v153, v155
	v_div_fixup_f32 v178, v149, v147, 1.0
	v_pk_mul_f32 v[156:157], v[94:95], v[178:179] op_sel_hi:[1,0]
	v_pk_mul_f32 v[154:155], v[92:93], v[178:179] op_sel_hi:[1,0]
	v_pk_mul_f32 v[172:173], v[90:91], v[178:179] op_sel_hi:[1,0]
	v_pk_mul_f32 v[170:171], v[88:89], v[178:179] op_sel_hi:[1,0]
	v_pk_mul_f32 v[176:177], v[86:87], v[178:179] op_sel_hi:[1,0]
	v_pk_mul_f32 v[174:175], v[84:85], v[178:179] op_sel_hi:[1,0]
	v_pk_mul_f32 v[180:181], v[82:83], v[178:179] op_sel_hi:[1,0]
	v_pk_mul_f32 v[178:179], v[80:81], v[178:179] op_sel_hi:[1,0]
	global_store_dwordx4 v[182:183], v[154:157], off
	global_store_dwordx4 v[182:183], v[170:173], off offset:16
	global_store_dwordx4 v[182:183], v[174:177], off offset:512
	global_store_dwordx4 v[182:183], v[178:181], off offset:528
	s_waitcnt vmcnt(16)
	v_mov_b32_e32 v147, v238
	v_add_u32_e32 v154, 0x80, v148
	v_add_u32_e32 v156, s14, v154
	v_ashrrev_i32_e32 v157, 31, v156
	v_lshl_add_u64 v[182:183], v[156:157], 2, s[38:39]
	v_ashrrev_i32_e32 v153, 31, v152
	v_lshlrev_b64 v[152:153], 11, v[152:153]
	v_lshl_add_u64 v[152:153], v[150:151], 0, v[152:153]
	v_fmamk_f32 v147, v147, 0x3a000000, v167
	v_mul_f32_e32 v149, 0x4f800000, v147
	v_cmp_gt_f32_e32 vcc, s88, v147
	s_nop 1
	v_cndmask_b32_e32 v147, v147, v149, vcc
	v_sqrt_f32_e32 v149, v147
	s_nop 0
	v_add_u32_e32 v155, -1, v149
	v_add_u32_e32 v156, 1, v149
	v_fma_f32 v157, -v155, v149, v147
	v_fma_f32 v158, -v156, v149, v147
	v_cmp_ge_f32_e64 s[10:11], 0, v157
	s_nop 1
	v_cndmask_b32_e64 v149, v149, v155, s[10:11]
	v_cmp_lt_f32_e64 s[10:11], 0, v158
	s_nop 1
	v_cndmask_b32_e64 v149, v149, v156, s[10:11]
	v_mul_f32_e32 v155, 0x37800000, v149
	v_cndmask_b32_e32 v149, v149, v155, vcc
	v_cmp_class_f32_e32 vcc, v147, v168
	s_nop 1
	v_cndmask_b32_e32 v147, v149, v147, vcc
	v_div_scale_f32 v149, s[0:1], v147, v147, 1.0
	v_rcp_f32_e32 v155, v149
	v_div_scale_f32 v156, vcc, 1.0, v147, 1.0
	v_fma_f32 v157, -v149, v155, 1.0
	v_fmac_f32_e32 v155, v157, v155
	v_mul_f32_e32 v157, v156, v155
	v_fma_f32 v158, -v149, v157, v156
	v_fmac_f32_e32 v157, v158, v155
	v_fma_f32 v149, -v149, v157, v156
	v_div_fmas_f32 v149, v149, v155, v157
	v_div_fixup_f32 v178, v149, v147, 1.0
	v_pk_mul_f32 v[158:159], v[78:79], v[178:179] op_sel_hi:[1,0]
	v_pk_mul_f32 v[156:157], v[76:77], v[178:179] op_sel_hi:[1,0]
	v_pk_mul_f32 v[172:173], v[74:75], v[178:179] op_sel_hi:[1,0]
	v_pk_mul_f32 v[170:171], v[72:73], v[178:179] op_sel_hi:[1,0]
	v_pk_mul_f32 v[176:177], v[70:71], v[178:179] op_sel_hi:[1,0]
	v_pk_mul_f32 v[174:175], v[68:69], v[178:179] op_sel_hi:[1,0]
	v_pk_mul_f32 v[180:181], v[66:67], v[178:179] op_sel_hi:[1,0]
	v_pk_mul_f32 v[178:179], v[64:65], v[178:179] op_sel_hi:[1,0]
	global_store_dwordx4 v[152:153], v[156:159], off
	global_store_dwordx4 v[152:153], v[170:173], off offset:16
	global_store_dwordx4 v[152:153], v[174:177], off offset:512
	global_store_dwordx4 v[152:153], v[178:181], off offset:528
	s_waitcnt vmcnt(19)
	v_mov_b32_e32 v147, v239
	v_add_u32_e32 v152, 0x90, v148
	v_add_u32_e32 v156, s14, v152
	v_ashrrev_i32_e32 v157, 31, v156
	v_lshl_add_u64 v[158:159], v[156:157], 2, s[38:39]
	v_ashrrev_i32_e32 v155, 31, v154
	v_lshlrev_b64 v[154:155], 11, v[154:155]
	v_lshl_add_u64 v[182:183], v[150:151], 0, v[154:155]
	v_fmamk_f32 v147, v147, 0x3a000000, v167
	v_mul_f32_e32 v149, 0x4f800000, v147
	v_cmp_gt_f32_e32 vcc, s88, v147
	s_nop 1
	v_cndmask_b32_e32 v147, v147, v149, vcc
	v_sqrt_f32_e32 v149, v147
	s_nop 0
	v_add_u32_e32 v153, -1, v149
	v_add_u32_e32 v156, 1, v149
	v_fma_f32 v157, -v153, v149, v147
	v_fma_f32 v170, -v156, v149, v147
	v_cmp_ge_f32_e64 s[10:11], 0, v157
	s_nop 1
	v_cndmask_b32_e64 v149, v149, v153, s[10:11]
	v_cmp_lt_f32_e64 s[10:11], 0, v170
	s_nop 1
	v_cndmask_b32_e64 v149, v149, v156, s[10:11]
	v_mul_f32_e32 v153, 0x37800000, v149
	v_cndmask_b32_e32 v149, v149, v153, vcc
	v_cmp_class_f32_e32 vcc, v147, v168
	s_nop 1
	v_cndmask_b32_e32 v147, v149, v147, vcc
	v_div_scale_f32 v149, s[0:1], v147, v147, 1.0
	v_rcp_f32_e32 v153, v149
	v_div_scale_f32 v154, vcc, 1.0, v147, 1.0
	v_fma_f32 v155, -v149, v153, 1.0
	v_fmac_f32_e32 v153, v155, v153
	v_mul_f32_e32 v155, v154, v153
	v_fma_f32 v156, -v149, v155, v154
	v_fmac_f32_e32 v155, v156, v153
	v_fma_f32 v149, -v149, v155, v154
	v_div_fmas_f32 v149, v149, v153, v155
	v_div_fixup_f32 v178, v149, v147, 1.0
	v_pk_mul_f32 v[156:157], v[62:63], v[178:179] op_sel_hi:[1,0]
	v_pk_mul_f32 v[154:155], v[60:61], v[178:179] op_sel_hi:[1,0]
	v_pk_mul_f32 v[172:173], v[58:59], v[178:179] op_sel_hi:[1,0]
	v_pk_mul_f32 v[170:171], v[56:57], v[178:179] op_sel_hi:[1,0]
	v_pk_mul_f32 v[176:177], v[54:55], v[178:179] op_sel_hi:[1,0]
	v_pk_mul_f32 v[174:175], v[52:53], v[178:179] op_sel_hi:[1,0]
	v_pk_mul_f32 v[180:181], v[50:51], v[178:179] op_sel_hi:[1,0]
	v_pk_mul_f32 v[178:179], v[48:49], v[178:179] op_sel_hi:[1,0]
	global_store_dwordx4 v[182:183], v[154:157], off
	global_store_dwordx4 v[182:183], v[170:173], off offset:16
	global_store_dwordx4 v[182:183], v[174:177], off offset:512
	global_store_dwordx4 v[182:183], v[178:181], off offset:528
	s_waitcnt vmcnt(22)
; DI float rs_of(const float* ss, int row) { return 1.0f / sqrtf(ss[row] * (1.0f / DM) + EPS); }
;     DI void operator()(AccRef acc, const Unit& u, int wr, int wc, int fr, int fq) const {
;     ...
;         } else if (pn < 17) {
;             float* fo = smp ? out + O_CKVS : out + O_CKVP + (size_t)pm * 256 * 512; const int c0 = (pn - 15) * 256 + cc0;
; #pragma unroll
;             for (int ai = 0; ai < 2; ++ai)
; #pragma unroll
;                 for (int m = 0; m < 4; ++m) { const int rl = rl0 + ai * 128 + m * 16; const float r = rs_of(ss, pm * 256 + rl);
; #pragma unroll
;                     for (int bj = 0; bj < 2; ++bj) { float* p = fo + (size_t)rl * 512 + c0 + bj * 128; *(f32x4*)p = (acc[ai][bj][m][0] * r); *(f32x4*)(p + 4) = (acc[ai][bj][m][1] * r); } }
	v_mov_b32_e32 v147, v232
	v_add_u32_e32 v154, 0xa0, v148
	v_add_u32_e32 v156, s14, v154
	v_ashrrev_i32_e32 v157, 31, v156
	v_lshl_add_u64 v[182:183], v[156:157], 2, s[38:39]
	v_ashrrev_i32_e32 v153, 31, v152
	v_lshlrev_b64 v[152:153], 11, v[152:153]
	v_lshl_add_u64 v[152:153], v[150:151], 0, v[152:153]
	v_fmamk_f32 v147, v147, 0x3a000000, v167
	v_mul_f32_e32 v149, 0x4f800000, v147
	v_cmp_gt_f32_e32 vcc, s88, v147
	s_nop 1
	v_cndmask_b32_e32 v147, v147, v149, vcc
	v_sqrt_f32_e32 v149, v147
	s_nop 0
	v_add_u32_e32 v155, -1, v149
	v_add_u32_e32 v156, 1, v149
	v_fma_f32 v157, -v155, v149, v147
	v_fma_f32 v158, -v156, v149, v147
	v_cmp_ge_f32_e64 s[10:11], 0, v157
	s_nop 1
	v_cndmask_b32_e64 v149, v149, v155, s[10:11]
	v_cmp_lt_f32_e64 s[10:11], 0, v158
	s_nop 1
	v_cndmask_b32_e64 v149, v149, v156, s[10:11]
	v_mul_f32_e32 v155, 0x37800000, v149
	v_cndmask_b32_e32 v149, v149, v155, vcc
	v_cmp_class_f32_e32 vcc, v147, v168
	s_nop 1
	v_cndmask_b32_e32 v147, v149, v147, vcc
	v_div_scale_f32 v149, s[0:1], v147, v147, 1.0
	v_rcp_f32_e32 v155, v149
	v_div_scale_f32 v156, vcc, 1.0, v147, 1.0
	v_fma_f32 v157, -v149, v155, 1.0
	v_fmac_f32_e32 v155, v157, v155
	v_mul_f32_e32 v157, v156, v155
	v_fma_f32 v158, -v149, v157, v156
	v_fmac_f32_e32 v157, v158, v155
	v_fma_f32 v149, -v149, v157, v156
	v_div_fmas_f32 v149, v149, v155, v157
	v_div_fixup_f32 v178, v149, v147, 1.0
	v_pk_mul_f32 v[158:159], v[46:47], v[178:179] op_sel_hi:[1,0]
	v_pk_mul_f32 v[156:157], v[44:45], v[178:179] op_sel_hi:[1,0]
	v_pk_mul_f32 v[172:173], v[42:43], v[178:179] op_sel_hi:[1,0]
	v_pk_mul_f32 v[170:171], v[40:41], v[178:179] op_sel_hi:[1,0]
	v_pk_mul_f32 v[176:177], v[38:39], v[178:179] op_sel_hi:[1,0]
	v_pk_mul_f32 v[174:175], v[36:37], v[178:179] op_sel_hi:[1,0]
	v_pk_mul_f32 v[180:181], v[34:35], v[178:179] op_sel_hi:[1,0]
	v_pk_mul_f32 v[178:179], v[32:33], v[178:179] op_sel_hi:[1,0]
	global_store_dwordx4 v[152:153], v[156:159], off
	global_store_dwordx4 v[152:153], v[170:173], off offset:16
	global_store_dwordx4 v[152:153], v[174:177], off offset:512
	global_store_dwordx4 v[152:153], v[178:181], off offset:528
	s_waitcnt vmcnt(25)
	v_mov_b32_e32 v147, v233
	v_add_u32_e32 v152, 0xb0, v148
	v_add_u32_e32 v156, s14, v152
	v_ashrrev_i32_e32 v157, 31, v156
	v_lshl_add_u64 v[158:159], v[156:157], 2, s[38:39]
	v_ashrrev_i32_e32 v155, 31, v154
	v_lshlrev_b64 v[154:155], 11, v[154:155]
	v_lshl_add_u64 v[182:183], v[150:151], 0, v[154:155]
	v_fmamk_f32 v147, v147, 0x3a000000, v167
	v_mul_f32_e32 v149, 0x4f800000, v147
	v_cmp_gt_f32_e32 vcc, s88, v147
	s_nop 1
	v_cndmask_b32_e32 v147, v147, v149, vcc
	v_sqrt_f32_e32 v149, v147
	s_nop 0
	v_add_u32_e32 v153, -1, v149
	v_add_u32_e32 v156, 1, v149
	v_fma_f32 v157, -v153, v149, v147
	v_fma_f32 v170, -v156, v149, v147
	v_cmp_ge_f32_e64 s[10:11], 0, v157
	s_nop 1
	v_cndmask_b32_e64 v149, v149, v153, s[10:11]
	v_cmp_lt_f32_e64 s[10:11], 0, v170
	s_nop 1
	v_cndmask_b32_e64 v149, v149, v156, s[10:11]
	v_mul_f32_e32 v153, 0x37800000, v149
	v_cndmask_b32_e32 v149, v149, v153, vcc
	v_cmp_class_f32_e32 vcc, v147, v168
	s_nop 1
	v_cndmask_b32_e32 v147, v149, v147, vcc
	v_div_scale_f32 v149, s[0:1], v147, v147, 1.0
	v_rcp_f32_e32 v153, v149
	v_div_scale_f32 v154, vcc, 1.0, v147, 1.0
	v_fma_f32 v155, -v149, v153, 1.0
	v_fmac_f32_e32 v153, v155, v153
	v_mul_f32_e32 v155, v154, v153
	v_fma_f32 v156, -v149, v155, v154
	v_fmac_f32_e32 v155, v156, v153
	v_fma_f32 v149, -v149, v155, v154
	v_div_fmas_f32 v149, v149, v153, v155
	v_div_fixup_f32 v178, v149, v147, 1.0
	v_pk_mul_f32 v[156:157], v[30:31], v[178:179] op_sel_hi:[1,0]
	v_pk_mul_f32 v[154:155], v[28:29], v[178:179] op_sel_hi:[1,0]
	v_pk_mul_f32 v[172:173], v[26:27], v[178:179] op_sel_hi:[1,0]
	v_pk_mul_f32 v[170:171], v[24:25], v[178:179] op_sel_hi:[1,0]
	v_pk_mul_f32 v[176:177], v[22:23], v[178:179] op_sel_hi:[1,0]
	v_pk_mul_f32 v[174:175], v[20:21], v[178:179] op_sel_hi:[1,0]
	v_pk_mul_f32 v[180:181], v[18:19], v[178:179] op_sel_hi:[1,0]
	v_pk_mul_f32 v[178:179], v[16:17], v[178:179] op_sel_hi:[1,0]
	global_store_dwordx4 v[182:183], v[154:157], off
	global_store_dwordx4 v[182:183], v[170:173], off offset:16
	global_store_dwordx4 v[182:183], v[174:177], off offset:512
	global_store_dwordx4 v[182:183], v[178:181], off offset:528
	s_waitcnt vmcnt(28)
	v_mov_b32_e32 v147, v234
	v_ashrrev_i32_e32 v153, 31, v152
	v_lshlrev_b64 v[152:153], 11, v[152:153]
	v_lshl_add_u64 v[158:159], v[150:151], 0, v[152:153]
	v_fmamk_f32 v147, v147, 0x3a000000, v167
	v_mul_f32_e32 v149, 0x4f800000, v147
	v_cmp_gt_f32_e32 vcc, s88, v147
	s_nop 1
	v_cndmask_b32_e32 v147, v147, v149, vcc
	v_sqrt_f32_e32 v149, v147
	s_nop 0
	v_add_u32_e32 v154, -1, v149
	v_add_u32_e32 v155, 1, v149
	v_fma_f32 v156, -v154, v149, v147
	v_fma_f32 v157, -v155, v149, v147
	v_cmp_ge_f32_e64 s[10:11], 0, v156
	s_nop 1
	v_cndmask_b32_e64 v149, v149, v154, s[10:11]
	v_cmp_lt_f32_e64 s[10:11], 0, v157
	s_nop 1
	v_cndmask_b32_e64 v149, v149, v155, s[10:11]
	v_mul_f32_e32 v154, 0x37800000, v149
	v_cndmask_b32_e32 v149, v149, v154, vcc
	v_cmp_class_f32_e32 vcc, v147, v168
	s_nop 1
	v_cndmask_b32_e32 v147, v149, v147, vcc
	v_div_scale_f32 v149, s[0:1], v147, v147, 1.0
	v_rcp_f32_e32 v154, v149
	v_div_scale_f32 v150, vcc, 1.0, v147, 1.0
	v_fma_f32 v151, -v149, v154, 1.0
	v_fmac_f32_e32 v154, v151, v154
	v_mul_f32_e32 v151, v150, v154
	v_fma_f32 v152, -v149, v151, v150
	v_fmac_f32_e32 v151, v152, v154
	v_fma_f32 v149, -v149, v151, v150
	v_div_fmas_f32 v149, v149, v154, v151
	v_div_fixup_f32 v174, v149, v147, 1.0
	v_pk_mul_f32 v[152:153], v[14:15], v[174:175] op_sel_hi:[1,0]
	v_pk_mul_f32 v[150:151], v[12:13], v[174:175] op_sel_hi:[1,0]
	v_pk_mul_f32 v[156:157], v[10:11], v[174:175] op_sel_hi:[1,0]
	v_pk_mul_f32 v[154:155], v[8:9], v[174:175] op_sel_hi:[1,0]
	v_pk_mul_f32 v[172:173], v[6:7], v[174:175] op_sel_hi:[1,0]
	v_pk_mul_f32 v[170:171], v[4:5], v[174:175] op_sel_hi:[1,0]
	v_pk_mul_f32 v[176:177], v[2:3], v[174:175] op_sel_hi:[1,0]
	v_pk_mul_f32 v[174:175], v[0:1], v[174:175] op_sel_hi:[1,0]
	global_store_dwordx4 v[158:159], v[150:153], off
	global_store_dwordx4 v[158:159], v[154:157], off offset:16
	global_store_dwordx4 v[158:159], v[170:173], off offset:512
	global_store_dwordx4 v[158:159], v[174:177], off offset:528

; DI float rs_of(const float* ss, int row) { return 1.0f / sqrtf(ss[row] * (1.0f / DM) + EPS); }
; DI u32x4 pack8(f32x4 a, f32x4 b) { u32x4 w; w.x = cvt_pk_bf16(a[0], a[1]); w.y = cvt_pk_bf16(a[2], a[3]); w.z = cvt_pk_bf16(b[0], b[1]); w.w = cvt_pk_bf16(b[2], b[3]); return w; }
;     DI void operator()(AccRef acc, const Unit& u, int wr, int wc, int fr, int fq) const {
;     ...
;         if (pn < 4 || (pn >= 12 && pn < 15)) {
;             bf16_t* dst = (pn < 4) ? QA + pn * 256 : CQ + (pn - 12) * 256; const int ld = (pn < 4) ? 1024 : 768;
; #pragma unroll
;             for (int ai = 0; ai < 2; ++ai)
; #pragma unroll
;                 for (int m = 0; m < 4; ++m) { const size_t row = (size_t)pm * 256 + rl0 + ai * 128 + m * 16; const float r = rs_of(ss, (int)row) * ((pn < 4) ? 0.08838834764831845f * LOG2E : 1.0f);
; #pragma unroll
;                     for (int bj = 0; bj < 2; ++bj) *(u32x4*)(dst + row * ld + cc0 + bj * 128) = pack8((acc[ai][bj][m][0] * r), (acc[ai][bj][m][1] * r)); }
.LBB0_684:
	s_andn2_b64 vcc, exec, s[10:11]
	s_cbranch_vccnz .LBB0_519
	s_lshl_b32 s0, s58, 8
	s_ashr_i32 s1, s0, 31
	s_lshl_b64 s[4:5], s[0:1], 1
	s_add_u32 s4, s78, s4
	s_mov_b32 s1, s29
	s_addc_u32 s5, s79, s5
	s_lshl_b64 s[0:1], s[0:1], 1
	s_add_u32 s0, s22, s0
	s_addc_u32 s1, s23, s1
	s_add_u32 s10, s0, 0x23a01800
	s_addc_u32 s11, s1, 0
	s_and_b64 s[0:1], s[8:9], exec
	s_cselect_b32 s0, s69, 0x300
	s_cselect_b32 s1, s5, s11
	s_cselect_b32 s10, s4, s10
	s_ashr_i32 s57, s56, 31
	s_lshl_b64 s[4:5], s[56:57], 8
	v_ashrrev_i32_e32 v149, 31, v148
	v_lshl_add_u64 v[148:149], s[4:5], 0, v[148:149]
	v_mov_b32_e32 v137, v148
	v_ashrrev_i64 v[150:151], 30, v[136:137]
	v_lshl_add_u64 v[150:151], s[38:39], 0, v[150:151]
	v_mov_b64_e32 v[240:241], v[150:151]
	s_mov_b32 s13, 0
	global_load_dword v192, v[240:241], off
	s_mov_b32 s12, 0x40
	v_lshl_add_u64 v[240:241], v[240:241], 0, s[12:13]
	global_load_dword v236, v[240:241], off
	s_mov_b32 s12, 0x40
	v_lshl_add_u64 v[240:241], v[240:241], 0, s[12:13]
	global_load_dword v237, v[240:241], off
	s_mov_b32 s12, 0x40
	v_lshl_add_u64 v[240:241], v[240:241], 0, s[12:13]
	global_load_dword v238, v[240:241], off
	s_mov_b32 s12, 0x140
	v_lshl_add_u64 v[240:241], v[240:241], 0, s[12:13]
	global_load_dword v239, v[240:241], off
	s_mov_b32 s12, 0x40
	v_lshl_add_u64 v[240:241], v[240:241], 0, s[12:13]
	global_load_dword v232, v[240:241], off
	s_mov_b32 s12, 0x40
	v_lshl_add_u64 v[240:241], v[240:241], 0, s[12:13]
	global_load_dword v233, v[240:241], off
	s_mov_b32 s12, 0x40
	v_lshl_add_u64 v[240:241], v[240:241], 0, s[12:13]
	global_load_dword v234, v[240:241], off
	s_waitcnt vmcnt(7)
	v_mov_b32_e32 v137, v192
	v_cndmask_b32_e64 v150, 1.0, v169, s[8:9]
	v_ashrrev_i32_e32 v147, 31, v146
	v_mov_b32_e32 v152, s10
	v_mov_b32_e32 v153, s1
	v_lshl_add_u64 v[146:147], v[146:147], 1, v[152:153]
	v_mad_u64_u32 v[152:153], s[4:5], v148, s0, 0
	v_mad_i32_i24 v153, v149, s0, v153
	v_lshl_add_u64 v[152:153], v[152:153], 1, v[146:147]
	s_lshl_b32 s28, s0, 4
	s_mov_b32 s1, s29
	v_fmamk_f32 v137, v137, 0x3a000000, v167
	v_mul_f32_e32 v151, 0x4f800000, v137
	v_cmp_gt_f32_e32 vcc, s88, v137
	s_nop 1
	v_cndmask_b32_e32 v151, v137, v151, vcc
	v_sqrt_f32_e32 v156, v151
	v_add_u32_e32 v137, 16, v148
	v_ashrrev_i64 v[154:155], 30, v[136:137]
	v_lshl_add_u64 v[154:155], s[38:39], 0, v[154:155]
	v_add_u32_e32 v137, -1, v156
	v_add_u32_e32 v157, 1, v156
	v_fma_f32 v158, -v137, v156, v151
	v_fma_f32 v159, -v157, v156, v151
	v_cmp_ge_f32_e64 s[8:9], 0, v158
	s_nop 1
	v_cndmask_b32_e64 v137, v156, v137, s[8:9]
	v_cmp_lt_f32_e64 s[8:9], 0, v159
	s_nop 1
	v_cndmask_b32_e64 v137, v137, v157, s[8:9]
	v_mul_f32_e32 v156, 0x37800000, v137
	v_cndmask_b32_e32 v137, v137, v156, vcc
	v_cmp_class_f32_e32 vcc, v151, v168
	s_nop 1
	v_cndmask_b32_e32 v137, v137, v151, vcc
	v_div_scale_f32 v151, s[4:5], v137, v137, 1.0
	v_rcp_f32_e32 v156, v151
	v_div_scale_f32 v157, vcc, 1.0, v137, 1.0
	v_fma_f32 v158, -v151, v156, 1.0
	v_fmac_f32_e32 v156, v158, v156
	v_mul_f32_e32 v158, v157, v156
	v_fma_f32 v159, -v151, v158, v157
	v_fmac_f32_e32 v158, v159, v156
	v_fma_f32 v151, -v151, v158, v157
	v_div_fmas_f32 v151, v151, v156, v158
	v_div_fixup_f32 v137, v151, v137, 1.0
	v_mul_f32_e32 v156, v150, v137
	v_pk_mul_f32 v[126:127], v[126:127], v[156:157] op_sel_hi:[1,0]
	v_pk_mul_f32 v[124:125], v[124:125], v[156:157] op_sel_hi:[1,0]
	v_pk_mul_f32 v[122:123], v[122:123], v[156:157] op_sel_hi:[1,0]
	v_pk_mul_f32 v[120:121], v[120:121], v[156:157] op_sel_hi:[1,0]
	v_pk_mul_f32 v[118:119], v[118:119], v[156:157] op_sel_hi:[1,0]
	v_pk_mul_f32 v[116:117], v[116:117], v[156:157] op_sel_hi:[1,0]
	v_pk_mul_f32 v[158:159], v[114:115], v[156:157] op_sel_hi:[1,0]
	v_pk_mul_f32 v[156:157], v[112:113], v[156:157] op_sel_hi:[1,0]
	v_cvt_pk_bf16_f32 v112, v124, v125
	v_cvt_pk_bf16_f32 v113, v126, v127
	v_cvt_pk_bf16_f32 v114, v120, v121
	v_cvt_pk_bf16_f32 v115, v122, v123
	global_store_dwordx4 v[152:153], v[112:115], off
	v_add_u32_e32 v137, 32, v148
	s_nop 0
	v_cvt_pk_bf16_f32 v112, v116, v117
	v_cvt_pk_bf16_f32 v113, v118, v119
	v_cvt_pk_bf16_f32 v114, v156, v157
	v_cvt_pk_bf16_f32 v115, v158, v159
	global_store_dwordx4 v[152:153], v[112:115], off offset:256
	s_waitcnt vmcnt(8)
	s_nop 1
	v_mov_b32_e32 v114, v236
	v_ashrrev_i64 v[116:117], 30, v[136:137]
	v_mov_b64_e32 v[112:113], s[28:29]
	v_mad_u64_u32 v[112:113], s[4:5], v148, s0, v[112:113]
	v_mad_i32_i24 v113, v149, s0, v113
	v_lshl_add_u64 v[116:117], s[38:39], 0, v[116:117]
	v_add_u32_e32 v137, 48, v148
	s_mulk_i32 s0, 0x50
	v_fmamk_f32 v114, v114, 0x3a000000, v167
	v_mul_f32_e32 v115, 0x4f800000, v114
	v_cmp_gt_f32_e32 vcc, s88, v114
	s_nop 1
	v_cndmask_b32_e32 v118, v114, v115, vcc
	v_sqrt_f32_e32 v119, v118
	v_lshl_add_u64 v[114:115], v[112:113], 1, v[146:147]
	v_add_u32_e32 v120, -1, v119
	v_add_u32_e32 v121, 1, v119
	v_fma_f32 v122, -v120, v119, v118
	v_fma_f32 v123, -v121, v119, v118
	v_cmp_ge_f32_e64 s[8:9], 0, v122
	s_nop 1
	v_cndmask_b32_e64 v119, v119, v120, s[8:9]
	v_cmp_lt_f32_e64 s[8:9], 0, v123
	s_nop 1
	v_cndmask_b32_e64 v119, v119, v121, s[8:9]
	v_mul_f32_e32 v120, 0x37800000, v119
	v_cndmask_b32_e32 v119, v119, v120, vcc
	v_cmp_class_f32_e32 vcc, v118, v168
	s_nop 1
	v_cndmask_b32_e32 v118, v119, v118, vcc
	v_div_scale_f32 v119, s[4:5], v118, v118, 1.0
	v_rcp_f32_e32 v120, v119
	v_div_scale_f32 v121, vcc, 1.0, v118, 1.0
	v_fma_f32 v122, -v119, v120, 1.0
	v_fmac_f32_e32 v120, v122, v120
	v_mul_f32_e32 v122, v121, v120
	v_fma_f32 v123, -v119, v122, v121
	v_fmac_f32_e32 v122, v123, v120
	v_fma_f32 v119, -v119, v122, v121
	v_div_fmas_f32 v119, v119, v120, v122
	v_div_fixup_f32 v118, v119, v118, 1.0
	v_mul_f32_e32 v118, v150, v118
	v_pk_mul_f32 v[110:111], v[110:111], v[118:119] op_sel_hi:[1,0]
	v_pk_mul_f32 v[108:109], v[108:109], v[118:119] op_sel_hi:[1,0]
	v_pk_mul_f32 v[106:107], v[106:107], v[118:119] op_sel_hi:[1,0]
	v_pk_mul_f32 v[104:105], v[104:105], v[118:119] op_sel_hi:[1,0]
	v_pk_mul_f32 v[102:103], v[102:103], v[118:119] op_sel_hi:[1,0]
	v_pk_mul_f32 v[100:101], v[100:101], v[118:119] op_sel_hi:[1,0]
	v_pk_mul_f32 v[120:121], v[98:99], v[118:119] op_sel_hi:[1,0]
	v_pk_mul_f32 v[118:119], v[96:97], v[118:119] op_sel_hi:[1,0]
	v_cvt_pk_bf16_f32 v96, v108, v109
	v_cvt_pk_bf16_f32 v97, v110, v111
	v_cvt_pk_bf16_f32 v98, v104, v105
	v_cvt_pk_bf16_f32 v99, v106, v107
	global_store_dwordx4 v[114:115], v[96:99], off
	s_nop 1
	v_cvt_pk_bf16_f32 v96, v100, v101
	v_cvt_pk_bf16_f32 v97, v102, v103
	v_cvt_pk_bf16_f32 v98, v118, v119
	v_cvt_pk_bf16_f32 v99, v120, v121
	global_store_dwordx4 v[114:115], v[96:99], off offset:256
	s_waitcnt vmcnt(9)
; DI float rs_of(const float* ss, int row) { return 1.0f / sqrtf(ss[row] * (1.0f / DM) + EPS); }
; DI u32x4 pack8(f32x4 a, f32x4 b) { u32x4 w; w.x = cvt_pk_bf16(a[0], a[1]); w.y = cvt_pk_bf16(a[2], a[3]); w.z = cvt_pk_bf16(b[0], b[1]); w.w = cvt_pk_bf16(b[2], b[3]); return w; }
;     DI void operator()(AccRef acc, const Unit& u, int wr, int wc, int fr, int fq) const {
;     ...
;         if (pn < 4 || (pn >= 12 && pn < 15)) {
;             bf16_t* dst = (pn < 4) ? QA + pn * 256 : CQ + (pn - 12) * 256; const int ld = (pn < 4) ? 1024 : 768;
; #pragma unroll
;             for (int ai = 0; ai < 2; ++ai)
; #pragma unroll
;                 for (int m = 0; m < 4; ++m) { const size_t row = (size_t)pm * 256 + rl0 + ai * 128 + m * 16; const float r = rs_of(ss, (int)row) * ((pn < 4) ? 0.08838834764831845f * LOG2E : 1.0f);
; #pragma unroll
;                     for (int bj = 0; bj < 2; ++bj) *(u32x4*)(dst + row * ld + cc0 + bj * 128) = pack8((acc[ai][bj][m][0] * r), (acc[ai][bj][m][1] * r)); }
	s_nop 1
	v_mov_b32_e32 v98, v237
	v_ashrrev_i64 v[100:101], 30, v[136:137]
	v_lshl_add_u64 v[96:97], v[112:113], 0, s[28:29]
	v_lshl_add_u64 v[100:101], s[38:39], 0, v[100:101]
	v_add_u32_e32 v137, 0x80, v148
	v_fmamk_f32 v98, v98, 0x3a000000, v167
	v_mul_f32_e32 v99, 0x4f800000, v98
	v_cmp_gt_f32_e32 vcc, s88, v98
	s_nop 1
	v_cndmask_b32_e32 v102, v98, v99, vcc
	v_sqrt_f32_e32 v103, v102
	v_lshl_add_u64 v[98:99], v[96:97], 1, v[146:147]
	v_add_u32_e32 v104, -1, v103
	v_add_u32_e32 v105, 1, v103
	v_fma_f32 v106, -v104, v103, v102
	v_fma_f32 v107, -v105, v103, v102
	v_cmp_ge_f32_e64 s[8:9], 0, v106
	s_nop 1
	v_cndmask_b32_e64 v103, v103, v104, s[8:9]
	v_cmp_lt_f32_e64 s[8:9], 0, v107
	s_nop 1
	v_cndmask_b32_e64 v103, v103, v105, s[8:9]
	v_mul_f32_e32 v104, 0x37800000, v103
	v_cndmask_b32_e32 v103, v103, v104, vcc
	v_cmp_class_f32_e32 vcc, v102, v168
	s_nop 1
	v_cndmask_b32_e32 v102, v103, v102, vcc
	v_div_scale_f32 v103, s[4:5], v102, v102, 1.0
	v_rcp_f32_e32 v104, v103
	v_div_scale_f32 v105, vcc, 1.0, v102, 1.0
	v_fma_f32 v106, -v103, v104, 1.0
	v_fmac_f32_e32 v104, v106, v104
	v_mul_f32_e32 v106, v105, v104
	v_fma_f32 v107, -v103, v106, v105
	v_fmac_f32_e32 v106, v107, v104
	v_fma_f32 v103, -v103, v106, v105
	v_div_fmas_f32 v103, v103, v104, v106
	v_div_fixup_f32 v102, v103, v102, 1.0
	v_mul_f32_e32 v102, v150, v102
	v_pk_mul_f32 v[94:95], v[94:95], v[102:103] op_sel_hi:[1,0]
	v_pk_mul_f32 v[92:93], v[92:93], v[102:103] op_sel_hi:[1,0]
	v_pk_mul_f32 v[90:91], v[90:91], v[102:103] op_sel_hi:[1,0]
	v_pk_mul_f32 v[88:89], v[88:89], v[102:103] op_sel_hi:[1,0]
	v_pk_mul_f32 v[86:87], v[86:87], v[102:103] op_sel_hi:[1,0]
	v_pk_mul_f32 v[84:85], v[84:85], v[102:103] op_sel_hi:[1,0]
	v_pk_mul_f32 v[104:105], v[82:83], v[102:103] op_sel_hi:[1,0]
	v_pk_mul_f32 v[102:103], v[80:81], v[102:103] op_sel_hi:[1,0]
	v_cvt_pk_bf16_f32 v80, v92, v93
	v_cvt_pk_bf16_f32 v81, v94, v95
	v_cvt_pk_bf16_f32 v82, v88, v89
	v_cvt_pk_bf16_f32 v83, v90, v91
	global_store_dwordx4 v[98:99], v[80:83], off
	s_nop 1
	v_cvt_pk_bf16_f32 v80, v84, v85
	v_cvt_pk_bf16_f32 v81, v86, v87
	v_cvt_pk_bf16_f32 v82, v102, v103
	v_cvt_pk_bf16_f32 v83, v104, v105
	global_store_dwordx4 v[98:99], v[80:83], off offset:256
	s_waitcnt vmcnt(10)
	s_nop 1
	v_mov_b32_e32 v82, v238
	v_ashrrev_i64 v[84:85], 30, v[136:137]
	v_lshl_add_u64 v[80:81], v[96:97], 0, s[28:29]
	v_lshl_add_u64 v[84:85], s[38:39], 0, v[84:85]
	v_add_u32_e32 v137, 0x90, v148
	v_fmamk_f32 v82, v82, 0x3a000000, v167
	v_mul_f32_e32 v83, 0x4f800000, v82
	v_cmp_gt_f32_e32 vcc, s88, v82
	s_nop 1
	v_cndmask_b32_e32 v86, v82, v83, vcc
	v_sqrt_f32_e32 v87, v86
	v_lshl_add_u64 v[82:83], v[80:81], 1, v[146:147]
	v_add_u32_e32 v88, -1, v87
	v_add_u32_e32 v89, 1, v87
	v_fma_f32 v90, -v88, v87, v86
	v_fma_f32 v91, -v89, v87, v86
	v_cmp_ge_f32_e64 s[8:9], 0, v90
	s_nop 1
	v_cndmask_b32_e64 v87, v87, v88, s[8:9]
	v_cmp_lt_f32_e64 s[8:9], 0, v91
	s_nop 1
	v_cndmask_b32_e64 v87, v87, v89, s[8:9]
	v_mul_f32_e32 v88, 0x37800000, v87
	v_cndmask_b32_e32 v87, v87, v88, vcc
	v_cmp_class_f32_e32 vcc, v86, v168
	s_nop 1
	v_cndmask_b32_e32 v86, v87, v86, vcc
	v_div_scale_f32 v87, s[4:5], v86, v86, 1.0
	v_rcp_f32_e32 v88, v87
	v_div_scale_f32 v89, vcc, 1.0, v86, 1.0
	v_fma_f32 v90, -v87, v88, 1.0
	v_fmac_f32_e32 v88, v90, v88
	v_mul_f32_e32 v90, v89, v88
	v_fma_f32 v91, -v87, v90, v89
	v_fmac_f32_e32 v90, v91, v88
	v_fma_f32 v87, -v87, v90, v89
	v_div_fmas_f32 v87, v87, v88, v90
	v_div_fixup_f32 v86, v87, v86, 1.0
	v_mul_f32_e32 v86, v150, v86
	v_pk_mul_f32 v[78:79], v[78:79], v[86:87] op_sel_hi:[1,0]
	v_pk_mul_f32 v[76:77], v[76:77], v[86:87] op_sel_hi:[1,0]
	v_pk_mul_f32 v[74:75], v[74:75], v[86:87] op_sel_hi:[1,0]
	v_pk_mul_f32 v[72:73], v[72:73], v[86:87] op_sel_hi:[1,0]
	v_pk_mul_f32 v[70:71], v[70:71], v[86:87] op_sel_hi:[1,0]
	v_pk_mul_f32 v[68:69], v[68:69], v[86:87] op_sel_hi:[1,0]
	v_pk_mul_f32 v[88:89], v[66:67], v[86:87] op_sel_hi:[1,0]
	v_pk_mul_f32 v[86:87], v[64:65], v[86:87] op_sel_hi:[1,0]
	v_cvt_pk_bf16_f32 v64, v76, v77
	v_cvt_pk_bf16_f32 v65, v78, v79
	v_cvt_pk_bf16_f32 v66, v72, v73
	v_cvt_pk_bf16_f32 v67, v74, v75
	global_store_dwordx4 v[82:83], v[64:67], off
	s_nop 1
	v_cvt_pk_bf16_f32 v64, v68, v69
	v_cvt_pk_bf16_f32 v65, v70, v71
	v_cvt_pk_bf16_f32 v66, v86, v87
	v_cvt_pk_bf16_f32 v67, v88, v89
	global_store_dwordx4 v[82:83], v[64:67], off offset:256
	s_waitcnt vmcnt(11)
	s_nop 1
	v_mov_b32_e32 v66, v239
	v_ashrrev_i64 v[68:69], 30, v[136:137]
	v_lshl_add_u64 v[64:65], v[80:81], 0, s[0:1]
	v_lshl_add_u64 v[68:69], s[38:39], 0, v[68:69]
	v_add_u32_e32 v137, 0xa0, v148
	v_fmamk_f32 v66, v66, 0x3a000000, v167
	v_mul_f32_e32 v67, 0x4f800000, v66
	v_cmp_gt_f32_e32 vcc, s88, v66
	s_nop 1
	v_cndmask_b32_e32 v70, v66, v67, vcc
	v_sqrt_f32_e32 v71, v70
	v_lshl_add_u64 v[66:67], v[64:65], 1, v[146:147]
	v_add_u32_e32 v72, -1, v71
	v_add_u32_e32 v73, 1, v71
	v_fma_f32 v74, -v72, v71, v70
	v_fma_f32 v75, -v73, v71, v70
	v_cmp_ge_f32_e64 s[8:9], 0, v74
	s_nop 1
	v_cndmask_b32_e64 v71, v71, v72, s[8:9]
	v_cmp_lt_f32_e64 s[8:9], 0, v75
	s_nop 1
	v_cndmask_b32_e64 v71, v71, v73, s[8:9]
	v_mul_f32_e32 v72, 0x37800000, v71
	v_cndmask_b32_e32 v71, v71, v72, vcc
	v_cmp_class_f32_e32 vcc, v70, v168
	s_nop 1
	v_cndmask_b32_e32 v70, v71, v70, vcc
	v_div_scale_f32 v71, s[0:1], v70, v70, 1.0
	v_rcp_f32_e32 v72, v71
	v_div_scale_f32 v73, vcc, 1.0, v70, 1.0
	v_fma_f32 v74, -v71, v72, 1.0
	v_fmac_f32_e32 v72, v74, v72
	v_mul_f32_e32 v74, v73, v72
	v_fma_f32 v75, -v71, v74, v73
	v_fmac_f32_e32 v74, v75, v72
	v_fma_f32 v71, -v71, v74, v73
	v_div_fmas_f32 v71, v71, v72, v74
	v_div_fixup_f32 v70, v71, v70, 1.0
	v_mul_f32_e32 v70, v150, v70
	v_pk_mul_f32 v[62:63], v[62:63], v[70:71] op_sel_hi:[1,0]
	v_pk_mul_f32 v[60:61], v[60:61], v[70:71] op_sel_hi:[1,0]
	v_pk_mul_f32 v[58:59], v[58:59], v[70:71] op_sel_hi:[1,0]
	v_pk_mul_f32 v[56:57], v[56:57], v[70:71] op_sel_hi:[1,0]
	v_pk_mul_f32 v[54:55], v[54:55], v[70:71] op_sel_hi:[1,0]
	v_pk_mul_f32 v[52:53], v[52:53], v[70:71] op_sel_hi:[1,0]
	v_pk_mul_f32 v[72:73], v[50:51], v[70:71] op_sel_hi:[1,0]
	v_pk_mul_f32 v[70:71], v[48:49], v[70:71] op_sel_hi:[1,0]
	v_cvt_pk_bf16_f32 v48, v60, v61
	v_cvt_pk_bf16_f32 v49, v62, v63
	v_cvt_pk_bf16_f32 v50, v56, v57
	v_cvt_pk_bf16_f32 v51, v58, v59
	global_store_dwordx4 v[66:67], v[48:51], off
	s_nop 1
	v_cvt_pk_bf16_f32 v48, v52, v53
	v_cvt_pk_bf16_f32 v49, v54, v55
	v_cvt_pk_bf16_f32 v50, v70, v71
	v_cvt_pk_bf16_f32 v51, v72, v73
	global_store_dwordx4 v[66:67], v[48:51], off offset:256
	s_waitcnt vmcnt(12)
; DI float rs_of(const float* ss, int row) { return 1.0f / sqrtf(ss[row] * (1.0f / DM) + EPS); }
; DI u32x4 pack8(f32x4 a, f32x4 b) { u32x4 w; w.x = cvt_pk_bf16(a[0], a[1]); w.y = cvt_pk_bf16(a[2], a[3]); w.z = cvt_pk_bf16(b[0], b[1]); w.w = cvt_pk_bf16(b[2], b[3]); return w; }
;     DI void operator()(AccRef acc, const Unit& u, int wr, int wc, int fr, int fq) const {
;     ...
;         if (pn < 4 || (pn >= 12 && pn < 15)) {
;             bf16_t* dst = (pn < 4) ? QA + pn * 256 : CQ + (pn - 12) * 256; const int ld = (pn < 4) ? 1024 : 768;
; #pragma unroll
;             for (int ai = 0; ai < 2; ++ai)
; #pragma unroll
;                 for (int m = 0; m < 4; ++m) { const size_t row = (size_t)pm * 256 + rl0 + ai * 128 + m * 16; const float r = rs_of(ss, (int)row) * ((pn < 4) ? 0.08838834764831845f * LOG2E : 1.0f);
; #pragma unroll
;                     for (int bj = 0; bj < 2; ++bj) *(u32x4*)(dst + row * ld + cc0 + bj * 128) = pack8((acc[ai][bj][m][0] * r), (acc[ai][bj][m][1] * r)); }
	s_nop 1
	v_mov_b32_e32 v50, v232
	v_ashrrev_i64 v[52:53], 30, v[136:137]
	v_lshl_add_u64 v[48:49], v[64:65], 0, s[28:29]
	v_lshl_add_u64 v[52:53], s[38:39], 0, v[52:53]
	v_add_u32_e32 v137, 0xb0, v148
	v_fmamk_f32 v50, v50, 0x3a000000, v167
	v_mul_f32_e32 v51, 0x4f800000, v50
	v_cmp_gt_f32_e32 vcc, s88, v50
	s_nop 1
	v_cndmask_b32_e32 v54, v50, v51, vcc
	v_sqrt_f32_e32 v55, v54
	v_lshl_add_u64 v[50:51], v[48:49], 1, v[146:147]
	v_add_u32_e32 v56, -1, v55
	v_add_u32_e32 v57, 1, v55
	v_fma_f32 v58, -v56, v55, v54
	v_fma_f32 v59, -v57, v55, v54
	v_cmp_ge_f32_e64 s[8:9], 0, v58
	s_nop 1
	v_cndmask_b32_e64 v55, v55, v56, s[8:9]
	v_cmp_lt_f32_e64 s[8:9], 0, v59
	s_nop 1
	v_cndmask_b32_e64 v55, v55, v57, s[8:9]
	v_mul_f32_e32 v56, 0x37800000, v55
	v_cndmask_b32_e32 v55, v55, v56, vcc
	v_cmp_class_f32_e32 vcc, v54, v168
	s_nop 1
	v_cndmask_b32_e32 v54, v55, v54, vcc
	v_div_scale_f32 v55, s[0:1], v54, v54, 1.0
	v_rcp_f32_e32 v56, v55
	v_div_scale_f32 v57, vcc, 1.0, v54, 1.0
	v_fma_f32 v58, -v55, v56, 1.0
	v_fmac_f32_e32 v56, v58, v56
	v_mul_f32_e32 v58, v57, v56
	v_fma_f32 v59, -v55, v58, v57
	v_fmac_f32_e32 v58, v59, v56
	v_fma_f32 v55, -v55, v58, v57
	v_div_fmas_f32 v55, v55, v56, v58
	v_div_fixup_f32 v54, v55, v54, 1.0
	v_mul_f32_e32 v54, v150, v54
	v_pk_mul_f32 v[46:47], v[46:47], v[54:55] op_sel_hi:[1,0]
	v_pk_mul_f32 v[44:45], v[44:45], v[54:55] op_sel_hi:[1,0]
	v_pk_mul_f32 v[42:43], v[42:43], v[54:55] op_sel_hi:[1,0]
	v_pk_mul_f32 v[40:41], v[40:41], v[54:55] op_sel_hi:[1,0]
	v_pk_mul_f32 v[38:39], v[38:39], v[54:55] op_sel_hi:[1,0]
	v_pk_mul_f32 v[36:37], v[36:37], v[54:55] op_sel_hi:[1,0]
	v_pk_mul_f32 v[56:57], v[34:35], v[54:55] op_sel_hi:[1,0]
	v_pk_mul_f32 v[54:55], v[32:33], v[54:55] op_sel_hi:[1,0]
	v_cvt_pk_bf16_f32 v32, v44, v45
	v_cvt_pk_bf16_f32 v33, v46, v47
	v_cvt_pk_bf16_f32 v34, v40, v41
	v_cvt_pk_bf16_f32 v35, v42, v43
	global_store_dwordx4 v[50:51], v[32:35], off
	s_nop 1
	v_cvt_pk_bf16_f32 v32, v36, v37
	v_cvt_pk_bf16_f32 v33, v38, v39
	v_cvt_pk_bf16_f32 v34, v54, v55
	v_cvt_pk_bf16_f32 v35, v56, v57
	global_store_dwordx4 v[50:51], v[32:35], off offset:256
	s_waitcnt vmcnt(13)
	s_nop 1
	v_mov_b32_e32 v34, v233
	v_ashrrev_i64 v[36:37], 30, v[136:137]
	v_lshl_add_u64 v[32:33], v[48:49], 0, s[28:29]
	v_lshl_add_u64 v[36:37], s[38:39], 0, v[36:37]
	v_fmamk_f32 v34, v34, 0x3a000000, v167
	v_mul_f32_e32 v35, 0x4f800000, v34
	v_cmp_gt_f32_e32 vcc, s88, v34
	s_nop 1
	v_cndmask_b32_e32 v38, v34, v35, vcc
	v_sqrt_f32_e32 v39, v38
	v_lshl_add_u64 v[34:35], v[32:33], 1, v[146:147]
	v_add_u32_e32 v40, -1, v39
	v_add_u32_e32 v41, 1, v39
	v_fma_f32 v42, -v40, v39, v38
	v_fma_f32 v43, -v41, v39, v38
	v_cmp_ge_f32_e64 s[8:9], 0, v42
	s_nop 1
	v_cndmask_b32_e64 v39, v39, v40, s[8:9]
	v_cmp_lt_f32_e64 s[8:9], 0, v43
	s_nop 1
	v_cndmask_b32_e64 v39, v39, v41, s[8:9]
	v_mul_f32_e32 v40, 0x37800000, v39
	v_cndmask_b32_e32 v39, v39, v40, vcc
	v_cmp_class_f32_e32 vcc, v38, v168
	s_nop 1
	v_cndmask_b32_e32 v38, v39, v38, vcc
	v_div_scale_f32 v39, s[0:1], v38, v38, 1.0
	v_rcp_f32_e32 v40, v39
	v_div_scale_f32 v41, vcc, 1.0, v38, 1.0
	v_fma_f32 v42, -v39, v40, 1.0
	v_fmac_f32_e32 v40, v42, v40
	v_mul_f32_e32 v42, v41, v40
	v_fma_f32 v43, -v39, v42, v41
	v_fmac_f32_e32 v42, v43, v40
	v_fma_f32 v39, -v39, v42, v41
	v_div_fmas_f32 v39, v39, v40, v42
	v_div_fixup_f32 v38, v39, v38, 1.0
	v_mul_f32_e32 v38, v150, v38
	v_pk_mul_f32 v[30:31], v[30:31], v[38:39] op_sel_hi:[1,0]
	v_pk_mul_f32 v[28:29], v[28:29], v[38:39] op_sel_hi:[1,0]
	v_pk_mul_f32 v[26:27], v[26:27], v[38:39] op_sel_hi:[1,0]
	v_pk_mul_f32 v[24:25], v[24:25], v[38:39] op_sel_hi:[1,0]
	v_pk_mul_f32 v[22:23], v[22:23], v[38:39] op_sel_hi:[1,0]
	v_pk_mul_f32 v[20:21], v[20:21], v[38:39] op_sel_hi:[1,0]
	v_pk_mul_f32 v[40:41], v[18:19], v[38:39] op_sel_hi:[1,0]
	v_pk_mul_f32 v[38:39], v[16:17], v[38:39] op_sel_hi:[1,0]
	v_cvt_pk_bf16_f32 v16, v28, v29
	v_cvt_pk_bf16_f32 v17, v30, v31
	v_cvt_pk_bf16_f32 v18, v24, v25
	v_cvt_pk_bf16_f32 v19, v26, v27
	global_store_dwordx4 v[34:35], v[16:19], off
	s_nop 1
	v_cvt_pk_bf16_f32 v16, v20, v21
	v_cvt_pk_bf16_f32 v17, v22, v23
	v_cvt_pk_bf16_f32 v18, v38, v39
	v_cvt_pk_bf16_f32 v19, v40, v41
	global_store_dwordx4 v[34:35], v[16:19], off offset:256
	s_waitcnt vmcnt(14)
	s_nop 1
	v_mov_b32_e32 v16, v234
	v_fmamk_f32 v16, v16, 0x3a000000, v167
	v_mul_f32_e32 v17, 0x4f800000, v16
	v_cmp_gt_f32_e32 vcc, s88, v16
	s_nop 1
	v_cndmask_b32_e32 v18, v16, v17, vcc
	v_sqrt_f32_e32 v19, v18
	v_lshl_add_u64 v[16:17], v[32:33], 0, s[28:29]
	v_lshl_add_u64 v[16:17], v[16:17], 1, v[146:147]
	v_add_u32_e32 v20, -1, v19
	v_add_u32_e32 v21, 1, v19
	v_fma_f32 v22, -v20, v19, v18
	v_fma_f32 v23, -v21, v19, v18
	v_cmp_ge_f32_e64 s[8:9], 0, v22
	s_nop 1
	v_cndmask_b32_e64 v19, v19, v20, s[8:9]
	v_cmp_lt_f32_e64 s[8:9], 0, v23
	s_nop 1
	v_cndmask_b32_e64 v19, v19, v21, s[8:9]
	v_mul_f32_e32 v20, 0x37800000, v19
	v_cndmask_b32_e32 v19, v19, v20, vcc
	v_cmp_class_f32_e32 vcc, v18, v168
	s_nop 1
	v_cndmask_b32_e32 v18, v19, v18, vcc
	v_div_scale_f32 v19, s[0:1], v18, v18, 1.0
	v_rcp_f32_e32 v20, v19
	v_div_scale_f32 v21, vcc, 1.0, v18, 1.0
	v_fma_f32 v22, -v19, v20, 1.0
	v_fmac_f32_e32 v20, v22, v20
	v_mul_f32_e32 v22, v21, v20
	v_fma_f32 v23, -v19, v22, v21
	v_fmac_f32_e32 v22, v23, v20
	v_fma_f32 v19, -v19, v22, v21
	v_div_fmas_f32 v19, v19, v20, v22
	v_div_fixup_f32 v18, v19, v18, 1.0
	v_mul_f32_e32 v18, v150, v18
	v_pk_mul_f32 v[14:15], v[14:15], v[18:19] op_sel_hi:[1,0]
	v_pk_mul_f32 v[12:13], v[12:13], v[18:19] op_sel_hi:[1,0]
	v_pk_mul_f32 v[10:11], v[10:11], v[18:19] op_sel_hi:[1,0]
	v_pk_mul_f32 v[8:9], v[8:9], v[18:19] op_sel_hi:[1,0]
	v_pk_mul_f32 v[6:7], v[6:7], v[18:19] op_sel_hi:[1,0]
	v_pk_mul_f32 v[4:5], v[4:5], v[18:19] op_sel_hi:[1,0]
	v_pk_mul_f32 v[20:21], v[2:3], v[18:19] op_sel_hi:[1,0]
	v_pk_mul_f32 v[18:19], v[0:1], v[18:19] op_sel_hi:[1,0]
	v_cvt_pk_bf16_f32 v0, v12, v13
	v_cvt_pk_bf16_f32 v1, v14, v15
	v_cvt_pk_bf16_f32 v2, v8, v9
	v_cvt_pk_bf16_f32 v3, v10, v11
	global_store_dwordx4 v[16:17], v[0:3], off
	s_nop 1
	v_cvt_pk_bf16_f32 v0, v4, v5
	v_cvt_pk_bf16_f32 v1, v6, v7
	v_cvt_pk_bf16_f32 v2, v18, v19
	v_cvt_pk_bf16_f32 v3, v20, v21
	global_store_dwordx4 v[16:17], v[0:3], off offset:256
	s_branch .LBB0_519

; DI unsigned cvt_pk_bf16(float lo, float hi) { unsigned r; asm volatile("v_cvt_pk_bf16_f32 %0, %1, %2" : "=v"(r) : "v"(lo), "v"(hi)); return r; }
; DI float bf_lo(unsigned u) { return __uint_as_float(u << 16); }
; DI float bf_hi(unsigned u) { return __uint_as_float(u & 0xffff0000u); }
; __global__ void __launch_bounds__(512) mk_fwd(Params p) {
;     ...
;         for (int row = gw; row < R; row += nw) {
;             const bool smp = row >= RP; const int lr = row - RP;
;             const size_t dr = smp ? (size_t)RP + (size_t)(lr >> 5) * LM + PAST + (lr & 31) : (size_t)row;
;             const int pos = smp ? PAST + (lr & 31) : (row & 4095);
;             float* ck = smp ? out + O_CKVS + (size_t)lr * 512 : out + O_CKVP + (size_t)row * 512;
;             f32x4 a = *(const f32x4*)(ck + lane * 4), b2 = *(const f32x4*)(ck + 256 + lane * 4);
;             float ss = a[0] * a[0] + a[1] * a[1] + a[2] * a[2] + a[3] * a[3] + b2[0] * b2[0] + b2[1] * b2[1] + b2[2] * b2[2] + b2[3] * b2[3];
;             ss = wave_sum(ss); const float r = 1.0f / sqrtf(ss * (1.0f / 512.0f) + EPS);
;             a = a * r * *(const f32x4*)(gck + lane * 4); b2 = b2 * r * *(const f32x4*)(gck + 256 + lane * 4);
;             *(f32x4*)(ck + lane * 4) = a; *(f32x4*)(ck + 256 + lane * 4) = b2;
;             u32x2 w; w.x = cvt_pk_bf16(a[0], a[1]); w.y = cvt_pk_bf16(a[2], a[3]); *(u32x2*)(CKVn + dr * 512 + lane * 4) = w;
;             w.x = cvt_pk_bf16(b2[0], b2[1]); w.y = cvt_pk_bf16(b2[2], b2[3]); *(u32x2*)(CKVn + dr * 512 + 256 + lane * 4) = w;
;             float* kr = smp ? out + O_KRS + (size_t)lr * 64 : out + O_KRP + (size_t)row * 64;
;             const float xv = kr[lane], xo = __shfl_xor(xv, 32); const f32x2 c = cst[pos * 32 + (lane & 31)];
;             const float o = (lane < 32) ? xv * c.x - xo * c.y : xv * c.x + xo * c.y;
;             kr[lane] = o; KRall[dr * 64 + lane] = (bf16_t)(cvt_pk_bf16(o, o) & 0xffff);
;             const bf16_t* cqr = CQ + (size_t)row * 768; float sq = 0.f;
; #pragma unroll
;             for (int i = 0; i < 3; ++i) { const u32x2 v = *(const u32x2*)(cqr + i * 256 + lane * 4); const float f0 = bf_lo(v.x), f1 = bf_hi(v.x), f2 = bf_lo(v.y), f3 = bf_hi(v.y); sq += f0 * f0 + f1 * f1 + f2 * f2 + f3 * f3; }
;             sq = wave_sum(sq); if (lane == 0) rcq[row] = 1.0f / sqrtf(sq * (1.0f / 768.0f) + EPS);
.LBB0_854:
	v_cmp_lt_i32_e64 s[10:11], s0, v0
	v_cmp_gt_i32_e64 s[12:13], s1, v0
	s_waitcnt lgkmcnt(0)
	v_and_b32_e32 v15, 31, v0
	s_and_saveexec_b64 s[14:15], s[12:13]
	s_xor_b64 s[14:15], exec, s[14:15]
	v_ashrrev_i32_e32 v19, 31, v0
	v_mov_b32_e32 v18, v0
	v_and_b32_e32 v15, 31, v0
	s_or_saveexec_b64 s[14:15], s[14:15]
	v_add_u32_e32 v2, 0xffff8000, v0
	v_mov_b64_e32 v[20:21], 0x12200000
	v_mov_b64_e32 v[16:17], v[0:1]
	s_xor_b64 exec, exec, s[14:15]
	v_lshrrev_b32_e32 v16, 5, v2
	v_mad_u64_u32 v[16:17], s[34:35], v16, s3, 0
	v_or_b32_e32 v16, v16, v15
	v_lshl_add_u64 v[16:17], v[16:17], 0, s[40:41]
	v_mov_b64_e32 v[20:21], 0x16c00000
	v_mov_b64_e32 v[18:19], v[0:1]
	s_or_b64 exec, exec, s[14:15]
	v_cndmask_b32_e64 v23, v19, 0, s[10:11]
	v_cndmask_b32_e64 v22, v18, v2, s[10:11]
	v_lshl_add_u64 v[20:21], s[20:21], 0, v[20:21]
	v_lshlrev_b64 v[22:23], 11, v[22:23]
	v_lshl_add_u64 v[20:21], v[20:21], 0, v[22:23]
	v_lshl_add_u64 v[22:23], v[20:21], 0, v[12:13]
	global_load_dwordx4 v[34:37], v[22:23], off
	global_load_dwordx4 v[38:41], v[22:23], off offset:1024
	global_load_dwordx4 v[42:45], v[4:5], off
	global_load_dwordx4 v[46:49], v[4:5], off offset:1024
	v_mov_b32_e32 v209, 0
	v_lshlrev_b32_e32 v208, 8, v0
	v_lshl_add_u64 v[210:211], s[28:29], 0, v[208:209]
	v_lshlrev_b32_e32 v208, 8, v2
	v_lshl_add_u64 v[212:213], s[30:31], 0, v[208:209]
	v_cndmask_b32_e64 v210, v212, v210, s[12:13]
	v_cndmask_b32_e64 v211, v213, v211, s[12:13]
	v_mov_b32_e32 v208, v14
	v_lshl_add_u64 v[210:211], v[210:211], 0, v[208:209]
	global_load_dword v214, v[210:211], off
	v_and_b32_e32 v212, 31, v0
	v_or_b32_e32 v212, 0x1000, v212
	v_and_b32_e32 v213, 0xfff, v0
	v_cndmask_b32_e64 v208, v213, v212, s[10:11]
	v_lshl_or_b32 v208, v208, 5, v24
	v_lshl_add_u64 v[212:213], v[208:209], 3, s[22:23]
	global_load_dwordx2 v[216:217], v[212:213], off
	v_mad_u64_u32 v[212:213], s[46:47], v0, s5, v[8:9]
	global_load_dwordx2 v[218:219], v[212:213], off
	global_load_dwordx2 v[220:221], v[212:213], off offset:512
	global_load_dwordx2 v[222:223], v[212:213], off offset:1024
	v_lshlrev_b64 v[50:51], 10, v[16:17]
	v_lshl_add_u64 v[50:51], v[10:11], 0, v[50:51]
	s_waitcnt vmcnt(0)
	v_mul_f32_e32 v33, v35, v35
	v_fmac_f32_e32 v33, v34, v34
	v_fmac_f32_e32 v33, v36, v36
	v_fmac_f32_e32 v33, v37, v37
	v_fmac_f32_e32 v33, v38, v38
	v_pk_mul_f32 v[20:21], v[40:41], v[40:41]
	v_fmac_f32_e32 v33, v39, v39
	v_add_f32_e32 v20, v20, v33
	v_add_f32_e32 v20, v21, v20
	ds_bpermute_b32 v21, v25, v20
	s_waitcnt lgkmcnt(0)
	v_add_f32_e32 v20, v20, v21
	ds_bpermute_b32 v21, v26, v20
	s_waitcnt lgkmcnt(0)
	v_add_f32_e32 v20, v20, v21
	ds_bpermute_b32 v21, v27, v20
	s_waitcnt lgkmcnt(0)
	v_add_f32_e32 v20, v20, v21
	ds_bpermute_b32 v21, v28, v20
	s_waitcnt lgkmcnt(0)
	v_add_f32_e32 v20, v20, v21
	ds_bpermute_b32 v21, v29, v20
	s_waitcnt lgkmcnt(0)
	v_add_f32_e32 v20, v20, v21
	ds_bpermute_b32 v21, v30, v20
	s_waitcnt lgkmcnt(0)
; DI unsigned cvt_pk_bf16(float lo, float hi) { unsigned r; asm volatile("v_cvt_pk_bf16_f32 %0, %1, %2" : "=v"(r) : "v"(lo), "v"(hi)); return r; }
; DI float bf_lo(unsigned u) { return __uint_as_float(u << 16); }
; DI float bf_hi(unsigned u) { return __uint_as_float(u & 0xffff0000u); }
; __global__ void __launch_bounds__(512) mk_fwd(Params p) {
;     ...
;             f32x4 a = *(const f32x4*)(ck + lane * 4), b2 = *(const f32x4*)(ck + 256 + lane * 4);
;             float ss = a[0] * a[0] + a[1] * a[1] + a[2] * a[2] + a[3] * a[3] + b2[0] * b2[0] + b2[1] * b2[1] + b2[2] * b2[2] + b2[3] * b2[3];
;             ss = wave_sum(ss); const float r = 1.0f / sqrtf(ss * (1.0f / 512.0f) + EPS);
;             a = a * r * *(const f32x4*)(gck + lane * 4); b2 = b2 * r * *(const f32x4*)(gck + 256 + lane * 4);
;             *(f32x4*)(ck + lane * 4) = a; *(f32x4*)(ck + 256 + lane * 4) = b2;
;             u32x2 w; w.x = cvt_pk_bf16(a[0], a[1]); w.y = cvt_pk_bf16(a[2], a[3]); *(u32x2*)(CKVn + dr * 512 + lane * 4) = w;
;             w.x = cvt_pk_bf16(b2[0], b2[1]); w.y = cvt_pk_bf16(b2[2], b2[3]); *(u32x2*)(CKVn + dr * 512 + 256 + lane * 4) = w;
;             float* kr = smp ? out + O_KRS + (size_t)lr * 64 : out + O_KRP + (size_t)row * 64;
;             const float xv = kr[lane], xo = __shfl_xor(xv, 32); const f32x2 c = cst[pos * 32 + (lane & 31)];
;             const float o = (lane < 32) ? xv * c.x - xo * c.y : xv * c.x + xo * c.y;
;             kr[lane] = o; KRall[dr * 64 + lane] = (bf16_t)(cvt_pk_bf16(o, o) & 0xffff);
;             const bf16_t* cqr = CQ + (size_t)row * 768; float sq = 0.f;
; #pragma unroll
;             for (int i = 0; i < 3; ++i) { const u32x2 v = *(const u32x2*)(cqr + i * 256 + lane * 4); const float f0 = bf_lo(v.x), f1 = bf_hi(v.x), f2 = bf_lo(v.y), f3 = bf_hi(v.y); sq += f0 * f0 + f1 * f1 + f2 * f2 + f3 * f3; }
;             sq = wave_sum(sq); if (lane == 0) rcq[row] = 1.0f / sqrtf(sq * (1.0f / 768.0f) + EPS);
	v_add_f32_e32 v20, v20, v21
	v_fmamk_f32 v20, v20, 0x3b000000, v31
	v_mul_f32_e32 v21, 0x4f800000, v20
	v_cmp_gt_f32_e32 vcc, s4, v20
	s_nop 1
	v_cndmask_b32_e32 v21, v20, v21, vcc
	v_sqrt_f32_e32 v33, v21
	v_mov_b32_e32 v20, v0
	v_add_u32_e32 v52, -1, v33
	v_add_u32_e32 v53, 1, v33
	v_fma_f32 v54, -v52, v33, v21
	v_fma_f32 v55, -v53, v33, v21
	v_cmp_ge_f32_e64 s[14:15], 0, v54
	s_nop 1
	v_cndmask_b32_e64 v33, v33, v52, s[14:15]
	v_cmp_lt_f32_e64 s[14:15], 0, v55
	s_nop 1
	v_cndmask_b32_e64 v33, v33, v53, s[14:15]
	v_mul_f32_e32 v52, 0x37800000, v33
	v_cndmask_b32_e32 v33, v33, v52, vcc
	v_cmp_class_f32_e32 vcc, v21, v32
	s_nop 1
	v_cndmask_b32_e32 v21, v33, v21, vcc
	v_div_scale_f32 v33, s[14:15], v21, v21, 1.0
	v_rcp_f32_e32 v52, v33
	v_div_scale_f32 v53, vcc, 1.0, v21, 1.0
	v_fma_f32 v54, -v33, v52, 1.0
	v_fmac_f32_e32 v52, v54, v52
	v_mul_f32_e32 v54, v53, v52
	v_fma_f32 v55, -v33, v54, v53
	v_fmac_f32_e32 v54, v55, v52
	v_fma_f32 v33, -v33, v54, v53
	v_div_fmas_f32 v33, v33, v52, v54
	v_div_fixup_f32 v52, v33, v21, 1.0
	v_pk_mul_f32 v[34:35], v[34:35], v[52:53] op_sel_hi:[1,0]
	v_pk_mul_f32 v[36:37], v[36:37], v[52:53] op_sel_hi:[1,0]
	v_pk_mul_f32 v[38:39], v[38:39], v[52:53] op_sel_hi:[1,0]
	v_pk_mul_f32 v[40:41], v[40:41], v[52:53] op_sel_hi:[1,0]
	v_pk_mul_f32 v[36:37], v[44:45], v[36:37]
	v_pk_mul_f32 v[34:35], v[42:43], v[34:35]
	v_pk_mul_f32 v[40:41], v[48:49], v[40:41]
	v_pk_mul_f32 v[38:39], v[46:47], v[38:39]
	global_store_dwordx4 v[22:23], v[34:37], off
	global_store_dwordx4 v[22:23], v[38:41], off offset:1024
	v_cvt_pk_bf16_f32 v22, v34, v35
	v_cvt_pk_bf16_f32 v23, v36, v37
	global_store_dwordx2 v[50:51], v[22:23], off
	v_cvt_pk_bf16_f32 v22, v38, v39
	v_cvt_pk_bf16_f32 v23, v40, v41
	v_mov_b32_e32 v21, v3
	global_store_dwordx2 v[50:51], v[22:23], off offset:512
	s_and_saveexec_b64 s[14:15], s[12:13]
	s_xor_b64 s[12:13], exec, s[14:15]
	v_lshlrev_b64 v[20:21], 8, v[18:19]
	v_lshl_add_u64 v[22:23], s[28:29], 0, v[20:21]
	v_mov_b64_e32 v[20:21], v[18:19]
	s_andn2_saveexec_b64 s[12:13], s[12:13]
	v_lshlrev_b64 v[18:19], 8, v[2:3]
	v_lshl_add_u64 v[22:23], s[30:31], 0, v[18:19]
	s_or_b64 exec, exec, s[12:13]
	v_or_b32_e32 v2, 0x1000, v15
	v_mov_b32_e32 v15, v3
	v_lshl_add_u64 v[18:19], v[22:23], 0, v[14:15]
	v_mov_b32_e32 v15, v214
	v_and_b32_e32 v22, 0xfff, v0
	v_cndmask_b32_e64 v2, v22, v2, s[10:11]
	v_lshl_or_b32 v2, v2, 5, v24
	v_lshl_add_u64 v[22:23], v[2:3], 3, s[22:23]
	v_mov_b64_e32 v[22:23], v[216:217]
	v_mad_u64_u32 v[34:35], s[10:11], v20, s5, v[8:9]
	v_mov_b32_e32 v2, v35
	v_mad_u64_u32 v[36:37], s[10:11], v21, s5, v[2:3]
	v_lshlrev_b64 v[16:17], 7, v[16:17]
	v_lshl_add_u64 v[16:17], v[6:7], 0, v[16:17]
	v_mov_b32_e32 v35, v36
	ds_bpermute_b32 v33, v25, v15
	s_waitcnt lgkmcnt(0)
	v_mul_f32_e32 v2, v23, v33
	v_cndmask_b32_e64 v2, v2, -v2, s[6:7]
	v_fmac_f32_e32 v2, v15, v22
	global_store_dword v[18:19], v2, off
	v_cvt_pk_bf16_f32 v2, v2, v2
	global_store_short v[16:17], v2, off
	v_mov_b64_e32 v[16:17], v[218:219]
	s_nop 0
	v_mov_b64_e32 v[18:19], v[220:221]
	v_mov_b64_e32 v[22:23], v[222:223]
	v_and_b32_e32 v15, 0xffff0000, v16
	v_lshlrev_b32_e32 v33, 16, v18
	v_and_b32_e32 v18, 0xffff0000, v18
	v_lshlrev_b32_e32 v2, 16, v16
	v_lshlrev_b32_e32 v35, 16, v22
	v_and_b32_e32 v22, 0xffff0000, v22
	v_mul_f32_e32 v15, v15, v15
	v_mul_f32_e32 v18, v18, v18
	v_lshlrev_b32_e32 v16, 16, v17
	v_lshlrev_b32_e32 v34, 16, v19
	v_mul_f32_e32 v22, v22, v22
	v_fmac_f32_e32 v15, v2, v2
	v_fmac_f32_e32 v18, v33, v33
	v_and_b32_e32 v17, 0xffff0000, v17
	v_and_b32_e32 v19, 0xffff0000, v19
	v_lshlrev_b32_e32 v36, 16, v23
	v_fmac_f32_e32 v22, v35, v35
	v_fmac_f32_e32 v15, v16, v16
	v_fmac_f32_e32 v18, v34, v34
	v_and_b32_e32 v23, 0xffff0000, v23
	v_fmac_f32_e32 v22, v36, v36
	v_fmac_f32_e32 v15, v17, v17
	v_fmac_f32_e32 v18, v19, v19
	v_add_f32_e32 v2, v15, v18
	v_fmac_f32_e32 v22, v23, v23
	v_add_f32_e32 v2, v2, v22
	ds_bpermute_b32 v15, v25, v2
	s_waitcnt lgkmcnt(0)
	v_add_f32_e32 v2, v2, v15
	ds_bpermute_b32 v15, v26, v2
	s_waitcnt lgkmcnt(0)
	v_add_f32_e32 v2, v2, v15
	ds_bpermute_b32 v15, v27, v2
	s_waitcnt lgkmcnt(0)
	v_add_f32_e32 v2, v2, v15
	ds_bpermute_b32 v15, v28, v2
	s_waitcnt lgkmcnt(0)
	v_add_f32_e32 v2, v2, v15
	ds_bpermute_b32 v15, v29, v2
	s_waitcnt lgkmcnt(0)
	v_add_f32_e32 v2, v2, v15
	ds_bpermute_b32 v15, v30, v2
	s_and_saveexec_b64 s[12:13], s[8:9]
	s_cbranch_execz .LBB0_853
	s_waitcnt lgkmcnt(0)
	v_add_f32_e32 v2, v2, v15
	v_fmamk_f32 v2, v2, 0x3aaaaaab, v31
	v_mul_f32_e32 v15, 0x4f800000, v2
	v_cmp_gt_f32_e32 vcc, s4, v2
	s_nop 1
	v_cndmask_b32_e32 v2, v2, v15, vcc
	v_sqrt_f32_e32 v15, v2
	s_nop 0
	v_add_u32_e32 v16, -1, v15
	v_fma_f32 v18, -v16, v15, v2
	v_add_u32_e32 v17, 1, v15
	v_cmp_ge_f32_e64 s[10:11], 0, v18
	s_nop 1
	v_cndmask_b32_e64 v16, v15, v16, s[10:11]
	v_fma_f32 v15, -v17, v15, v2
	v_cmp_lt_f32_e64 s[10:11], 0, v15
	s_nop 1
	v_cndmask_b32_e64 v15, v16, v17, s[10:11]
	v_mul_f32_e32 v16, 0x37800000, v15
	v_cndmask_b32_e32 v15, v15, v16, vcc
	v_cmp_class_f32_e32 vcc, v2, v32
	s_nop 1
	v_cndmask_b32_e32 v2, v15, v2, vcc
	v_div_scale_f32 v15, s[10:11], v2, v2, 1.0
	v_rcp_f32_e32 v16, v15
	s_nop 0
	v_fma_f32 v17, -v15, v16, 1.0
	v_fmac_f32_e32 v16, v17, v16
	v_div_scale_f32 v17, vcc, 1.0, v2, 1.0
	v_mul_f32_e32 v18, v17, v16
	v_fma_f32 v19, -v15, v18, v17
	v_fmac_f32_e32 v18, v19, v16
	v_fma_f32 v15, -v15, v18, v17
	v_div_fmas_f32 v15, v15, v16, v18
	v_div_fixup_f32 v2, v15, v2, 1.0
	v_lshl_add_u64 v[16:17], v[20:21], 2, s[36:37]
	global_store_dword v[16:17], v2, off
	s_branch .LBB0_853

; DI float sigmoidf_(float x) { return __builtin_amdgcn_rcpf(1.0f + __builtin_amdgcn_exp2f(-x * LOG2E)); }
; DI float rs_of(const float* ss, int row) { return 1.0f / sqrtf(ss[row] * (1.0f / DM) + EPS); }
; DI u32x4 pack8(f32x4 a, f32x4 b) { u32x4 w; w.x = cvt_pk_bf16(a[0], a[1]); w.y = cvt_pk_bf16(a[2], a[3]); w.z = cvt_pk_bf16(b[0], b[1]); w.w = cvt_pk_bf16(b[2], b[3]); return w; }
;     DI void operator()(AccRef acc, const Unit& u, int wr, int wc, int fr, int fq) const {
;     ...
;             for (int m = 0; m < 4; ++m) { const int row = u.pm * 256 + ai * 128 + wr * 64 + m * 16 + fr; const float r = rs_of(ss, row); f32x4 ra[2], sb[2];
; #pragma unroll
;                 for (int n = 0; n < 2; ++n)
; #pragma unroll
;                     for (int j = 0; j < 4; ++j) { const float a = sigmoidf_(acc[ai][0][m][n][j] * r), b = fmaxf(sigmoidf_(acc[ai][1][m][n][j] * r), 1e-4f); sb[n][j] = b; ra[n][j] = a * __builtin_amdgcn_rcpf(b); }
;                 *(u32x4*)(RAT + (size_t)row * DM + col0) = pack8(ra[0], ra[1]); *(u32x4*)(SB + (size_t)row * DM + col0) = pack8(sb[0], sb[1]); }
;     DI void operator()(AccRef acc, const Unit& u, int wr, int wc, int fr, int fq) const {
;     ...
;         else { EpiGates G{RAT, SB, ss}; Unit g; g.pm = u.pm; g.pn = 2 * u.pn + u.ks; g.ks = 0; G(acc, g, wr, wc, fr, fq); }
.LBB0_1351:
	v_mov_b32_e32 v134, v192
	v_mov_b32_e32 v1, v194
	s_mov_b64 s[40:41], -1
	s_and_b64 vcc, exec, s[8:9]
	s_cbranch_vccz .LBB0_1353
	s_add_i32 s0, s31, s57
	v_add_u32_e32 v2, s0, v1
	v_ashrrev_i32_e32 v3, 31, v2
	v_lshl_add_u64 v[132:133], v[2:3], 2, s[14:15]
	v_mov_b64_e32 v[166:167], v[132:133]
	s_mov_b32 s5, 0
	global_load_dword v157, v[166:167], off
	s_mov_b32 s4, 0x40
	v_lshl_add_u64 v[166:167], v[166:167], 0, s[4:5]
	global_load_dword v207, v[166:167], off
	s_mov_b32 s4, 0x40
	v_lshl_add_u64 v[166:167], v[166:167], 0, s[4:5]
	global_load_dword v240, v[166:167], off
	s_mov_b32 s4, 0x40
	v_lshl_add_u64 v[166:167], v[166:167], 0, s[4:5]
	global_load_dword v241, v[166:167], off
	s_mov_b32 s4, 0x140
	v_lshl_add_u64 v[166:167], v[166:167], 0, s[4:5]
	global_load_dword v242, v[166:167], off
	s_mov_b32 s4, 0x40
	v_lshl_add_u64 v[166:167], v[166:167], 0, s[4:5]
	global_load_dword v243, v[166:167], off
	s_mov_b32 s4, 0x40
	v_lshl_add_u64 v[166:167], v[166:167], 0, s[4:5]
	global_load_dword v236, v[166:167], off
	s_mov_b32 s4, 0x40
	v_lshl_add_u64 v[166:167], v[166:167], 0, s[4:5]
	global_load_dword v237, v[166:167], off
	s_waitcnt vmcnt(7)
	v_mov_b32_e32 v132, v157
	s_lshl_b32 s0, s34, 7
	s_or_b32 s0, s0, s58
	s_add_i32 s0, s0, s35
	s_mov_b64 s[40:41], 0
	v_fmamk_f32 v132, v132, 0x3a000000, v205
	v_mul_f32_e32 v133, 0x4f800000, v132
	v_cmp_gt_f32_e32 vcc, s65, v132
	s_nop 1
	v_cndmask_b32_e32 v133, v132, v133, vcc
	v_sqrt_f32_e32 v135, v133
	v_lshl_add_u32 v132, v134, 3, s0
	v_add_u32_e32 v136, -1, v135
	v_add_u32_e32 v137, 1, v135
	v_fma_f32 v138, -v136, v135, v133
	v_fma_f32 v139, -v137, v135, v133
	v_cmp_ge_f32_e64 s[8:9], 0, v138
	s_nop 1
	v_cndmask_b32_e64 v135, v135, v136, s[8:9]
	v_cmp_lt_f32_e64 s[8:9], 0, v139
	s_nop 1
	v_cndmask_b32_e64 v135, v135, v137, s[8:9]
	v_mul_f32_e32 v136, 0x37800000, v135
	v_cndmask_b32_e32 v135, v135, v136, vcc
	v_cmp_class_f32_e32 vcc, v133, v206
	s_nop 1
	v_cndmask_b32_e32 v135, v135, v133, vcc
	v_div_scale_f32 v136, s[0:1], v135, v135, 1.0
	v_rcp_f32_e32 v137, v136
	v_div_scale_f32 v138, vcc, 1.0, v135, 1.0
	v_ashrrev_i32_e32 v133, 31, v132
	v_fma_f32 v139, -v136, v137, 1.0
	v_fmac_f32_e32 v137, v139, v137
	v_mul_f32_e32 v139, v138, v137
	v_fma_f32 v140, -v136, v139, v138
	v_fmac_f32_e32 v139, v140, v137
	v_fma_f32 v136, -v136, v139, v138
	v_div_fmas_f32 v136, v136, v137, v139
	v_div_fixup_f32 v135, v136, v135, 1.0
	v_mul_f32_e32 v137, v120, v135
	v_mul_f32_e32 v139, v121, v135
	v_mul_f32_e32 v141, v122, v135
	v_mul_f32_e32 v137, 0xbfb8aa3b, v137
	v_mul_f32_e32 v139, 0xbfb8aa3b, v139
	v_mul_f32_e32 v141, 0xbfb8aa3b, v141
	v_exp_f32_e32 v137, v137
	v_exp_f32_e32 v139, v139
	v_exp_f32_e32 v141, v141
	v_mul_f32_e32 v136, v128, v135
	v_mul_f32_e32 v138, v129, v135
	v_mul_f32_e32 v140, v130, v135
	v_mul_f32_e32 v136, 0xbfb8aa3b, v136
	v_mul_f32_e32 v138, 0xbfb8aa3b, v138
	v_mul_f32_e32 v140, 0xbfb8aa3b, v140
	v_add_f32_e32 v137, 1.0, v137
	v_add_f32_e32 v139, 1.0, v139
	v_add_f32_e32 v141, 1.0, v141
	v_exp_f32_e32 v136, v136
	v_exp_f32_e32 v138, v138
	v_exp_f32_e32 v140, v140
	v_rcp_f32_e32 v137, v137
	v_rcp_f32_e32 v139, v139
	v_rcp_f32_e32 v141, v141
	v_add_f32_e32 v136, 1.0, v136
	v_add_f32_e32 v138, 1.0, v138
	v_add_f32_e32 v140, 1.0, v140
	v_max_f32_e32 v150, 0x38d1b717, v137
	v_max_f32_e32 v151, 0x38d1b717, v139
	v_max_f32_e32 v152, 0x38d1b717, v141
	v_rcp_f32_e32 v136, v136
	v_rcp_f32_e32 v138, v138
	v_rcp_f32_e32 v140, v140
	v_rcp_f32_e32 v137, v150
	v_rcp_f32_e32 v139, v151
	v_rcp_f32_e32 v141, v152
	v_mul_f32_e32 v143, v123, v135
	v_mul_f32_e32 v149, v118, v135
	v_mul_f32_e32 v145, v116, v135
	v_mul_f32_e32 v147, v117, v135
	v_mul_f32_e32 v143, 0xbfb8aa3b, v143
	v_mul_f32_e32 v149, 0xbfb8aa3b, v149
	v_mul_f32_e32 v136, v136, v137
	v_mul_f32_e32 v137, v138, v139
	v_mul_f32_e32 v138, v140, v141
	v_mul_f32_e32 v140, v119, v135
	v_mul_f32_e32 v145, 0xbfb8aa3b, v145
	v_mul_f32_e32 v147, 0xbfb8aa3b, v147
	v_exp_f32_e32 v143, v143
	v_exp_f32_e32 v149, v149
	v_mul_f32_e32 v140, 0xbfb8aa3b, v140
	v_exp_f32_e32 v145, v145
	v_exp_f32_e32 v147, v147
	v_exp_f32_e32 v140, v140
	v_mul_f32_e32 v142, v131, v135
	v_mul_f32_e32 v148, v126, v135
	v_mul_f32_e32 v144, v124, v135
	v_mul_f32_e32 v146, v125, v135
	v_mul_f32_e32 v142, 0xbfb8aa3b, v142
	v_mul_f32_e32 v148, 0xbfb8aa3b, v148
	v_add_f32_e32 v143, 1.0, v143
	v_add_f32_e32 v149, 1.0, v149
	v_mul_f32_e32 v135, v127, v135
	v_mul_f32_e32 v144, 0xbfb8aa3b, v144
	v_mul_f32_e32 v146, 0xbfb8aa3b, v146
	v_exp_f32_e32 v142, v142
	v_exp_f32_e32 v148, v148
	v_add_f32_e32 v145, 1.0, v145
	v_add_f32_e32 v147, 1.0, v147
	v_rcp_f32_e32 v143, v143
	v_rcp_f32_e32 v149, v149
	v_mul_f32_e32 v135, 0xbfb8aa3b, v135
	v_add_f32_e32 v140, 1.0, v140
	v_exp_f32_e32 v144, v144
	v_exp_f32_e32 v146, v146
	v_rcp_f32_e32 v145, v145
	v_rcp_f32_e32 v147, v147
	v_exp_f32_e32 v135, v135
	v_rcp_f32_e32 v140, v140
	v_add_f32_e32 v142, 1.0, v142
	v_add_f32_e32 v148, 1.0, v148
	v_max_f32_e32 v153, 0x38d1b717, v143
	v_max_f32_e32 v149, 0x38d1b717, v149
	v_add_f32_e32 v144, 1.0, v144
	v_add_f32_e32 v146, 1.0, v146
	v_rcp_f32_e32 v142, v142
	v_rcp_f32_e32 v148, v148
	v_max_f32_e32 v145, 0x38d1b717, v145
	v_max_f32_e32 v147, 0x38d1b717, v147
	v_rcp_f32_e32 v143, v153
	v_rcp_f32_e32 v141, v149
	v_add_f32_e32 v135, 1.0, v135
	v_max_f32_e32 v156, 0x38d1b717, v140
	v_rcp_f32_e32 v144, v144
	v_rcp_f32_e32 v146, v146
	v_rcp_f32_e32 v154, v145
	v_rcp_f32_e32 v155, v147
	v_rcp_f32_e32 v135, v135
	v_rcp_f32_e32 v140, v156
	v_mul_f32_e32 v139, v142, v143
	v_mul_f32_e32 v141, v148, v141
	v_mul_f32_e32 v142, v144, v154
	v_mul_f32_e32 v143, v146, v155
	v_mul_f32_e32 v135, v135, v140
	v_cvt_pk_bf16_f32 v136, v136, v137
	v_cvt_pk_bf16_f32 v137, v138, v139
	v_cvt_pk_bf16_f32 v138, v142, v143
	v_cvt_pk_bf16_f32 v139, v141, v135
	v_lshlrev_b64 v[140:141], 12, v[2:3]
	v_lshl_add_u64 v[142:143], s[16:17], 0, v[140:141]
	v_lshlrev_b64 v[132:133], 1, v[132:133]
	v_lshl_add_u64 v[140:141], s[18:19], 0, v[140:141]
	v_lshl_add_u64 v[142:143], v[142:143], 0, v[132:133]
	v_lshl_add_u64 v[140:141], v[140:141], 0, v[132:133]
	global_store_dwordx4 v[142:143], v[136:139], off
	s_nop 1
	v_cvt_pk_bf16_f32 v136, v150, v151
	v_cvt_pk_bf16_f32 v137, v152, v153
	v_cvt_pk_bf16_f32 v138, v145, v147
	v_cvt_pk_bf16_f32 v139, v149, v156
	global_store_dwordx4 v[140:141], v[136:139], off
	v_add_u32_e32 v140, 16, v2
	v_ashrrev_i32_e32 v141, 31, v140
	v_lshl_add_u64 v[136:137], v[140:141], 2, s[14:15]
	s_waitcnt vmcnt(8)
; DI float sigmoidf_(float x) { return __builtin_amdgcn_rcpf(1.0f + __builtin_amdgcn_exp2f(-x * LOG2E)); }
; DI float rs_of(const float* ss, int row) { return 1.0f / sqrtf(ss[row] * (1.0f / DM) + EPS); }
; DI u32x4 pack8(f32x4 a, f32x4 b) { u32x4 w; w.x = cvt_pk_bf16(a[0], a[1]); w.y = cvt_pk_bf16(a[2], a[3]); w.z = cvt_pk_bf16(b[0], b[1]); w.w = cvt_pk_bf16(b[2], b[3]); return w; }
;     DI void operator()(AccRef acc, const Unit& u, int wr, int wc, int fr, int fq) const {
;     ...
;             for (int m = 0; m < 4; ++m) { const int row = u.pm * 256 + ai * 128 + wr * 64 + m * 16 + fr; const float r = rs_of(ss, row); f32x4 ra[2], sb[2];
; #pragma unroll
;                 for (int n = 0; n < 2; ++n)
; #pragma unroll
;                     for (int j = 0; j < 4; ++j) { const float a = sigmoidf_(acc[ai][0][m][n][j] * r), b = fmaxf(sigmoidf_(acc[ai][1][m][n][j] * r), 1e-4f); sb[n][j] = b; ra[n][j] = a * __builtin_amdgcn_rcpf(b); }
;                 *(u32x4*)(RAT + (size_t)row * DM + col0) = pack8(ra[0], ra[1]); *(u32x4*)(SB + (size_t)row * DM + col0) = pack8(sb[0], sb[1]); }
	v_mov_b32_e32 v3, v207
	v_lshlrev_b64 v[140:141], 12, v[140:141]
	v_fmamk_f32 v3, v3, 0x3a000000, v205
	v_mul_f32_e32 v135, 0x4f800000, v3
	v_cmp_gt_f32_e32 vcc, s65, v3
	s_nop 1
	v_cndmask_b32_e32 v3, v3, v135, vcc
	v_sqrt_f32_e32 v135, v3
	s_nop 0
	v_add_u32_e32 v136, -1, v135
	v_add_u32_e32 v137, 1, v135
	v_fma_f32 v138, -v136, v135, v3
	v_fma_f32 v139, -v137, v135, v3
	v_cmp_ge_f32_e64 s[8:9], 0, v138
	s_nop 1
	v_cndmask_b32_e64 v135, v135, v136, s[8:9]
	v_cmp_lt_f32_e64 s[8:9], 0, v139
	s_nop 1
	v_cndmask_b32_e64 v135, v135, v137, s[8:9]
	v_mul_f32_e32 v136, 0x37800000, v135
	v_cndmask_b32_e32 v135, v135, v136, vcc
	v_cmp_class_f32_e32 vcc, v3, v206
	s_nop 1
	v_cndmask_b32_e32 v3, v135, v3, vcc
	v_div_scale_f32 v135, s[0:1], v3, v3, 1.0
	v_rcp_f32_e32 v136, v135
	v_div_scale_f32 v137, vcc, 1.0, v3, 1.0
	v_fma_f32 v138, -v135, v136, 1.0
	v_fmac_f32_e32 v136, v138, v136
	v_mul_f32_e32 v138, v137, v136
	v_fma_f32 v139, -v135, v138, v137
	v_fmac_f32_e32 v138, v139, v136
	v_fma_f32 v135, -v135, v138, v137
	v_div_fmas_f32 v135, v135, v136, v138
	v_div_fixup_f32 v3, v135, v3, 1.0
	v_mul_f32_e32 v136, v104, v3
	v_mul_f32_e32 v138, v105, v3
	v_mul_f32_e32 v142, v106, v3
	v_mul_f32_e32 v136, 0xbfb8aa3b, v136
	v_mul_f32_e32 v138, 0xbfb8aa3b, v138
	v_mul_f32_e32 v142, 0xbfb8aa3b, v142
	v_exp_f32_e32 v136, v136
	v_exp_f32_e32 v138, v138
	v_exp_f32_e32 v142, v142
	v_mul_f32_e32 v135, v112, v3
	v_mul_f32_e32 v137, v113, v3
	v_mul_f32_e32 v139, v114, v3
	v_mul_f32_e32 v135, 0xbfb8aa3b, v135
	v_mul_f32_e32 v137, 0xbfb8aa3b, v137
	v_mul_f32_e32 v139, 0xbfb8aa3b, v139
	v_add_f32_e32 v136, 1.0, v136
	v_add_f32_e32 v138, 1.0, v138
	v_add_f32_e32 v142, 1.0, v142
	v_exp_f32_e32 v135, v135
	v_exp_f32_e32 v137, v137
	v_exp_f32_e32 v139, v139
	v_rcp_f32_e32 v136, v136
	v_rcp_f32_e32 v138, v138
	v_rcp_f32_e32 v142, v142
	v_mul_f32_e32 v144, v107, v3
	v_add_f32_e32 v135, 1.0, v135
	v_add_f32_e32 v137, 1.0, v137
	v_add_f32_e32 v139, 1.0, v139
	v_max_f32_e32 v147, 0x38d1b717, v136
	v_max_f32_e32 v148, 0x38d1b717, v138
	v_max_f32_e32 v149, 0x38d1b717, v142
	v_mul_f32_e32 v144, 0xbfb8aa3b, v144
	v_rcp_f32_e32 v135, v135
	v_rcp_f32_e32 v137, v137
	v_rcp_f32_e32 v139, v139
	v_rcp_f32_e32 v136, v147
	v_rcp_f32_e32 v138, v148
	v_rcp_f32_e32 v142, v149
	v_exp_f32_e32 v144, v144
	v_mul_f32_e32 v143, v115, v3
	v_mul_f32_e32 v135, v135, v136
	v_mul_f32_e32 v136, v137, v138
	v_mul_f32_e32 v137, v139, v142
	v_mul_f32_e32 v142, v101, v3
	v_mul_f32_e32 v143, 0xbfb8aa3b, v143
	v_add_f32_e32 v144, 1.0, v144
	v_mul_f32_e32 v142, 0xbfb8aa3b, v142
	v_exp_f32_e32 v143, v143
	v_rcp_f32_e32 v144, v144
	v_exp_f32_e32 v142, v142
	v_mul_f32_e32 v146, v100, v3
	v_add_f32_e32 v143, 1.0, v143
	v_max_f32_e32 v144, 0x38d1b717, v144
	v_add_f32_e32 v142, 1.0, v142
	v_rcp_f32_e32 v143, v143
	v_rcp_f32_e32 v150, v144
	v_rcp_f32_e32 v142, v142
	v_mul_f32_e32 v146, 0xbfb8aa3b, v146
	v_exp_f32_e32 v146, v146
	v_mul_f32_e32 v138, v143, v150
	v_max_f32_e32 v150, 0x38d1b717, v142
	v_mul_f32_e32 v142, v102, v3
	v_mul_f32_e32 v142, 0xbfb8aa3b, v142
	v_exp_f32_e32 v142, v142
	v_mul_f32_e32 v143, v109, v3
	v_mul_f32_e32 v145, v108, v3
	v_mul_f32_e32 v143, 0xbfb8aa3b, v143
	v_add_f32_e32 v142, 1.0, v142
	v_rcp_f32_e32 v142, v142
	v_mul_f32_e32 v151, v110, v3
	v_mul_f32_e32 v145, 0xbfb8aa3b, v145
	v_add_f32_e32 v146, 1.0, v146
	v_max_f32_e32 v153, 0x38d1b717, v142
	v_mul_f32_e32 v142, v103, v3
	v_mul_f32_e32 v142, 0xbfb8aa3b, v142
	v_exp_f32_e32 v142, v142
	v_mul_f32_e32 v3, v111, v3
	v_exp_f32_e32 v143, v143
	v_mul_f32_e32 v3, 0xbfb8aa3b, v3
	v_add_f32_e32 v142, 1.0, v142
	v_exp_f32_e32 v145, v145
	v_rcp_f32_e32 v146, v146
	v_mul_f32_e32 v151, 0xbfb8aa3b, v151
	v_exp_f32_e32 v3, v3
	v_rcp_f32_e32 v142, v142
	v_exp_f32_e32 v151, v151
	v_add_f32_e32 v143, 1.0, v143
	v_add_f32_e32 v139, 1.0, v145
	v_max_f32_e32 v145, 0x38d1b717, v146
	v_rcp_f32_e32 v143, v143
	v_rcp_f32_e32 v152, v150
	v_add_f32_e32 v3, 1.0, v3
	v_max_f32_e32 v155, 0x38d1b717, v142
	v_rcp_f32_e32 v139, v139
	v_rcp_f32_e32 v146, v145
	v_add_f32_e32 v151, 1.0, v151
	v_rcp_f32_e32 v3, v3
	v_rcp_f32_e32 v142, v155
	v_rcp_f32_e32 v151, v151
	v_rcp_f32_e32 v154, v153
	v_mul_f32_e32 v143, v143, v152
	v_mul_f32_e32 v139, v139, v146
	v_mul_f32_e32 v3, v3, v142
	v_cvt_pk_bf16_f32 v136, v135, v136
	v_cvt_pk_bf16_f32 v137, v137, v138
	v_cvt_pk_bf16_f32 v138, v139, v143
	v_lshl_add_u64 v[142:143], s[16:17], 0, v[140:141]
	v_lshl_add_u64 v[140:141], s[18:19], 0, v[140:141]
	v_mul_f32_e32 v146, v151, v154
	v_cvt_pk_bf16_f32 v139, v146, v3
	v_lshl_add_u64 v[142:143], v[142:143], 0, v[132:133]
	v_lshl_add_u64 v[140:141], v[140:141], 0, v[132:133]
	global_store_dwordx4 v[142:143], v[136:139], off
	s_nop 1
	v_cvt_pk_bf16_f32 v136, v147, v148
	v_cvt_pk_bf16_f32 v137, v149, v144
	v_cvt_pk_bf16_f32 v138, v145, v150
	v_cvt_pk_bf16_f32 v139, v153, v155
	global_store_dwordx4 v[140:141], v[136:139], off
	v_add_u32_e32 v140, 32, v2
	v_ashrrev_i32_e32 v141, 31, v140
	v_lshl_add_u64 v[136:137], v[140:141], 2, s[14:15]
	s_waitcnt vmcnt(9)
; DI float sigmoidf_(float x) { return __builtin_amdgcn_rcpf(1.0f + __builtin_amdgcn_exp2f(-x * LOG2E)); }
; DI float rs_of(const float* ss, int row) { return 1.0f / sqrtf(ss[row] * (1.0f / DM) + EPS); }
; DI u32x4 pack8(f32x4 a, f32x4 b) { u32x4 w; w.x = cvt_pk_bf16(a[0], a[1]); w.y = cvt_pk_bf16(a[2], a[3]); w.z = cvt_pk_bf16(b[0], b[1]); w.w = cvt_pk_bf16(b[2], b[3]); return w; }
;     DI void operator()(AccRef acc, const Unit& u, int wr, int wc, int fr, int fq) const {
;     ...
;             for (int m = 0; m < 4; ++m) { const int row = u.pm * 256 + ai * 128 + wr * 64 + m * 16 + fr; const float r = rs_of(ss, row); f32x4 ra[2], sb[2];
; #pragma unroll
;                 for (int n = 0; n < 2; ++n)
; #pragma unroll
;                     for (int j = 0; j < 4; ++j) { const float a = sigmoidf_(acc[ai][0][m][n][j] * r), b = fmaxf(sigmoidf_(acc[ai][1][m][n][j] * r), 1e-4f); sb[n][j] = b; ra[n][j] = a * __builtin_amdgcn_rcpf(b); }
;                 *(u32x4*)(RAT + (size_t)row * DM + col0) = pack8(ra[0], ra[1]); *(u32x4*)(SB + (size_t)row * DM + col0) = pack8(sb[0], sb[1]); }
	v_mov_b32_e32 v3, v240
	v_lshlrev_b64 v[140:141], 12, v[140:141]
	v_fmamk_f32 v3, v3, 0x3a000000, v205
	v_mul_f32_e32 v135, 0x4f800000, v3
	v_cmp_gt_f32_e32 vcc, s65, v3
	s_nop 1
	v_cndmask_b32_e32 v3, v3, v135, vcc
	v_sqrt_f32_e32 v135, v3
	s_nop 0
	v_add_u32_e32 v136, -1, v135
	v_add_u32_e32 v137, 1, v135
	v_fma_f32 v138, -v136, v135, v3
	v_fma_f32 v139, -v137, v135, v3
	v_cmp_ge_f32_e64 s[8:9], 0, v138
	s_nop 1
	v_cndmask_b32_e64 v135, v135, v136, s[8:9]
	v_cmp_lt_f32_e64 s[8:9], 0, v139
	s_nop 1
	v_cndmask_b32_e64 v135, v135, v137, s[8:9]
	v_mul_f32_e32 v136, 0x37800000, v135
	v_cndmask_b32_e32 v135, v135, v136, vcc
	v_cmp_class_f32_e32 vcc, v3, v206
	s_nop 1
	v_cndmask_b32_e32 v3, v135, v3, vcc
	v_div_scale_f32 v135, s[0:1], v3, v3, 1.0
	v_rcp_f32_e32 v136, v135
	v_div_scale_f32 v137, vcc, 1.0, v3, 1.0
	v_fma_f32 v138, -v135, v136, 1.0
	v_fmac_f32_e32 v136, v138, v136
	v_mul_f32_e32 v138, v137, v136
	v_fma_f32 v139, -v135, v138, v137
	v_fmac_f32_e32 v138, v139, v136
	v_fma_f32 v135, -v135, v138, v137
	v_div_fmas_f32 v135, v135, v136, v138
	v_div_fixup_f32 v3, v135, v3, 1.0
	v_mul_f32_e32 v136, v88, v3
	v_mul_f32_e32 v136, 0xbfb8aa3b, v136
	v_exp_f32_e32 v136, v136
	v_mul_f32_e32 v138, v89, v3
	v_mul_f32_e32 v135, v96, v3
	v_mul_f32_e32 v138, 0xbfb8aa3b, v138
	v_mul_f32_e32 v135, 0xbfb8aa3b, v135
	v_exp_f32_e32 v138, v138
	v_add_f32_e32 v136, 1.0, v136
	v_exp_f32_e32 v135, v135
	v_rcp_f32_e32 v136, v136
	v_mul_f32_e32 v137, v97, v3
	v_mul_f32_e32 v142, v90, v3
	v_mul_f32_e32 v137, 0xbfb8aa3b, v137
	v_mul_f32_e32 v142, 0xbfb8aa3b, v142
	v_add_f32_e32 v138, 1.0, v138
	v_exp_f32_e32 v137, v137
	v_exp_f32_e32 v142, v142
	v_add_f32_e32 v135, 1.0, v135
	v_rcp_f32_e32 v138, v138
	v_max_f32_e32 v144, 0x38d1b717, v136
	v_rcp_f32_e32 v135, v135
	v_rcp_f32_e32 v136, v144
	v_mul_f32_e32 v139, v98, v3
	v_mul_f32_e32 v139, 0xbfb8aa3b, v139
	v_add_f32_e32 v137, 1.0, v137
	v_max_f32_e32 v145, 0x38d1b717, v138
	v_add_f32_e32 v142, 1.0, v142
	v_exp_f32_e32 v139, v139
	v_rcp_f32_e32 v137, v137
	v_rcp_f32_e32 v138, v145
	v_mul_f32_e32 v135, v135, v136
	v_rcp_f32_e32 v136, v142
	v_mul_f32_e32 v142, v99, v3
	v_mul_f32_e32 v137, v137, v138
	v_add_f32_e32 v138, 1.0, v139
	v_max_f32_e32 v146, 0x38d1b717, v136
	v_mul_f32_e32 v142, 0xbfb8aa3b, v142
	v_rcp_f32_e32 v138, v138
	v_rcp_f32_e32 v136, v146
	v_exp_f32_e32 v142, v142
	v_mul_f32_e32 v139, v91, v3
	v_mul_f32_e32 v139, 0xbfb8aa3b, v139
	v_mul_f32_e32 v138, v138, v136
	v_add_f32_e32 v136, 1.0, v142
	v_mul_f32_e32 v142, v84, v3
	v_mul_f32_e32 v142, 0xbfb8aa3b, v142
	v_exp_f32_e32 v142, v142
	v_exp_f32_e32 v139, v139
	v_mul_f32_e32 v143, v92, v3
	v_mul_f32_e32 v143, 0xbfb8aa3b, v143
	v_add_f32_e32 v142, 1.0, v142
	v_rcp_f32_e32 v142, v142
	v_add_f32_e32 v139, 1.0, v139
	v_rcp_f32_e32 v139, v139
	v_rcp_f32_e32 v136, v136
	v_max_f32_e32 v148, 0x38d1b717, v142
	v_mul_f32_e32 v142, v85, v3
	v_mul_f32_e32 v142, 0xbfb8aa3b, v142
	v_exp_f32_e32 v142, v142
	v_max_f32_e32 v147, 0x38d1b717, v139
	v_rcp_f32_e32 v139, v147
	v_exp_f32_e32 v143, v143
	v_add_f32_e32 v142, 1.0, v142
	v_rcp_f32_e32 v142, v142
	v_mul_f32_e32 v139, v136, v139
	v_add_f32_e32 v136, 1.0, v143
	v_mul_f32_e32 v143, v93, v3
	v_max_f32_e32 v150, 0x38d1b717, v142
	v_mul_f32_e32 v142, v86, v3
	v_mul_f32_e32 v142, 0xbfb8aa3b, v142
	v_exp_f32_e32 v142, v142
	v_mul_f32_e32 v143, 0xbfb8aa3b, v143
	v_mul_f32_e32 v151, v94, v3
	v_exp_f32_e32 v143, v143
	v_add_f32_e32 v142, 1.0, v142
	v_rcp_f32_e32 v142, v142
	v_mul_f32_e32 v151, 0xbfb8aa3b, v151
	v_exp_f32_e32 v151, v151
	v_add_f32_e32 v143, 1.0, v143
	v_max_f32_e32 v153, 0x38d1b717, v142
	v_mul_f32_e32 v142, v87, v3
	v_mul_f32_e32 v142, 0xbfb8aa3b, v142
	v_exp_f32_e32 v142, v142
	v_mul_f32_e32 v3, v95, v3
	v_mul_f32_e32 v3, 0xbfb8aa3b, v3
	v_exp_f32_e32 v3, v3
	v_add_f32_e32 v142, 1.0, v142
	v_rcp_f32_e32 v142, v142
	v_rcp_f32_e32 v143, v143
	v_rcp_f32_e32 v152, v150
	v_add_f32_e32 v3, 1.0, v3
	v_max_f32_e32 v155, 0x38d1b717, v142
	v_rcp_f32_e32 v136, v136
	v_rcp_f32_e32 v149, v148
	v_add_f32_e32 v151, 1.0, v151
	v_rcp_f32_e32 v3, v3
	v_rcp_f32_e32 v142, v155
	v_rcp_f32_e32 v151, v151
	v_rcp_f32_e32 v154, v153
	v_mul_f32_e32 v143, v143, v152
	v_mul_f32_e32 v149, v136, v149
	v_mul_f32_e32 v3, v3, v142
	v_cvt_pk_bf16_f32 v136, v135, v137
	v_cvt_pk_bf16_f32 v137, v138, v139
	v_cvt_pk_bf16_f32 v138, v149, v143
	v_lshl_add_u64 v[142:143], s[16:17], 0, v[140:141]
	v_lshl_add_u64 v[140:141], s[18:19], 0, v[140:141]
	v_mul_f32_e32 v151, v151, v154
	v_cvt_pk_bf16_f32 v139, v151, v3
	v_lshl_add_u64 v[142:143], v[142:143], 0, v[132:133]
	v_lshl_add_u64 v[140:141], v[140:141], 0, v[132:133]
	global_store_dwordx4 v[142:143], v[136:139], off
	s_nop 1
	v_cvt_pk_bf16_f32 v136, v144, v145
	v_cvt_pk_bf16_f32 v137, v146, v147
	v_cvt_pk_bf16_f32 v138, v148, v150
	v_cvt_pk_bf16_f32 v139, v153, v155
	global_store_dwordx4 v[140:141], v[136:139], off
	v_add_u32_e32 v140, 48, v2
	v_ashrrev_i32_e32 v141, 31, v140
	v_lshl_add_u64 v[136:137], v[140:141], 2, s[14:15]
	s_waitcnt vmcnt(10)
; DI float sigmoidf_(float x) { return __builtin_amdgcn_rcpf(1.0f + __builtin_amdgcn_exp2f(-x * LOG2E)); }
; DI float rs_of(const float* ss, int row) { return 1.0f / sqrtf(ss[row] * (1.0f / DM) + EPS); }
; DI u32x4 pack8(f32x4 a, f32x4 b) { u32x4 w; w.x = cvt_pk_bf16(a[0], a[1]); w.y = cvt_pk_bf16(a[2], a[3]); w.z = cvt_pk_bf16(b[0], b[1]); w.w = cvt_pk_bf16(b[2], b[3]); return w; }
;     DI void operator()(AccRef acc, const Unit& u, int wr, int wc, int fr, int fq) const {
;     ...
;             for (int m = 0; m < 4; ++m) { const int row = u.pm * 256 + ai * 128 + wr * 64 + m * 16 + fr; const float r = rs_of(ss, row); f32x4 ra[2], sb[2];
; #pragma unroll
;                 for (int n = 0; n < 2; ++n)
; #pragma unroll
;                     for (int j = 0; j < 4; ++j) { const float a = sigmoidf_(acc[ai][0][m][n][j] * r), b = fmaxf(sigmoidf_(acc[ai][1][m][n][j] * r), 1e-4f); sb[n][j] = b; ra[n][j] = a * __builtin_amdgcn_rcpf(b); }
;                 *(u32x4*)(RAT + (size_t)row * DM + col0) = pack8(ra[0], ra[1]); *(u32x4*)(SB + (size_t)row * DM + col0) = pack8(sb[0], sb[1]); }
	v_mov_b32_e32 v3, v241
	v_lshlrev_b64 v[140:141], 12, v[140:141]
	v_fmamk_f32 v3, v3, 0x3a000000, v205
	v_mul_f32_e32 v135, 0x4f800000, v3
	v_cmp_gt_f32_e32 vcc, s65, v3
	s_nop 1
	v_cndmask_b32_e32 v3, v3, v135, vcc
	v_sqrt_f32_e32 v135, v3
	s_nop 0
	v_add_u32_e32 v136, -1, v135
	v_fma_f32 v137, -v136, v135, v3
	v_cmp_ge_f32_e64 s[8:9], 0, v137
	v_add_u32_e32 v137, 1, v135
	s_nop 0
	v_cndmask_b32_e64 v136, v135, v136, s[8:9]
	v_fma_f32 v135, -v137, v135, v3
	v_cmp_lt_f32_e64 s[8:9], 0, v135
	s_nop 1
	v_cndmask_b32_e64 v135, v136, v137, s[8:9]
	v_mul_f32_e32 v136, 0x37800000, v135
	v_cndmask_b32_e32 v135, v135, v136, vcc
	v_cmp_class_f32_e32 vcc, v3, v206
	s_nop 1
	v_cndmask_b32_e32 v3, v135, v3, vcc
	v_div_scale_f32 v135, s[0:1], v3, v3, 1.0
	v_rcp_f32_e32 v136, v135
	s_nop 0
	v_fma_f32 v137, -v135, v136, 1.0
	v_fmac_f32_e32 v136, v137, v136
	v_div_scale_f32 v137, vcc, 1.0, v3, 1.0
	v_mul_f32_e32 v138, v137, v136
	v_fma_f32 v139, -v135, v138, v137
	v_fmac_f32_e32 v138, v139, v136
	v_fma_f32 v135, -v135, v138, v137
	v_div_fmas_f32 v135, v135, v136, v138
	v_div_fixup_f32 v3, v135, v3, 1.0
	v_mul_f32_e32 v135, v72, v3
	v_mul_f32_e32 v135, 0xbfb8aa3b, v135
	v_exp_f32_e32 v135, v135
	v_mul_f32_e32 v136, v80, v3
	v_mul_f32_e32 v136, 0xbfb8aa3b, v136
	v_exp_f32_e32 v136, v136
	v_add_f32_e32 v135, 1.0, v135
	v_rcp_f32_e32 v135, v135
	v_mul_f32_e32 v139, v81, v3
	v_add_f32_e32 v136, 1.0, v136
	v_mul_f32_e32 v138, v73, v3
	v_max_f32_e32 v135, 0x38d1b717, v135
	v_mul_f32_e32 v139, 0xbfb8aa3b, v139
	v_rcp_f32_e32 v136, v136
	v_rcp_f32_e32 v137, v135
	v_mul_f32_e32 v138, 0xbfb8aa3b, v138
	v_exp_f32_e32 v139, v139
	v_exp_f32_e32 v138, v138
	v_mul_f32_e32 v136, v136, v137
	v_mul_f32_e32 v142, v82, v3
	v_add_f32_e32 v137, 1.0, v139
	v_mul_f32_e32 v139, v74, v3
	v_add_f32_e32 v138, 1.0, v138
	v_mul_f32_e32 v139, 0xbfb8aa3b, v139
	v_rcp_f32_e32 v138, v138
	v_exp_f32_e32 v139, v139
	v_mul_f32_e32 v142, 0xbfb8aa3b, v142
	v_rcp_f32_e32 v137, v137
	v_max_f32_e32 v144, 0x38d1b717, v138
	v_add_f32_e32 v139, 1.0, v139
	v_rcp_f32_e32 v138, v144
	v_exp_f32_e32 v142, v142
	v_rcp_f32_e32 v139, v139
	v_mul_f32_e32 v143, v83, v3
	v_mul_f32_e32 v137, v137, v138
	v_add_f32_e32 v138, 1.0, v142
	v_max_f32_e32 v145, 0x38d1b717, v139
	v_mul_f32_e32 v142, v75, v3
	v_mul_f32_e32 v143, 0xbfb8aa3b, v143
	v_rcp_f32_e32 v138, v138
	v_rcp_f32_e32 v139, v145
	v_mul_f32_e32 v142, 0xbfb8aa3b, v142
	v_exp_f32_e32 v143, v143
	v_exp_f32_e32 v142, v142
	v_mul_f32_e32 v138, v138, v139
	v_mul_f32_e32 v147, v76, v3
	v_add_f32_e32 v139, 1.0, v143
	v_mul_f32_e32 v143, v68, v3
	v_add_f32_e32 v142, 1.0, v142
	v_mul_f32_e32 v143, 0xbfb8aa3b, v143
	v_rcp_f32_e32 v142, v142
	v_exp_f32_e32 v143, v143
	v_mul_f32_e32 v147, 0xbfb8aa3b, v147
	v_rcp_f32_e32 v139, v139
	v_max_f32_e32 v146, 0x38d1b717, v142
	v_add_f32_e32 v143, 1.0, v143
	v_rcp_f32_e32 v142, v146
	v_exp_f32_e32 v147, v147
	v_rcp_f32_e32 v143, v143
	v_mul_f32_e32 v148, v77, v3
	v_mul_f32_e32 v139, v139, v142
	v_add_f32_e32 v142, 1.0, v147
	v_max_f32_e32 v147, 0x38d1b717, v143
	v_mul_f32_e32 v143, v69, v3
	v_mul_f32_e32 v143, 0xbfb8aa3b, v143
	v_exp_f32_e32 v143, v143
	v_mul_f32_e32 v151, v78, v3
	v_mul_f32_e32 v148, 0xbfb8aa3b, v148
	v_exp_f32_e32 v148, v148
	v_add_f32_e32 v143, 1.0, v143
	v_rcp_f32_e32 v143, v143
	v_mul_f32_e32 v151, 0xbfb8aa3b, v151
	v_exp_f32_e32 v151, v151
	v_rcp_f32_e32 v142, v142
	v_max_f32_e32 v150, 0x38d1b717, v143
	v_mul_f32_e32 v143, v70, v3
	v_mul_f32_e32 v143, 0xbfb8aa3b, v143
	v_exp_f32_e32 v143, v143
	v_rcp_f32_e32 v149, v147
	v_add_f32_e32 v148, 1.0, v148
	v_rcp_f32_e32 v148, v148
	v_add_f32_e32 v143, 1.0, v143
	v_rcp_f32_e32 v143, v143
	v_rcp_f32_e32 v152, v150
	v_add_f32_e32 v151, 1.0, v151
	v_rcp_f32_e32 v151, v151
	v_max_f32_e32 v153, 0x38d1b717, v143
	v_mul_f32_e32 v143, v71, v3
	v_mul_f32_e32 v143, 0xbfb8aa3b, v143
	v_exp_f32_e32 v143, v143
	v_mul_f32_e32 v3, v79, v3
	v_mul_f32_e32 v3, 0xbfb8aa3b, v3
	v_exp_f32_e32 v3, v3
	v_add_f32_e32 v143, 1.0, v143
	v_rcp_f32_e32 v143, v143
	v_rcp_f32_e32 v154, v153
	v_add_f32_e32 v3, 1.0, v3
	v_rcp_f32_e32 v3, v3
	v_max_f32_e32 v155, 0x38d1b717, v143
	v_rcp_f32_e32 v143, v155
	v_mul_f32_e32 v142, v142, v149
	v_mul_f32_e32 v148, v148, v152
	v_cvt_pk_bf16_f32 v136, v136, v137
	v_mul_f32_e32 v3, v3, v143
	v_cvt_pk_bf16_f32 v137, v138, v139
	v_cvt_pk_bf16_f32 v138, v142, v148
	v_lshl_add_u64 v[142:143], s[16:17], 0, v[140:141]
	v_lshl_add_u64 v[140:141], s[18:19], 0, v[140:141]
	v_mul_f32_e32 v149, v151, v154
	v_cvt_pk_bf16_f32 v139, v149, v3
	v_lshl_add_u64 v[142:143], v[142:143], 0, v[132:133]
	v_lshl_add_u64 v[140:141], v[140:141], 0, v[132:133]
	global_store_dwordx4 v[142:143], v[136:139], off
	s_nop 1
	v_cvt_pk_bf16_f32 v136, v135, v144
	v_cvt_pk_bf16_f32 v137, v145, v146
	v_cvt_pk_bf16_f32 v138, v147, v150
	v_cvt_pk_bf16_f32 v139, v153, v155
	global_store_dwordx4 v[140:141], v[136:139], off
	v_add_u32_e32 v140, 0x80, v2
	v_ashrrev_i32_e32 v141, 31, v140
	v_lshl_add_u64 v[136:137], v[140:141], 2, s[14:15]
	s_waitcnt vmcnt(11)
; DI float sigmoidf_(float x) { return __builtin_amdgcn_rcpf(1.0f + __builtin_amdgcn_exp2f(-x * LOG2E)); }
; DI float rs_of(const float* ss, int row) { return 1.0f / sqrtf(ss[row] * (1.0f / DM) + EPS); }
; DI u32x4 pack8(f32x4 a, f32x4 b) { u32x4 w; w.x = cvt_pk_bf16(a[0], a[1]); w.y = cvt_pk_bf16(a[2], a[3]); w.z = cvt_pk_bf16(b[0], b[1]); w.w = cvt_pk_bf16(b[2], b[3]); return w; }
;     DI void operator()(AccRef acc, const Unit& u, int wr, int wc, int fr, int fq) const {
;     ...
;             for (int m = 0; m < 4; ++m) { const int row = u.pm * 256 + ai * 128 + wr * 64 + m * 16 + fr; const float r = rs_of(ss, row); f32x4 ra[2], sb[2];
; #pragma unroll
;                 for (int n = 0; n < 2; ++n)
; #pragma unroll
;                     for (int j = 0; j < 4; ++j) { const float a = sigmoidf_(acc[ai][0][m][n][j] * r), b = fmaxf(sigmoidf_(acc[ai][1][m][n][j] * r), 1e-4f); sb[n][j] = b; ra[n][j] = a * __builtin_amdgcn_rcpf(b); }
;                 *(u32x4*)(RAT + (size_t)row * DM + col0) = pack8(ra[0], ra[1]); *(u32x4*)(SB + (size_t)row * DM + col0) = pack8(sb[0], sb[1]); }
	v_mov_b32_e32 v3, v242
	v_lshlrev_b64 v[140:141], 12, v[140:141]
	v_fmamk_f32 v3, v3, 0x3a000000, v205
	v_mul_f32_e32 v135, 0x4f800000, v3
	v_cmp_gt_f32_e32 vcc, s65, v3
	s_nop 1
	v_cndmask_b32_e32 v3, v3, v135, vcc
	v_sqrt_f32_e32 v135, v3
	s_nop 0
	v_add_u32_e32 v136, -1, v135
	v_fma_f32 v137, -v136, v135, v3
	v_cmp_ge_f32_e64 s[8:9], 0, v137
	v_add_u32_e32 v137, 1, v135
	s_nop 0
	v_cndmask_b32_e64 v136, v135, v136, s[8:9]
	v_fma_f32 v135, -v137, v135, v3
	v_cmp_lt_f32_e64 s[8:9], 0, v135
	s_nop 1
	v_cndmask_b32_e64 v135, v136, v137, s[8:9]
	v_mul_f32_e32 v136, 0x37800000, v135
	v_cndmask_b32_e32 v135, v135, v136, vcc
	v_cmp_class_f32_e32 vcc, v3, v206
	s_nop 1
	v_cndmask_b32_e32 v3, v135, v3, vcc
	v_div_scale_f32 v135, s[0:1], v3, v3, 1.0
	v_rcp_f32_e32 v136, v135
	s_nop 0
	v_fma_f32 v137, -v135, v136, 1.0
	v_fmac_f32_e32 v136, v137, v136
	v_div_scale_f32 v137, vcc, 1.0, v3, 1.0
	v_mul_f32_e32 v138, v137, v136
	v_fma_f32 v139, -v135, v138, v137
	v_fmac_f32_e32 v138, v139, v136
	v_fma_f32 v135, -v135, v138, v137
	v_div_fmas_f32 v135, v135, v136, v138
	v_div_fixup_f32 v3, v135, v3, 1.0
	v_mul_f32_e32 v135, v56, v3
	v_mul_f32_e32 v135, 0xbfb8aa3b, v135
	v_exp_f32_e32 v135, v135
	v_mul_f32_e32 v136, v64, v3
	v_mul_f32_e32 v136, 0xbfb8aa3b, v136
	v_exp_f32_e32 v136, v136
	v_add_f32_e32 v135, 1.0, v135
	v_rcp_f32_e32 v135, v135
	v_mul_f32_e32 v139, v65, v3
	v_add_f32_e32 v136, 1.0, v136
	v_mul_f32_e32 v138, v57, v3
	v_max_f32_e32 v135, 0x38d1b717, v135
	v_mul_f32_e32 v139, 0xbfb8aa3b, v139
	v_rcp_f32_e32 v136, v136
	v_rcp_f32_e32 v137, v135
	v_mul_f32_e32 v138, 0xbfb8aa3b, v138
	v_exp_f32_e32 v139, v139
	v_exp_f32_e32 v138, v138
	v_mul_f32_e32 v136, v136, v137
	v_mul_f32_e32 v142, v66, v3
	v_add_f32_e32 v137, 1.0, v139
	v_mul_f32_e32 v139, v58, v3
	v_add_f32_e32 v138, 1.0, v138
	v_mul_f32_e32 v139, 0xbfb8aa3b, v139
	v_rcp_f32_e32 v138, v138
	v_exp_f32_e32 v139, v139
	v_mul_f32_e32 v142, 0xbfb8aa3b, v142
	v_rcp_f32_e32 v137, v137
	v_max_f32_e32 v144, 0x38d1b717, v138
	v_add_f32_e32 v139, 1.0, v139
	v_rcp_f32_e32 v138, v144
	v_exp_f32_e32 v142, v142
	v_rcp_f32_e32 v139, v139
	v_mul_f32_e32 v143, v67, v3
	v_mul_f32_e32 v137, v137, v138
	v_add_f32_e32 v138, 1.0, v142
	v_max_f32_e32 v145, 0x38d1b717, v139
	v_mul_f32_e32 v142, v59, v3
	v_mul_f32_e32 v143, 0xbfb8aa3b, v143
	v_rcp_f32_e32 v138, v138
	v_rcp_f32_e32 v139, v145
	v_mul_f32_e32 v142, 0xbfb8aa3b, v142
	v_exp_f32_e32 v143, v143
	v_exp_f32_e32 v142, v142
	v_mul_f32_e32 v138, v138, v139
	v_mul_f32_e32 v147, v60, v3
	v_add_f32_e32 v139, 1.0, v143
	v_mul_f32_e32 v143, v52, v3
	v_add_f32_e32 v142, 1.0, v142
	v_mul_f32_e32 v143, 0xbfb8aa3b, v143
	v_rcp_f32_e32 v142, v142
	v_exp_f32_e32 v143, v143
	v_mul_f32_e32 v147, 0xbfb8aa3b, v147
	v_rcp_f32_e32 v139, v139
	v_max_f32_e32 v146, 0x38d1b717, v142
	v_add_f32_e32 v143, 1.0, v143
	v_rcp_f32_e32 v142, v146
	v_exp_f32_e32 v147, v147
	v_rcp_f32_e32 v143, v143
	v_mul_f32_e32 v148, v61, v3
	v_mul_f32_e32 v139, v139, v142
	v_add_f32_e32 v142, 1.0, v147
	v_max_f32_e32 v147, 0x38d1b717, v143
	v_mul_f32_e32 v143, v53, v3
	v_mul_f32_e32 v143, 0xbfb8aa3b, v143
	v_exp_f32_e32 v143, v143
	v_mul_f32_e32 v151, v62, v3
	v_mul_f32_e32 v148, 0xbfb8aa3b, v148
	v_exp_f32_e32 v148, v148
	v_add_f32_e32 v143, 1.0, v143
	v_rcp_f32_e32 v143, v143
	v_mul_f32_e32 v151, 0xbfb8aa3b, v151
	v_exp_f32_e32 v151, v151
	v_rcp_f32_e32 v142, v142
	v_max_f32_e32 v150, 0x38d1b717, v143
	v_mul_f32_e32 v143, v54, v3
	v_mul_f32_e32 v143, 0xbfb8aa3b, v143
	v_exp_f32_e32 v143, v143
	v_rcp_f32_e32 v149, v147
	v_add_f32_e32 v148, 1.0, v148
	v_rcp_f32_e32 v148, v148
	v_add_f32_e32 v143, 1.0, v143
	v_rcp_f32_e32 v143, v143
	v_rcp_f32_e32 v152, v150
	v_add_f32_e32 v151, 1.0, v151
	v_rcp_f32_e32 v151, v151
	v_max_f32_e32 v153, 0x38d1b717, v143
	v_mul_f32_e32 v143, v55, v3
	v_mul_f32_e32 v143, 0xbfb8aa3b, v143
	v_exp_f32_e32 v143, v143
	v_mul_f32_e32 v3, v63, v3
	v_mul_f32_e32 v3, 0xbfb8aa3b, v3
	v_exp_f32_e32 v3, v3
	v_add_f32_e32 v143, 1.0, v143
	v_rcp_f32_e32 v143, v143
	v_rcp_f32_e32 v154, v153
	v_add_f32_e32 v3, 1.0, v3
	v_rcp_f32_e32 v3, v3
	v_max_f32_e32 v155, 0x38d1b717, v143
	v_rcp_f32_e32 v143, v155
	v_mul_f32_e32 v142, v142, v149
	v_mul_f32_e32 v148, v148, v152
	v_cvt_pk_bf16_f32 v136, v136, v137
	v_mul_f32_e32 v3, v3, v143
	v_cvt_pk_bf16_f32 v137, v138, v139
	v_cvt_pk_bf16_f32 v138, v142, v148
	v_lshl_add_u64 v[142:143], s[16:17], 0, v[140:141]
	v_lshl_add_u64 v[140:141], s[18:19], 0, v[140:141]
	v_mul_f32_e32 v149, v151, v154
	v_cvt_pk_bf16_f32 v139, v149, v3
	v_lshl_add_u64 v[142:143], v[142:143], 0, v[132:133]
	v_lshl_add_u64 v[140:141], v[140:141], 0, v[132:133]
	global_store_dwordx4 v[142:143], v[136:139], off
	s_nop 1
	v_cvt_pk_bf16_f32 v136, v135, v144
	v_cvt_pk_bf16_f32 v137, v145, v146
	v_cvt_pk_bf16_f32 v138, v147, v150
	v_cvt_pk_bf16_f32 v139, v153, v155
	global_store_dwordx4 v[140:141], v[136:139], off
	v_add_u32_e32 v140, 0x90, v2
	v_ashrrev_i32_e32 v141, 31, v140
	v_lshl_add_u64 v[136:137], v[140:141], 2, s[14:15]
	s_waitcnt vmcnt(12)
; DI float sigmoidf_(float x) { return __builtin_amdgcn_rcpf(1.0f + __builtin_amdgcn_exp2f(-x * LOG2E)); }
; DI float rs_of(const float* ss, int row) { return 1.0f / sqrtf(ss[row] * (1.0f / DM) + EPS); }
; DI u32x4 pack8(f32x4 a, f32x4 b) { u32x4 w; w.x = cvt_pk_bf16(a[0], a[1]); w.y = cvt_pk_bf16(a[2], a[3]); w.z = cvt_pk_bf16(b[0], b[1]); w.w = cvt_pk_bf16(b[2], b[3]); return w; }
;     DI void operator()(AccRef acc, const Unit& u, int wr, int wc, int fr, int fq) const {
;     ...
;             for (int m = 0; m < 4; ++m) { const int row = u.pm * 256 + ai * 128 + wr * 64 + m * 16 + fr; const float r = rs_of(ss, row); f32x4 ra[2], sb[2];
; #pragma unroll
;                 for (int n = 0; n < 2; ++n)
; #pragma unroll
;                     for (int j = 0; j < 4; ++j) { const float a = sigmoidf_(acc[ai][0][m][n][j] * r), b = fmaxf(sigmoidf_(acc[ai][1][m][n][j] * r), 1e-4f); sb[n][j] = b; ra[n][j] = a * __builtin_amdgcn_rcpf(b); }
;                 *(u32x4*)(RAT + (size_t)row * DM + col0) = pack8(ra[0], ra[1]); *(u32x4*)(SB + (size_t)row * DM + col0) = pack8(sb[0], sb[1]); }
	v_mov_b32_e32 v3, v243
	v_lshlrev_b64 v[140:141], 12, v[140:141]
	v_fmamk_f32 v3, v3, 0x3a000000, v205
	v_mul_f32_e32 v135, 0x4f800000, v3
	v_cmp_gt_f32_e32 vcc, s65, v3
	s_nop 1
	v_cndmask_b32_e32 v3, v3, v135, vcc
	v_sqrt_f32_e32 v135, v3
	s_nop 0
	v_add_u32_e32 v136, -1, v135
	v_fma_f32 v137, -v136, v135, v3
	v_cmp_ge_f32_e64 s[8:9], 0, v137
	v_add_u32_e32 v137, 1, v135
	s_nop 0
	v_cndmask_b32_e64 v136, v135, v136, s[8:9]
	v_fma_f32 v135, -v137, v135, v3
	v_cmp_lt_f32_e64 s[8:9], 0, v135
	s_nop 1
	v_cndmask_b32_e64 v135, v136, v137, s[8:9]
	v_mul_f32_e32 v136, 0x37800000, v135
	v_cndmask_b32_e32 v135, v135, v136, vcc
	v_cmp_class_f32_e32 vcc, v3, v206
	s_nop 1
	v_cndmask_b32_e32 v3, v135, v3, vcc
	v_div_scale_f32 v135, s[0:1], v3, v3, 1.0
	v_rcp_f32_e32 v136, v135
	s_nop 0
	v_fma_f32 v137, -v135, v136, 1.0
	v_fmac_f32_e32 v136, v137, v136
	v_div_scale_f32 v137, vcc, 1.0, v3, 1.0
	v_mul_f32_e32 v138, v137, v136
	v_fma_f32 v139, -v135, v138, v137
	v_fmac_f32_e32 v138, v139, v136
	v_fma_f32 v135, -v135, v138, v137
	v_div_fmas_f32 v135, v135, v136, v138
	v_div_fixup_f32 v3, v135, v3, 1.0
	v_mul_f32_e32 v135, v40, v3
	v_mul_f32_e32 v135, 0xbfb8aa3b, v135
	v_exp_f32_e32 v135, v135
	v_mul_f32_e32 v136, v48, v3
	v_mul_f32_e32 v136, 0xbfb8aa3b, v136
	v_exp_f32_e32 v136, v136
	v_add_f32_e32 v135, 1.0, v135
	v_rcp_f32_e32 v135, v135
	v_mul_f32_e32 v139, v49, v3
	v_add_f32_e32 v136, 1.0, v136
	v_mul_f32_e32 v138, v41, v3
	v_max_f32_e32 v135, 0x38d1b717, v135
	v_mul_f32_e32 v139, 0xbfb8aa3b, v139
	v_rcp_f32_e32 v136, v136
	v_rcp_f32_e32 v137, v135
	v_mul_f32_e32 v138, 0xbfb8aa3b, v138
	v_exp_f32_e32 v139, v139
	v_exp_f32_e32 v138, v138
	v_mul_f32_e32 v136, v136, v137
	v_mul_f32_e32 v142, v50, v3
	v_add_f32_e32 v137, 1.0, v139
	v_mul_f32_e32 v139, v42, v3
	v_add_f32_e32 v138, 1.0, v138
	v_mul_f32_e32 v139, 0xbfb8aa3b, v139
	v_rcp_f32_e32 v138, v138
	v_exp_f32_e32 v139, v139
	v_mul_f32_e32 v142, 0xbfb8aa3b, v142
	v_rcp_f32_e32 v137, v137
	v_max_f32_e32 v144, 0x38d1b717, v138
	v_add_f32_e32 v139, 1.0, v139
	v_rcp_f32_e32 v138, v144
	v_exp_f32_e32 v142, v142
	v_rcp_f32_e32 v139, v139
	v_mul_f32_e32 v143, v51, v3
	v_mul_f32_e32 v137, v137, v138
	v_add_f32_e32 v138, 1.0, v142
	v_max_f32_e32 v145, 0x38d1b717, v139
	v_mul_f32_e32 v142, v43, v3
	v_mul_f32_e32 v143, 0xbfb8aa3b, v143
	v_rcp_f32_e32 v138, v138
	v_rcp_f32_e32 v139, v145
	v_mul_f32_e32 v142, 0xbfb8aa3b, v142
	v_exp_f32_e32 v143, v143
	v_exp_f32_e32 v142, v142
	v_mul_f32_e32 v138, v138, v139
	v_mul_f32_e32 v147, v44, v3
	v_add_f32_e32 v139, 1.0, v143
	v_mul_f32_e32 v143, v36, v3
	v_add_f32_e32 v142, 1.0, v142
	v_mul_f32_e32 v143, 0xbfb8aa3b, v143
	v_rcp_f32_e32 v142, v142
	v_exp_f32_e32 v143, v143
	v_mul_f32_e32 v147, 0xbfb8aa3b, v147
	v_rcp_f32_e32 v139, v139
	v_max_f32_e32 v146, 0x38d1b717, v142
	v_add_f32_e32 v143, 1.0, v143
	v_rcp_f32_e32 v142, v146
	v_exp_f32_e32 v147, v147
	v_rcp_f32_e32 v143, v143
	v_mul_f32_e32 v148, v45, v3
	v_mul_f32_e32 v139, v139, v142
	v_add_f32_e32 v142, 1.0, v147
	v_max_f32_e32 v147, 0x38d1b717, v143
	v_mul_f32_e32 v143, v37, v3
	v_mul_f32_e32 v143, 0xbfb8aa3b, v143
	v_exp_f32_e32 v143, v143
	v_mul_f32_e32 v151, v46, v3
	v_mul_f32_e32 v148, 0xbfb8aa3b, v148
	v_exp_f32_e32 v148, v148
	v_add_f32_e32 v143, 1.0, v143
	v_rcp_f32_e32 v143, v143
	v_mul_f32_e32 v151, 0xbfb8aa3b, v151
	v_exp_f32_e32 v151, v151
	v_rcp_f32_e32 v142, v142
	v_max_f32_e32 v150, 0x38d1b717, v143
	v_mul_f32_e32 v143, v38, v3
	v_mul_f32_e32 v143, 0xbfb8aa3b, v143
	v_exp_f32_e32 v143, v143
	v_rcp_f32_e32 v149, v147
	v_add_f32_e32 v148, 1.0, v148
	v_rcp_f32_e32 v148, v148
	v_add_f32_e32 v143, 1.0, v143
	v_rcp_f32_e32 v143, v143
	v_rcp_f32_e32 v152, v150
	v_add_f32_e32 v151, 1.0, v151
	v_rcp_f32_e32 v151, v151
	v_max_f32_e32 v153, 0x38d1b717, v143
	v_mul_f32_e32 v143, v39, v3
	v_mul_f32_e32 v143, 0xbfb8aa3b, v143
	v_exp_f32_e32 v143, v143
	v_mul_f32_e32 v3, v47, v3
	v_mul_f32_e32 v3, 0xbfb8aa3b, v3
	v_exp_f32_e32 v3, v3
	v_add_f32_e32 v143, 1.0, v143
	v_rcp_f32_e32 v143, v143
	v_rcp_f32_e32 v154, v153
	v_add_f32_e32 v3, 1.0, v3
	v_rcp_f32_e32 v3, v3
	v_max_f32_e32 v155, 0x38d1b717, v143
	v_rcp_f32_e32 v143, v155
	v_mul_f32_e32 v142, v142, v149
	v_mul_f32_e32 v148, v148, v152
	v_cvt_pk_bf16_f32 v136, v136, v137
	v_mul_f32_e32 v3, v3, v143
	v_cvt_pk_bf16_f32 v137, v138, v139
	v_cvt_pk_bf16_f32 v138, v142, v148
	v_lshl_add_u64 v[142:143], s[16:17], 0, v[140:141]
	v_lshl_add_u64 v[140:141], s[18:19], 0, v[140:141]
	v_mul_f32_e32 v149, v151, v154
	v_cvt_pk_bf16_f32 v139, v149, v3
	v_lshl_add_u64 v[142:143], v[142:143], 0, v[132:133]
	v_lshl_add_u64 v[140:141], v[140:141], 0, v[132:133]
	global_store_dwordx4 v[142:143], v[136:139], off
	s_nop 1
	v_cvt_pk_bf16_f32 v136, v135, v144
	v_cvt_pk_bf16_f32 v137, v145, v146
	v_cvt_pk_bf16_f32 v138, v147, v150
	v_cvt_pk_bf16_f32 v139, v153, v155
	global_store_dwordx4 v[140:141], v[136:139], off
	v_add_u32_e32 v140, 0xa0, v2
	v_ashrrev_i32_e32 v141, 31, v140
	v_lshl_add_u64 v[136:137], v[140:141], 2, s[14:15]
	s_waitcnt vmcnt(13)
; DI float sigmoidf_(float x) { return __builtin_amdgcn_rcpf(1.0f + __builtin_amdgcn_exp2f(-x * LOG2E)); }
; DI float rs_of(const float* ss, int row) { return 1.0f / sqrtf(ss[row] * (1.0f / DM) + EPS); }
; DI u32x4 pack8(f32x4 a, f32x4 b) { u32x4 w; w.x = cvt_pk_bf16(a[0], a[1]); w.y = cvt_pk_bf16(a[2], a[3]); w.z = cvt_pk_bf16(b[0], b[1]); w.w = cvt_pk_bf16(b[2], b[3]); return w; }
;     DI void operator()(AccRef acc, const Unit& u, int wr, int wc, int fr, int fq) const {
;     ...
;             for (int m = 0; m < 4; ++m) { const int row = u.pm * 256 + ai * 128 + wr * 64 + m * 16 + fr; const float r = rs_of(ss, row); f32x4 ra[2], sb[2];
; #pragma unroll
;                 for (int n = 0; n < 2; ++n)
; #pragma unroll
;                     for (int j = 0; j < 4; ++j) { const float a = sigmoidf_(acc[ai][0][m][n][j] * r), b = fmaxf(sigmoidf_(acc[ai][1][m][n][j] * r), 1e-4f); sb[n][j] = b; ra[n][j] = a * __builtin_amdgcn_rcpf(b); }
;                 *(u32x4*)(RAT + (size_t)row * DM + col0) = pack8(ra[0], ra[1]); *(u32x4*)(SB + (size_t)row * DM + col0) = pack8(sb[0], sb[1]); }
	v_mov_b32_e32 v3, v236
	v_lshlrev_b64 v[140:141], 12, v[140:141]
	v_add_u32_e32 v2, 0xb0, v2
	v_fmamk_f32 v3, v3, 0x3a000000, v205
	v_mul_f32_e32 v135, 0x4f800000, v3
	v_cmp_gt_f32_e32 vcc, s65, v3
	s_nop 1
	v_cndmask_b32_e32 v3, v3, v135, vcc
	v_sqrt_f32_e32 v135, v3
	s_nop 0
	v_add_u32_e32 v136, -1, v135
	v_fma_f32 v137, -v136, v135, v3
	v_cmp_ge_f32_e64 s[8:9], 0, v137
	v_add_u32_e32 v137, 1, v135
	s_nop 0
	v_cndmask_b32_e64 v136, v135, v136, s[8:9]
	v_fma_f32 v135, -v137, v135, v3
	v_cmp_lt_f32_e64 s[8:9], 0, v135
	s_nop 1
	v_cndmask_b32_e64 v135, v136, v137, s[8:9]
	v_mul_f32_e32 v136, 0x37800000, v135
	v_cndmask_b32_e32 v135, v135, v136, vcc
	v_cmp_class_f32_e32 vcc, v3, v206
	s_nop 1
	v_cndmask_b32_e32 v3, v135, v3, vcc
	v_div_scale_f32 v135, s[0:1], v3, v3, 1.0
	v_rcp_f32_e32 v136, v135
	s_nop 0
	v_fma_f32 v137, -v135, v136, 1.0
	v_fmac_f32_e32 v136, v137, v136
	v_div_scale_f32 v137, vcc, 1.0, v3, 1.0
	v_mul_f32_e32 v138, v137, v136
	v_fma_f32 v139, -v135, v138, v137
	v_fmac_f32_e32 v138, v139, v136
	v_fma_f32 v135, -v135, v138, v137
	v_div_fmas_f32 v135, v135, v136, v138
	v_div_fixup_f32 v3, v135, v3, 1.0
	v_mul_f32_e32 v135, v24, v3
	v_mul_f32_e32 v135, 0xbfb8aa3b, v135
	v_exp_f32_e32 v135, v135
	v_mul_f32_e32 v136, v32, v3
	v_mul_f32_e32 v136, 0xbfb8aa3b, v136
	v_exp_f32_e32 v136, v136
	v_add_f32_e32 v135, 1.0, v135
	v_rcp_f32_e32 v135, v135
	v_mul_f32_e32 v139, v33, v3
	v_add_f32_e32 v136, 1.0, v136
	v_mul_f32_e32 v138, v25, v3
	v_max_f32_e32 v135, 0x38d1b717, v135
	v_mul_f32_e32 v139, 0xbfb8aa3b, v139
	v_rcp_f32_e32 v136, v136
	v_rcp_f32_e32 v137, v135
	v_mul_f32_e32 v138, 0xbfb8aa3b, v138
	v_exp_f32_e32 v139, v139
	v_exp_f32_e32 v138, v138
	v_mul_f32_e32 v136, v136, v137
	v_mul_f32_e32 v142, v34, v3
	v_add_f32_e32 v137, 1.0, v139
	v_mul_f32_e32 v139, v26, v3
	v_add_f32_e32 v138, 1.0, v138
	v_mul_f32_e32 v139, 0xbfb8aa3b, v139
	v_rcp_f32_e32 v138, v138
	v_exp_f32_e32 v139, v139
	v_mul_f32_e32 v142, 0xbfb8aa3b, v142
	v_rcp_f32_e32 v137, v137
	v_max_f32_e32 v144, 0x38d1b717, v138
	v_add_f32_e32 v139, 1.0, v139
	v_rcp_f32_e32 v138, v144
	v_exp_f32_e32 v142, v142
	v_rcp_f32_e32 v139, v139
	v_mul_f32_e32 v143, v35, v3
	v_mul_f32_e32 v137, v137, v138
	v_add_f32_e32 v138, 1.0, v142
	v_max_f32_e32 v145, 0x38d1b717, v139
	v_mul_f32_e32 v142, v27, v3
	v_mul_f32_e32 v143, 0xbfb8aa3b, v143
	v_rcp_f32_e32 v138, v138
	v_rcp_f32_e32 v139, v145
	v_mul_f32_e32 v142, 0xbfb8aa3b, v142
	v_exp_f32_e32 v143, v143
	v_exp_f32_e32 v142, v142
	v_mul_f32_e32 v138, v138, v139
	v_mul_f32_e32 v147, v28, v3
	v_add_f32_e32 v139, 1.0, v143
	v_mul_f32_e32 v143, v20, v3
	v_add_f32_e32 v142, 1.0, v142
	v_mul_f32_e32 v143, 0xbfb8aa3b, v143
	v_rcp_f32_e32 v142, v142
	v_exp_f32_e32 v143, v143
	v_mul_f32_e32 v147, 0xbfb8aa3b, v147
	v_rcp_f32_e32 v139, v139
	v_max_f32_e32 v146, 0x38d1b717, v142
	v_add_f32_e32 v143, 1.0, v143
	v_rcp_f32_e32 v142, v146
	v_exp_f32_e32 v147, v147
	v_rcp_f32_e32 v143, v143
	v_mul_f32_e32 v148, v29, v3
	v_mul_f32_e32 v139, v139, v142
	v_add_f32_e32 v142, 1.0, v147
	v_max_f32_e32 v147, 0x38d1b717, v143
	v_mul_f32_e32 v143, v21, v3
	v_mul_f32_e32 v143, 0xbfb8aa3b, v143
	v_exp_f32_e32 v143, v143
	v_mul_f32_e32 v151, v30, v3
	v_mul_f32_e32 v148, 0xbfb8aa3b, v148
	v_exp_f32_e32 v148, v148
	v_add_f32_e32 v143, 1.0, v143
	v_rcp_f32_e32 v143, v143
	v_mul_f32_e32 v151, 0xbfb8aa3b, v151
	v_exp_f32_e32 v151, v151
	v_rcp_f32_e32 v142, v142
	v_max_f32_e32 v150, 0x38d1b717, v143
	v_mul_f32_e32 v143, v22, v3
	v_mul_f32_e32 v143, 0xbfb8aa3b, v143
	v_exp_f32_e32 v143, v143
	v_rcp_f32_e32 v149, v147
	v_add_f32_e32 v148, 1.0, v148
	v_rcp_f32_e32 v148, v148
	v_add_f32_e32 v143, 1.0, v143
	v_rcp_f32_e32 v143, v143
	v_rcp_f32_e32 v152, v150
	v_add_f32_e32 v151, 1.0, v151
	v_rcp_f32_e32 v151, v151
	v_max_f32_e32 v153, 0x38d1b717, v143
	v_mul_f32_e32 v143, v23, v3
	v_mul_f32_e32 v143, 0xbfb8aa3b, v143
	v_exp_f32_e32 v143, v143
	v_mul_f32_e32 v3, v31, v3
	v_mul_f32_e32 v3, 0xbfb8aa3b, v3
	v_exp_f32_e32 v3, v3
	v_add_f32_e32 v143, 1.0, v143
	v_rcp_f32_e32 v143, v143
	v_rcp_f32_e32 v154, v153
	v_add_f32_e32 v3, 1.0, v3
	v_rcp_f32_e32 v3, v3
	v_max_f32_e32 v155, 0x38d1b717, v143
	v_rcp_f32_e32 v143, v155
	v_mul_f32_e32 v142, v142, v149
	v_mul_f32_e32 v148, v148, v152
	v_cvt_pk_bf16_f32 v136, v136, v137
	v_mul_f32_e32 v3, v3, v143
	v_cvt_pk_bf16_f32 v137, v138, v139
	v_cvt_pk_bf16_f32 v138, v142, v148
	v_lshl_add_u64 v[142:143], s[16:17], 0, v[140:141]
	v_lshl_add_u64 v[142:143], v[142:143], 0, v[132:133]
	v_lshl_add_u64 v[140:141], s[18:19], 0, v[140:141]
	v_mul_f32_e32 v149, v151, v154
	v_cvt_pk_bf16_f32 v139, v149, v3
	global_store_dwordx4 v[142:143], v[136:139], off
	v_lshl_add_u64 v[140:141], v[140:141], 0, v[132:133]
	v_ashrrev_i32_e32 v3, 31, v2
	v_cvt_pk_bf16_f32 v136, v135, v144
	v_cvt_pk_bf16_f32 v137, v145, v146
	v_cvt_pk_bf16_f32 v138, v147, v150
	v_cvt_pk_bf16_f32 v139, v153, v155
	global_store_dwordx4 v[140:141], v[136:139], off
	s_nop 1
	v_lshl_add_u64 v[136:137], v[2:3], 2, s[14:15]
	s_waitcnt vmcnt(14)
; DI float sigmoidf_(float x) { return __builtin_amdgcn_rcpf(1.0f + __builtin_amdgcn_exp2f(-x * LOG2E)); }
; DI float rs_of(const float* ss, int row) { return 1.0f / sqrtf(ss[row] * (1.0f / DM) + EPS); }
; DI u32x4 pack8(f32x4 a, f32x4 b) { u32x4 w; w.x = cvt_pk_bf16(a[0], a[1]); w.y = cvt_pk_bf16(a[2], a[3]); w.z = cvt_pk_bf16(b[0], b[1]); w.w = cvt_pk_bf16(b[2], b[3]); return w; }
;     DI void operator()(AccRef acc, const Unit& u, int wr, int wc, int fr, int fq) const {
;     ...
;             for (int m = 0; m < 4; ++m) { const int row = u.pm * 256 + ai * 128 + wr * 64 + m * 16 + fr; const float r = rs_of(ss, row); f32x4 ra[2], sb[2];
; #pragma unroll
;                 for (int n = 0; n < 2; ++n)
; #pragma unroll
;                     for (int j = 0; j < 4; ++j) { const float a = sigmoidf_(acc[ai][0][m][n][j] * r), b = fmaxf(sigmoidf_(acc[ai][1][m][n][j] * r), 1e-4f); sb[n][j] = b; ra[n][j] = a * __builtin_amdgcn_rcpf(b); }
;                 *(u32x4*)(RAT + (size_t)row * DM + col0) = pack8(ra[0], ra[1]); *(u32x4*)(SB + (size_t)row * DM + col0) = pack8(sb[0], sb[1]); }
	v_mov_b32_e32 v135, v237
	v_lshlrev_b64 v[2:3], 12, v[2:3]
	v_fmamk_f32 v135, v135, 0x3a000000, v205
	v_mul_f32_e32 v136, 0x4f800000, v135
	v_cmp_gt_f32_e32 vcc, s65, v135
	s_nop 1
	v_cndmask_b32_e32 v135, v135, v136, vcc
	v_sqrt_f32_e32 v136, v135
	s_nop 0
	v_add_u32_e32 v137, -1, v136
	v_fma_f32 v138, -v137, v136, v135
	v_cmp_ge_f32_e64 s[8:9], 0, v138
	v_add_u32_e32 v138, 1, v136
	s_nop 0
	v_cndmask_b32_e64 v137, v136, v137, s[8:9]
	v_fma_f32 v136, -v138, v136, v135
	v_cmp_lt_f32_e64 s[8:9], 0, v136
	s_nop 1
	v_cndmask_b32_e64 v136, v137, v138, s[8:9]
	v_mul_f32_e32 v137, 0x37800000, v136
	v_cndmask_b32_e32 v136, v136, v137, vcc
	v_cmp_class_f32_e32 vcc, v135, v206
	s_nop 1
	v_cndmask_b32_e32 v135, v136, v135, vcc
	v_div_scale_f32 v136, s[0:1], v135, v135, 1.0
	v_rcp_f32_e32 v137, v136
	s_nop 0
	v_fma_f32 v138, -v136, v137, 1.0
	v_fmac_f32_e32 v137, v138, v137
	v_div_scale_f32 v138, vcc, 1.0, v135, 1.0
	v_mul_f32_e32 v139, v138, v137
	v_fma_f32 v140, -v136, v139, v138
	v_fmac_f32_e32 v139, v140, v137
	v_fma_f32 v136, -v136, v139, v138
	v_div_fmas_f32 v136, v136, v137, v139
	v_div_fixup_f32 v135, v136, v135, 1.0
	v_mul_f32_e32 v136, v8, v135
	v_mul_f32_e32 v136, 0xbfb8aa3b, v136
	v_exp_f32_e32 v136, v136
	v_mul_f32_e32 v137, v16, v135
	v_mul_f32_e32 v137, 0xbfb8aa3b, v137
	v_exp_f32_e32 v137, v137
	v_add_f32_e32 v136, 1.0, v136
	v_rcp_f32_e32 v136, v136
	v_mul_f32_e32 v139, v17, v135
	v_add_f32_e32 v137, 1.0, v137
	v_mul_f32_e32 v138, v9, v135
	v_max_f32_e32 v142, 0x38d1b717, v136
	v_mul_f32_e32 v139, 0xbfb8aa3b, v139
	v_rcp_f32_e32 v137, v137
	v_rcp_f32_e32 v136, v142
	v_mul_f32_e32 v138, 0xbfb8aa3b, v138
	v_exp_f32_e32 v139, v139
	v_exp_f32_e32 v138, v138
	v_mul_f32_e32 v136, v137, v136
	v_mul_f32_e32 v140, v18, v135
	v_add_f32_e32 v137, 1.0, v139
	v_mul_f32_e32 v139, v10, v135
	v_add_f32_e32 v138, 1.0, v138
	v_mul_f32_e32 v139, 0xbfb8aa3b, v139
	v_rcp_f32_e32 v138, v138
	v_exp_f32_e32 v139, v139
	v_mul_f32_e32 v140, 0xbfb8aa3b, v140
	v_rcp_f32_e32 v137, v137
	v_max_f32_e32 v143, 0x38d1b717, v138
	v_add_f32_e32 v139, 1.0, v139
	v_rcp_f32_e32 v138, v143
	v_exp_f32_e32 v140, v140
	v_rcp_f32_e32 v139, v139
	v_mul_f32_e32 v141, v19, v135
	v_mul_f32_e32 v137, v137, v138
	v_add_f32_e32 v138, 1.0, v140
	v_max_f32_e32 v144, 0x38d1b717, v139
	v_mul_f32_e32 v140, v11, v135
	v_mul_f32_e32 v141, 0xbfb8aa3b, v141
	v_rcp_f32_e32 v138, v138
	v_rcp_f32_e32 v139, v144
	v_mul_f32_e32 v140, 0xbfb8aa3b, v140
	v_exp_f32_e32 v141, v141
	v_exp_f32_e32 v140, v140
	v_mul_f32_e32 v138, v138, v139
	v_mul_f32_e32 v146, v12, v135
	v_add_f32_e32 v139, 1.0, v141
	v_mul_f32_e32 v141, v4, v135
	v_add_f32_e32 v140, 1.0, v140
	v_mul_f32_e32 v141, 0xbfb8aa3b, v141
	v_rcp_f32_e32 v140, v140
	v_exp_f32_e32 v141, v141
	v_mul_f32_e32 v146, 0xbfb8aa3b, v146
	v_rcp_f32_e32 v139, v139
	v_max_f32_e32 v145, 0x38d1b717, v140
	v_add_f32_e32 v141, 1.0, v141
	v_rcp_f32_e32 v140, v145
	v_exp_f32_e32 v146, v146
	v_rcp_f32_e32 v141, v141
	v_mul_f32_e32 v147, v13, v135
	v_mul_f32_e32 v139, v139, v140
	v_add_f32_e32 v140, 1.0, v146
	v_max_f32_e32 v146, 0x38d1b717, v141
	v_mul_f32_e32 v141, v5, v135
	v_mul_f32_e32 v141, 0xbfb8aa3b, v141
	v_exp_f32_e32 v141, v141
	v_mul_f32_e32 v150, v14, v135
	v_mul_f32_e32 v147, 0xbfb8aa3b, v147
	v_exp_f32_e32 v147, v147
	v_add_f32_e32 v141, 1.0, v141
	v_rcp_f32_e32 v141, v141
	v_mul_f32_e32 v150, 0xbfb8aa3b, v150
	v_exp_f32_e32 v150, v150
	v_rcp_f32_e32 v140, v140
	v_max_f32_e32 v149, 0x38d1b717, v141
	v_mul_f32_e32 v141, v6, v135
	v_mul_f32_e32 v141, 0xbfb8aa3b, v141
	v_exp_f32_e32 v141, v141
	v_rcp_f32_e32 v148, v146
	v_add_f32_e32 v147, 1.0, v147
	v_rcp_f32_e32 v147, v147
	v_add_f32_e32 v141, 1.0, v141
	v_rcp_f32_e32 v141, v141
	v_rcp_f32_e32 v151, v149
	v_add_f32_e32 v150, 1.0, v150
	v_rcp_f32_e32 v150, v150
	v_max_f32_e32 v152, 0x38d1b717, v141
	v_mul_f32_e32 v141, v7, v135
	v_mul_f32_e32 v141, 0xbfb8aa3b, v141
	v_exp_f32_e32 v141, v141
	v_mul_f32_e32 v135, v15, v135
	v_mul_f32_e32 v135, 0xbfb8aa3b, v135
	v_exp_f32_e32 v135, v135
	v_add_f32_e32 v141, 1.0, v141
	v_rcp_f32_e32 v141, v141
	v_rcp_f32_e32 v153, v152
	v_add_f32_e32 v135, 1.0, v135
	v_rcp_f32_e32 v135, v135
	v_max_f32_e32 v154, 0x38d1b717, v141
	v_rcp_f32_e32 v141, v154
	v_mul_f32_e32 v140, v140, v148
	v_mul_f32_e32 v147, v147, v151
	v_cvt_pk_bf16_f32 v136, v136, v137
	v_mul_f32_e32 v135, v135, v141
	v_cvt_pk_bf16_f32 v137, v138, v139
	v_cvt_pk_bf16_f32 v138, v140, v147
	v_lshl_add_u64 v[140:141], s[16:17], 0, v[2:3]
	v_lshl_add_u64 v[2:3], s[18:19], 0, v[2:3]
	v_mul_f32_e32 v148, v150, v153
	v_cvt_pk_bf16_f32 v139, v148, v135
	v_lshl_add_u64 v[140:141], v[140:141], 0, v[132:133]
	v_lshl_add_u64 v[2:3], v[2:3], 0, v[132:133]
	global_store_dwordx4 v[140:141], v[136:139], off
	s_nop 1
	v_cvt_pk_bf16_f32 v136, v142, v143
	v_cvt_pk_bf16_f32 v137, v144, v145
	v_cvt_pk_bf16_f32 v138, v146, v149
	v_cvt_pk_bf16_f32 v139, v152, v154
	global_store_dwordx4 v[2:3], v[136:139], off
; DI float bf_lo(unsigned u) { return __uint_as_float(u << 16); }
; DI float bf_hi(unsigned u) { return __uint_as_float(u & 0xffff0000u); }
; DI u32x4 pack8(f32x4 a, f32x4 b) { u32x4 w; w.x = cvt_pk_bf16(a[0], a[1]); w.y = cvt_pk_bf16(a[2], a[3]); w.z = cvt_pk_bf16(b[0], b[1]); w.w = cvt_pk_bf16(b[2], b[3]); return w; }
;     DI void operator()(AccRef acc, const Unit& u, int wr, int wc, int fr, int fq) const {
;     ...
;             for (int m = 0; m < 4; ++m) { const size_t off = (size_t)(u.pm * 256 + ai * 128 + wr * 64 + m * 16 + fr) * DM + col0;
; #pragma unroll
;                 for (int bj = 0; bj < 2; ++bj) { const u32x4 v = *(const u32x4*)(SB + off + bj * 128);
;                     const f32x4 s0 = {bf_lo(v.x), bf_hi(v.x), bf_lo(v.y), bf_hi(v.y)}, s1 = {bf_lo(v.z), bf_hi(v.z), bf_lo(v.w), bf_hi(v.w)};
;                     *(u32x4*)(M + off + bj * 128) = pack8(acc[ai][bj][m][0] * s0, acc[ai][bj][m][1] * s1); } }
.LBB0_1353:
	s_andn2_b64 vcc, exec, s[40:41]
	s_cbranch_vccnz .LBB0_1337
	s_add_i32 s31, s31, s57
	v_add_u32_e32 v132, s31, v1
	v_lshl_add_u32 v2, v134, 3, s69
	v_ashrrev_i32_e32 v133, 31, v132
	v_ashrrev_i32_e32 v3, 31, v2
	v_lshlrev_b64 v[134:135], 11, v[132:133]
	v_lshl_add_u64 v[134:135], v[134:135], 0, v[2:3]
	v_lshlrev_b64 v[138:139], 1, v[134:135]
	v_lshl_add_u64 v[140:141], s[18:19], 0, v[138:139]
	v_mov_b64_e32 v[166:167], v[140:141]
	s_mov_b32 s1, 0
	global_load_dwordx4 v[150:153], v[166:167], off
	global_load_dwordx4 v[154:157], v[166:167], off offset:256
	s_mov_b32 s0, 0x10000
	v_lshl_add_u64 v[166:167], v[166:167], 0, s[0:1]
	global_load_dwordx4 v[158:161], v[166:167], off
	global_load_dwordx4 v[162:165], v[166:167], off offset:256
	s_mov_b32 s0, 0x10000
	v_lshl_add_u64 v[166:167], v[166:167], 0, s[0:1]
	global_load_dwordx4 v[188:191], v[166:167], off
	global_load_dwordx4 v[208:211], v[166:167], off offset:256
	s_mov_b32 s0, 0x10000
	v_lshl_add_u64 v[166:167], v[166:167], 0, s[0:1]
	global_load_dwordx4 v[212:215], v[166:167], off
	global_load_dwordx4 v[216:219], v[166:167], off offset:256
	s_mov_b32 s0, 0x50000
	v_lshl_add_u64 v[166:167], v[166:167], 0, s[0:1]
	global_load_dwordx4 v[220:223], v[166:167], off
	global_load_dwordx4 v[224:227], v[166:167], off offset:256
	s_mov_b32 s0, 0x10000
	v_lshl_add_u64 v[166:167], v[166:167], 0, s[0:1]
	global_load_dwordx4 v[228:231], v[166:167], off
	global_load_dwordx4 v[232:235], v[166:167], off offset:256
	s_mov_b32 s0, 0x10000
	v_lshl_add_u64 v[166:167], v[166:167], 0, s[0:1]
	global_load_dwordx4 v[236:239], v[166:167], off
	global_load_dwordx4 v[240:243], v[166:167], off offset:256
	s_waitcnt vmcnt(13)
	v_mov_b64_e32 v[134:135], v[150:151]
	v_mov_b64_e32 v[136:137], v[152:153]
	s_mov_b32 s0, 0x10000
	v_lshl_add_u64 v[166:167], v[166:167], 0, s[0:1]
	global_load_dwordx4 v[150:153], v[166:167], off
	v_lshlrev_b32_e32 v142, 16, v134
	v_and_b32_e32 v143, 0xffff0000, v134
	v_lshlrev_b32_e32 v134, 16, v135
	v_and_b32_e32 v135, 0xffff0000, v135
	v_lshlrev_b32_e32 v144, 16, v136
	v_and_b32_e32 v145, 0xffff0000, v136
	v_lshlrev_b32_e32 v136, 16, v137
	v_and_b32_e32 v137, 0xffff0000, v137
	v_pk_mul_f32 v[130:131], v[130:131], v[134:135]
	v_pk_mul_f32 v[128:129], v[128:129], v[142:143]
	v_pk_mul_f32 v[134:135], v[126:127], v[136:137]
	v_pk_mul_f32 v[126:127], v[124:125], v[144:145]
	v_cvt_pk_bf16_f32 v124, v128, v129
	v_cvt_pk_bf16_f32 v125, v130, v131
	v_lshl_add_u64 v[136:137], s[12:13], 0, v[138:139]
	v_cvt_pk_bf16_f32 v126, v126, v127
	v_cvt_pk_bf16_f32 v127, v134, v135
	s_waitcnt vmcnt(13)
	v_mov_b64_e32 v[128:129], v[154:155]
	v_mov_b64_e32 v[130:131], v[156:157]
	global_load_dwordx4 v[154:157], v[166:167], off offset:256
	v_add_u32_e32 v134, 16, v132
	v_ashrrev_i32_e32 v135, 31, v134
	v_lshlrev_b64 v[134:135], 11, v[134:135]
	v_lshl_add_u64 v[134:135], v[134:135], 0, v[2:3]
	global_store_dwordx4 v[136:137], v[124:127], off
	v_lshlrev_b64 v[134:135], 1, v[134:135]
	v_lshl_add_u64 v[138:139], s[18:19], 0, v[134:135]
	v_lshlrev_b32_e32 v124, 16, v128
	v_and_b32_e32 v125, 0xffff0000, v128
	v_lshlrev_b32_e32 v126, 16, v129
	v_and_b32_e32 v127, 0xffff0000, v129
	v_lshlrev_b32_e32 v128, 16, v130
	v_and_b32_e32 v129, 0xffff0000, v130
	v_lshlrev_b32_e32 v130, 16, v131
	v_and_b32_e32 v131, 0xffff0000, v131
	v_pk_mul_f32 v[120:121], v[120:121], v[124:125]
	v_pk_mul_f32 v[124:125], v[118:119], v[130:131]
	v_pk_mul_f32 v[118:119], v[116:117], v[128:129]
	v_pk_mul_f32 v[122:123], v[122:123], v[126:127]
	v_cvt_pk_bf16_f32 v116, v120, v121
	s_nop 0
	v_cvt_pk_bf16_f32 v117, v122, v123
	v_cvt_pk_bf16_f32 v118, v118, v119
	v_cvt_pk_bf16_f32 v119, v124, v125
	global_store_dwordx4 v[136:137], v[116:119], off offset:256
	s_waitcnt vmcnt(15)
	s_nop 1
	v_mov_b64_e32 v[116:117], v[158:159]
	v_mov_b64_e32 v[118:119], v[160:161]
	v_lshlrev_b32_e32 v120, 16, v116
	v_and_b32_e32 v121, 0xffff0000, v116
	v_lshlrev_b32_e32 v116, 16, v117
	v_and_b32_e32 v117, 0xffff0000, v117
	v_lshlrev_b32_e32 v122, 16, v118
	v_and_b32_e32 v123, 0xffff0000, v118
	v_lshlrev_b32_e32 v118, 16, v119
	v_and_b32_e32 v119, 0xffff0000, v119
	v_pk_mul_f32 v[114:115], v[114:115], v[116:117]
	v_pk_mul_f32 v[112:113], v[112:113], v[120:121]
	v_pk_mul_f32 v[116:117], v[110:111], v[118:119]
	v_pk_mul_f32 v[110:111], v[108:109], v[122:123]
	v_cvt_pk_bf16_f32 v108, v112, v113
	v_cvt_pk_bf16_f32 v109, v114, v115
	v_lshl_add_u64 v[118:119], s[12:13], 0, v[134:135]
	v_cvt_pk_bf16_f32 v110, v110, v111
	v_cvt_pk_bf16_f32 v111, v116, v117
	s_waitcnt vmcnt(14)
	v_mov_b64_e32 v[112:113], v[162:163]
	v_mov_b64_e32 v[114:115], v[164:165]
	v_add_u32_e32 v116, 32, v132
	v_ashrrev_i32_e32 v117, 31, v116
	v_lshlrev_b64 v[116:117], 11, v[116:117]
	v_lshl_add_u64 v[116:117], v[116:117], 0, v[2:3]
	global_store_dwordx4 v[118:119], v[108:111], off
	v_lshlrev_b64 v[116:117], 1, v[116:117]
	v_lshl_add_u64 v[120:121], s[18:19], 0, v[116:117]
	v_lshlrev_b32_e32 v108, 16, v112
	v_and_b32_e32 v109, 0xffff0000, v112
	v_lshlrev_b32_e32 v110, 16, v113
	v_and_b32_e32 v111, 0xffff0000, v113
	v_lshlrev_b32_e32 v112, 16, v114
	v_and_b32_e32 v113, 0xffff0000, v114
	v_lshlrev_b32_e32 v114, 16, v115
	v_and_b32_e32 v115, 0xffff0000, v115
	v_pk_mul_f32 v[104:105], v[104:105], v[108:109]
	v_pk_mul_f32 v[108:109], v[102:103], v[114:115]
	v_pk_mul_f32 v[102:103], v[100:101], v[112:113]
	v_pk_mul_f32 v[106:107], v[106:107], v[110:111]
	v_cvt_pk_bf16_f32 v100, v104, v105
	s_nop 0
	v_cvt_pk_bf16_f32 v101, v106, v107
	v_cvt_pk_bf16_f32 v102, v102, v103
	v_cvt_pk_bf16_f32 v103, v108, v109
	global_store_dwordx4 v[118:119], v[100:103], off offset:256
	s_waitcnt vmcnt(15)
; DI float bf_lo(unsigned u) { return __uint_as_float(u << 16); }
; DI float bf_hi(unsigned u) { return __uint_as_float(u & 0xffff0000u); }
; DI u32x4 pack8(f32x4 a, f32x4 b) { u32x4 w; w.x = cvt_pk_bf16(a[0], a[1]); w.y = cvt_pk_bf16(a[2], a[3]); w.z = cvt_pk_bf16(b[0], b[1]); w.w = cvt_pk_bf16(b[2], b[3]); return w; }
;     DI void operator()(AccRef acc, const Unit& u, int wr, int wc, int fr, int fq) const {
;     ...
;             for (int m = 0; m < 4; ++m) { const size_t off = (size_t)(u.pm * 256 + ai * 128 + wr * 64 + m * 16 + fr) * DM + col0;
; #pragma unroll
;                 for (int bj = 0; bj < 2; ++bj) { const u32x4 v = *(const u32x4*)(SB + off + bj * 128);
;                     const f32x4 s0 = {bf_lo(v.x), bf_hi(v.x), bf_lo(v.y), bf_hi(v.y)}, s1 = {bf_lo(v.z), bf_hi(v.z), bf_lo(v.w), bf_hi(v.w)};
;                     *(u32x4*)(M + off + bj * 128) = pack8(acc[ai][bj][m][0] * s0, acc[ai][bj][m][1] * s1); } }
	s_nop 1
	v_mov_b64_e32 v[100:101], v[188:189]
	v_mov_b64_e32 v[102:103], v[190:191]
	v_lshlrev_b32_e32 v104, 16, v100
	v_and_b32_e32 v105, 0xffff0000, v100
	v_lshlrev_b32_e32 v100, 16, v101
	v_and_b32_e32 v101, 0xffff0000, v101
	v_lshlrev_b32_e32 v106, 16, v102
	v_and_b32_e32 v107, 0xffff0000, v102
	v_lshlrev_b32_e32 v102, 16, v103
	v_and_b32_e32 v103, 0xffff0000, v103
	v_pk_mul_f32 v[98:99], v[98:99], v[100:101]
	v_pk_mul_f32 v[96:97], v[96:97], v[104:105]
	v_pk_mul_f32 v[100:101], v[94:95], v[102:103]
	v_pk_mul_f32 v[94:95], v[92:93], v[106:107]
	v_cvt_pk_bf16_f32 v92, v96, v97
	v_cvt_pk_bf16_f32 v93, v98, v99
	v_lshl_add_u64 v[102:103], s[12:13], 0, v[116:117]
	v_cvt_pk_bf16_f32 v94, v94, v95
	v_cvt_pk_bf16_f32 v95, v100, v101
	s_waitcnt vmcnt(14)
	v_mov_b64_e32 v[96:97], v[208:209]
	v_mov_b64_e32 v[98:99], v[210:211]
	v_add_u32_e32 v100, 48, v132
	v_ashrrev_i32_e32 v101, 31, v100
	v_lshlrev_b64 v[100:101], 11, v[100:101]
	v_lshl_add_u64 v[100:101], v[100:101], 0, v[2:3]
	global_store_dwordx4 v[102:103], v[92:95], off
	v_lshlrev_b64 v[100:101], 1, v[100:101]
	v_lshl_add_u64 v[104:105], s[18:19], 0, v[100:101]
	v_lshlrev_b32_e32 v92, 16, v96
	v_and_b32_e32 v93, 0xffff0000, v96
	v_lshlrev_b32_e32 v94, 16, v97
	v_and_b32_e32 v95, 0xffff0000, v97
	v_lshlrev_b32_e32 v96, 16, v98
	v_and_b32_e32 v97, 0xffff0000, v98
	v_lshlrev_b32_e32 v98, 16, v99
	v_and_b32_e32 v99, 0xffff0000, v99
	v_pk_mul_f32 v[88:89], v[88:89], v[92:93]
	v_pk_mul_f32 v[92:93], v[86:87], v[98:99]
	v_pk_mul_f32 v[86:87], v[84:85], v[96:97]
	v_pk_mul_f32 v[90:91], v[90:91], v[94:95]
	v_cvt_pk_bf16_f32 v84, v88, v89
	s_nop 0
	v_cvt_pk_bf16_f32 v85, v90, v91
	v_cvt_pk_bf16_f32 v86, v86, v87
	v_cvt_pk_bf16_f32 v87, v92, v93
	global_store_dwordx4 v[102:103], v[84:87], off offset:256
	s_waitcnt vmcnt(15)
	s_nop 1
	v_mov_b64_e32 v[84:85], v[212:213]
	v_mov_b64_e32 v[86:87], v[214:215]
	v_lshlrev_b32_e32 v88, 16, v84
	v_and_b32_e32 v89, 0xffff0000, v84
	v_lshlrev_b32_e32 v84, 16, v85
	v_and_b32_e32 v85, 0xffff0000, v85
	v_lshlrev_b32_e32 v90, 16, v86
	v_and_b32_e32 v91, 0xffff0000, v86
	v_lshlrev_b32_e32 v86, 16, v87
	v_and_b32_e32 v87, 0xffff0000, v87
	v_pk_mul_f32 v[82:83], v[82:83], v[84:85]
	v_pk_mul_f32 v[80:81], v[80:81], v[88:89]
	v_pk_mul_f32 v[84:85], v[78:79], v[86:87]
	v_pk_mul_f32 v[78:79], v[76:77], v[90:91]
	v_cvt_pk_bf16_f32 v76, v80, v81
	v_cvt_pk_bf16_f32 v77, v82, v83
	v_lshl_add_u64 v[86:87], s[12:13], 0, v[100:101]
	v_cvt_pk_bf16_f32 v78, v78, v79
	v_cvt_pk_bf16_f32 v79, v84, v85
	s_waitcnt vmcnt(14)
	v_mov_b64_e32 v[80:81], v[216:217]
	v_mov_b64_e32 v[82:83], v[218:219]
	v_add_u32_e32 v84, 0x80, v132
	v_ashrrev_i32_e32 v85, 31, v84
	v_lshlrev_b64 v[84:85], 11, v[84:85]
	v_lshl_add_u64 v[84:85], v[84:85], 0, v[2:3]
	global_store_dwordx4 v[86:87], v[76:79], off
	v_lshlrev_b64 v[84:85], 1, v[84:85]
	v_lshl_add_u64 v[88:89], s[18:19], 0, v[84:85]
	v_lshlrev_b32_e32 v76, 16, v80
	v_and_b32_e32 v77, 0xffff0000, v80
	v_lshlrev_b32_e32 v78, 16, v81
	v_and_b32_e32 v79, 0xffff0000, v81
	v_lshlrev_b32_e32 v80, 16, v82
	v_and_b32_e32 v81, 0xffff0000, v82
	v_lshlrev_b32_e32 v82, 16, v83
	v_and_b32_e32 v83, 0xffff0000, v83
	v_pk_mul_f32 v[72:73], v[72:73], v[76:77]
	v_pk_mul_f32 v[76:77], v[70:71], v[82:83]
	v_pk_mul_f32 v[70:71], v[68:69], v[80:81]
	v_pk_mul_f32 v[74:75], v[74:75], v[78:79]
	v_cvt_pk_bf16_f32 v68, v72, v73
	s_nop 0
	v_cvt_pk_bf16_f32 v69, v74, v75
	v_cvt_pk_bf16_f32 v70, v70, v71
	v_cvt_pk_bf16_f32 v71, v76, v77
	global_store_dwordx4 v[86:87], v[68:71], off offset:256
	s_waitcnt vmcnt(15)
	s_nop 1
	v_mov_b64_e32 v[68:69], v[220:221]
	v_mov_b64_e32 v[70:71], v[222:223]
	v_lshlrev_b32_e32 v72, 16, v68
	v_and_b32_e32 v73, 0xffff0000, v68
	v_lshlrev_b32_e32 v68, 16, v69
	v_and_b32_e32 v69, 0xffff0000, v69
	v_lshlrev_b32_e32 v74, 16, v70
	v_and_b32_e32 v75, 0xffff0000, v70
	v_lshlrev_b32_e32 v70, 16, v71
	v_and_b32_e32 v71, 0xffff0000, v71
	v_pk_mul_f32 v[66:67], v[66:67], v[68:69]
	v_pk_mul_f32 v[64:65], v[64:65], v[72:73]
	v_pk_mul_f32 v[68:69], v[62:63], v[70:71]
	v_pk_mul_f32 v[62:63], v[60:61], v[74:75]
	v_cvt_pk_bf16_f32 v60, v64, v65
	v_cvt_pk_bf16_f32 v61, v66, v67
	v_lshl_add_u64 v[70:71], s[12:13], 0, v[84:85]
	v_cvt_pk_bf16_f32 v62, v62, v63
	v_cvt_pk_bf16_f32 v63, v68, v69
	s_waitcnt vmcnt(14)
	v_mov_b64_e32 v[64:65], v[224:225]
	v_mov_b64_e32 v[66:67], v[226:227]
	v_add_u32_e32 v68, 0x90, v132
	v_ashrrev_i32_e32 v69, 31, v68
	v_lshlrev_b64 v[68:69], 11, v[68:69]
	v_lshl_add_u64 v[68:69], v[68:69], 0, v[2:3]
	global_store_dwordx4 v[70:71], v[60:63], off
	v_lshlrev_b64 v[68:69], 1, v[68:69]
	v_lshl_add_u64 v[72:73], s[18:19], 0, v[68:69]
	v_lshlrev_b32_e32 v60, 16, v64
	v_and_b32_e32 v61, 0xffff0000, v64
	v_lshlrev_b32_e32 v62, 16, v65
	v_and_b32_e32 v63, 0xffff0000, v65
	v_lshlrev_b32_e32 v64, 16, v66
	v_and_b32_e32 v65, 0xffff0000, v66
	v_lshlrev_b32_e32 v66, 16, v67
	v_and_b32_e32 v67, 0xffff0000, v67
	v_pk_mul_f32 v[56:57], v[56:57], v[60:61]
	v_pk_mul_f32 v[60:61], v[54:55], v[66:67]
	v_pk_mul_f32 v[54:55], v[52:53], v[64:65]
	v_pk_mul_f32 v[58:59], v[58:59], v[62:63]
	v_cvt_pk_bf16_f32 v52, v56, v57
	s_nop 0
	v_cvt_pk_bf16_f32 v53, v58, v59
	v_cvt_pk_bf16_f32 v54, v54, v55
	v_cvt_pk_bf16_f32 v55, v60, v61
	global_store_dwordx4 v[70:71], v[52:55], off offset:256
	s_waitcnt vmcnt(15)
; DI float bf_lo(unsigned u) { return __uint_as_float(u << 16); }
; DI float bf_hi(unsigned u) { return __uint_as_float(u & 0xffff0000u); }
; DI u32x4 pack8(f32x4 a, f32x4 b) { u32x4 w; w.x = cvt_pk_bf16(a[0], a[1]); w.y = cvt_pk_bf16(a[2], a[3]); w.z = cvt_pk_bf16(b[0], b[1]); w.w = cvt_pk_bf16(b[2], b[3]); return w; }
;     DI void operator()(AccRef acc, const Unit& u, int wr, int wc, int fr, int fq) const {
;     ...
;             for (int m = 0; m < 4; ++m) { const size_t off = (size_t)(u.pm * 256 + ai * 128 + wr * 64 + m * 16 + fr) * DM + col0;
; #pragma unroll
;                 for (int bj = 0; bj < 2; ++bj) { const u32x4 v = *(const u32x4*)(SB + off + bj * 128);
;                     const f32x4 s0 = {bf_lo(v.x), bf_hi(v.x), bf_lo(v.y), bf_hi(v.y)}, s1 = {bf_lo(v.z), bf_hi(v.z), bf_lo(v.w), bf_hi(v.w)};
;                     *(u32x4*)(M + off + bj * 128) = pack8(acc[ai][bj][m][0] * s0, acc[ai][bj][m][1] * s1); } }
	s_nop 1
	v_mov_b64_e32 v[52:53], v[228:229]
	v_mov_b64_e32 v[54:55], v[230:231]
	v_lshlrev_b32_e32 v56, 16, v52
	v_and_b32_e32 v57, 0xffff0000, v52
	v_lshlrev_b32_e32 v52, 16, v53
	v_and_b32_e32 v53, 0xffff0000, v53
	v_lshlrev_b32_e32 v58, 16, v54
	v_and_b32_e32 v59, 0xffff0000, v54
	v_lshlrev_b32_e32 v54, 16, v55
	v_and_b32_e32 v55, 0xffff0000, v55
	v_pk_mul_f32 v[50:51], v[50:51], v[52:53]
	v_pk_mul_f32 v[48:49], v[48:49], v[56:57]
	v_pk_mul_f32 v[52:53], v[46:47], v[54:55]
	v_pk_mul_f32 v[46:47], v[44:45], v[58:59]
	v_cvt_pk_bf16_f32 v44, v48, v49
	v_cvt_pk_bf16_f32 v45, v50, v51
	v_lshl_add_u64 v[54:55], s[12:13], 0, v[68:69]
	v_cvt_pk_bf16_f32 v46, v46, v47
	v_cvt_pk_bf16_f32 v47, v52, v53
	s_waitcnt vmcnt(14)
	v_mov_b64_e32 v[48:49], v[232:233]
	v_mov_b64_e32 v[50:51], v[234:235]
	v_add_u32_e32 v52, 0xa0, v132
	v_ashrrev_i32_e32 v53, 31, v52
	v_lshlrev_b64 v[52:53], 11, v[52:53]
	v_lshl_add_u64 v[52:53], v[52:53], 0, v[2:3]
	global_store_dwordx4 v[54:55], v[44:47], off
	v_lshlrev_b64 v[52:53], 1, v[52:53]
	v_lshl_add_u64 v[56:57], s[18:19], 0, v[52:53]
	v_lshlrev_b32_e32 v44, 16, v48
	v_and_b32_e32 v45, 0xffff0000, v48
	v_lshlrev_b32_e32 v46, 16, v49
	v_and_b32_e32 v47, 0xffff0000, v49
	v_lshlrev_b32_e32 v48, 16, v50
	v_and_b32_e32 v49, 0xffff0000, v50
	v_lshlrev_b32_e32 v50, 16, v51
	v_and_b32_e32 v51, 0xffff0000, v51
	v_pk_mul_f32 v[40:41], v[40:41], v[44:45]
	v_pk_mul_f32 v[44:45], v[38:39], v[50:51]
	v_pk_mul_f32 v[38:39], v[36:37], v[48:49]
	v_pk_mul_f32 v[42:43], v[42:43], v[46:47]
	v_cvt_pk_bf16_f32 v36, v40, v41
	s_nop 0
	v_cvt_pk_bf16_f32 v37, v42, v43
	v_cvt_pk_bf16_f32 v38, v38, v39
	v_cvt_pk_bf16_f32 v39, v44, v45
	global_store_dwordx4 v[54:55], v[36:39], off offset:256
	s_waitcnt vmcnt(15)
	s_nop 1
	v_mov_b64_e32 v[36:37], v[236:237]
	v_mov_b64_e32 v[38:39], v[238:239]
	v_lshlrev_b32_e32 v40, 16, v36
	v_and_b32_e32 v41, 0xffff0000, v36
	v_lshlrev_b32_e32 v36, 16, v37
	v_and_b32_e32 v37, 0xffff0000, v37
	v_lshlrev_b32_e32 v42, 16, v38
	v_and_b32_e32 v43, 0xffff0000, v38
	v_lshlrev_b32_e32 v38, 16, v39
	v_and_b32_e32 v39, 0xffff0000, v39
	v_pk_mul_f32 v[34:35], v[34:35], v[36:37]
	v_pk_mul_f32 v[32:33], v[32:33], v[40:41]
	v_pk_mul_f32 v[36:37], v[30:31], v[38:39]
	v_pk_mul_f32 v[30:31], v[28:29], v[42:43]
	v_cvt_pk_bf16_f32 v28, v32, v33
	v_cvt_pk_bf16_f32 v29, v34, v35
	s_nop 0
	v_cvt_pk_bf16_f32 v30, v30, v31
	v_cvt_pk_bf16_f32 v31, v36, v37
	s_waitcnt vmcnt(14)
	v_mov_b64_e32 v[32:33], v[240:241]
	v_mov_b64_e32 v[34:35], v[242:243]
	v_add_u32_e32 v36, 0xb0, v132
	v_ashrrev_i32_e32 v37, 31, v36
	v_lshlrev_b64 v[36:37], 11, v[36:37]
	v_lshl_add_u64 v[2:3], v[36:37], 0, v[2:3]
	v_lshl_add_u64 v[36:37], s[12:13], 0, v[52:53]
	global_store_dwordx4 v[36:37], v[28:31], off
	v_lshlrev_b64 v[2:3], 1, v[2:3]
	v_lshl_add_u64 v[38:39], s[18:19], 0, v[2:3]
	v_lshlrev_b32_e32 v28, 16, v32
	v_and_b32_e32 v29, 0xffff0000, v32
	v_lshlrev_b32_e32 v30, 16, v33
	v_and_b32_e32 v31, 0xffff0000, v33
	v_lshlrev_b32_e32 v32, 16, v34
	v_and_b32_e32 v33, 0xffff0000, v34
	v_lshlrev_b32_e32 v34, 16, v35
	v_and_b32_e32 v35, 0xffff0000, v35
	v_pk_mul_f32 v[24:25], v[24:25], v[28:29]
	v_pk_mul_f32 v[28:29], v[22:23], v[34:35]
	v_pk_mul_f32 v[22:23], v[20:21], v[32:33]
	v_pk_mul_f32 v[26:27], v[26:27], v[30:31]
	v_cvt_pk_bf16_f32 v20, v24, v25
	s_nop 0
	v_cvt_pk_bf16_f32 v21, v26, v27
	v_cvt_pk_bf16_f32 v22, v22, v23
	v_cvt_pk_bf16_f32 v23, v28, v29
	global_store_dwordx4 v[36:37], v[20:23], off offset:256
	s_waitcnt vmcnt(15)
	s_nop 1
	v_mov_b64_e32 v[20:21], v[150:151]
	v_mov_b64_e32 v[22:23], v[152:153]
	v_lshlrev_b32_e32 v24, 16, v20
	v_and_b32_e32 v25, 0xffff0000, v20
	v_lshlrev_b32_e32 v20, 16, v21
	v_and_b32_e32 v21, 0xffff0000, v21
	v_lshlrev_b32_e32 v26, 16, v22
	v_and_b32_e32 v27, 0xffff0000, v22
	v_lshlrev_b32_e32 v22, 16, v23
	v_and_b32_e32 v23, 0xffff0000, v23
	v_pk_mul_f32 v[18:19], v[18:19], v[20:21]
	v_pk_mul_f32 v[16:17], v[16:17], v[24:25]
	v_pk_mul_f32 v[20:21], v[14:15], v[22:23]
	v_pk_mul_f32 v[14:15], v[12:13], v[26:27]
	v_cvt_pk_bf16_f32 v12, v16, v17
	v_cvt_pk_bf16_f32 v13, v18, v19
	s_nop 0
	v_cvt_pk_bf16_f32 v14, v14, v15
	v_cvt_pk_bf16_f32 v15, v20, v21
	s_waitcnt vmcnt(14)
	v_mov_b64_e32 v[16:17], v[154:155]
	v_mov_b64_e32 v[18:19], v[156:157]
	v_lshl_add_u64 v[20:21], s[12:13], 0, v[2:3]
	global_store_dwordx4 v[20:21], v[12:15], off
	v_lshlrev_b32_e32 v2, 16, v16
	v_and_b32_e32 v3, 0xffff0000, v16
	v_lshlrev_b32_e32 v14, 16, v18
	v_and_b32_e32 v15, 0xffff0000, v18
	v_lshlrev_b32_e32 v12, 16, v17
	v_and_b32_e32 v13, 0xffff0000, v17
	v_lshlrev_b32_e32 v16, 16, v19
	v_and_b32_e32 v17, 0xffff0000, v19
	v_pk_mul_f32 v[2:3], v[8:9], v[2:3]
	v_pk_mul_f32 v[4:5], v[4:5], v[14:15]
	v_pk_mul_f32 v[10:11], v[10:11], v[12:13]
	v_pk_mul_f32 v[6:7], v[6:7], v[16:17]
	v_cvt_pk_bf16_f32 v2, v2, v3
	v_cvt_pk_bf16_f32 v3, v10, v11
	v_cvt_pk_bf16_f32 v4, v4, v5
	s_nop 0
	v_cvt_pk_bf16_f32 v5, v6, v7
	global_store_dwordx4 v[20:21], v[2:5], off offset:256
	s_branch .LBB0_1337

; #define PG8_STAGE(bufoff, gbase, voff) do { _Pragma("unroll") for (int _i = 0; _i < 2; ++_i) \
;         __builtin_amdgcn_global_load_lds((const unsigned*)((const char*)(gbase) + (voff)[_i]), (LAS unsigned*)(lds + (bufoff) + ldsw + _i * 8192), 16, 0, 0); } while (0)
; #define PG8_LDA(dst, b, h) do { _Pragma("unroll") for (int m = 0; m < 4; ++m) _Pragma("unroll") for (int k = 0; k < 2; ++k) dst[m][k] = *(const LAS bf16x8*)(lds + PG8_SA(b, h) + aoff + m * 2048 + k * 1024); } while (0)
; #define PG8_LDB(dst, b, h) do { _Pragma("unroll") for (int n = 0; n < 2; ++n) _Pragma("unroll") for (int k = 0; k < 2; ++k) dst[n][k] = *(const LAS bf16x8*)(lds + PG8_SB(b, h) + boff + n * 2048 + k * 1024); } while (0)
; #define PG8_WAIT_V(n) asm volatile("s_waitcnt vmcnt(" #n ")" ::: "memory")
; #define PG8_WAIT_L(n) asm volatile("s_waitcnt lgkmcnt(" #n ")" ::: "memory")
; #define PG8_BAR __builtin_amdgcn_s_barrier()
; #define PG8_SCHED __builtin_amdgcn_sched_barrier(0)
; template <class Epi, class Sched>
; DI void gemm_phase(LAS unsigned char* lds, const Gemm g, const Sched& S, const Epi& E) {
;     ...
;             PG8_LDB(B0, 0, 0); PG8_SCHED; PG8_LDA(At, 0, 0); PG8_STAGE(PG8_SA(1, 1), a1 + hstep, voffA);
;             PG8_WAIT_L(8); PG8_BAR; PG8_WAIT_L(0); PG8_MMA(0, 0, At, B0); PG8_BAR; PG8_SCHED;
;             PG8_LDB(B1, 0, 1); PG8_STAGE(PG8_SB(0, 0), b2, voffB);
;             PG8_BAR; PG8_WAIT_L(0); PG8_MMA(0, 1, At, B1); PG8_BAR;
;             PG8_LDA(At, 0, 1); PG8_STAGE(PG8_SA(0, 0), a2, voffA);
;             PG8_BAR; PG8_WAIT_L(0); PG8_MMA(1, 0, At, B0); PG8_BAR; PG8_SCHED;
;             PG8_STAGE(PG8_SB(0, 1), b2 + hstep, voffB);
;             PG8_WAIT_V(6); PG8_BAR; PG8_MMA(1, 1, At, B1); PG8_BAR;
;             PG8_LDB(B0, 1, 0); PG8_SCHED; PG8_LDA(At, 1, 0); PG8_STAGE(PG8_SA(0, 1), a2 + hstep, voffA);
;             PG8_WAIT_L(8); PG8_BAR; PG8_WAIT_L(0); PG8_MMA(0, 0, At, B0); PG8_BAR; PG8_SCHED;
;             PG8_LDB(B1, 1, 1); PG8_STAGE(PG8_SB(1, 0), b3, voffB);
;             PG8_BAR; PG8_WAIT_L(0); PG8_MMA(0, 1, At, B1); PG8_BAR;
;             PG8_LDA(At, 1, 1); PG8_STAGE(PG8_SA(1, 0), a3, voffA);
;             PG8_BAR; PG8_WAIT_L(0); PG8_MMA(1, 0, At, B0); PG8_BAR; PG8_SCHED;
;             PG8_STAGE(PG8_SB(1, 1), b3 + hstep, voffB);
;             PG8_WAIT_V(6); PG8_BAR; PG8_MMA(1, 1, At, B1); PG8_BAR;
.LBB0_1508:
	ds_read_b128 v[144:147], v150
	ds_read_b128 v[154:157], v150 offset:1024
	ds_read_b128 v[158:161], v150 offset:2048
	ds_read_b128 v[162:165], v150 offset:3072
	s_add_u32 s0, s44, 0xfff80080
	s_addc_u32 s1, s45, -1
	s_cmp_eq_u32 s69, 28
	s_cselect_b32 s49, s34, s1
	s_cselect_b32 s48, s35, s0
	s_cselect_b32 s47, s31, s68
	s_cselect_b32 s46, s37, s43
	v_lshl_add_u64 v[182:183], s[44:45], 0, v[136:137]
	s_add_i32 m0, s52, 0xc000
	ds_read_b128 v[166:169], v151
	ds_read_b128 v[170:173], v151 offset:1024
	ds_read_b128 v[174:177], v151 offset:2048
	ds_read_b128 v[178:181], v151 offset:3072
	ds_read_b128 v[188:191], v151 offset:4096
	ds_read_b128 v[206:209], v151 offset:5120
	ds_read_b128 v[210:213], v151 offset:6144
	ds_read_b128 v[214:217], v151 offset:7168
	global_load_lds_dwordx4 v[182:183], off
	v_lshl_add_u64 v[182:183], s[44:45], 0, v[138:139]
	s_add_i32 m0, s52, 0xe000
	s_nop 0
	global_load_lds_dwordx4 v[182:183], off
	s_waitcnt lgkmcnt(8)
	s_barrier
	s_waitcnt lgkmcnt(0)
	s_setprio 1
	s_waitcnt lgkmcnt(0)
	v_mfma_f32_16x16x32_bf16 v[124:127], v[144:147], v[166:169], v[124:127]
	v_mfma_f32_16x16x32_bf16 v[120:123], v[158:161], v[166:169], v[120:123]
	v_mfma_f32_16x16x32_bf16 v[108:111], v[144:147], v[174:177], v[108:111]
	v_mfma_f32_16x16x32_bf16 v[104:107], v[158:161], v[174:177], v[104:107]
	v_mfma_f32_16x16x32_bf16 v[92:95], v[144:147], v[188:191], v[92:95]
	v_mfma_f32_16x16x32_bf16 v[88:91], v[158:161], v[188:191], v[88:91]
	v_mfma_f32_16x16x32_bf16 v[76:79], v[144:147], v[210:213], v[76:79]
	v_mfma_f32_16x16x32_bf16 v[72:75], v[158:161], v[210:213], v[72:75]
	v_mfma_f32_16x16x32_bf16 v[124:127], v[154:157], v[170:173], v[124:127]
	v_mfma_f32_16x16x32_bf16 v[120:123], v[162:165], v[170:173], v[120:123]
	v_mfma_f32_16x16x32_bf16 v[108:111], v[154:157], v[178:181], v[108:111]
	v_mfma_f32_16x16x32_bf16 v[104:107], v[162:165], v[178:181], v[104:107]
	v_mfma_f32_16x16x32_bf16 v[92:95], v[154:157], v[206:209], v[92:95]
	v_mfma_f32_16x16x32_bf16 v[88:91], v[162:165], v[206:209], v[88:91]
	v_mfma_f32_16x16x32_bf16 v[76:79], v[154:157], v[214:217], v[76:79]
	v_mfma_f32_16x16x32_bf16 v[72:75], v[162:165], v[214:217], v[72:75]
	s_setprio 0
	s_barrier
	s_add_i32 s0, s65, s51
	v_lshl_add_u64 v[182:183], s[46:47], 0, v[132:133]
	s_mov_b32 m0, s0
	ds_read_b128 v[218:221], v152
	ds_read_b128 v[222:225], v152 offset:1024
	ds_read_b128 v[226:229], v152 offset:2048
	ds_read_b128 v[230:233], v152 offset:3072
	global_load_lds_dwordx4 v[182:183], off
	v_lshl_add_u64 v[202:203], s[46:47], 0, v[134:135]
	s_add_i32 m0, s0, 0x2000
	s_nop 0
	global_load_lds_dwordx4 v[202:203], off
	s_barrier
	s_waitcnt lgkmcnt(0)
	s_setprio 1
	s_waitcnt lgkmcnt(0)
	v_mfma_f32_16x16x32_bf16 v[116:119], v[218:221], v[166:169], v[116:119]
	v_mfma_f32_16x16x32_bf16 v[112:115], v[226:229], v[166:169], v[112:115]
	v_mfma_f32_16x16x32_bf16 v[100:103], v[218:221], v[174:177], v[100:103]
	v_mfma_f32_16x16x32_bf16 v[96:99], v[226:229], v[174:177], v[96:99]
	v_mfma_f32_16x16x32_bf16 v[84:87], v[218:221], v[188:191], v[84:87]
	v_mfma_f32_16x16x32_bf16 v[80:83], v[226:229], v[188:191], v[80:83]
	v_mfma_f32_16x16x32_bf16 v[68:71], v[218:221], v[210:213], v[68:71]
	v_mfma_f32_16x16x32_bf16 v[64:67], v[226:229], v[210:213], v[64:67]
	v_mfma_f32_16x16x32_bf16 v[116:119], v[222:225], v[170:173], v[116:119]
	v_mfma_f32_16x16x32_bf16 v[112:115], v[230:233], v[170:173], v[112:115]
	v_mfma_f32_16x16x32_bf16 v[100:103], v[222:225], v[178:181], v[100:103]
	v_mfma_f32_16x16x32_bf16 v[96:99], v[230:233], v[178:181], v[96:99]
	v_mfma_f32_16x16x32_bf16 v[84:87], v[222:225], v[206:209], v[84:87]
	v_mfma_f32_16x16x32_bf16 v[80:83], v[230:233], v[206:209], v[80:83]
	v_mfma_f32_16x16x32_bf16 v[68:71], v[222:225], v[214:217], v[68:71]
	v_mfma_f32_16x16x32_bf16 v[64:67], v[230:233], v[214:217], v[64:67]
	s_setprio 0
	s_mov_b32 m0, s52
	v_lshl_add_u64 v[234:235], s[48:49], 0, v[128:129]
	s_barrier
	ds_read_b128 v[166:169], v151 offset:16384
	ds_read_b128 v[170:173], v151 offset:17408
	ds_read_b128 v[174:177], v151 offset:18432
	ds_read_b128 v[178:181], v151 offset:19456
	ds_read_b128 v[188:191], v151 offset:20480
	ds_read_b128 v[206:209], v151 offset:21504
	ds_read_b128 v[210:213], v151 offset:22528
	ds_read_b128 v[214:217], v151 offset:23552
	global_load_lds_dwordx4 v[234:235], off
	v_lshl_add_u64 v[236:237], s[48:49], 0, v[130:131]
	s_mov_b32 m0, s53
	s_nop 0
	global_load_lds_dwordx4 v[236:237], off
	s_barrier
	s_waitcnt lgkmcnt(0)
	s_setprio 1
	s_waitcnt lgkmcnt(0)
	v_mfma_f32_16x16x32_bf16 v[60:63], v[144:147], v[166:169], v[60:63]
	v_mfma_f32_16x16x32_bf16 v[56:59], v[158:161], v[166:169], v[56:59]
	v_mfma_f32_16x16x32_bf16 v[44:47], v[144:147], v[174:177], v[44:47]
	v_mfma_f32_16x16x32_bf16 v[40:43], v[158:161], v[174:177], v[40:43]
	v_mfma_f32_16x16x32_bf16 v[28:31], v[144:147], v[188:191], v[28:31]
	v_mfma_f32_16x16x32_bf16 v[24:27], v[158:161], v[188:191], v[24:27]
	v_mfma_f32_16x16x32_bf16 v[12:15], v[144:147], v[210:213], v[12:15]
	v_mfma_f32_16x16x32_bf16 v[8:11], v[158:161], v[210:213], v[8:11]
	v_mfma_f32_16x16x32_bf16 v[60:63], v[154:157], v[170:173], v[60:63]
	v_mfma_f32_16x16x32_bf16 v[56:59], v[162:165], v[170:173], v[56:59]
	v_mfma_f32_16x16x32_bf16 v[44:47], v[154:157], v[178:181], v[44:47]
	v_mfma_f32_16x16x32_bf16 v[40:43], v[162:165], v[178:181], v[40:43]
	v_mfma_f32_16x16x32_bf16 v[28:31], v[154:157], v[206:209], v[28:31]
	v_mfma_f32_16x16x32_bf16 v[24:27], v[162:165], v[206:209], v[24:27]
	v_mfma_f32_16x16x32_bf16 v[12:15], v[154:157], v[214:217], v[12:15]
	v_mfma_f32_16x16x32_bf16 v[8:11], v[162:165], v[214:217], v[8:11]
	s_setprio 0
	s_barrier
; #define PG8_STAGE(bufoff, gbase, voff) do { _Pragma("unroll") for (int _i = 0; _i < 2; ++_i) \
;         __builtin_amdgcn_global_load_lds((const unsigned*)((const char*)(gbase) + (voff)[_i]), (LAS unsigned*)(lds + (bufoff) + ldsw + _i * 8192), 16, 0, 0); } while (0)
; #define PG8_LDA(dst, b, h) do { _Pragma("unroll") for (int m = 0; m < 4; ++m) _Pragma("unroll") for (int k = 0; k < 2; ++k) dst[m][k] = *(const LAS bf16x8*)(lds + PG8_SA(b, h) + aoff + m * 2048 + k * 1024); } while (0)
; #define PG8_LDB(dst, b, h) do { _Pragma("unroll") for (int n = 0; n < 2; ++n) _Pragma("unroll") for (int k = 0; k < 2; ++k) dst[n][k] = *(const LAS bf16x8*)(lds + PG8_SB(b, h) + boff + n * 2048 + k * 1024); } while (0)
; #define PG8_WAIT_V(n) asm volatile("s_waitcnt vmcnt(" #n ")" ::: "memory")
; #define PG8_WAIT_L(n) asm volatile("s_waitcnt lgkmcnt(" #n ")" ::: "memory")
; #define PG8_BAR __builtin_amdgcn_s_barrier()
; #define PG8_SCHED __builtin_amdgcn_sched_barrier(0)
; template <class Epi, class Sched>
; DI void gemm_phase(LAS unsigned char* lds, const Gemm g, const Sched& S, const Epi& E) {
;     ...
;             PG8_LDB(B0, 0, 0); PG8_SCHED; PG8_LDA(At, 0, 0); PG8_STAGE(PG8_SA(1, 1), a1 + hstep, voffA);
;             PG8_WAIT_L(8); PG8_BAR; PG8_WAIT_L(0); PG8_MMA(0, 0, At, B0); PG8_BAR; PG8_SCHED;
;             PG8_LDB(B1, 0, 1); PG8_STAGE(PG8_SB(0, 0), b2, voffB);
;             PG8_BAR; PG8_WAIT_L(0); PG8_MMA(0, 1, At, B1); PG8_BAR;
;             PG8_LDA(At, 0, 1); PG8_STAGE(PG8_SA(0, 0), a2, voffA);
;             PG8_BAR; PG8_WAIT_L(0); PG8_MMA(1, 0, At, B0); PG8_BAR; PG8_SCHED;
;             PG8_STAGE(PG8_SB(0, 1), b2 + hstep, voffB);
;             PG8_WAIT_V(6); PG8_BAR; PG8_MMA(1, 1, At, B1); PG8_BAR;
;             PG8_LDB(B0, 1, 0); PG8_SCHED; PG8_LDA(At, 1, 0); PG8_STAGE(PG8_SA(0, 1), a2 + hstep, voffA);
;             PG8_WAIT_L(8); PG8_BAR; PG8_WAIT_L(0); PG8_MMA(0, 0, At, B0); PG8_BAR; PG8_SCHED;
;             PG8_LDB(B1, 1, 1); PG8_STAGE(PG8_SB(1, 0), b3, voffB);
;             PG8_BAR; PG8_WAIT_L(0); PG8_MMA(0, 1, At, B1); PG8_BAR;
;             PG8_LDA(At, 1, 1); PG8_STAGE(PG8_SA(1, 0), a3, voffA);
;             PG8_BAR; PG8_WAIT_L(0); PG8_MMA(1, 0, At, B0); PG8_BAR; PG8_SCHED;
;             PG8_STAGE(PG8_SB(1, 1), b3 + hstep, voffB);
;             PG8_WAIT_V(6); PG8_BAR; PG8_MMA(1, 1, At, B1); PG8_BAR;
	s_add_u32 s0, s46, 0x80000
	s_addc_u32 s1, s47, 0
	s_add_i32 s4, s66, s51
	v_lshl_add_u64 v[144:145], s[0:1], 0, v[132:133]
	s_mov_b32 m0, s4
	s_nop 0
	global_load_lds_dwordx4 v[144:145], off
	v_lshl_add_u64 v[144:145], s[0:1], 0, v[134:135]
	s_add_i32 m0, s4, 0x2000
	s_nop 0
	global_load_lds_dwordx4 v[144:145], off
	s_waitcnt vmcnt(6)
	s_barrier
	s_setprio 1
	v_mfma_f32_16x16x32_bf16 v[52:55], v[218:221], v[166:169], v[52:55]
	v_mfma_f32_16x16x32_bf16 v[48:51], v[226:229], v[166:169], v[48:51]
	v_mfma_f32_16x16x32_bf16 v[36:39], v[218:221], v[174:177], v[36:39]
	v_mfma_f32_16x16x32_bf16 v[32:35], v[226:229], v[174:177], v[32:35]
	v_mfma_f32_16x16x32_bf16 v[20:23], v[218:221], v[188:191], v[20:23]
	v_mfma_f32_16x16x32_bf16 v[16:19], v[226:229], v[188:191], v[16:19]
	v_mfma_f32_16x16x32_bf16 v[4:7], v[218:221], v[210:213], v[4:7]
	v_mfma_f32_16x16x32_bf16 v[0:3], v[226:229], v[210:213], v[0:3]
	v_mfma_f32_16x16x32_bf16 v[52:55], v[222:225], v[170:173], v[52:55]
	v_mfma_f32_16x16x32_bf16 v[48:51], v[230:233], v[170:173], v[48:51]
	v_mfma_f32_16x16x32_bf16 v[36:39], v[222:225], v[178:181], v[36:39]
	v_mfma_f32_16x16x32_bf16 v[32:35], v[230:233], v[178:181], v[32:35]
	v_mfma_f32_16x16x32_bf16 v[20:23], v[222:225], v[206:209], v[20:23]
	v_mfma_f32_16x16x32_bf16 v[16:19], v[230:233], v[206:209], v[16:19]
	v_mfma_f32_16x16x32_bf16 v[4:7], v[222:225], v[214:217], v[4:7]
	v_mfma_f32_16x16x32_bf16 v[0:3], v[230:233], v[214:217], v[0:3]
	s_setprio 0
	s_add_i32 s4, 0, 0x18000
	v_add_u32_e32 v162, s4, v149
	s_barrier
	ds_read_b128 v[144:147], v162
	ds_read_b128 v[154:157], v162 offset:1024
	ds_read_b128 v[158:161], v162 offset:2048
	ds_read_b128 v[162:165], v162 offset:3072
	s_add_u32 s0, s48, 0x80000
	s_addc_u32 s1, s49, 0
	s_mov_b32 m0, s58
	v_lshl_add_u64 v[218:219], s[0:1], 0, v[128:129]
	ds_read_b128 v[166:169], v151 offset:32768
	ds_read_b128 v[170:173], v151 offset:33792
	ds_read_b128 v[174:177], v151 offset:34816
	ds_read_b128 v[178:181], v151 offset:35840
	ds_read_b128 v[188:191], v151 offset:36864
	ds_read_b128 v[206:209], v151 offset:37888
	ds_read_b128 v[210:213], v151 offset:38912
	ds_read_b128 v[214:217], v151 offset:39936
	global_load_lds_dwordx4 v[218:219], off
	v_lshl_add_u64 v[218:219], s[0:1], 0, v[130:131]
	s_mov_b32 m0, s59
	s_nop 0
	global_load_lds_dwordx4 v[218:219], off
	s_waitcnt lgkmcnt(8)
	s_barrier
	s_waitcnt lgkmcnt(0)
	s_setprio 1
	s_waitcnt lgkmcnt(0)
	v_mfma_f32_16x16x32_bf16 v[124:127], v[144:147], v[166:169], v[124:127]
	v_mfma_f32_16x16x32_bf16 v[120:123], v[158:161], v[166:169], v[120:123]
	v_mfma_f32_16x16x32_bf16 v[108:111], v[144:147], v[174:177], v[108:111]
	v_mfma_f32_16x16x32_bf16 v[104:107], v[158:161], v[174:177], v[104:107]
	v_mfma_f32_16x16x32_bf16 v[92:95], v[144:147], v[188:191], v[92:95]
	v_mfma_f32_16x16x32_bf16 v[88:91], v[158:161], v[188:191], v[88:91]
	v_mfma_f32_16x16x32_bf16 v[76:79], v[144:147], v[210:213], v[76:79]
	v_mfma_f32_16x16x32_bf16 v[72:75], v[158:161], v[210:213], v[72:75]
	v_mfma_f32_16x16x32_bf16 v[124:127], v[154:157], v[170:173], v[124:127]
	v_mfma_f32_16x16x32_bf16 v[120:123], v[162:165], v[170:173], v[120:123]
	v_mfma_f32_16x16x32_bf16 v[108:111], v[154:157], v[178:181], v[108:111]
	v_mfma_f32_16x16x32_bf16 v[104:107], v[162:165], v[178:181], v[104:107]
	v_mfma_f32_16x16x32_bf16 v[92:95], v[154:157], v[206:209], v[92:95]
	v_mfma_f32_16x16x32_bf16 v[88:91], v[162:165], v[206:209], v[88:91]
	v_mfma_f32_16x16x32_bf16 v[76:79], v[154:157], v[214:217], v[76:79]
	v_mfma_f32_16x16x32_bf16 v[72:75], v[162:165], v[214:217], v[72:75]
	s_setprio 0
	s_barrier
	s_add_i32 s5, 0, 0x1c000
	s_add_i32 s0, s4, s51
	v_add_u32_e32 v201, s5, v149
	v_lshl_add_u64 v[182:183], v[182:183], 0, s[28:29]
	s_mov_b32 m0, s0
	ds_read_b128 v[218:221], v201
	ds_read_b128 v[222:225], v201 offset:1024
	ds_read_b128 v[226:229], v201 offset:2048
	ds_read_b128 v[230:233], v201 offset:3072
	global_load_lds_dwordx4 v[182:183], off
	v_lshl_add_u64 v[182:183], v[202:203], 0, s[28:29]
	s_add_i32 m0, s0, 0x2000
	s_nop 0
	global_load_lds_dwordx4 v[182:183], off
	s_barrier
	s_waitcnt lgkmcnt(0)
	s_setprio 1
	s_waitcnt lgkmcnt(0)
	v_mfma_f32_16x16x32_bf16 v[116:119], v[218:221], v[166:169], v[116:119]
	v_mfma_f32_16x16x32_bf16 v[112:115], v[226:229], v[166:169], v[112:115]
	v_mfma_f32_16x16x32_bf16 v[100:103], v[218:221], v[174:177], v[100:103]
	v_mfma_f32_16x16x32_bf16 v[96:99], v[226:229], v[174:177], v[96:99]
	v_mfma_f32_16x16x32_bf16 v[84:87], v[218:221], v[188:191], v[84:87]
	v_mfma_f32_16x16x32_bf16 v[80:83], v[226:229], v[188:191], v[80:83]
	v_mfma_f32_16x16x32_bf16 v[68:71], v[218:221], v[210:213], v[68:71]
	v_mfma_f32_16x16x32_bf16 v[64:67], v[226:229], v[210:213], v[64:67]
	v_mfma_f32_16x16x32_bf16 v[116:119], v[222:225], v[170:173], v[116:119]
	v_mfma_f32_16x16x32_bf16 v[112:115], v[230:233], v[170:173], v[112:115]
	v_mfma_f32_16x16x32_bf16 v[100:103], v[222:225], v[178:181], v[100:103]
	v_mfma_f32_16x16x32_bf16 v[96:99], v[230:233], v[178:181], v[96:99]
	v_mfma_f32_16x16x32_bf16 v[84:87], v[222:225], v[206:209], v[84:87]
	v_mfma_f32_16x16x32_bf16 v[80:83], v[230:233], v[206:209], v[80:83]
	v_mfma_f32_16x16x32_bf16 v[68:71], v[222:225], v[214:217], v[68:71]
	v_mfma_f32_16x16x32_bf16 v[64:67], v[230:233], v[214:217], v[64:67]
	s_setprio 0
	s_mov_b32 m0, s63
	v_lshl_add_u64 v[182:183], v[234:235], 0, s[28:29]
	s_barrier
	ds_read_b128 v[166:169], v151 offset:49152
	ds_read_b128 v[170:173], v151 offset:50176
	ds_read_b128 v[174:177], v151 offset:51200
	ds_read_b128 v[178:181], v151 offset:52224
	ds_read_b128 v[188:191], v151 offset:53248
	ds_read_b128 v[206:209], v151 offset:54272
	ds_read_b128 v[210:213], v151 offset:55296
	ds_read_b128 v[214:217], v151 offset:56320
	global_load_lds_dwordx4 v[182:183], off
	v_lshl_add_u64 v[182:183], v[236:237], 0, s[28:29]
	s_mov_b32 m0, s64
	s_nop 0
	global_load_lds_dwordx4 v[182:183], off
	s_barrier
; DI float bf_lo(unsigned u) { return __uint_as_float(u << 16); }
; DI float bf_hi(unsigned u) { return __uint_as_float(u & 0xffff0000u); }
; DI u32x4 pack8(f32x4 a, f32x4 b) { u32x4 w; w.x = cvt_pk_bf16(a[0], a[1]); w.y = cvt_pk_bf16(a[2], a[3]); w.z = cvt_pk_bf16(b[0], b[1]); w.w = cvt_pk_bf16(b[2], b[3]); return w; }
; #define PG8_STAGE(bufoff, gbase, voff) do { _Pragma("unroll") for (int _i = 0; _i < 2; ++_i) \
;         __builtin_amdgcn_global_load_lds((const unsigned*)((const char*)(gbase) + (voff)[_i]), (LAS unsigned*)(lds + (bufoff) + ldsw + _i * 8192), 16, 0, 0); } while (0)
; template <class Epi, class Sched>
; DI void gemm_phase(LAS unsigned char* lds, const Gemm g, const Sched& S, const Epi& E) {
;     ...
;             PG8_BAR; PG8_WAIT_L(0); PG8_MMA(0, 1, At, B1); PG8_BAR;
;             PG8_LDA(At, 1, 1); PG8_STAGE(PG8_SA(1, 0), a3, voffA);
;             PG8_BAR; PG8_WAIT_L(0); PG8_MMA(1, 0, At, B0); PG8_BAR; PG8_SCHED;
;             PG8_STAGE(PG8_SB(1, 1), b3 + hstep, voffB);
;             PG8_WAIT_V(6); PG8_BAR; PG8_MMA(1, 1, At, B1); PG8_BAR;
;         }
;     DI void operator()(AccRef acc, const Unit& u, int wr, int wc, int fr, int fq) const {
;     ...
;             for (int m = 0; m < 4; ++m) { const int row = u.pm * 256 + ai * 128 + wr * 64 + m * 16 + fr; const size_t off = (size_t)row * DM + col0; float q = 0.f;
; #pragma unroll
;                 for (int bj = 0; bj < 2; ++bj) {
;                     f32x4 b0, b1;
;                     if (F32BASE) { b0 = *(const f32x4*)(bp + off + bj * 128); b1 = *(const f32x4*)(bp + off + bj * 128 + 4); }
;                     else { const u32x4 uv = *(const u32x4*)(Ui + off + bj * 128); b0 = (f32x4){bf_lo(uv.x), bf_hi(uv.x), bf_lo(uv.y), bf_hi(uv.y)}; b1 = (f32x4){bf_lo(uv.z), bf_hi(uv.z), bf_lo(uv.w), bf_hi(uv.w)}; }
;                     const u32x4 w = pack8(b0 + acc[ai][bj][m][0] * (0.5f * S2), b1 + acc[ai][bj][m][1] * (0.5f * S2));
;                     *(u32x4*)(Uo + (size_t)row * ldo + col0 + bj * 128) = w;
;                     const float r0 = bf_lo(w.x), r1 = bf_hi(w.x), r2 = bf_lo(w.y), r3 = bf_hi(w.y), r4 = bf_lo(w.z), r5 = bf_hi(w.z), r6 = bf_lo(w.w), r7 = bf_hi(w.w);
;                     q += (r0 * r0 + r1 * r1) + (r2 * r2 + r3 * r3) + (r4 * r4 + r5 * r5) + (r6 * r6 + r7 * r7); }
;                 q += __shfl_xor(q, 16); q += __shfl_xor(q, 32); if (fq == 0) ssp[(size_t)row * 32 + u.pn * 4 + wc] = q; }
	s_waitcnt lgkmcnt(0)
	s_setprio 1
	s_waitcnt lgkmcnt(0)
	v_mfma_f32_16x16x32_bf16 v[60:63], v[144:147], v[166:169], v[60:63]
	v_mfma_f32_16x16x32_bf16 v[56:59], v[158:161], v[166:169], v[56:59]
	v_mfma_f32_16x16x32_bf16 v[44:47], v[144:147], v[174:177], v[44:47]
	v_mfma_f32_16x16x32_bf16 v[40:43], v[158:161], v[174:177], v[40:43]
	v_mfma_f32_16x16x32_bf16 v[28:31], v[144:147], v[188:191], v[28:31]
	v_mfma_f32_16x16x32_bf16 v[24:27], v[158:161], v[188:191], v[24:27]
	v_mfma_f32_16x16x32_bf16 v[12:15], v[144:147], v[210:213], v[12:15]
	v_mfma_f32_16x16x32_bf16 v[8:11], v[158:161], v[210:213], v[8:11]
	v_mfma_f32_16x16x32_bf16 v[60:63], v[154:157], v[170:173], v[60:63]
	v_mfma_f32_16x16x32_bf16 v[56:59], v[162:165], v[170:173], v[56:59]
	v_mfma_f32_16x16x32_bf16 v[44:47], v[154:157], v[178:181], v[44:47]
	v_mfma_f32_16x16x32_bf16 v[40:43], v[162:165], v[178:181], v[40:43]
	v_mfma_f32_16x16x32_bf16 v[28:31], v[154:157], v[206:209], v[28:31]
	v_mfma_f32_16x16x32_bf16 v[24:27], v[162:165], v[206:209], v[24:27]
	v_mfma_f32_16x16x32_bf16 v[12:15], v[154:157], v[214:217], v[12:15]
	v_mfma_f32_16x16x32_bf16 v[8:11], v[162:165], v[214:217], v[8:11]
	s_setprio 0
	s_barrier
	s_add_u32 s0, s46, 0x80080
	s_addc_u32 s1, s47, 0
	s_add_i32 s4, s5, s51
	v_lshl_add_u64 v[144:145], s[0:1], 0, v[132:133]
	s_mov_b32 m0, s4
	s_nop 0
	global_load_lds_dwordx4 v[144:145], off
	v_lshl_add_u64 v[144:145], s[0:1], 0, v[134:135]
	s_add_i32 m0, s4, 0x2000
	s_nop 0
	global_load_lds_dwordx4 v[144:145], off
	s_waitcnt vmcnt(6)
	s_barrier
	s_setprio 1
	v_mfma_f32_16x16x32_bf16 v[52:55], v[218:221], v[166:169], v[52:55]
	v_mfma_f32_16x16x32_bf16 v[48:51], v[226:229], v[166:169], v[48:51]
	v_mfma_f32_16x16x32_bf16 v[36:39], v[218:221], v[174:177], v[36:39]
	v_mfma_f32_16x16x32_bf16 v[32:35], v[226:229], v[174:177], v[32:35]
	v_mfma_f32_16x16x32_bf16 v[20:23], v[218:221], v[188:191], v[20:23]
	v_mfma_f32_16x16x32_bf16 v[16:19], v[226:229], v[188:191], v[16:19]
	v_mfma_f32_16x16x32_bf16 v[4:7], v[218:221], v[210:213], v[4:7]
	v_mfma_f32_16x16x32_bf16 v[0:3], v[226:229], v[210:213], v[0:3]
	v_mfma_f32_16x16x32_bf16 v[52:55], v[222:225], v[170:173], v[52:55]
	v_mfma_f32_16x16x32_bf16 v[48:51], v[230:233], v[170:173], v[48:51]
	v_mfma_f32_16x16x32_bf16 v[36:39], v[222:225], v[178:181], v[36:39]
	v_mfma_f32_16x16x32_bf16 v[32:35], v[230:233], v[178:181], v[32:35]
	v_mfma_f32_16x16x32_bf16 v[20:23], v[222:225], v[206:209], v[20:23]
	v_mfma_f32_16x16x32_bf16 v[16:19], v[230:233], v[206:209], v[16:19]
	v_mfma_f32_16x16x32_bf16 v[4:7], v[222:225], v[214:217], v[4:7]
	v_mfma_f32_16x16x32_bf16 v[0:3], v[230:233], v[214:217], v[0:3]
	s_setprio 0
	s_add_i32 s69, s69, 2
	s_add_u32 s44, s44, 0x100
	s_addc_u32 s45, s45, 0
	s_add_u32 s43, s43, 0x100
	s_addc_u32 s68, s68, 0
	s_cmp_gt_u32 s69, 29
	s_barrier
	s_cbranch_scc0 .LBB0_1508
	s_lshl_b32 s0, s14, 8
	v_mov_b32_e32 v145, v194
	v_mov_b32_e32 v164, v192
	s_or_b32 s0, s0, s62
	s_nop 0
	v_lshl_add_u32 v144, v164, 3, s0
	s_lshl_b32 s0, s42, 8
	s_add_i32 s0, s0, s61
	v_add_u32_e32 v146, s0, v145
	v_ashrrev_i32_e32 v147, 31, v146
	v_lshlrev_b64 v[154:155], 12, v[146:147]
	v_ashrrev_i32_e32 v145, 31, v144
	v_lshl_add_u64 v[154:155], s[16:17], 0, v[154:155]
	v_lshl_add_u64 v[158:159], v[144:145], 1, v[154:155]
	v_mov_b64_e32 v[182:183], v[158:159]
	s_mov_b32 s47, 0
	global_load_dwordx4 v[166:169], v[182:183], off
	global_load_dwordx4 v[170:173], v[182:183], off offset:256
	s_mov_b32 s46, 0x10000
	v_lshl_add_u64 v[182:183], v[182:183], 0, s[46:47]
	global_load_dwordx4 v[174:177], v[182:183], off
	global_load_dwordx4 v[178:181], v[182:183], off offset:256
	s_mov_b32 s46, 0x10000
	v_lshl_add_u64 v[182:183], v[182:183], 0, s[46:47]
	global_load_dwordx4 v[188:191], v[182:183], off
	global_load_dwordx4 v[206:209], v[182:183], off offset:256
	s_mov_b32 s46, 0x10000
	v_lshl_add_u64 v[182:183], v[182:183], 0, s[46:47]
	global_load_dwordx4 v[210:213], v[182:183], off
	global_load_dwordx4 v[214:217], v[182:183], off offset:256
	s_mov_b32 s46, 0x50000
	v_lshl_add_u64 v[182:183], v[182:183], 0, s[46:47]
	global_load_dwordx4 v[218:221], v[182:183], off
	global_load_dwordx4 v[222:225], v[182:183], off offset:256
	s_mov_b32 s46, 0x10000
	v_lshl_add_u64 v[182:183], v[182:183], 0, s[46:47]
	global_load_dwordx4 v[226:229], v[182:183], off
	global_load_dwordx4 v[230:233], v[182:183], off offset:256
	s_mov_b32 s46, 0x10000
	v_lshl_add_u64 v[182:183], v[182:183], 0, s[46:47]
	global_load_dwordx4 v[234:237], v[182:183], off
	global_load_dwordx4 v[238:241], v[182:183], off offset:256
	v_mov_b64_e32 v[202:203], v[182:183]
	s_mov_b32 s46, 0x10000
	v_lshl_add_u64 v[202:203], v[202:203], 0, s[46:47]
	global_load_dword v165, v[202:203], off
	global_load_dword v165, v[202:203], off offset:256
	s_waitcnt vmcnt(15)
	v_mov_b64_e32 v[154:155], v[166:167]
	v_mov_b64_e32 v[156:157], v[168:169]
	s_mov_b32 s46, 0x10000
	v_lshl_add_u64 v[182:183], v[182:183], 0, s[46:47]
	global_load_dwordx4 v[166:169], v[182:183], off
	s_lshl_b32 s42, s14, 2
	s_ashr_i32 s43, s42, 31
	v_lshlrev_b32_e32 v160, 16, v154
	v_and_b32_e32 v161, 0xffff0000, v154
	v_lshlrev_b32_e32 v154, 16, v155
	v_and_b32_e32 v155, 0xffff0000, v155
	v_lshlrev_b32_e32 v162, 16, v156
	v_and_b32_e32 v163, 0xffff0000, v156
	v_lshlrev_b32_e32 v156, 16, v157
	v_and_b32_e32 v157, 0xffff0000, v157
	v_pk_add_f32 v[126:127], v[126:127], v[154:155]
	v_pk_add_f32 v[124:125], v[124:125], v[160:161]
	v_pk_add_f32 v[154:155], v[122:123], v[156:157]
	v_pk_add_f32 v[120:121], v[120:121], v[162:163]
	v_cvt_pk_bf16_f32 v122, v124, v125
	v_cvt_pk_bf16_f32 v123, v126, v127
	s_nop 0
	v_cvt_pk_bf16_f32 v124, v120, v121
	v_cvt_pk_bf16_f32 v125, v154, v155
	s_waitcnt vmcnt(15)
; DI float bf_lo(unsigned u) { return __uint_as_float(u << 16); }
; DI float bf_hi(unsigned u) { return __uint_as_float(u & 0xffff0000u); }
; DI u32x4 pack8(f32x4 a, f32x4 b) { u32x4 w; w.x = cvt_pk_bf16(a[0], a[1]); w.y = cvt_pk_bf16(a[2], a[3]); w.z = cvt_pk_bf16(b[0], b[1]); w.w = cvt_pk_bf16(b[2], b[3]); return w; }
;     DI void operator()(AccRef acc, const Unit& u, int wr, int wc, int fr, int fq) const {
;     ...
;             for (int m = 0; m < 4; ++m) { const int row = u.pm * 256 + ai * 128 + wr * 64 + m * 16 + fr; const size_t off = (size_t)row * DM + col0; float q = 0.f;
; #pragma unroll
;                 for (int bj = 0; bj < 2; ++bj) {
;                     f32x4 b0, b1;
;                     if (F32BASE) { b0 = *(const f32x4*)(bp + off + bj * 128); b1 = *(const f32x4*)(bp + off + bj * 128 + 4); }
;                     else { const u32x4 uv = *(const u32x4*)(Ui + off + bj * 128); b0 = (f32x4){bf_lo(uv.x), bf_hi(uv.x), bf_lo(uv.y), bf_hi(uv.y)}; b1 = (f32x4){bf_lo(uv.z), bf_hi(uv.z), bf_lo(uv.w), bf_hi(uv.w)}; }
;                     const u32x4 w = pack8(b0 + acc[ai][bj][m][0] * (0.5f * S2), b1 + acc[ai][bj][m][1] * (0.5f * S2));
;                     *(u32x4*)(Uo + (size_t)row * ldo + col0 + bj * 128) = w;
;                     const float r0 = bf_lo(w.x), r1 = bf_hi(w.x), r2 = bf_lo(w.y), r3 = bf_hi(w.y), r4 = bf_lo(w.z), r5 = bf_hi(w.z), r6 = bf_lo(w.w), r7 = bf_hi(w.w);
;                     q += (r0 * r0 + r1 * r1) + (r2 * r2 + r3 * r3) + (r4 * r4 + r5 * r5) + (r6 * r6 + r7 * r7); }
;                 q += __shfl_xor(q, 16); q += __shfl_xor(q, 32); if (fq == 0) ssp[(size_t)row * 32 + u.pn * 4 + wc] = q; }
	v_mov_b64_e32 v[154:155], v[170:171]
	v_mov_b64_e32 v[156:157], v[172:173]
	global_load_dwordx4 v[170:173], v[182:183], off offset:256
	v_lshlrev_b32_e32 v126, 16, v122
	global_store_dwordx4 v[158:159], v[122:125], off
	v_lshlrev_b32_e32 v127, 16, v123
	v_lshlrev_b32_e32 v160, 16, v124
	v_and_b32_e32 v122, 0xffff0000, v122
	v_and_b32_e32 v123, 0xffff0000, v123
	v_and_b32_e32 v124, 0xffff0000, v124
	v_mul_f32_e32 v122, v122, v122
	v_mul_f32_e32 v123, v123, v123
	v_lshlrev_b32_e32 v161, 16, v125
	v_and_b32_e32 v125, 0xffff0000, v125
	v_mul_f32_e32 v124, v124, v124
	v_fmac_f32_e32 v122, v126, v126
	v_fmac_f32_e32 v123, v127, v127
	v_mul_f32_e32 v125, v125, v125
	v_fmac_f32_e32 v124, v160, v160
	v_add_f32_e32 v122, v122, v123
	v_fmac_f32_e32 v125, v161, v161
	v_add_f32_e32 v122, v122, v124
	v_add_f32_e32 v160, v122, v125
	v_and_b32_e32 v121, 64, v153
	v_xor_b32_e32 v120, 16, v153
	v_add_u32_e32 v121, 64, v121
	v_cmp_lt_i32_e32 vcc, v120, v121
	v_lshlrev_b32_e32 v122, 16, v154
	v_and_b32_e32 v123, 0xffff0000, v154
	v_lshlrev_b32_e32 v124, 16, v155
	v_and_b32_e32 v125, 0xffff0000, v155
	v_lshlrev_b32_e32 v126, 16, v156
	v_and_b32_e32 v127, 0xffff0000, v156
	v_lshlrev_b32_e32 v154, 16, v157
	v_and_b32_e32 v155, 0xffff0000, v157
	v_pk_add_f32 v[118:119], v[118:119], v[124:125]
	v_pk_add_f32 v[116:117], v[116:117], v[122:123]
	v_pk_add_f32 v[114:115], v[114:115], v[154:155]
	v_pk_add_f32 v[112:113], v[112:113], v[126:127]
	v_cvt_pk_bf16_f32 v116, v116, v117
	v_cvt_pk_bf16_f32 v117, v118, v119
	v_cndmask_b32_e32 v120, v153, v120, vcc
	v_cvt_pk_bf16_f32 v118, v112, v113
	v_cvt_pk_bf16_f32 v119, v114, v115
	v_and_b32_e32 v113, 0xffff0000, v116
	v_and_b32_e32 v115, 0xffff0000, v117
	v_lshlrev_b32_e32 v112, 16, v116
	v_lshlrev_b32_e32 v114, 16, v117
	v_and_b32_e32 v123, 0xffff0000, v118
	v_mul_f32_e32 v113, v113, v113
	v_mul_f32_e32 v115, v115, v115
	v_lshlrev_b32_e32 v122, 16, v118
	v_and_b32_e32 v125, 0xffff0000, v119
	v_mul_f32_e32 v123, v123, v123
	v_fmac_f32_e32 v113, v112, v112
	v_fmac_f32_e32 v115, v114, v114
	v_lshlrev_b32_e32 v124, 16, v119
	v_mul_f32_e32 v125, v125, v125
	v_fmac_f32_e32 v123, v122, v122
	v_add_f32_e32 v112, v113, v115
	v_fmac_f32_e32 v125, v124, v124
	v_add_f32_e32 v112, v112, v123
	v_add_f32_e32 v112, v112, v125
	v_lshlrev_b32_e32 v120, 2, v120
	v_add_f32_e32 v112, v160, v112
	ds_bpermute_b32 v113, v120, v112
	v_xor_b32_e32 v114, 32, v153
	v_cmp_lt_i32_e32 vcc, v114, v121
	global_store_dwordx4 v[158:159], v[116:119], off offset:256
	s_waitcnt lgkmcnt(0)
	v_add_f32_e32 v112, v112, v113
	v_cndmask_b32_e32 v114, v153, v114, vcc
	v_lshlrev_b32_e32 v114, 2, v114
	ds_bpermute_b32 v113, v114, v112
	v_cmp_eq_u32_e32 vcc, 0, v164
	s_and_saveexec_b64 s[44:45], vcc
	s_cbranch_execz .LBB0_1511
	v_lshlrev_b64 v[116:117], 7, v[146:147]
	v_lshl_add_u64 v[116:117], s[18:19], 0, v[116:117]
	v_lshl_add_u64 v[116:117], s[42:43], 2, v[116:117]
	s_lshl_b32 s14, s60, 2
	v_lshl_add_u64 v[116:117], v[116:117], 0, s[14:15]
	s_waitcnt lgkmcnt(0)
	v_add_f32_e32 v112, v112, v113
	global_store_dword v[116:117], v112, off
.LBB0_1511:
	s_or_b64 exec, exec, s[44:45]
	v_add_u32_e32 v112, 16, v146
	s_waitcnt lgkmcnt(0)
	v_ashrrev_i32_e32 v113, 31, v112
	v_lshlrev_b64 v[116:117], 12, v[112:113]
	v_lshl_add_u64 v[116:117], s[16:17], 0, v[116:117]
	v_lshl_add_u64 v[122:123], v[144:145], 1, v[116:117]
	s_waitcnt vmcnt(17)
	v_mov_b64_e32 v[116:117], v[174:175]
	v_mov_b64_e32 v[118:119], v[176:177]
	v_lshlrev_b32_e32 v124, 16, v116
	v_and_b32_e32 v125, 0xffff0000, v116
	v_lshlrev_b32_e32 v116, 16, v117
	v_and_b32_e32 v117, 0xffff0000, v117
	v_lshlrev_b32_e32 v126, 16, v118
	v_and_b32_e32 v127, 0xffff0000, v118
	v_lshlrev_b32_e32 v118, 16, v119
	v_and_b32_e32 v119, 0xffff0000, v119
	v_pk_add_f32 v[110:111], v[110:111], v[116:117]
	v_pk_add_f32 v[108:109], v[108:109], v[124:125]
	v_pk_add_f32 v[116:117], v[106:107], v[118:119]
	v_pk_add_f32 v[106:107], v[104:105], v[126:127]
	v_cvt_pk_bf16_f32 v104, v108, v109
	v_cvt_pk_bf16_f32 v105, v110, v111
	s_nop 0
	v_cvt_pk_bf16_f32 v106, v106, v107
	v_cvt_pk_bf16_f32 v107, v116, v117
	s_waitcnt vmcnt(16)
	v_mov_b64_e32 v[108:109], v[178:179]
	v_mov_b64_e32 v[110:111], v[180:181]
	v_lshlrev_b32_e32 v115, 16, v104
	global_store_dwordx4 v[122:123], v[104:107], off
	v_lshlrev_b32_e32 v116, 16, v105
	v_lshlrev_b32_e32 v117, 16, v106
	v_and_b32_e32 v104, 0xffff0000, v104
	v_and_b32_e32 v105, 0xffff0000, v105
	v_and_b32_e32 v106, 0xffff0000, v106
	v_mul_f32_e32 v104, v104, v104
	v_mul_f32_e32 v105, v105, v105
	v_lshlrev_b32_e32 v118, 16, v107
	v_and_b32_e32 v107, 0xffff0000, v107
	v_mul_f32_e32 v106, v106, v106
	v_fmac_f32_e32 v104, v115, v115
	v_fmac_f32_e32 v105, v116, v116
	v_mul_f32_e32 v107, v107, v107
	v_fmac_f32_e32 v106, v117, v117
	v_add_f32_e32 v104, v104, v105
	v_fmac_f32_e32 v107, v118, v118
	v_add_f32_e32 v104, v104, v106
	v_add_f32_e32 v115, v104, v107
	v_lshlrev_b32_e32 v104, 16, v108
	v_and_b32_e32 v105, 0xffff0000, v108
	v_lshlrev_b32_e32 v106, 16, v109
	v_and_b32_e32 v107, 0xffff0000, v109
	v_lshlrev_b32_e32 v108, 16, v110
	v_and_b32_e32 v109, 0xffff0000, v110
	v_lshlrev_b32_e32 v110, 16, v111
	v_and_b32_e32 v111, 0xffff0000, v111
	v_pk_add_f32 v[102:103], v[102:103], v[106:107]
	v_pk_add_f32 v[100:101], v[100:101], v[104:105]
	v_pk_add_f32 v[96:97], v[96:97], v[108:109]
	v_pk_add_f32 v[104:105], v[98:99], v[110:111]
	v_cvt_pk_bf16_f32 v98, v100, v101
	v_cvt_pk_bf16_f32 v99, v102, v103
	v_cvt_pk_bf16_f32 v100, v96, v97
	s_nop 0
	v_and_b32_e32 v97, 0xffff0000, v98
	v_and_b32_e32 v103, 0xffff0000, v99
	v_cvt_pk_bf16_f32 v101, v104, v105
	v_lshlrev_b32_e32 v96, 16, v98
	v_lshlrev_b32_e32 v102, 16, v99
	v_and_b32_e32 v105, 0xffff0000, v100
	v_mul_f32_e32 v97, v97, v97
	v_mul_f32_e32 v103, v103, v103
	v_lshlrev_b32_e32 v104, 16, v100
	v_and_b32_e32 v107, 0xffff0000, v101
	v_mul_f32_e32 v105, v105, v105
	v_fmac_f32_e32 v97, v96, v96
	v_fmac_f32_e32 v103, v102, v102
	v_lshlrev_b32_e32 v106, 16, v101
	v_mul_f32_e32 v107, v107, v107
	v_fmac_f32_e32 v105, v104, v104
	v_add_f32_e32 v96, v97, v103
	v_add_f32_e32 v96, v96, v105
	v_fmac_f32_e32 v107, v106, v106
	v_add_f32_e32 v96, v96, v107
	v_add_f32_e32 v96, v115, v96
	ds_bpermute_b32 v97, v120, v96
	global_store_dwordx4 v[122:123], v[98:101], off offset:256
	s_waitcnt lgkmcnt(0)
	v_add_f32_e32 v96, v96, v97
	ds_bpermute_b32 v97, v114, v96
	s_and_saveexec_b64 s[44:45], vcc
	s_cbranch_execz .LBB0_1513
	v_lshlrev_b64 v[98:99], 7, v[112:113]
	v_lshl_add_u64 v[98:99], s[18:19], 0, v[98:99]
	v_lshl_add_u64 v[98:99], s[42:43], 2, v[98:99]
	s_lshl_b32 s14, s60, 2
	v_lshl_add_u64 v[98:99], v[98:99], 0, s[14:15]
	s_waitcnt lgkmcnt(0)
	v_add_f32_e32 v96, v96, v97
	global_store_dword v[98:99], v96, off
; DI float bf_lo(unsigned u) { return __uint_as_float(u << 16); }
; DI float bf_hi(unsigned u) { return __uint_as_float(u & 0xffff0000u); }
; DI u32x4 pack8(f32x4 a, f32x4 b) { u32x4 w; w.x = cvt_pk_bf16(a[0], a[1]); w.y = cvt_pk_bf16(a[2], a[3]); w.z = cvt_pk_bf16(b[0], b[1]); w.w = cvt_pk_bf16(b[2], b[3]); return w; }
;     DI void operator()(AccRef acc, const Unit& u, int wr, int wc, int fr, int fq) const {
;     ...
;             for (int m = 0; m < 4; ++m) { const int row = u.pm * 256 + ai * 128 + wr * 64 + m * 16 + fr; const size_t off = (size_t)row * DM + col0; float q = 0.f;
; #pragma unroll
;                 for (int bj = 0; bj < 2; ++bj) {
;                     f32x4 b0, b1;
;                     if (F32BASE) { b0 = *(const f32x4*)(bp + off + bj * 128); b1 = *(const f32x4*)(bp + off + bj * 128 + 4); }
;                     else { const u32x4 uv = *(const u32x4*)(Ui + off + bj * 128); b0 = (f32x4){bf_lo(uv.x), bf_hi(uv.x), bf_lo(uv.y), bf_hi(uv.y)}; b1 = (f32x4){bf_lo(uv.z), bf_hi(uv.z), bf_lo(uv.w), bf_hi(uv.w)}; }
;                     const u32x4 w = pack8(b0 + acc[ai][bj][m][0] * (0.5f * S2), b1 + acc[ai][bj][m][1] * (0.5f * S2));
;                     *(u32x4*)(Uo + (size_t)row * ldo + col0 + bj * 128) = w;
;                     const float r0 = bf_lo(w.x), r1 = bf_hi(w.x), r2 = bf_lo(w.y), r3 = bf_hi(w.y), r4 = bf_lo(w.z), r5 = bf_hi(w.z), r6 = bf_lo(w.w), r7 = bf_hi(w.w);
;                     q += (r0 * r0 + r1 * r1) + (r2 * r2 + r3 * r3) + (r4 * r4 + r5 * r5) + (r6 * r6 + r7 * r7); }
;                 q += __shfl_xor(q, 16); q += __shfl_xor(q, 32); if (fq == 0) ssp[(size_t)row * 32 + u.pn * 4 + wc] = q; }
.LBB0_1513:
	s_or_b64 exec, exec, s[44:45]
	v_add_u32_e32 v96, 32, v146
	s_waitcnt lgkmcnt(0)
	v_ashrrev_i32_e32 v97, 31, v96
	v_lshlrev_b64 v[98:99], 12, v[96:97]
	v_lshl_add_u64 v[98:99], s[16:17], 0, v[98:99]
	v_lshl_add_u64 v[102:103], v[144:145], 1, v[98:99]
	s_waitcnt vmcnt(17)
	v_mov_b64_e32 v[98:99], v[188:189]
	v_mov_b64_e32 v[100:101], v[190:191]
	v_lshlrev_b32_e32 v104, 16, v98
	v_and_b32_e32 v105, 0xffff0000, v98
	v_lshlrev_b32_e32 v98, 16, v99
	v_and_b32_e32 v99, 0xffff0000, v99
	v_lshlrev_b32_e32 v106, 16, v100
	v_and_b32_e32 v107, 0xffff0000, v100
	v_lshlrev_b32_e32 v100, 16, v101
	v_and_b32_e32 v101, 0xffff0000, v101
	v_pk_add_f32 v[94:95], v[94:95], v[98:99]
	v_pk_add_f32 v[92:93], v[92:93], v[104:105]
	v_pk_add_f32 v[98:99], v[90:91], v[100:101]
	v_pk_add_f32 v[90:91], v[88:89], v[106:107]
	v_cvt_pk_bf16_f32 v88, v92, v93
	v_cvt_pk_bf16_f32 v89, v94, v95
	s_nop 0
	v_cvt_pk_bf16_f32 v90, v90, v91
	v_cvt_pk_bf16_f32 v91, v98, v99
	s_waitcnt vmcnt(16)
	v_mov_b64_e32 v[92:93], v[206:207]
	v_mov_b64_e32 v[94:95], v[208:209]
	v_lshlrev_b32_e32 v98, 16, v88
	global_store_dwordx4 v[102:103], v[88:91], off
	v_lshlrev_b32_e32 v99, 16, v89
	v_lshlrev_b32_e32 v100, 16, v90
	v_and_b32_e32 v88, 0xffff0000, v88
	v_and_b32_e32 v89, 0xffff0000, v89
	v_and_b32_e32 v90, 0xffff0000, v90
	v_mul_f32_e32 v88, v88, v88
	v_mul_f32_e32 v89, v89, v89
	v_lshlrev_b32_e32 v101, 16, v91
	v_and_b32_e32 v91, 0xffff0000, v91
	v_mul_f32_e32 v90, v90, v90
	v_fmac_f32_e32 v88, v98, v98
	v_fmac_f32_e32 v89, v99, v99
	v_mul_f32_e32 v91, v91, v91
	v_fmac_f32_e32 v90, v100, v100
	v_add_f32_e32 v88, v88, v89
	v_fmac_f32_e32 v91, v101, v101
	v_add_f32_e32 v88, v88, v90
	v_add_f32_e32 v98, v88, v91
	v_lshlrev_b32_e32 v88, 16, v92
	v_and_b32_e32 v89, 0xffff0000, v92
	v_lshlrev_b32_e32 v90, 16, v93
	v_and_b32_e32 v91, 0xffff0000, v93
	v_lshlrev_b32_e32 v92, 16, v94
	v_and_b32_e32 v93, 0xffff0000, v94
	v_lshlrev_b32_e32 v94, 16, v95
	v_and_b32_e32 v95, 0xffff0000, v95
	v_pk_add_f32 v[86:87], v[86:87], v[90:91]
	v_pk_add_f32 v[84:85], v[84:85], v[88:89]
	v_pk_add_f32 v[80:81], v[80:81], v[92:93]
	v_pk_add_f32 v[88:89], v[82:83], v[94:95]
	v_cvt_pk_bf16_f32 v82, v84, v85
	v_cvt_pk_bf16_f32 v83, v86, v87
	v_cvt_pk_bf16_f32 v84, v80, v81
	s_nop 0
	v_and_b32_e32 v81, 0xffff0000, v82
	v_and_b32_e32 v87, 0xffff0000, v83
	v_cvt_pk_bf16_f32 v85, v88, v89
	v_lshlrev_b32_e32 v80, 16, v82
	v_lshlrev_b32_e32 v86, 16, v83
	v_and_b32_e32 v89, 0xffff0000, v84
	v_mul_f32_e32 v81, v81, v81
	v_mul_f32_e32 v87, v87, v87
	v_lshlrev_b32_e32 v88, 16, v84
	v_and_b32_e32 v91, 0xffff0000, v85
	v_mul_f32_e32 v89, v89, v89
	v_fmac_f32_e32 v81, v80, v80
	v_fmac_f32_e32 v87, v86, v86
	v_lshlrev_b32_e32 v90, 16, v85
	v_mul_f32_e32 v91, v91, v91
	v_fmac_f32_e32 v89, v88, v88
	v_add_f32_e32 v80, v81, v87
	v_add_f32_e32 v80, v80, v89
	v_fmac_f32_e32 v91, v90, v90
	v_add_f32_e32 v80, v80, v91
	v_add_f32_e32 v80, v98, v80
	ds_bpermute_b32 v81, v120, v80
	global_store_dwordx4 v[102:103], v[82:85], off offset:256
	s_waitcnt lgkmcnt(0)
	v_add_f32_e32 v80, v80, v81
	ds_bpermute_b32 v81, v114, v80
	s_and_saveexec_b64 s[44:45], vcc
	s_cbranch_execz .LBB0_1515
	v_lshlrev_b64 v[82:83], 7, v[96:97]
	v_lshl_add_u64 v[82:83], s[18:19], 0, v[82:83]
	v_lshl_add_u64 v[82:83], s[42:43], 2, v[82:83]
	s_lshl_b32 s14, s60, 2
	v_lshl_add_u64 v[82:83], v[82:83], 0, s[14:15]
	s_waitcnt lgkmcnt(0)
	v_add_f32_e32 v80, v80, v81
	global_store_dword v[82:83], v80, off
.LBB0_1515:
	s_or_b64 exec, exec, s[44:45]
	v_add_u32_e32 v80, 48, v146
	s_waitcnt lgkmcnt(0)
	v_ashrrev_i32_e32 v81, 31, v80
	v_lshlrev_b64 v[82:83], 12, v[80:81]
	v_lshl_add_u64 v[82:83], s[16:17], 0, v[82:83]
	v_lshl_add_u64 v[86:87], v[144:145], 1, v[82:83]
	s_waitcnt vmcnt(17)
	v_mov_b64_e32 v[82:83], v[210:211]
	v_mov_b64_e32 v[84:85], v[212:213]
	v_lshlrev_b32_e32 v88, 16, v82
	v_and_b32_e32 v89, 0xffff0000, v82
	v_lshlrev_b32_e32 v82, 16, v83
	v_and_b32_e32 v83, 0xffff0000, v83
	v_lshlrev_b32_e32 v90, 16, v84
	v_and_b32_e32 v91, 0xffff0000, v84
	v_lshlrev_b32_e32 v84, 16, v85
	v_and_b32_e32 v85, 0xffff0000, v85
	v_pk_add_f32 v[78:79], v[78:79], v[82:83]
	v_pk_add_f32 v[76:77], v[76:77], v[88:89]
	v_pk_add_f32 v[82:83], v[74:75], v[84:85]
	v_pk_add_f32 v[74:75], v[72:73], v[90:91]
	v_cvt_pk_bf16_f32 v72, v76, v77
	v_cvt_pk_bf16_f32 v73, v78, v79
	s_nop 0
	v_cvt_pk_bf16_f32 v74, v74, v75
	v_cvt_pk_bf16_f32 v75, v82, v83
	s_waitcnt vmcnt(16)
	v_mov_b64_e32 v[76:77], v[214:215]
	v_mov_b64_e32 v[78:79], v[216:217]
	v_lshlrev_b32_e32 v82, 16, v72
	global_store_dwordx4 v[86:87], v[72:75], off
	v_lshlrev_b32_e32 v83, 16, v73
	v_lshlrev_b32_e32 v84, 16, v74
	v_and_b32_e32 v72, 0xffff0000, v72
	v_and_b32_e32 v73, 0xffff0000, v73
	v_and_b32_e32 v74, 0xffff0000, v74
	v_mul_f32_e32 v72, v72, v72
	v_mul_f32_e32 v73, v73, v73
	v_lshlrev_b32_e32 v85, 16, v75
	v_and_b32_e32 v75, 0xffff0000, v75
	v_mul_f32_e32 v74, v74, v74
	v_fmac_f32_e32 v72, v82, v82
	v_fmac_f32_e32 v73, v83, v83
	v_mul_f32_e32 v75, v75, v75
	v_fmac_f32_e32 v74, v84, v84
	v_add_f32_e32 v72, v72, v73
	v_fmac_f32_e32 v75, v85, v85
	v_add_f32_e32 v72, v72, v74
	v_add_f32_e32 v82, v72, v75
	v_lshlrev_b32_e32 v72, 16, v76
	v_and_b32_e32 v73, 0xffff0000, v76
	v_lshlrev_b32_e32 v74, 16, v77
	v_and_b32_e32 v75, 0xffff0000, v77
	v_lshlrev_b32_e32 v76, 16, v78
	v_and_b32_e32 v77, 0xffff0000, v78
	v_lshlrev_b32_e32 v78, 16, v79
	v_and_b32_e32 v79, 0xffff0000, v79
	v_pk_add_f32 v[70:71], v[70:71], v[74:75]
	v_pk_add_f32 v[68:69], v[68:69], v[72:73]
	v_pk_add_f32 v[64:65], v[64:65], v[76:77]
	v_pk_add_f32 v[72:73], v[66:67], v[78:79]
	v_cvt_pk_bf16_f32 v66, v68, v69
	v_cvt_pk_bf16_f32 v67, v70, v71
	v_cvt_pk_bf16_f32 v68, v64, v65
	s_nop 0
	v_and_b32_e32 v65, 0xffff0000, v66
	v_and_b32_e32 v71, 0xffff0000, v67
	v_cvt_pk_bf16_f32 v69, v72, v73
	v_lshlrev_b32_e32 v64, 16, v66
	v_lshlrev_b32_e32 v70, 16, v67
	v_and_b32_e32 v73, 0xffff0000, v68
	v_mul_f32_e32 v65, v65, v65
	v_mul_f32_e32 v71, v71, v71
	v_lshlrev_b32_e32 v72, 16, v68
	v_and_b32_e32 v75, 0xffff0000, v69
	v_mul_f32_e32 v73, v73, v73
	v_fmac_f32_e32 v65, v64, v64
	v_fmac_f32_e32 v71, v70, v70
	v_lshlrev_b32_e32 v74, 16, v69
	v_mul_f32_e32 v75, v75, v75
	v_fmac_f32_e32 v73, v72, v72
	v_add_f32_e32 v64, v65, v71
	v_add_f32_e32 v64, v64, v73
	v_fmac_f32_e32 v75, v74, v74
	v_add_f32_e32 v64, v64, v75
	v_add_f32_e32 v64, v82, v64
	ds_bpermute_b32 v65, v120, v64
	global_store_dwordx4 v[86:87], v[66:69], off offset:256
	s_waitcnt lgkmcnt(0)
	v_add_f32_e32 v64, v64, v65
	ds_bpermute_b32 v65, v114, v64
	s_and_saveexec_b64 s[44:45], vcc
	s_cbranch_execz .LBB0_1517
	v_lshlrev_b64 v[66:67], 7, v[80:81]
	v_lshl_add_u64 v[66:67], s[18:19], 0, v[66:67]
	v_lshl_add_u64 v[66:67], s[42:43], 2, v[66:67]
	s_lshl_b32 s14, s60, 2
	v_lshl_add_u64 v[66:67], v[66:67], 0, s[14:15]
	s_waitcnt lgkmcnt(0)
	v_add_f32_e32 v64, v64, v65
	global_store_dword v[66:67], v64, off
; DI float bf_lo(unsigned u) { return __uint_as_float(u << 16); }
; DI float bf_hi(unsigned u) { return __uint_as_float(u & 0xffff0000u); }
; DI u32x4 pack8(f32x4 a, f32x4 b) { u32x4 w; w.x = cvt_pk_bf16(a[0], a[1]); w.y = cvt_pk_bf16(a[2], a[3]); w.z = cvt_pk_bf16(b[0], b[1]); w.w = cvt_pk_bf16(b[2], b[3]); return w; }
;     DI void operator()(AccRef acc, const Unit& u, int wr, int wc, int fr, int fq) const {
;     ...
;             for (int m = 0; m < 4; ++m) { const int row = u.pm * 256 + ai * 128 + wr * 64 + m * 16 + fr; const size_t off = (size_t)row * DM + col0; float q = 0.f;
; #pragma unroll
;                 for (int bj = 0; bj < 2; ++bj) {
;                     f32x4 b0, b1;
;                     if (F32BASE) { b0 = *(const f32x4*)(bp + off + bj * 128); b1 = *(const f32x4*)(bp + off + bj * 128 + 4); }
;                     else { const u32x4 uv = *(const u32x4*)(Ui + off + bj * 128); b0 = (f32x4){bf_lo(uv.x), bf_hi(uv.x), bf_lo(uv.y), bf_hi(uv.y)}; b1 = (f32x4){bf_lo(uv.z), bf_hi(uv.z), bf_lo(uv.w), bf_hi(uv.w)}; }
;                     const u32x4 w = pack8(b0 + acc[ai][bj][m][0] * (0.5f * S2), b1 + acc[ai][bj][m][1] * (0.5f * S2));
;                     *(u32x4*)(Uo + (size_t)row * ldo + col0 + bj * 128) = w;
;                     const float r0 = bf_lo(w.x), r1 = bf_hi(w.x), r2 = bf_lo(w.y), r3 = bf_hi(w.y), r4 = bf_lo(w.z), r5 = bf_hi(w.z), r6 = bf_lo(w.w), r7 = bf_hi(w.w);
;                     q += (r0 * r0 + r1 * r1) + (r2 * r2 + r3 * r3) + (r4 * r4 + r5 * r5) + (r6 * r6 + r7 * r7); }
;                 q += __shfl_xor(q, 16); q += __shfl_xor(q, 32); if (fq == 0) ssp[(size_t)row * 32 + u.pn * 4 + wc] = q; }
.LBB0_1517:
	s_or_b64 exec, exec, s[44:45]
	v_add_u32_e32 v64, 0x80, v146
	s_waitcnt lgkmcnt(0)
	v_ashrrev_i32_e32 v65, 31, v64
	v_lshlrev_b64 v[66:67], 12, v[64:65]
	v_lshl_add_u64 v[66:67], s[16:17], 0, v[66:67]
	v_lshl_add_u64 v[70:71], v[144:145], 1, v[66:67]
	s_waitcnt vmcnt(17)
	v_mov_b64_e32 v[66:67], v[218:219]
	v_mov_b64_e32 v[68:69], v[220:221]
	v_lshlrev_b32_e32 v72, 16, v66
	v_and_b32_e32 v73, 0xffff0000, v66
	v_lshlrev_b32_e32 v66, 16, v67
	v_and_b32_e32 v67, 0xffff0000, v67
	v_lshlrev_b32_e32 v74, 16, v68
	v_and_b32_e32 v75, 0xffff0000, v68
	v_lshlrev_b32_e32 v68, 16, v69
	v_and_b32_e32 v69, 0xffff0000, v69
	v_pk_add_f32 v[62:63], v[62:63], v[66:67]
	v_pk_add_f32 v[60:61], v[60:61], v[72:73]
	v_pk_add_f32 v[66:67], v[58:59], v[68:69]
	v_pk_add_f32 v[58:59], v[56:57], v[74:75]
	v_cvt_pk_bf16_f32 v56, v60, v61
	v_cvt_pk_bf16_f32 v57, v62, v63
	s_nop 0
	v_cvt_pk_bf16_f32 v58, v58, v59
	v_cvt_pk_bf16_f32 v59, v66, v67
	s_waitcnt vmcnt(16)
	v_mov_b64_e32 v[60:61], v[222:223]
	v_mov_b64_e32 v[62:63], v[224:225]
	v_lshlrev_b32_e32 v66, 16, v56
	global_store_dwordx4 v[70:71], v[56:59], off
	v_lshlrev_b32_e32 v67, 16, v57
	v_lshlrev_b32_e32 v68, 16, v58
	v_and_b32_e32 v56, 0xffff0000, v56
	v_and_b32_e32 v57, 0xffff0000, v57
	v_and_b32_e32 v58, 0xffff0000, v58
	v_mul_f32_e32 v56, v56, v56
	v_mul_f32_e32 v57, v57, v57
	v_lshlrev_b32_e32 v69, 16, v59
	v_and_b32_e32 v59, 0xffff0000, v59
	v_mul_f32_e32 v58, v58, v58
	v_fmac_f32_e32 v56, v66, v66
	v_fmac_f32_e32 v57, v67, v67
	v_mul_f32_e32 v59, v59, v59
	v_fmac_f32_e32 v58, v68, v68
	v_add_f32_e32 v56, v56, v57
	v_fmac_f32_e32 v59, v69, v69
	v_add_f32_e32 v56, v56, v58
	v_add_f32_e32 v66, v56, v59
	v_lshlrev_b32_e32 v56, 16, v60
	v_and_b32_e32 v57, 0xffff0000, v60
	v_lshlrev_b32_e32 v58, 16, v61
	v_and_b32_e32 v59, 0xffff0000, v61
	v_lshlrev_b32_e32 v60, 16, v62
	v_and_b32_e32 v61, 0xffff0000, v62
	v_lshlrev_b32_e32 v62, 16, v63
	v_and_b32_e32 v63, 0xffff0000, v63
	v_pk_add_f32 v[54:55], v[54:55], v[58:59]
	v_pk_add_f32 v[52:53], v[52:53], v[56:57]
	v_pk_add_f32 v[48:49], v[48:49], v[60:61]
	v_pk_add_f32 v[56:57], v[50:51], v[62:63]
	v_cvt_pk_bf16_f32 v50, v52, v53
	v_cvt_pk_bf16_f32 v51, v54, v55
	v_cvt_pk_bf16_f32 v52, v48, v49
	s_nop 0
	v_and_b32_e32 v49, 0xffff0000, v50
	v_and_b32_e32 v55, 0xffff0000, v51
	v_cvt_pk_bf16_f32 v53, v56, v57
	v_lshlrev_b32_e32 v48, 16, v50
	v_lshlrev_b32_e32 v54, 16, v51
	v_and_b32_e32 v57, 0xffff0000, v52
	v_mul_f32_e32 v49, v49, v49
	v_mul_f32_e32 v55, v55, v55
	v_lshlrev_b32_e32 v56, 16, v52
	v_and_b32_e32 v59, 0xffff0000, v53
	v_mul_f32_e32 v57, v57, v57
	v_fmac_f32_e32 v49, v48, v48
	v_fmac_f32_e32 v55, v54, v54
	v_lshlrev_b32_e32 v58, 16, v53
	v_mul_f32_e32 v59, v59, v59
	v_fmac_f32_e32 v57, v56, v56
	v_add_f32_e32 v48, v49, v55
	v_add_f32_e32 v48, v48, v57
	v_fmac_f32_e32 v59, v58, v58
	v_add_f32_e32 v48, v48, v59
	v_add_f32_e32 v48, v66, v48
	ds_bpermute_b32 v49, v120, v48
	global_store_dwordx4 v[70:71], v[50:53], off offset:256
	s_waitcnt lgkmcnt(0)
	v_add_f32_e32 v48, v48, v49
	ds_bpermute_b32 v49, v114, v48
	s_and_saveexec_b64 s[44:45], vcc
	s_cbranch_execz .LBB0_1519
	v_lshlrev_b64 v[50:51], 7, v[64:65]
	v_lshl_add_u64 v[50:51], s[18:19], 0, v[50:51]
	v_lshl_add_u64 v[50:51], s[42:43], 2, v[50:51]
	s_lshl_b32 s14, s60, 2
	v_lshl_add_u64 v[50:51], v[50:51], 0, s[14:15]
	s_waitcnt lgkmcnt(0)
	v_add_f32_e32 v48, v48, v49
	global_store_dword v[50:51], v48, off
; DI float bf_lo(unsigned u) { return __uint_as_float(u << 16); }
; DI float bf_hi(unsigned u) { return __uint_as_float(u & 0xffff0000u); }
; DI u32x4 pack8(f32x4 a, f32x4 b) { u32x4 w; w.x = cvt_pk_bf16(a[0], a[1]); w.y = cvt_pk_bf16(a[2], a[3]); w.z = cvt_pk_bf16(b[0], b[1]); w.w = cvt_pk_bf16(b[2], b[3]); return w; }
;     DI void operator()(AccRef acc, const Unit& u, int wr, int wc, int fr, int fq) const {
;     ...
;             for (int m = 0; m < 4; ++m) { const int row = u.pm * 256 + ai * 128 + wr * 64 + m * 16 + fr; const size_t off = (size_t)row * DM + col0; float q = 0.f;
; #pragma unroll
;                 for (int bj = 0; bj < 2; ++bj) {
;                     f32x4 b0, b1;
;                     if (F32BASE) { b0 = *(const f32x4*)(bp + off + bj * 128); b1 = *(const f32x4*)(bp + off + bj * 128 + 4); }
;                     else { const u32x4 uv = *(const u32x4*)(Ui + off + bj * 128); b0 = (f32x4){bf_lo(uv.x), bf_hi(uv.x), bf_lo(uv.y), bf_hi(uv.y)}; b1 = (f32x4){bf_lo(uv.z), bf_hi(uv.z), bf_lo(uv.w), bf_hi(uv.w)}; }
;                     const u32x4 w = pack8(b0 + acc[ai][bj][m][0] * (0.5f * S2), b1 + acc[ai][bj][m][1] * (0.5f * S2));
;                     *(u32x4*)(Uo + (size_t)row * ldo + col0 + bj * 128) = w;
;                     const float r0 = bf_lo(w.x), r1 = bf_hi(w.x), r2 = bf_lo(w.y), r3 = bf_hi(w.y), r4 = bf_lo(w.z), r5 = bf_hi(w.z), r6 = bf_lo(w.w), r7 = bf_hi(w.w);
;                     q += (r0 * r0 + r1 * r1) + (r2 * r2 + r3 * r3) + (r4 * r4 + r5 * r5) + (r6 * r6 + r7 * r7); }
;                 q += __shfl_xor(q, 16); q += __shfl_xor(q, 32); if (fq == 0) ssp[(size_t)row * 32 + u.pn * 4 + wc] = q; }
.LBB0_1519:
	s_or_b64 exec, exec, s[44:45]
	v_add_u32_e32 v48, 0x90, v146
	s_waitcnt lgkmcnt(0)
	v_ashrrev_i32_e32 v49, 31, v48
	v_lshlrev_b64 v[50:51], 12, v[48:49]
	v_lshl_add_u64 v[50:51], s[16:17], 0, v[50:51]
	v_lshl_add_u64 v[54:55], v[144:145], 1, v[50:51]
	s_waitcnt vmcnt(17)
	v_mov_b64_e32 v[50:51], v[226:227]
	v_mov_b64_e32 v[52:53], v[228:229]
	v_lshlrev_b32_e32 v56, 16, v50
	v_and_b32_e32 v57, 0xffff0000, v50
	v_lshlrev_b32_e32 v50, 16, v51
	v_and_b32_e32 v51, 0xffff0000, v51
	v_lshlrev_b32_e32 v58, 16, v52
	v_and_b32_e32 v59, 0xffff0000, v52
	v_lshlrev_b32_e32 v52, 16, v53
	v_and_b32_e32 v53, 0xffff0000, v53
	v_pk_add_f32 v[46:47], v[46:47], v[50:51]
	v_pk_add_f32 v[44:45], v[44:45], v[56:57]
	v_pk_add_f32 v[50:51], v[42:43], v[52:53]
	v_pk_add_f32 v[42:43], v[40:41], v[58:59]
	v_cvt_pk_bf16_f32 v40, v44, v45
	v_cvt_pk_bf16_f32 v41, v46, v47
	s_nop 0
	v_cvt_pk_bf16_f32 v42, v42, v43
	v_cvt_pk_bf16_f32 v43, v50, v51
	s_waitcnt vmcnt(16)
	v_mov_b64_e32 v[44:45], v[230:231]
	v_mov_b64_e32 v[46:47], v[232:233]
	v_lshlrev_b32_e32 v50, 16, v40
	global_store_dwordx4 v[54:55], v[40:43], off
	v_lshlrev_b32_e32 v51, 16, v41
	v_lshlrev_b32_e32 v52, 16, v42
	v_and_b32_e32 v40, 0xffff0000, v40
	v_and_b32_e32 v41, 0xffff0000, v41
	v_and_b32_e32 v42, 0xffff0000, v42
	v_mul_f32_e32 v40, v40, v40
	v_mul_f32_e32 v41, v41, v41
	v_lshlrev_b32_e32 v53, 16, v43
	v_and_b32_e32 v43, 0xffff0000, v43
	v_mul_f32_e32 v42, v42, v42
	v_fmac_f32_e32 v40, v50, v50
	v_fmac_f32_e32 v41, v51, v51
	v_mul_f32_e32 v43, v43, v43
	v_fmac_f32_e32 v42, v52, v52
	v_add_f32_e32 v40, v40, v41
	v_fmac_f32_e32 v43, v53, v53
	v_add_f32_e32 v40, v40, v42
	v_add_f32_e32 v50, v40, v43
	v_lshlrev_b32_e32 v40, 16, v44
	v_and_b32_e32 v41, 0xffff0000, v44
	v_lshlrev_b32_e32 v42, 16, v45
	v_and_b32_e32 v43, 0xffff0000, v45
	v_lshlrev_b32_e32 v44, 16, v46
	v_and_b32_e32 v45, 0xffff0000, v46
	v_lshlrev_b32_e32 v46, 16, v47
	v_and_b32_e32 v47, 0xffff0000, v47
	v_pk_add_f32 v[38:39], v[38:39], v[42:43]
	v_pk_add_f32 v[36:37], v[36:37], v[40:41]
	v_pk_add_f32 v[32:33], v[32:33], v[44:45]
	v_pk_add_f32 v[40:41], v[34:35], v[46:47]
	v_cvt_pk_bf16_f32 v34, v36, v37
	v_cvt_pk_bf16_f32 v35, v38, v39
	v_cvt_pk_bf16_f32 v36, v32, v33
	s_nop 0
	v_and_b32_e32 v33, 0xffff0000, v34
	v_and_b32_e32 v39, 0xffff0000, v35
	v_cvt_pk_bf16_f32 v37, v40, v41
	v_lshlrev_b32_e32 v32, 16, v34
	v_lshlrev_b32_e32 v38, 16, v35
	v_and_b32_e32 v41, 0xffff0000, v36
	v_mul_f32_e32 v33, v33, v33
	v_mul_f32_e32 v39, v39, v39
	v_lshlrev_b32_e32 v40, 16, v36
	v_and_b32_e32 v43, 0xffff0000, v37
	v_mul_f32_e32 v41, v41, v41
	v_fmac_f32_e32 v33, v32, v32
	v_fmac_f32_e32 v39, v38, v38
	v_lshlrev_b32_e32 v42, 16, v37
	v_mul_f32_e32 v43, v43, v43
	v_fmac_f32_e32 v41, v40, v40
	v_add_f32_e32 v32, v33, v39
	v_add_f32_e32 v32, v32, v41
	v_fmac_f32_e32 v43, v42, v42
	v_add_f32_e32 v32, v32, v43
	v_add_f32_e32 v32, v50, v32
	ds_bpermute_b32 v33, v120, v32
	global_store_dwordx4 v[54:55], v[34:37], off offset:256
	s_waitcnt lgkmcnt(0)
	v_add_f32_e32 v32, v32, v33
	ds_bpermute_b32 v33, v114, v32
	s_and_saveexec_b64 s[44:45], vcc
	s_cbranch_execz .LBB0_1521
	v_lshlrev_b64 v[34:35], 7, v[48:49]
	v_lshl_add_u64 v[34:35], s[18:19], 0, v[34:35]
	v_lshl_add_u64 v[34:35], s[42:43], 2, v[34:35]
	s_lshl_b32 s14, s60, 2
	v_lshl_add_u64 v[34:35], v[34:35], 0, s[14:15]
	s_waitcnt lgkmcnt(0)
	v_add_f32_e32 v32, v32, v33
	global_store_dword v[34:35], v32, off
.LBB0_1521:
	s_or_b64 exec, exec, s[44:45]
	v_add_u32_e32 v32, 0xa0, v146
	s_waitcnt lgkmcnt(0)
	v_ashrrev_i32_e32 v33, 31, v32
	v_lshlrev_b64 v[34:35], 12, v[32:33]
	v_lshl_add_u64 v[34:35], s[16:17], 0, v[34:35]
	v_lshl_add_u64 v[38:39], v[144:145], 1, v[34:35]
	s_waitcnt vmcnt(17)
	v_mov_b64_e32 v[34:35], v[234:235]
	v_mov_b64_e32 v[36:37], v[236:237]
	v_lshlrev_b32_e32 v40, 16, v34
	v_and_b32_e32 v41, 0xffff0000, v34
	v_lshlrev_b32_e32 v34, 16, v35
	v_and_b32_e32 v35, 0xffff0000, v35
	v_lshlrev_b32_e32 v42, 16, v36
	v_and_b32_e32 v43, 0xffff0000, v36
	v_lshlrev_b32_e32 v36, 16, v37
	v_and_b32_e32 v37, 0xffff0000, v37
	v_pk_add_f32 v[30:31], v[30:31], v[34:35]
	v_pk_add_f32 v[28:29], v[28:29], v[40:41]
	v_pk_add_f32 v[34:35], v[26:27], v[36:37]
	v_pk_add_f32 v[26:27], v[24:25], v[42:43]
	v_cvt_pk_bf16_f32 v24, v28, v29
	v_cvt_pk_bf16_f32 v25, v30, v31
	s_nop 0
	v_cvt_pk_bf16_f32 v26, v26, v27
	v_cvt_pk_bf16_f32 v27, v34, v35
	s_waitcnt vmcnt(16)
	v_mov_b64_e32 v[28:29], v[238:239]
	v_mov_b64_e32 v[30:31], v[240:241]
	v_lshlrev_b32_e32 v34, 16, v24
	global_store_dwordx4 v[38:39], v[24:27], off
	v_lshlrev_b32_e32 v35, 16, v25
	v_lshlrev_b32_e32 v36, 16, v26
	v_and_b32_e32 v24, 0xffff0000, v24
	v_and_b32_e32 v25, 0xffff0000, v25
	v_and_b32_e32 v26, 0xffff0000, v26
	v_mul_f32_e32 v24, v24, v24
	v_mul_f32_e32 v25, v25, v25
	v_lshlrev_b32_e32 v37, 16, v27
	v_and_b32_e32 v27, 0xffff0000, v27
	v_mul_f32_e32 v26, v26, v26
	v_fmac_f32_e32 v24, v34, v34
	v_fmac_f32_e32 v25, v35, v35
	v_mul_f32_e32 v27, v27, v27
	v_fmac_f32_e32 v26, v36, v36
	v_add_f32_e32 v24, v24, v25
	v_fmac_f32_e32 v27, v37, v37
	v_add_f32_e32 v24, v24, v26
	v_add_f32_e32 v34, v24, v27
	v_lshlrev_b32_e32 v24, 16, v28
	v_and_b32_e32 v25, 0xffff0000, v28
	v_lshlrev_b32_e32 v26, 16, v29
	v_and_b32_e32 v27, 0xffff0000, v29
	v_lshlrev_b32_e32 v28, 16, v30
	v_and_b32_e32 v29, 0xffff0000, v30
	v_lshlrev_b32_e32 v30, 16, v31
	v_and_b32_e32 v31, 0xffff0000, v31
	v_pk_add_f32 v[22:23], v[22:23], v[26:27]
	v_pk_add_f32 v[20:21], v[20:21], v[24:25]
	v_pk_add_f32 v[16:17], v[16:17], v[28:29]
	v_pk_add_f32 v[24:25], v[18:19], v[30:31]
	v_cvt_pk_bf16_f32 v18, v20, v21
	v_cvt_pk_bf16_f32 v19, v22, v23
	v_cvt_pk_bf16_f32 v20, v16, v17
	s_nop 0
	v_and_b32_e32 v17, 0xffff0000, v18
	v_and_b32_e32 v23, 0xffff0000, v19
	v_cvt_pk_bf16_f32 v21, v24, v25
	v_lshlrev_b32_e32 v16, 16, v18
	v_lshlrev_b32_e32 v22, 16, v19
	v_and_b32_e32 v25, 0xffff0000, v20
	v_mul_f32_e32 v17, v17, v17
	v_mul_f32_e32 v23, v23, v23
	v_lshlrev_b32_e32 v24, 16, v20
	v_and_b32_e32 v27, 0xffff0000, v21
	v_mul_f32_e32 v25, v25, v25
	v_fmac_f32_e32 v17, v16, v16
	v_fmac_f32_e32 v23, v22, v22
	v_lshlrev_b32_e32 v26, 16, v21
	v_mul_f32_e32 v27, v27, v27
	v_fmac_f32_e32 v25, v24, v24
	v_add_f32_e32 v16, v17, v23
	v_add_f32_e32 v16, v16, v25
	v_fmac_f32_e32 v27, v26, v26
	v_add_f32_e32 v16, v16, v27
	v_add_f32_e32 v16, v34, v16
	ds_bpermute_b32 v17, v120, v16
	global_store_dwordx4 v[38:39], v[18:21], off offset:256
	s_waitcnt lgkmcnt(0)
	v_add_f32_e32 v16, v16, v17
	ds_bpermute_b32 v17, v114, v16
	s_and_saveexec_b64 s[44:45], vcc
	s_cbranch_execz .LBB0_1523
	v_lshlrev_b64 v[18:19], 7, v[32:33]
	v_lshl_add_u64 v[18:19], s[18:19], 0, v[18:19]
	v_lshl_add_u64 v[18:19], s[42:43], 2, v[18:19]
	s_lshl_b32 s14, s60, 2
	v_lshl_add_u64 v[18:19], v[18:19], 0, s[14:15]
	s_waitcnt lgkmcnt(0)
	v_add_f32_e32 v16, v16, v17
	global_store_dword v[18:19], v16, off

; #define PG8_STAGE(bufoff, gbase, voff) do { _Pragma("unroll") for (int _i = 0; _i < 2; ++_i) \
;         __builtin_amdgcn_global_load_lds((const unsigned*)((const char*)(gbase) + (voff)[_i]), (LAS unsigned*)(lds + (bufoff) + ldsw + _i * 8192), 16, 0, 0); } while (0)
; #define PG8_LDA(dst, b, h) do { _Pragma("unroll") for (int m = 0; m < 4; ++m) _Pragma("unroll") for (int k = 0; k < 2; ++k) dst[m][k] = *(const LAS bf16x8*)(lds + PG8_SA(b, h) + aoff + m * 2048 + k * 1024); } while (0)
; #define PG8_LDB(dst, b, h) do { _Pragma("unroll") for (int n = 0; n < 2; ++n) _Pragma("unroll") for (int k = 0; k < 2; ++k) dst[n][k] = *(const LAS bf16x8*)(lds + PG8_SB(b, h) + boff + n * 2048 + k * 1024); } while (0)
; #define PG8_WAIT_V(n) asm volatile("s_waitcnt vmcnt(" #n ")" ::: "memory")
; #define PG8_WAIT_L(n) asm volatile("s_waitcnt lgkmcnt(" #n ")" ::: "memory")
; #define PG8_BAR __builtin_amdgcn_s_barrier()
; #define PG8_SCHED __builtin_amdgcn_sched_barrier(0)
; template <class Epi, class Sched>
; DI void gemm_phase(LAS unsigned char* lds, const Gemm g, const Sched& S, const Epi& E) {
;     ...
;             PG8_LDB(B0, 0, 0); PG8_SCHED; PG8_LDA(At, 0, 0); PG8_STAGE(PG8_SA(1, 1), a1 + hstep, voffA);
;             PG8_WAIT_L(8); PG8_BAR; PG8_WAIT_L(0); PG8_MMA(0, 0, At, B0); PG8_BAR; PG8_SCHED;
;             PG8_LDB(B1, 0, 1); PG8_STAGE(PG8_SB(0, 0), b2, voffB);
;             PG8_BAR; PG8_WAIT_L(0); PG8_MMA(0, 1, At, B1); PG8_BAR;
;             PG8_LDA(At, 0, 1); PG8_STAGE(PG8_SA(0, 0), a2, voffA);
;             PG8_BAR; PG8_WAIT_L(0); PG8_MMA(1, 0, At, B0); PG8_BAR; PG8_SCHED;
;             PG8_STAGE(PG8_SB(0, 1), b2 + hstep, voffB);
;             PG8_WAIT_V(6); PG8_BAR; PG8_MMA(1, 1, At, B1); PG8_BAR;
;             PG8_LDB(B0, 1, 0); PG8_SCHED; PG8_LDA(At, 1, 0); PG8_STAGE(PG8_SA(0, 1), a2 + hstep, voffA);
;             PG8_WAIT_L(8); PG8_BAR; PG8_WAIT_L(0); PG8_MMA(0, 0, At, B0); PG8_BAR; PG8_SCHED;
;             PG8_LDB(B1, 1, 1); PG8_STAGE(PG8_SB(1, 0), b3, voffB);
;             PG8_BAR; PG8_WAIT_L(0); PG8_MMA(0, 1, At, B1); PG8_BAR;
;             PG8_LDA(At, 1, 1); PG8_STAGE(PG8_SA(1, 0), a3, voffA);
;             PG8_BAR; PG8_WAIT_L(0); PG8_MMA(1, 0, At, B0); PG8_BAR; PG8_SCHED;
;             PG8_STAGE(PG8_SB(1, 1), b3 + hstep, voffB);
;             PG8_WAIT_V(6); PG8_BAR; PG8_MMA(1, 1, At, B1); PG8_BAR;
.LBB0_1668:
	ds_read_b128 v[144:147], v149
	ds_read_b128 v[156:159], v149 offset:1024
	ds_read_b128 v[160:163], v149 offset:2048
	ds_read_b128 v[164:167], v149 offset:3072
	s_add_u32 s0, s8, 0xfff80080
	s_addc_u32 s1, s9, -1
	s_cmp_eq_u32 s68, 28
	s_cselect_b32 s43, s29, s1
	s_cselect_b32 s42, s35, s0
	s_cselect_b32 s41, s19, s67
	s_cselect_b32 s40, s65, s66
	v_lshl_add_u64 v[202:203], s[8:9], 0, v[136:137]
	s_add_i32 m0, s39, 0xc000
	ds_read_b128 v[168:171], v150
	ds_read_b128 v[172:175], v150 offset:1024
	ds_read_b128 v[176:179], v150 offset:2048
	ds_read_b128 v[180:183], v150 offset:3072
	ds_read_b128 v[188:191], v150 offset:4096
	ds_read_b128 v[206:209], v150 offset:5120
	ds_read_b128 v[210:213], v150 offset:6144
	ds_read_b128 v[214:217], v150 offset:7168
	global_load_lds_dwordx4 v[202:203], off
	v_lshl_add_u64 v[202:203], s[8:9], 0, v[138:139]
	s_add_i32 m0, s39, 0xe000
	s_nop 0
	global_load_lds_dwordx4 v[202:203], off
	s_waitcnt lgkmcnt(8)
	s_barrier
	s_waitcnt lgkmcnt(0)
	s_setprio 1
	s_waitcnt lgkmcnt(0)
	v_mfma_f32_16x16x32_bf16 v[116:119], v[144:147], v[168:171], v[116:119]
	v_mfma_f32_16x16x32_bf16 v[112:115], v[160:163], v[168:171], v[112:115]
	v_mfma_f32_16x16x32_bf16 v[100:103], v[144:147], v[176:179], v[100:103]
	v_mfma_f32_16x16x32_bf16 v[96:99], v[160:163], v[176:179], v[96:99]
	v_mfma_f32_16x16x32_bf16 v[84:87], v[144:147], v[188:191], v[84:87]
	v_mfma_f32_16x16x32_bf16 v[80:83], v[160:163], v[188:191], v[80:83]
	v_mfma_f32_16x16x32_bf16 v[68:71], v[144:147], v[210:213], v[68:71]
	v_mfma_f32_16x16x32_bf16 v[64:67], v[160:163], v[210:213], v[64:67]
	v_mfma_f32_16x16x32_bf16 v[116:119], v[156:159], v[172:175], v[116:119]
	v_mfma_f32_16x16x32_bf16 v[112:115], v[164:167], v[172:175], v[112:115]
	v_mfma_f32_16x16x32_bf16 v[100:103], v[156:159], v[180:183], v[100:103]
	v_mfma_f32_16x16x32_bf16 v[96:99], v[164:167], v[180:183], v[96:99]
	v_mfma_f32_16x16x32_bf16 v[84:87], v[156:159], v[206:209], v[84:87]
	v_mfma_f32_16x16x32_bf16 v[80:83], v[164:167], v[206:209], v[80:83]
	v_mfma_f32_16x16x32_bf16 v[68:71], v[156:159], v[214:217], v[68:71]
	v_mfma_f32_16x16x32_bf16 v[64:67], v[164:167], v[214:217], v[64:67]
	s_setprio 0
	s_barrier
	s_add_i32 s0, s61, s50
	v_lshl_add_u64 v[202:203], s[40:41], 0, v[130:131]
	s_mov_b32 m0, s0
	ds_read_b128 v[218:221], v151
	ds_read_b128 v[222:225], v151 offset:1024
	ds_read_b128 v[226:229], v151 offset:2048
	ds_read_b128 v[230:233], v151 offset:3072
	global_load_lds_dwordx4 v[202:203], off
	v_lshl_add_u64 v[234:235], s[40:41], 0, v[134:135]
	s_add_i32 m0, s0, 0x2000
	s_nop 0
	global_load_lds_dwordx4 v[234:235], off
	s_barrier
	s_waitcnt lgkmcnt(0)
	s_setprio 1
	s_waitcnt lgkmcnt(0)
	v_mfma_f32_16x16x32_bf16 v[124:127], v[218:221], v[168:171], v[124:127]
	v_mfma_f32_16x16x32_bf16 v[120:123], v[226:229], v[168:171], v[120:123]
	v_mfma_f32_16x16x32_bf16 v[108:111], v[218:221], v[176:179], v[108:111]
	v_mfma_f32_16x16x32_bf16 v[104:107], v[226:229], v[176:179], v[104:107]
	v_mfma_f32_16x16x32_bf16 v[92:95], v[218:221], v[188:191], v[92:95]
	v_mfma_f32_16x16x32_bf16 v[88:91], v[226:229], v[188:191], v[88:91]
	v_mfma_f32_16x16x32_bf16 v[76:79], v[218:221], v[210:213], v[76:79]
	v_mfma_f32_16x16x32_bf16 v[72:75], v[226:229], v[210:213], v[72:75]
	v_mfma_f32_16x16x32_bf16 v[124:127], v[222:225], v[172:175], v[124:127]
	v_mfma_f32_16x16x32_bf16 v[120:123], v[230:233], v[172:175], v[120:123]
	v_mfma_f32_16x16x32_bf16 v[108:111], v[222:225], v[180:183], v[108:111]
	v_mfma_f32_16x16x32_bf16 v[104:107], v[230:233], v[180:183], v[104:107]
	v_mfma_f32_16x16x32_bf16 v[92:95], v[222:225], v[206:209], v[92:95]
	v_mfma_f32_16x16x32_bf16 v[88:91], v[230:233], v[206:209], v[88:91]
	v_mfma_f32_16x16x32_bf16 v[76:79], v[222:225], v[214:217], v[76:79]
	v_mfma_f32_16x16x32_bf16 v[72:75], v[230:233], v[214:217], v[72:75]
	s_setprio 0
	s_mov_b32 m0, s39
	v_lshl_add_u64 v[236:237], s[42:43], 0, v[128:129]
	s_barrier
	ds_read_b128 v[168:171], v150 offset:16384
	ds_read_b128 v[172:175], v150 offset:17408
	ds_read_b128 v[176:179], v150 offset:18432
	ds_read_b128 v[180:183], v150 offset:19456
	ds_read_b128 v[188:191], v150 offset:20480
	ds_read_b128 v[206:209], v150 offset:21504
	ds_read_b128 v[210:213], v150 offset:22528
	ds_read_b128 v[214:217], v150 offset:23552
	global_load_lds_dwordx4 v[236:237], off
	v_lshl_add_u64 v[238:239], s[42:43], 0, v[132:133]
	s_mov_b32 m0, s51
	s_nop 0
	global_load_lds_dwordx4 v[238:239], off
	s_barrier
	s_waitcnt lgkmcnt(0)
	s_setprio 1
	s_waitcnt lgkmcnt(0)
	v_mfma_f32_16x16x32_bf16 v[52:55], v[144:147], v[168:171], v[52:55]
	v_mfma_f32_16x16x32_bf16 v[48:51], v[160:163], v[168:171], v[48:51]
	v_mfma_f32_16x16x32_bf16 v[36:39], v[144:147], v[176:179], v[36:39]
	v_mfma_f32_16x16x32_bf16 v[32:35], v[160:163], v[176:179], v[32:35]
	v_mfma_f32_16x16x32_bf16 v[20:23], v[144:147], v[188:191], v[20:23]
	v_mfma_f32_16x16x32_bf16 v[16:19], v[160:163], v[188:191], v[16:19]
	v_mfma_f32_16x16x32_bf16 v[4:7], v[144:147], v[210:213], v[4:7]
	v_mfma_f32_16x16x32_bf16 v[0:3], v[160:163], v[210:213], v[0:3]
	v_mfma_f32_16x16x32_bf16 v[52:55], v[156:159], v[172:175], v[52:55]
	v_mfma_f32_16x16x32_bf16 v[48:51], v[164:167], v[172:175], v[48:51]
	v_mfma_f32_16x16x32_bf16 v[36:39], v[156:159], v[180:183], v[36:39]
	v_mfma_f32_16x16x32_bf16 v[32:35], v[164:167], v[180:183], v[32:35]
	v_mfma_f32_16x16x32_bf16 v[20:23], v[156:159], v[206:209], v[20:23]
	v_mfma_f32_16x16x32_bf16 v[16:19], v[164:167], v[206:209], v[16:19]
	v_mfma_f32_16x16x32_bf16 v[4:7], v[156:159], v[214:217], v[4:7]
	v_mfma_f32_16x16x32_bf16 v[0:3], v[164:167], v[214:217], v[0:3]
	s_setprio 0
	s_barrier
; #define PG8_STAGE(bufoff, gbase, voff) do { _Pragma("unroll") for (int _i = 0; _i < 2; ++_i) \
;         __builtin_amdgcn_global_load_lds((const unsigned*)((const char*)(gbase) + (voff)[_i]), (LAS unsigned*)(lds + (bufoff) + ldsw + _i * 8192), 16, 0, 0); } while (0)
; #define PG8_LDA(dst, b, h) do { _Pragma("unroll") for (int m = 0; m < 4; ++m) _Pragma("unroll") for (int k = 0; k < 2; ++k) dst[m][k] = *(const LAS bf16x8*)(lds + PG8_SA(b, h) + aoff + m * 2048 + k * 1024); } while (0)
; #define PG8_LDB(dst, b, h) do { _Pragma("unroll") for (int n = 0; n < 2; ++n) _Pragma("unroll") for (int k = 0; k < 2; ++k) dst[n][k] = *(const LAS bf16x8*)(lds + PG8_SB(b, h) + boff + n * 2048 + k * 1024); } while (0)
; #define PG8_WAIT_V(n) asm volatile("s_waitcnt vmcnt(" #n ")" ::: "memory")
; #define PG8_WAIT_L(n) asm volatile("s_waitcnt lgkmcnt(" #n ")" ::: "memory")
; #define PG8_BAR __builtin_amdgcn_s_barrier()
; #define PG8_SCHED __builtin_amdgcn_sched_barrier(0)
; template <class Epi, class Sched>
; DI void gemm_phase(LAS unsigned char* lds, const Gemm g, const Sched& S, const Epi& E) {
;     ...
;             PG8_LDB(B0, 0, 0); PG8_SCHED; PG8_LDA(At, 0, 0); PG8_STAGE(PG8_SA(1, 1), a1 + hstep, voffA);
;             PG8_WAIT_L(8); PG8_BAR; PG8_WAIT_L(0); PG8_MMA(0, 0, At, B0); PG8_BAR; PG8_SCHED;
;             PG8_LDB(B1, 0, 1); PG8_STAGE(PG8_SB(0, 0), b2, voffB);
;             PG8_BAR; PG8_WAIT_L(0); PG8_MMA(0, 1, At, B1); PG8_BAR;
;             PG8_LDA(At, 0, 1); PG8_STAGE(PG8_SA(0, 0), a2, voffA);
;             PG8_BAR; PG8_WAIT_L(0); PG8_MMA(1, 0, At, B0); PG8_BAR; PG8_SCHED;
;             PG8_STAGE(PG8_SB(0, 1), b2 + hstep, voffB);
;             PG8_WAIT_V(6); PG8_BAR; PG8_MMA(1, 1, At, B1); PG8_BAR;
;             PG8_LDB(B0, 1, 0); PG8_SCHED; PG8_LDA(At, 1, 0); PG8_STAGE(PG8_SA(0, 1), a2 + hstep, voffA);
;             PG8_WAIT_L(8); PG8_BAR; PG8_WAIT_L(0); PG8_MMA(0, 0, At, B0); PG8_BAR; PG8_SCHED;
;             PG8_LDB(B1, 1, 1); PG8_STAGE(PG8_SB(1, 0), b3, voffB);
;             PG8_BAR; PG8_WAIT_L(0); PG8_MMA(0, 1, At, B1); PG8_BAR;
;             PG8_LDA(At, 1, 1); PG8_STAGE(PG8_SA(1, 0), a3, voffA);
;             PG8_BAR; PG8_WAIT_L(0); PG8_MMA(1, 0, At, B0); PG8_BAR; PG8_SCHED;
;             PG8_STAGE(PG8_SB(1, 1), b3 + hstep, voffB);
;             PG8_WAIT_V(6); PG8_BAR; PG8_MMA(1, 1, At, B1); PG8_BAR;
	s_add_u32 s0, s40, 0x80000
	s_addc_u32 s1, s41, 0
	s_add_i32 s4, s62, s50
	v_lshl_add_u64 v[144:145], s[0:1], 0, v[130:131]
	s_mov_b32 m0, s4
	s_nop 0
	global_load_lds_dwordx4 v[144:145], off
	v_lshl_add_u64 v[144:145], s[0:1], 0, v[134:135]
	s_add_i32 m0, s4, 0x2000
	s_nop 0
	global_load_lds_dwordx4 v[144:145], off
	s_waitcnt vmcnt(6)
	s_barrier
	s_setprio 1
	v_mfma_f32_16x16x32_bf16 v[60:63], v[218:221], v[168:171], v[60:63]
	v_mfma_f32_16x16x32_bf16 v[56:59], v[226:229], v[168:171], v[56:59]
	v_mfma_f32_16x16x32_bf16 v[44:47], v[218:221], v[176:179], v[44:47]
	v_mfma_f32_16x16x32_bf16 v[40:43], v[226:229], v[176:179], v[40:43]
	v_mfma_f32_16x16x32_bf16 v[28:31], v[218:221], v[188:191], v[28:31]
	v_mfma_f32_16x16x32_bf16 v[24:27], v[226:229], v[188:191], v[24:27]
	v_mfma_f32_16x16x32_bf16 v[12:15], v[218:221], v[210:213], v[12:15]
	v_mfma_f32_16x16x32_bf16 v[8:11], v[226:229], v[210:213], v[8:11]
	v_mfma_f32_16x16x32_bf16 v[60:63], v[222:225], v[172:175], v[60:63]
	v_mfma_f32_16x16x32_bf16 v[56:59], v[230:233], v[172:175], v[56:59]
	v_mfma_f32_16x16x32_bf16 v[44:47], v[222:225], v[180:183], v[44:47]
	v_mfma_f32_16x16x32_bf16 v[40:43], v[230:233], v[180:183], v[40:43]
	v_mfma_f32_16x16x32_bf16 v[28:31], v[222:225], v[206:209], v[28:31]
	v_mfma_f32_16x16x32_bf16 v[24:27], v[230:233], v[206:209], v[24:27]
	v_mfma_f32_16x16x32_bf16 v[12:15], v[222:225], v[214:217], v[12:15]
	v_mfma_f32_16x16x32_bf16 v[8:11], v[230:233], v[214:217], v[8:11]
	s_setprio 0
	s_add_i32 s4, 0, 0x18000
	v_add_u32_e32 v155, s4, v148
	s_barrier
	ds_read_b128 v[144:147], v155
	ds_read_b128 v[156:159], v155 offset:1024
	ds_read_b128 v[160:163], v155 offset:2048
	ds_read_b128 v[164:167], v155 offset:3072
	s_add_u32 s0, s42, 0x80000
	s_addc_u32 s1, s43, 0
	s_mov_b32 m0, s52
	v_lshl_add_u64 v[218:219], s[0:1], 0, v[128:129]
	ds_read_b128 v[168:171], v150 offset:32768
	ds_read_b128 v[172:175], v150 offset:33792
	ds_read_b128 v[176:179], v150 offset:34816
	ds_read_b128 v[180:183], v150 offset:35840
	ds_read_b128 v[188:191], v150 offset:36864
	ds_read_b128 v[206:209], v150 offset:37888
	ds_read_b128 v[210:213], v150 offset:38912
	ds_read_b128 v[214:217], v150 offset:39936
	global_load_lds_dwordx4 v[218:219], off
	v_lshl_add_u64 v[218:219], s[0:1], 0, v[132:133]
	s_mov_b32 m0, s53
	s_nop 0
	global_load_lds_dwordx4 v[218:219], off
	s_waitcnt lgkmcnt(8)
	s_barrier
	s_waitcnt lgkmcnt(0)
	s_setprio 1
	s_waitcnt lgkmcnt(0)
	v_mfma_f32_16x16x32_bf16 v[116:119], v[144:147], v[168:171], v[116:119]
	v_mfma_f32_16x16x32_bf16 v[112:115], v[160:163], v[168:171], v[112:115]
	v_mfma_f32_16x16x32_bf16 v[100:103], v[144:147], v[176:179], v[100:103]
	v_mfma_f32_16x16x32_bf16 v[96:99], v[160:163], v[176:179], v[96:99]
	v_mfma_f32_16x16x32_bf16 v[84:87], v[144:147], v[188:191], v[84:87]
	v_mfma_f32_16x16x32_bf16 v[80:83], v[160:163], v[188:191], v[80:83]
	v_mfma_f32_16x16x32_bf16 v[68:71], v[144:147], v[210:213], v[68:71]
	v_mfma_f32_16x16x32_bf16 v[64:67], v[160:163], v[210:213], v[64:67]
	v_mfma_f32_16x16x32_bf16 v[116:119], v[156:159], v[172:175], v[116:119]
	v_mfma_f32_16x16x32_bf16 v[112:115], v[164:167], v[172:175], v[112:115]
	v_mfma_f32_16x16x32_bf16 v[100:103], v[156:159], v[180:183], v[100:103]
	v_mfma_f32_16x16x32_bf16 v[96:99], v[164:167], v[180:183], v[96:99]
	v_mfma_f32_16x16x32_bf16 v[84:87], v[156:159], v[206:209], v[84:87]
	v_mfma_f32_16x16x32_bf16 v[80:83], v[164:167], v[206:209], v[80:83]
	v_mfma_f32_16x16x32_bf16 v[68:71], v[156:159], v[214:217], v[68:71]
	v_mfma_f32_16x16x32_bf16 v[64:67], v[164:167], v[214:217], v[64:67]
	s_setprio 0
	s_barrier
	s_add_i32 s5, 0, 0x1c000
	s_add_i32 s0, s4, s50
	v_add_u32_e32 v155, s5, v148
	v_lshl_add_u64 v[202:203], v[202:203], 0, s[16:17]
	s_mov_b32 m0, s0
	ds_read_b128 v[218:221], v155
	ds_read_b128 v[222:225], v155 offset:1024
	ds_read_b128 v[226:229], v155 offset:2048
	ds_read_b128 v[230:233], v155 offset:3072
	global_load_lds_dwordx4 v[202:203], off
	v_lshl_add_u64 v[202:203], v[234:235], 0, s[16:17]
	s_add_i32 m0, s0, 0x2000
	s_nop 0
	global_load_lds_dwordx4 v[202:203], off
	s_barrier
	s_waitcnt lgkmcnt(0)
	s_setprio 1
	s_waitcnt lgkmcnt(0)
	v_mfma_f32_16x16x32_bf16 v[124:127], v[218:221], v[168:171], v[124:127]
	v_mfma_f32_16x16x32_bf16 v[120:123], v[226:229], v[168:171], v[120:123]
	v_mfma_f32_16x16x32_bf16 v[108:111], v[218:221], v[176:179], v[108:111]
	v_mfma_f32_16x16x32_bf16 v[104:107], v[226:229], v[176:179], v[104:107]
	v_mfma_f32_16x16x32_bf16 v[92:95], v[218:221], v[188:191], v[92:95]
	v_mfma_f32_16x16x32_bf16 v[88:91], v[226:229], v[188:191], v[88:91]
	v_mfma_f32_16x16x32_bf16 v[76:79], v[218:221], v[210:213], v[76:79]
	v_mfma_f32_16x16x32_bf16 v[72:75], v[226:229], v[210:213], v[72:75]
	v_mfma_f32_16x16x32_bf16 v[124:127], v[222:225], v[172:175], v[124:127]
	v_mfma_f32_16x16x32_bf16 v[120:123], v[230:233], v[172:175], v[120:123]
	v_mfma_f32_16x16x32_bf16 v[108:111], v[222:225], v[180:183], v[108:111]
	v_mfma_f32_16x16x32_bf16 v[104:107], v[230:233], v[180:183], v[104:107]
	v_mfma_f32_16x16x32_bf16 v[92:95], v[222:225], v[206:209], v[92:95]
	v_mfma_f32_16x16x32_bf16 v[88:91], v[230:233], v[206:209], v[88:91]
	v_mfma_f32_16x16x32_bf16 v[76:79], v[222:225], v[214:217], v[76:79]
	v_mfma_f32_16x16x32_bf16 v[72:75], v[230:233], v[214:217], v[72:75]
	s_setprio 0
	s_mov_b32 m0, s57
	v_lshl_add_u64 v[202:203], v[236:237], 0, s[16:17]
	s_barrier
	ds_read_b128 v[168:171], v150 offset:49152
	ds_read_b128 v[172:175], v150 offset:50176
	ds_read_b128 v[176:179], v150 offset:51200
	ds_read_b128 v[180:183], v150 offset:52224
	ds_read_b128 v[188:191], v150 offset:53248
	ds_read_b128 v[206:209], v150 offset:54272
	ds_read_b128 v[210:213], v150 offset:55296
	ds_read_b128 v[214:217], v150 offset:56320
	global_load_lds_dwordx4 v[202:203], off
	v_lshl_add_u64 v[202:203], v[238:239], 0, s[16:17]
	s_mov_b32 m0, s58
	s_nop 0
	global_load_lds_dwordx4 v[202:203], off
	s_barrier
; DI float sigmoidf_(float x) { return __builtin_amdgcn_rcpf(1.0f + __builtin_amdgcn_exp2f(-x * LOG2E)); }
; DI float rs_of(const float* ss, int row) { return 1.0f / sqrtf(ss[row] * (1.0f / DM) + EPS); }
; DI u32x4 pack8(f32x4 a, f32x4 b) { u32x4 w; w.x = cvt_pk_bf16(a[0], a[1]); w.y = cvt_pk_bf16(a[2], a[3]); w.z = cvt_pk_bf16(b[0], b[1]); w.w = cvt_pk_bf16(b[2], b[3]); return w; }
; #define PG8_MMA(ai, bj, At, Bt) do { __builtin_amdgcn_s_setprio(1); _Pragma("unroll") for (int m = 0; m < 4; ++m) _Pragma("unroll") for (int n = 0; n < 2; ++n) _Pragma("unroll") for (int k = 0; k < 2; ++k) \
;         acc[ai][bj][m][n] = __builtin_amdgcn_mfma_f32_16x16x32_bf16(Bt[n][k], At[m][k], acc[ai][bj][m][n], 0, 0, 0); __builtin_amdgcn_s_setprio(0); } while (0)
; #define PG8_WAIT_V(n) asm volatile("s_waitcnt vmcnt(" #n ")" ::: "memory")
; #define PG8_BAR __builtin_amdgcn_s_barrier()
; template <class Epi, class Sched>
; DI void gemm_phase(LAS unsigned char* lds, const Gemm g, const Sched& S, const Epi& E) {
;     ...
;             PG8_WAIT_V(6); PG8_BAR; PG8_MMA(1, 1, At, B1); PG8_BAR;
;         }
;     DI void operator()(AccRef acc, const Unit& u, int wr, int wc, int fr, int fq) const {
;     ...
;                 f32x4 o[2]; const float r = ss ? rs_of(ss, row0 + ai * 128 + m * 16) : 1.0f;
; #pragma unroll
;                 for (int n = 0; n < 2; ++n)
; #pragma unroll
;                     for (int j = 0; j < 4; ++j) { const float gt = acc[ai][0][m][n][j] * r, up = acc[ai][1][m][n][j] * r; o[n][j] = gt * sigmoidf_(gt) * up; }
;                 *(u32x4*)(Hd + (size_t)(row0 + ai * 128 + m * 16) * DFF + col0) = pack8(o[0], o[1]);
	s_waitcnt lgkmcnt(0)
	s_setprio 1
	s_waitcnt lgkmcnt(0)
	v_mfma_f32_16x16x32_bf16 v[52:55], v[144:147], v[168:171], v[52:55]
	v_mfma_f32_16x16x32_bf16 v[48:51], v[160:163], v[168:171], v[48:51]
	v_mfma_f32_16x16x32_bf16 v[36:39], v[144:147], v[176:179], v[36:39]
	v_mfma_f32_16x16x32_bf16 v[32:35], v[160:163], v[176:179], v[32:35]
	v_mfma_f32_16x16x32_bf16 v[20:23], v[144:147], v[188:191], v[20:23]
	v_mfma_f32_16x16x32_bf16 v[16:19], v[160:163], v[188:191], v[16:19]
	v_mfma_f32_16x16x32_bf16 v[4:7], v[144:147], v[210:213], v[4:7]
	v_mfma_f32_16x16x32_bf16 v[0:3], v[160:163], v[210:213], v[0:3]
	v_mfma_f32_16x16x32_bf16 v[52:55], v[156:159], v[172:175], v[52:55]
	v_mfma_f32_16x16x32_bf16 v[48:51], v[164:167], v[172:175], v[48:51]
	v_mfma_f32_16x16x32_bf16 v[36:39], v[156:159], v[180:183], v[36:39]
	v_mfma_f32_16x16x32_bf16 v[32:35], v[164:167], v[180:183], v[32:35]
	v_mfma_f32_16x16x32_bf16 v[20:23], v[156:159], v[206:209], v[20:23]
	v_mfma_f32_16x16x32_bf16 v[16:19], v[164:167], v[206:209], v[16:19]
	v_mfma_f32_16x16x32_bf16 v[4:7], v[156:159], v[214:217], v[4:7]
	v_mfma_f32_16x16x32_bf16 v[0:3], v[164:167], v[214:217], v[0:3]
	s_setprio 0
	s_barrier
	s_add_u32 s0, s40, 0x80080
	s_addc_u32 s1, s41, 0
	s_add_i32 s4, s5, s50
	v_lshl_add_u64 v[144:145], s[0:1], 0, v[130:131]
	s_mov_b32 m0, s4
	s_nop 0
	global_load_lds_dwordx4 v[144:145], off
	v_lshl_add_u64 v[144:145], s[0:1], 0, v[134:135]
	s_add_i32 m0, s4, 0x2000
	s_nop 0
	global_load_lds_dwordx4 v[144:145], off
	s_waitcnt vmcnt(6)
	s_barrier
	s_setprio 1
	v_mfma_f32_16x16x32_bf16 v[60:63], v[218:221], v[168:171], v[60:63]
	v_mfma_f32_16x16x32_bf16 v[56:59], v[226:229], v[168:171], v[56:59]
	v_mfma_f32_16x16x32_bf16 v[44:47], v[218:221], v[176:179], v[44:47]
	v_mfma_f32_16x16x32_bf16 v[40:43], v[226:229], v[176:179], v[40:43]
	v_mfma_f32_16x16x32_bf16 v[28:31], v[218:221], v[188:191], v[28:31]
	v_mfma_f32_16x16x32_bf16 v[24:27], v[226:229], v[188:191], v[24:27]
	v_mfma_f32_16x16x32_bf16 v[12:15], v[218:221], v[210:213], v[12:15]
	v_mfma_f32_16x16x32_bf16 v[8:11], v[226:229], v[210:213], v[8:11]
	v_mfma_f32_16x16x32_bf16 v[60:63], v[222:225], v[172:175], v[60:63]
	v_mfma_f32_16x16x32_bf16 v[56:59], v[230:233], v[172:175], v[56:59]
	v_mfma_f32_16x16x32_bf16 v[44:47], v[222:225], v[180:183], v[44:47]
	v_mfma_f32_16x16x32_bf16 v[40:43], v[230:233], v[180:183], v[40:43]
	v_mfma_f32_16x16x32_bf16 v[28:31], v[222:225], v[206:209], v[28:31]
	v_mfma_f32_16x16x32_bf16 v[24:27], v[230:233], v[206:209], v[24:27]
	v_mfma_f32_16x16x32_bf16 v[12:15], v[222:225], v[214:217], v[12:15]
	v_mfma_f32_16x16x32_bf16 v[8:11], v[230:233], v[214:217], v[8:11]
	s_setprio 0
	s_add_i32 s68, s68, 2
	s_add_u32 s8, s8, 0x100
	s_addc_u32 s9, s9, 0
	s_add_u32 s66, s66, 0x100
	s_addc_u32 s67, s67, 0
	s_cmp_gt_u32 s68, 29
	s_barrier
	s_cbranch_scc0 .LBB0_1668
	v_mov_b32_e32 v144, v194
	v_mov_b32_e32 v155, v192
	s_lshl_b32 s0, s38, 8
	s_add_i32 s0, s0, s55
	v_add_u32_e32 v144, s0, v144
	v_ashrrev_i32_e32 v145, 31, v144
	v_lshl_add_u64 v[146:147], v[144:145], 2, s[14:15]
	v_mov_b64_e32 v[202:203], v[146:147]
	s_mov_b32 s69, 0
	global_load_dword v201, v[202:203], off
	global_load_dword v205, v[202:203], off offset:64
	global_load_dword v242, v[202:203], off offset:128
	global_load_dword v243, v[202:203], off offset:192
	global_load_dword v238, v[202:203], off offset:512
	global_load_dword v239, v[202:203], off offset:576
	global_load_dword v240, v[202:203], off offset:640
	global_load_dword v241, v[202:203], off offset:704
	s_waitcnt vmcnt(7)
	v_mov_b32_e32 v145, v201
	s_lshl_b32 s0, s34, 7
	s_or_b32 s0, s0, s56
	v_mov_b32_e32 v156, v124
	v_mov_b32_e32 v124, v126
	v_mov_b32_e32 v126, v120
	v_lshl_add_u32 v120, v155, 3, s0
	v_mov_b32_e32 v159, v114
	v_mov_b32_e32 v114, v123
	v_mov_b32_e32 v157, v116
	v_mov_b32_e32 v116, v125
	v_mov_b32_e32 v125, v118
	v_mov_b32_e32 v118, v127
	v_mov_b32_e32 v127, v112
	v_mov_b32_e32 v112, v121
	v_mov_b32_e32 v158, v122
	v_mov_b64_e32 v[122:123], s[12:13]
	v_ashrrev_i32_e32 v121, 31, v120
	v_mad_i64_i32 v[160:161], s[0:1], v144, s64, v[122:123]
	v_lshlrev_b64 v[120:121], 1, v[120:121]
	v_lshl_add_u64 v[160:161], v[160:161], 0, v[120:121]
	s_and_b64 s[6:7], exec, s[6:7]
	s_mov_b32 s34, s18
	s_mov_b32 s38, s28
	s_mov_b64 s[40:41], s[36:37]
	s_mov_b64 s[42:43], s[30:31]
	v_fmamk_f32 v145, v145, 0x3a000000, v153
	v_mul_f32_e32 v155, 0x4f800000, v145
	v_cmp_gt_f32_e32 vcc, s63, v145
	s_nop 1
	v_cndmask_b32_e32 v145, v145, v155, vcc
	v_sqrt_f32_e32 v155, v145
	s_nop 0
	v_add_u32_e32 v162, -1, v155
	v_add_u32_e32 v163, 1, v155
	v_fma_f32 v164, -v162, v155, v145
	v_fma_f32 v165, -v163, v155, v145
	v_cmp_ge_f32_e64 s[8:9], 0, v164
	s_nop 1
	v_cndmask_b32_e64 v155, v155, v162, s[8:9]
	v_cmp_lt_f32_e64 s[8:9], 0, v165
	s_nop 1
	v_cndmask_b32_e64 v155, v155, v163, s[8:9]
	v_mul_f32_e32 v162, 0x37800000, v155
	v_cndmask_b32_e32 v155, v155, v162, vcc
	v_cmp_class_f32_e32 vcc, v145, v154
	s_nop 1
	v_cndmask_b32_e32 v145, v155, v145, vcc
	v_div_scale_f32 v155, s[0:1], v145, v145, 1.0
	v_rcp_f32_e32 v162, v155
	v_div_scale_f32 v163, vcc, 1.0, v145, 1.0
	v_fma_f32 v164, -v155, v162, 1.0
	v_fmac_f32_e32 v162, v164, v162
	v_mul_f32_e32 v164, v163, v162
	v_fma_f32 v165, -v155, v164, v163
	v_fmac_f32_e32 v164, v165, v162
	v_fma_f32 v155, -v155, v164, v163
	v_div_fmas_f32 v155, v155, v162, v164
	v_div_fixup_f32 v162, v155, v145, 1.0
	v_pk_mul_f32 v[114:115], v[114:115], v[162:163] op_sel_hi:[1,0]
	v_pk_mul_f32 v[156:157], v[156:157], v[162:163] op_sel_hi:[1,0]
	v_pk_mul_f32 v[116:117], v[116:117], v[162:163] op_sel_hi:[1,0]
	v_pk_mul_f32 v[124:125], v[124:125], v[162:163] op_sel_hi:[1,0]
; DI float sigmoidf_(float x) { return __builtin_amdgcn_rcpf(1.0f + __builtin_amdgcn_exp2f(-x * LOG2E)); }
; DI float rs_of(const float* ss, int row) { return 1.0f / sqrtf(ss[row] * (1.0f / DM) + EPS); }
; DI u32x4 pack8(f32x4 a, f32x4 b) { u32x4 w; w.x = cvt_pk_bf16(a[0], a[1]); w.y = cvt_pk_bf16(a[2], a[3]); w.z = cvt_pk_bf16(b[0], b[1]); w.w = cvt_pk_bf16(b[2], b[3]); return w; }
;     DI void operator()(AccRef acc, const Unit& u, int wr, int wc, int fr, int fq) const {
;     ...
;                 f32x4 o[2]; const float r = ss ? rs_of(ss, row0 + ai * 128 + m * 16) : 1.0f;
; #pragma unroll
;                 for (int n = 0; n < 2; ++n)
; #pragma unroll
;                     for (int j = 0; j < 4; ++j) { const float gt = acc[ai][0][m][n][j] * r, up = acc[ai][1][m][n][j] * r; o[n][j] = gt * sigmoidf_(gt) * up; }
;                 *(u32x4*)(Hd + (size_t)(row0 + ai * 128 + m * 16) * DFF + col0) = pack8(o[0], o[1]);
	v_pk_mul_f32 v[118:119], v[118:119], v[162:163] op_sel_hi:[1,0]
	v_pk_mul_f32 v[126:127], v[126:127], v[162:163] op_sel_hi:[1,0]
	v_pk_mul_f32 v[112:113], v[112:113], v[162:163] op_sel_hi:[1,0]
	v_pk_mul_f32 v[158:159], v[158:159], v[162:163] op_sel_hi:[1,0]
	v_mul_f32_e32 v167, 0xbfb8aa3b, v115
	v_mul_f32_e32 v145, 0xbfb8aa3b, v157
	v_mul_f32_e32 v155, 0xbfb8aa3b, v117
	v_mul_f32_e32 v162, 0xbfb8aa3b, v125
	v_mul_f32_e32 v163, 0xbfb8aa3b, v119
	v_mul_f32_e32 v164, 0xbfb8aa3b, v127
	v_mul_f32_e32 v165, 0xbfb8aa3b, v113
	v_mul_f32_e32 v166, 0xbfb8aa3b, v159
	v_exp_f32_e32 v167, v167
	v_exp_f32_e32 v145, v145
	v_exp_f32_e32 v155, v155
	v_exp_f32_e32 v162, v162
	v_exp_f32_e32 v163, v163
	v_exp_f32_e32 v164, v164
	v_exp_f32_e32 v165, v165
	v_exp_f32_e32 v166, v166
	v_add_f32_e32 v167, 1.0, v167
	v_add_f32_e32 v145, 1.0, v145
	v_add_f32_e32 v155, 1.0, v155
	v_add_f32_e32 v162, 1.0, v162
	v_add_f32_e32 v163, 1.0, v163
	v_add_f32_e32 v164, 1.0, v164
	v_add_f32_e32 v165, 1.0, v165
	v_add_f32_e32 v166, 1.0, v166
	v_rcp_f32_e32 v167, v167
	v_rcp_f32_e32 v145, v145
	v_rcp_f32_e32 v155, v155
	v_rcp_f32_e32 v162, v162
	v_rcp_f32_e32 v163, v163
	v_rcp_f32_e32 v164, v164
	v_rcp_f32_e32 v165, v165
	v_rcp_f32_e32 v166, v166
	v_mul_f32_e32 v115, v115, v167
	v_mul_f32_e32 v145, v157, v145
	v_mul_f32_e32 v117, v117, v155
	v_mul_f32_e32 v125, v125, v162
	v_mul_f32_e32 v119, v119, v163
	v_mul_f32_e32 v127, v127, v164
	v_mul_f32_e32 v113, v113, v165
	v_mul_f32_e32 v155, v159, v166
	v_mul_f32_e32 v115, v114, v115
	v_mul_f32_e32 v145, v156, v145
	v_mul_f32_e32 v116, v116, v117
	v_mul_f32_e32 v117, v124, v125
	v_mul_f32_e32 v118, v118, v119
	v_mul_f32_e32 v119, v126, v127
	v_mul_f32_e32 v124, v112, v113
	v_mul_f32_e32 v125, v158, v155
	v_cvt_pk_bf16_f32 v112, v145, v116
	v_cvt_pk_bf16_f32 v113, v117, v118
	v_cvt_pk_bf16_f32 v114, v119, v124
	v_cvt_pk_bf16_f32 v115, v125, v115
	global_store_dwordx4 v[160:161], v[112:115], off
	s_waitcnt vmcnt(7)
	s_nop 1
	v_mov_b32_e32 v114, v205
	s_nop 0
	v_mov_b32_e32 v112, v108
	v_mov_b32_e32 v108, v110
	v_mov_b32_e32 v110, v104
	v_mov_b32_e32 v104, v106
	v_mov_b32_e32 v113, v100
	v_mov_b32_e32 v100, v109
	v_mov_b32_e32 v109, v102
	v_mov_b32_e32 v102, v111
	v_mov_b32_e32 v111, v96
	v_mov_b32_e32 v96, v105
	v_mov_b32_e32 v105, v98
	v_mov_b32_e32 v98, v107
	v_fmamk_f32 v106, v114, 0x3a000000, v153
	v_mul_f32_e32 v107, 0x4f800000, v106
	v_cmp_gt_f32_e32 vcc, s63, v106
	s_nop 1
	v_cndmask_b32_e32 v114, v106, v107, vcc
	v_sqrt_f32_e32 v115, v114
	v_add_u32_e32 v106, 16, v144
	v_mad_i64_i32 v[106:107], s[0:1], v106, s64, v[122:123]
	v_add_u32_e32 v116, -1, v115
	v_add_u32_e32 v117, 1, v115
	v_fma_f32 v118, -v116, v115, v114
	v_fma_f32 v119, -v117, v115, v114
	v_cmp_ge_f32_e64 s[8:9], 0, v118
	v_lshl_add_u64 v[106:107], v[106:107], 0, v[120:121]
	s_nop 0
	v_cndmask_b32_e64 v115, v115, v116, s[8:9]
	v_cmp_lt_f32_e64 s[8:9], 0, v119
	s_nop 1
	v_cndmask_b32_e64 v115, v115, v117, s[8:9]
	v_mul_f32_e32 v116, 0x37800000, v115
	v_cndmask_b32_e32 v115, v115, v116, vcc
	v_cmp_class_f32_e32 vcc, v114, v154
	s_nop 1
	v_cndmask_b32_e32 v114, v115, v114, vcc
	v_div_scale_f32 v115, s[0:1], v114, v114, 1.0
	v_rcp_f32_e32 v116, v115
	v_div_scale_f32 v117, vcc, 1.0, v114, 1.0
	v_fma_f32 v118, -v115, v116, 1.0
	v_fmac_f32_e32 v116, v118, v116
	v_mul_f32_e32 v118, v117, v116
	v_fma_f32 v119, -v115, v118, v117
	v_fmac_f32_e32 v118, v119, v116
	v_fma_f32 v115, -v115, v118, v117
	v_div_fmas_f32 v115, v115, v116, v118
	v_div_fixup_f32 v114, v115, v114, 1.0
	v_pk_mul_f32 v[98:99], v[98:99], v[114:115] op_sel_hi:[1,0]
	v_pk_mul_f32 v[112:113], v[112:113], v[114:115] op_sel_hi:[1,0]
	v_pk_mul_f32 v[100:101], v[100:101], v[114:115] op_sel_hi:[1,0]
	v_pk_mul_f32 v[108:109], v[108:109], v[114:115] op_sel_hi:[1,0]
	v_pk_mul_f32 v[102:103], v[102:103], v[114:115] op_sel_hi:[1,0]
	v_pk_mul_f32 v[110:111], v[110:111], v[114:115] op_sel_hi:[1,0]
	v_pk_mul_f32 v[96:97], v[96:97], v[114:115] op_sel_hi:[1,0]
	v_pk_mul_f32 v[104:105], v[104:105], v[114:115] op_sel_hi:[1,0]
	v_mul_f32_e32 v125, 0xbfb8aa3b, v99
	v_mul_f32_e32 v114, 0xbfb8aa3b, v113
	v_mul_f32_e32 v115, 0xbfb8aa3b, v101
	v_mul_f32_e32 v116, 0xbfb8aa3b, v109
	v_mul_f32_e32 v117, 0xbfb8aa3b, v103
	v_mul_f32_e32 v118, 0xbfb8aa3b, v111
	v_mul_f32_e32 v119, 0xbfb8aa3b, v97
	v_mul_f32_e32 v124, 0xbfb8aa3b, v105
	v_exp_f32_e32 v125, v125
	v_exp_f32_e32 v114, v114
	v_exp_f32_e32 v115, v115
	v_exp_f32_e32 v116, v116
	v_exp_f32_e32 v117, v117
	v_exp_f32_e32 v118, v118
	v_exp_f32_e32 v119, v119
	v_exp_f32_e32 v124, v124
	v_add_f32_e32 v125, 1.0, v125
	v_add_f32_e32 v114, 1.0, v114
	v_add_f32_e32 v115, 1.0, v115
	v_add_f32_e32 v116, 1.0, v116
	v_add_f32_e32 v117, 1.0, v117
	v_add_f32_e32 v118, 1.0, v118
	v_add_f32_e32 v119, 1.0, v119
	v_add_f32_e32 v124, 1.0, v124
	v_rcp_f32_e32 v125, v125
	v_rcp_f32_e32 v114, v114
	v_rcp_f32_e32 v115, v115
	v_rcp_f32_e32 v116, v116
	v_rcp_f32_e32 v117, v117
	v_rcp_f32_e32 v118, v118
	v_rcp_f32_e32 v119, v119
	v_rcp_f32_e32 v124, v124
	v_mul_f32_e32 v99, v99, v125
	v_mul_f32_e32 v113, v113, v114
	v_mul_f32_e32 v101, v101, v115
	v_mul_f32_e32 v109, v109, v116
	v_mul_f32_e32 v103, v103, v117
	v_mul_f32_e32 v111, v111, v118
	v_mul_f32_e32 v97, v97, v119
	v_mul_f32_e32 v105, v105, v124
	v_mul_f32_e32 v99, v98, v99
	v_mul_f32_e32 v112, v112, v113
	v_mul_f32_e32 v100, v100, v101
	v_mul_f32_e32 v101, v108, v109
	v_mul_f32_e32 v102, v102, v103
	v_mul_f32_e32 v103, v110, v111
	v_mul_f32_e32 v108, v96, v97
	v_mul_f32_e32 v104, v104, v105
	v_cvt_pk_bf16_f32 v96, v112, v100
	v_cvt_pk_bf16_f32 v97, v101, v102
	v_cvt_pk_bf16_f32 v98, v103, v108
	v_cvt_pk_bf16_f32 v99, v104, v99
	global_store_dwordx4 v[106:107], v[96:99], off
	s_waitcnt vmcnt(7)
; DI float sigmoidf_(float x) { return __builtin_amdgcn_rcpf(1.0f + __builtin_amdgcn_exp2f(-x * LOG2E)); }
; DI float rs_of(const float* ss, int row) { return 1.0f / sqrtf(ss[row] * (1.0f / DM) + EPS); }
; DI u32x4 pack8(f32x4 a, f32x4 b) { u32x4 w; w.x = cvt_pk_bf16(a[0], a[1]); w.y = cvt_pk_bf16(a[2], a[3]); w.z = cvt_pk_bf16(b[0], b[1]); w.w = cvt_pk_bf16(b[2], b[3]); return w; }
;     DI void operator()(AccRef acc, const Unit& u, int wr, int wc, int fr, int fq) const {
;     ...
;                 f32x4 o[2]; const float r = ss ? rs_of(ss, row0 + ai * 128 + m * 16) : 1.0f;
; #pragma unroll
;                 for (int n = 0; n < 2; ++n)
; #pragma unroll
;                     for (int j = 0; j < 4; ++j) { const float gt = acc[ai][0][m][n][j] * r, up = acc[ai][1][m][n][j] * r; o[n][j] = gt * sigmoidf_(gt) * up; }
;                 *(u32x4*)(Hd + (size_t)(row0 + ai * 128 + m * 16) * DFF + col0) = pack8(o[0], o[1]);
	s_nop 1
	v_mov_b32_e32 v98, v242
	s_nop 0
	v_mov_b32_e32 v96, v92
	v_mov_b32_e32 v92, v94
	v_mov_b32_e32 v94, v88
	v_mov_b32_e32 v88, v90
	v_mov_b32_e32 v97, v84
	v_mov_b32_e32 v84, v93
	v_mov_b32_e32 v93, v86
	v_mov_b32_e32 v86, v95
	v_mov_b32_e32 v95, v80
	v_mov_b32_e32 v80, v89
	v_mov_b32_e32 v89, v82
	v_mov_b32_e32 v82, v91
	v_fmamk_f32 v90, v98, 0x3a000000, v153
	v_mul_f32_e32 v91, 0x4f800000, v90
	v_cmp_gt_f32_e32 vcc, s63, v90
	s_nop 1
	v_cndmask_b32_e32 v98, v90, v91, vcc
	v_sqrt_f32_e32 v99, v98
	v_add_u32_e32 v90, 32, v144
	v_mad_i64_i32 v[90:91], s[0:1], v90, s64, v[122:123]
	v_add_u32_e32 v100, -1, v99
	v_add_u32_e32 v101, 1, v99
	v_fma_f32 v102, -v100, v99, v98
	v_fma_f32 v103, -v101, v99, v98
	v_cmp_ge_f32_e64 s[8:9], 0, v102
	v_lshl_add_u64 v[90:91], v[90:91], 0, v[120:121]
	s_nop 0
	v_cndmask_b32_e64 v99, v99, v100, s[8:9]
	v_cmp_lt_f32_e64 s[8:9], 0, v103
	s_nop 1
	v_cndmask_b32_e64 v99, v99, v101, s[8:9]
	v_mul_f32_e32 v100, 0x37800000, v99
	v_cndmask_b32_e32 v99, v99, v100, vcc
	v_cmp_class_f32_e32 vcc, v98, v154
	s_nop 1
	v_cndmask_b32_e32 v98, v99, v98, vcc
	v_div_scale_f32 v99, s[0:1], v98, v98, 1.0
	v_rcp_f32_e32 v100, v99
	v_div_scale_f32 v101, vcc, 1.0, v98, 1.0
	v_fma_f32 v102, -v99, v100, 1.0
	v_fmac_f32_e32 v100, v102, v100
	v_mul_f32_e32 v102, v101, v100
	v_fma_f32 v103, -v99, v102, v101
	v_fmac_f32_e32 v102, v103, v100
	v_fma_f32 v99, -v99, v102, v101
	v_div_fmas_f32 v99, v99, v100, v102
	v_div_fixup_f32 v98, v99, v98, 1.0
	v_pk_mul_f32 v[82:83], v[82:83], v[98:99] op_sel_hi:[1,0]
	v_pk_mul_f32 v[96:97], v[96:97], v[98:99] op_sel_hi:[1,0]
	v_pk_mul_f32 v[84:85], v[84:85], v[98:99] op_sel_hi:[1,0]
	v_pk_mul_f32 v[92:93], v[92:93], v[98:99] op_sel_hi:[1,0]
	v_pk_mul_f32 v[86:87], v[86:87], v[98:99] op_sel_hi:[1,0]
	v_pk_mul_f32 v[94:95], v[94:95], v[98:99] op_sel_hi:[1,0]
	v_pk_mul_f32 v[80:81], v[80:81], v[98:99] op_sel_hi:[1,0]
	v_pk_mul_f32 v[88:89], v[88:89], v[98:99] op_sel_hi:[1,0]
	v_mul_f32_e32 v105, 0xbfb8aa3b, v83
	v_mul_f32_e32 v98, 0xbfb8aa3b, v97
	v_mul_f32_e32 v99, 0xbfb8aa3b, v85
	v_mul_f32_e32 v100, 0xbfb8aa3b, v93
	v_mul_f32_e32 v101, 0xbfb8aa3b, v87
	v_mul_f32_e32 v102, 0xbfb8aa3b, v95
	v_mul_f32_e32 v103, 0xbfb8aa3b, v81
	v_mul_f32_e32 v104, 0xbfb8aa3b, v89
	v_exp_f32_e32 v105, v105
	v_exp_f32_e32 v98, v98
	v_exp_f32_e32 v99, v99
	v_exp_f32_e32 v100, v100
	v_exp_f32_e32 v101, v101
	v_exp_f32_e32 v102, v102
	v_exp_f32_e32 v103, v103
	v_exp_f32_e32 v104, v104
	v_add_f32_e32 v105, 1.0, v105
	v_add_f32_e32 v98, 1.0, v98
	v_add_f32_e32 v99, 1.0, v99
	v_add_f32_e32 v100, 1.0, v100
	v_add_f32_e32 v101, 1.0, v101
	v_add_f32_e32 v102, 1.0, v102
	v_add_f32_e32 v103, 1.0, v103
	v_add_f32_e32 v104, 1.0, v104
	v_rcp_f32_e32 v105, v105
	v_rcp_f32_e32 v98, v98
	v_rcp_f32_e32 v99, v99
	v_rcp_f32_e32 v100, v100
	v_rcp_f32_e32 v101, v101
	v_rcp_f32_e32 v102, v102
	v_rcp_f32_e32 v103, v103
	v_rcp_f32_e32 v104, v104
	v_mul_f32_e32 v83, v83, v105
	v_mul_f32_e32 v97, v97, v98
	v_mul_f32_e32 v85, v85, v99
	v_mul_f32_e32 v93, v93, v100
	v_mul_f32_e32 v87, v87, v101
	v_mul_f32_e32 v95, v95, v102
	v_mul_f32_e32 v81, v81, v103
	v_mul_f32_e32 v89, v89, v104
	v_mul_f32_e32 v83, v82, v83
	v_mul_f32_e32 v96, v96, v97
	v_mul_f32_e32 v84, v84, v85
	v_mul_f32_e32 v85, v92, v93
	v_mul_f32_e32 v86, v86, v87
	v_mul_f32_e32 v87, v94, v95
	v_mul_f32_e32 v92, v80, v81
	v_mul_f32_e32 v88, v88, v89
	v_cvt_pk_bf16_f32 v80, v96, v84
	v_cvt_pk_bf16_f32 v81, v85, v86
	v_cvt_pk_bf16_f32 v82, v87, v92
	v_cvt_pk_bf16_f32 v83, v88, v83
	global_store_dwordx4 v[90:91], v[80:83], off
	s_waitcnt vmcnt(7)
	s_nop 1
	v_mov_b32_e32 v82, v243
	s_nop 0
	v_mov_b32_e32 v80, v76
	v_mov_b32_e32 v76, v78
	v_mov_b32_e32 v78, v72
	v_mov_b32_e32 v72, v74
	v_mov_b32_e32 v81, v68
	v_mov_b32_e32 v68, v77
	v_mov_b32_e32 v77, v70
	v_mov_b32_e32 v70, v79
	v_mov_b32_e32 v79, v64
	v_mov_b32_e32 v64, v73
	v_mov_b32_e32 v73, v66
	v_mov_b32_e32 v66, v75
	v_fmamk_f32 v74, v82, 0x3a000000, v153
	v_mul_f32_e32 v75, 0x4f800000, v74
	v_cmp_gt_f32_e32 vcc, s63, v74
	s_nop 1
	v_cndmask_b32_e32 v82, v74, v75, vcc
	v_sqrt_f32_e32 v83, v82
	v_add_u32_e32 v74, 48, v144
	v_mad_i64_i32 v[74:75], s[0:1], v74, s64, v[122:123]
	v_add_u32_e32 v84, -1, v83
	v_add_u32_e32 v85, 1, v83
	v_fma_f32 v86, -v84, v83, v82
	v_fma_f32 v87, -v85, v83, v82
	v_cmp_ge_f32_e64 s[8:9], 0, v86
	v_lshl_add_u64 v[74:75], v[74:75], 0, v[120:121]
	s_nop 0
	v_cndmask_b32_e64 v83, v83, v84, s[8:9]
	v_cmp_lt_f32_e64 s[8:9], 0, v87
	s_nop 1
	v_cndmask_b32_e64 v83, v83, v85, s[8:9]
	v_mul_f32_e32 v84, 0x37800000, v83
	v_cndmask_b32_e32 v83, v83, v84, vcc
	v_cmp_class_f32_e32 vcc, v82, v154
	s_nop 1
	v_cndmask_b32_e32 v82, v83, v82, vcc
	v_div_scale_f32 v83, s[0:1], v82, v82, 1.0
	v_rcp_f32_e32 v84, v83
	v_div_scale_f32 v85, vcc, 1.0, v82, 1.0
	v_fma_f32 v86, -v83, v84, 1.0
	v_fmac_f32_e32 v84, v86, v84
	v_mul_f32_e32 v86, v85, v84
	v_fma_f32 v87, -v83, v86, v85
	v_fmac_f32_e32 v86, v87, v84
	v_fma_f32 v83, -v83, v86, v85
	v_div_fmas_f32 v83, v83, v84, v86
	v_div_fixup_f32 v82, v83, v82, 1.0
	v_pk_mul_f32 v[66:67], v[66:67], v[82:83] op_sel_hi:[1,0]
	v_pk_mul_f32 v[80:81], v[80:81], v[82:83] op_sel_hi:[1,0]
	v_pk_mul_f32 v[68:69], v[68:69], v[82:83] op_sel_hi:[1,0]
	v_pk_mul_f32 v[76:77], v[76:77], v[82:83] op_sel_hi:[1,0]
	v_pk_mul_f32 v[70:71], v[70:71], v[82:83] op_sel_hi:[1,0]
	v_pk_mul_f32 v[78:79], v[78:79], v[82:83] op_sel_hi:[1,0]
	v_pk_mul_f32 v[64:65], v[64:65], v[82:83] op_sel_hi:[1,0]
	v_pk_mul_f32 v[72:73], v[72:73], v[82:83] op_sel_hi:[1,0]
	v_mul_f32_e32 v89, 0xbfb8aa3b, v67
	v_mul_f32_e32 v82, 0xbfb8aa3b, v81
	v_mul_f32_e32 v83, 0xbfb8aa3b, v69
	v_mul_f32_e32 v84, 0xbfb8aa3b, v77
	v_mul_f32_e32 v85, 0xbfb8aa3b, v71
	v_mul_f32_e32 v86, 0xbfb8aa3b, v79
	v_mul_f32_e32 v87, 0xbfb8aa3b, v65
	v_mul_f32_e32 v88, 0xbfb8aa3b, v73
	v_exp_f32_e32 v89, v89
	v_exp_f32_e32 v82, v82
	v_exp_f32_e32 v83, v83
	v_exp_f32_e32 v84, v84
	v_exp_f32_e32 v85, v85
	v_exp_f32_e32 v86, v86
	v_exp_f32_e32 v87, v87
	v_exp_f32_e32 v88, v88
	v_add_f32_e32 v89, 1.0, v89
	v_add_f32_e32 v82, 1.0, v82
	v_add_f32_e32 v83, 1.0, v83
	v_add_f32_e32 v84, 1.0, v84
	v_add_f32_e32 v85, 1.0, v85
	v_add_f32_e32 v86, 1.0, v86
	v_add_f32_e32 v87, 1.0, v87
	v_add_f32_e32 v88, 1.0, v88
	v_rcp_f32_e32 v89, v89
	v_rcp_f32_e32 v82, v82
	v_rcp_f32_e32 v83, v83
	v_rcp_f32_e32 v84, v84
	v_rcp_f32_e32 v85, v85
	v_rcp_f32_e32 v86, v86
	v_rcp_f32_e32 v87, v87
	v_rcp_f32_e32 v88, v88
	v_mul_f32_e32 v67, v67, v89
	v_mul_f32_e32 v81, v81, v82
	v_mul_f32_e32 v69, v69, v83
	v_mul_f32_e32 v77, v77, v84
	v_mul_f32_e32 v71, v71, v85
	v_mul_f32_e32 v79, v79, v86
	v_mul_f32_e32 v65, v65, v87
	v_mul_f32_e32 v73, v73, v88
	v_mul_f32_e32 v67, v66, v67
	v_mul_f32_e32 v80, v80, v81
	v_mul_f32_e32 v68, v68, v69
	v_mul_f32_e32 v69, v76, v77
	v_mul_f32_e32 v70, v70, v71
	v_mul_f32_e32 v71, v78, v79
	v_mul_f32_e32 v76, v64, v65
	v_mul_f32_e32 v72, v72, v73
	v_cvt_pk_bf16_f32 v64, v80, v68
	v_cvt_pk_bf16_f32 v65, v69, v70
	v_cvt_pk_bf16_f32 v66, v71, v76
	v_cvt_pk_bf16_f32 v67, v72, v67
	global_store_dwordx4 v[74:75], v[64:67], off
	s_waitcnt vmcnt(7)
; DI float sigmoidf_(float x) { return __builtin_amdgcn_rcpf(1.0f + __builtin_amdgcn_exp2f(-x * LOG2E)); }
; DI float rs_of(const float* ss, int row) { return 1.0f / sqrtf(ss[row] * (1.0f / DM) + EPS); }
; DI u32x4 pack8(f32x4 a, f32x4 b) { u32x4 w; w.x = cvt_pk_bf16(a[0], a[1]); w.y = cvt_pk_bf16(a[2], a[3]); w.z = cvt_pk_bf16(b[0], b[1]); w.w = cvt_pk_bf16(b[2], b[3]); return w; }
;     DI void operator()(AccRef acc, const Unit& u, int wr, int wc, int fr, int fq) const {
;     ...
;                 f32x4 o[2]; const float r = ss ? rs_of(ss, row0 + ai * 128 + m * 16) : 1.0f;
; #pragma unroll
;                 for (int n = 0; n < 2; ++n)
; #pragma unroll
;                     for (int j = 0; j < 4; ++j) { const float gt = acc[ai][0][m][n][j] * r, up = acc[ai][1][m][n][j] * r; o[n][j] = gt * sigmoidf_(gt) * up; }
;                 *(u32x4*)(Hd + (size_t)(row0 + ai * 128 + m * 16) * DFF + col0) = pack8(o[0], o[1]);
	s_nop 1
	v_mov_b32_e32 v66, v238
	s_nop 0
	v_mov_b32_e32 v64, v60
	v_mov_b32_e32 v60, v62
	v_mov_b32_e32 v62, v56
	v_mov_b32_e32 v56, v58
	v_mov_b32_e32 v65, v52
	v_mov_b32_e32 v52, v61
	v_mov_b32_e32 v61, v54
	v_mov_b32_e32 v54, v63
	v_mov_b32_e32 v63, v48
	v_mov_b32_e32 v48, v57
	v_mov_b32_e32 v57, v50
	v_mov_b32_e32 v50, v59
	v_fmamk_f32 v58, v66, 0x3a000000, v153
	v_mul_f32_e32 v59, 0x4f800000, v58
	v_cmp_gt_f32_e32 vcc, s63, v58
	s_nop 1
	v_cndmask_b32_e32 v66, v58, v59, vcc
	v_sqrt_f32_e32 v67, v66
	v_add_u32_e32 v58, 0x80, v144
	v_mad_i64_i32 v[58:59], s[0:1], v58, s64, v[122:123]
	v_add_u32_e32 v68, -1, v67
	v_add_u32_e32 v69, 1, v67
	v_fma_f32 v70, -v68, v67, v66
	v_fma_f32 v71, -v69, v67, v66
	v_cmp_ge_f32_e64 s[8:9], 0, v70
	v_lshl_add_u64 v[58:59], v[58:59], 0, v[120:121]
	s_nop 0
	v_cndmask_b32_e64 v67, v67, v68, s[8:9]
	v_cmp_lt_f32_e64 s[8:9], 0, v71
	s_nop 1
	v_cndmask_b32_e64 v67, v67, v69, s[8:9]
	v_mul_f32_e32 v68, 0x37800000, v67
	v_cndmask_b32_e32 v67, v67, v68, vcc
	v_cmp_class_f32_e32 vcc, v66, v154
	s_nop 1
	v_cndmask_b32_e32 v66, v67, v66, vcc
	v_div_scale_f32 v67, s[0:1], v66, v66, 1.0
	v_rcp_f32_e32 v68, v67
	v_div_scale_f32 v69, vcc, 1.0, v66, 1.0
	v_fma_f32 v70, -v67, v68, 1.0
	v_fmac_f32_e32 v68, v70, v68
	v_mul_f32_e32 v70, v69, v68
	v_fma_f32 v71, -v67, v70, v69
	v_fmac_f32_e32 v70, v71, v68
	v_fma_f32 v67, -v67, v70, v69
	v_div_fmas_f32 v67, v67, v68, v70
	v_div_fixup_f32 v66, v67, v66, 1.0
	v_pk_mul_f32 v[50:51], v[50:51], v[66:67] op_sel_hi:[1,0]
	v_pk_mul_f32 v[64:65], v[64:65], v[66:67] op_sel_hi:[1,0]
	v_pk_mul_f32 v[52:53], v[52:53], v[66:67] op_sel_hi:[1,0]
	v_pk_mul_f32 v[60:61], v[60:61], v[66:67] op_sel_hi:[1,0]
	v_pk_mul_f32 v[54:55], v[54:55], v[66:67] op_sel_hi:[1,0]
	v_pk_mul_f32 v[62:63], v[62:63], v[66:67] op_sel_hi:[1,0]
	v_pk_mul_f32 v[48:49], v[48:49], v[66:67] op_sel_hi:[1,0]
	v_pk_mul_f32 v[56:57], v[56:57], v[66:67] op_sel_hi:[1,0]
	v_mul_f32_e32 v73, 0xbfb8aa3b, v51
	v_mul_f32_e32 v66, 0xbfb8aa3b, v65
	v_mul_f32_e32 v67, 0xbfb8aa3b, v53
	v_mul_f32_e32 v68, 0xbfb8aa3b, v61
	v_mul_f32_e32 v69, 0xbfb8aa3b, v55
	v_mul_f32_e32 v70, 0xbfb8aa3b, v63
	v_mul_f32_e32 v71, 0xbfb8aa3b, v49
	v_mul_f32_e32 v72, 0xbfb8aa3b, v57
	v_exp_f32_e32 v73, v73
	v_exp_f32_e32 v66, v66
	v_exp_f32_e32 v67, v67
	v_exp_f32_e32 v68, v68
	v_exp_f32_e32 v69, v69
	v_exp_f32_e32 v70, v70
	v_exp_f32_e32 v71, v71
	v_exp_f32_e32 v72, v72
	v_add_f32_e32 v73, 1.0, v73
	v_add_f32_e32 v66, 1.0, v66
	v_add_f32_e32 v67, 1.0, v67
	v_add_f32_e32 v68, 1.0, v68
	v_add_f32_e32 v69, 1.0, v69
	v_add_f32_e32 v70, 1.0, v70
	v_add_f32_e32 v71, 1.0, v71
	v_add_f32_e32 v72, 1.0, v72
	v_rcp_f32_e32 v73, v73
	v_rcp_f32_e32 v66, v66
	v_rcp_f32_e32 v67, v67
	v_rcp_f32_e32 v68, v68
	v_rcp_f32_e32 v69, v69
	v_rcp_f32_e32 v70, v70
	v_rcp_f32_e32 v71, v71
	v_rcp_f32_e32 v72, v72
	v_mul_f32_e32 v51, v51, v73
	v_mul_f32_e32 v65, v65, v66
	v_mul_f32_e32 v53, v53, v67
	v_mul_f32_e32 v61, v61, v68
	v_mul_f32_e32 v55, v55, v69
	v_mul_f32_e32 v63, v63, v70
	v_mul_f32_e32 v49, v49, v71
	v_mul_f32_e32 v57, v57, v72
	v_mul_f32_e32 v51, v50, v51
	v_mul_f32_e32 v64, v64, v65
	v_mul_f32_e32 v52, v52, v53
	v_mul_f32_e32 v53, v60, v61
	v_mul_f32_e32 v54, v54, v55
	v_mul_f32_e32 v55, v62, v63
	v_mul_f32_e32 v60, v48, v49
	v_mul_f32_e32 v56, v56, v57
	v_cvt_pk_bf16_f32 v48, v64, v52
	v_cvt_pk_bf16_f32 v49, v53, v54
	v_cvt_pk_bf16_f32 v50, v55, v60
	v_cvt_pk_bf16_f32 v51, v56, v51
	global_store_dwordx4 v[58:59], v[48:51], off
	s_waitcnt vmcnt(7)
	s_nop 1
	v_mov_b32_e32 v50, v239
	s_nop 0
	v_mov_b32_e32 v48, v44
	v_mov_b32_e32 v44, v46
	v_mov_b32_e32 v46, v40
	v_mov_b32_e32 v40, v42
	v_mov_b32_e32 v49, v36
	v_mov_b32_e32 v36, v45
	v_mov_b32_e32 v45, v38
	v_mov_b32_e32 v38, v47
	v_mov_b32_e32 v47, v32
	v_mov_b32_e32 v32, v41
	v_mov_b32_e32 v41, v34
	v_mov_b32_e32 v34, v43
	v_fmamk_f32 v42, v50, 0x3a000000, v153
	v_mul_f32_e32 v43, 0x4f800000, v42
	v_cmp_gt_f32_e32 vcc, s63, v42
	s_nop 1
	v_cndmask_b32_e32 v50, v42, v43, vcc
	v_sqrt_f32_e32 v51, v50
	v_add_u32_e32 v42, 0x90, v144
	v_mad_i64_i32 v[42:43], s[0:1], v42, s64, v[122:123]
	v_add_u32_e32 v52, -1, v51
	v_add_u32_e32 v53, 1, v51
	v_fma_f32 v54, -v52, v51, v50
	v_fma_f32 v55, -v53, v51, v50
	v_cmp_ge_f32_e64 s[8:9], 0, v54
	v_lshl_add_u64 v[42:43], v[42:43], 0, v[120:121]
	s_nop 0
	v_cndmask_b32_e64 v51, v51, v52, s[8:9]
	v_cmp_lt_f32_e64 s[8:9], 0, v55
	s_nop 1
	v_cndmask_b32_e64 v51, v51, v53, s[8:9]
	v_mul_f32_e32 v52, 0x37800000, v51
	v_cndmask_b32_e32 v51, v51, v52, vcc
	v_cmp_class_f32_e32 vcc, v50, v154
	s_nop 1
	v_cndmask_b32_e32 v50, v51, v50, vcc
	v_div_scale_f32 v51, s[0:1], v50, v50, 1.0
	v_rcp_f32_e32 v52, v51
	v_div_scale_f32 v53, vcc, 1.0, v50, 1.0
	v_fma_f32 v54, -v51, v52, 1.0
	v_fmac_f32_e32 v52, v54, v52
	v_mul_f32_e32 v54, v53, v52
	v_fma_f32 v55, -v51, v54, v53
	v_fmac_f32_e32 v54, v55, v52
	v_fma_f32 v51, -v51, v54, v53
	v_div_fmas_f32 v51, v51, v52, v54
	v_div_fixup_f32 v50, v51, v50, 1.0
	v_pk_mul_f32 v[34:35], v[34:35], v[50:51] op_sel_hi:[1,0]
	v_pk_mul_f32 v[48:49], v[48:49], v[50:51] op_sel_hi:[1,0]
	v_pk_mul_f32 v[36:37], v[36:37], v[50:51] op_sel_hi:[1,0]
	v_pk_mul_f32 v[44:45], v[44:45], v[50:51] op_sel_hi:[1,0]
	v_pk_mul_f32 v[38:39], v[38:39], v[50:51] op_sel_hi:[1,0]
	v_pk_mul_f32 v[46:47], v[46:47], v[50:51] op_sel_hi:[1,0]
	v_pk_mul_f32 v[32:33], v[32:33], v[50:51] op_sel_hi:[1,0]
	v_pk_mul_f32 v[40:41], v[40:41], v[50:51] op_sel_hi:[1,0]
	v_mul_f32_e32 v57, 0xbfb8aa3b, v35
	v_mul_f32_e32 v50, 0xbfb8aa3b, v49
	v_mul_f32_e32 v51, 0xbfb8aa3b, v37
	v_mul_f32_e32 v52, 0xbfb8aa3b, v45
	v_mul_f32_e32 v53, 0xbfb8aa3b, v39
	v_mul_f32_e32 v54, 0xbfb8aa3b, v47
	v_mul_f32_e32 v55, 0xbfb8aa3b, v33
	v_mul_f32_e32 v56, 0xbfb8aa3b, v41
	v_exp_f32_e32 v57, v57
	v_exp_f32_e32 v50, v50
	v_exp_f32_e32 v51, v51
	v_exp_f32_e32 v52, v52
	v_exp_f32_e32 v53, v53
	v_exp_f32_e32 v54, v54
	v_exp_f32_e32 v55, v55
	v_exp_f32_e32 v56, v56
	v_add_f32_e32 v57, 1.0, v57
	v_add_f32_e32 v50, 1.0, v50
	v_add_f32_e32 v51, 1.0, v51
	v_add_f32_e32 v52, 1.0, v52
	v_add_f32_e32 v53, 1.0, v53
	v_add_f32_e32 v54, 1.0, v54
	v_add_f32_e32 v55, 1.0, v55
	v_add_f32_e32 v56, 1.0, v56
	v_rcp_f32_e32 v57, v57
	v_rcp_f32_e32 v50, v50
	v_rcp_f32_e32 v51, v51
	v_rcp_f32_e32 v52, v52
	v_rcp_f32_e32 v53, v53
	v_rcp_f32_e32 v54, v54
	v_rcp_f32_e32 v55, v55
	v_rcp_f32_e32 v56, v56
	v_mul_f32_e32 v35, v35, v57
	v_mul_f32_e32 v49, v49, v50
	v_mul_f32_e32 v37, v37, v51
	v_mul_f32_e32 v45, v45, v52
	v_mul_f32_e32 v39, v39, v53
	v_mul_f32_e32 v47, v47, v54
	v_mul_f32_e32 v33, v33, v55
	v_mul_f32_e32 v41, v41, v56
	v_mul_f32_e32 v35, v34, v35
	v_mul_f32_e32 v48, v48, v49
	v_mul_f32_e32 v36, v36, v37
	v_mul_f32_e32 v37, v44, v45
	v_mul_f32_e32 v38, v38, v39
	v_mul_f32_e32 v39, v46, v47
	v_mul_f32_e32 v44, v32, v33
	v_mul_f32_e32 v40, v40, v41
	v_cvt_pk_bf16_f32 v32, v48, v36
	v_cvt_pk_bf16_f32 v33, v37, v38
	v_cvt_pk_bf16_f32 v34, v39, v44
	v_cvt_pk_bf16_f32 v35, v40, v35
	global_store_dwordx4 v[42:43], v[32:35], off
	s_waitcnt vmcnt(7)
; DI float sigmoidf_(float x) { return __builtin_amdgcn_rcpf(1.0f + __builtin_amdgcn_exp2f(-x * LOG2E)); }
; DI u32x4 pack8(f32x4 a, f32x4 b) { u32x4 w; w.x = cvt_pk_bf16(a[0], a[1]); w.y = cvt_pk_bf16(a[2], a[3]); w.z = cvt_pk_bf16(b[0], b[1]); w.w = cvt_pk_bf16(b[2], b[3]); return w; }
; DI float rs_of(const float* ss, int row) { return 1.0f / sqrtf(ss[row] * (1.0f / DM) + EPS); }
;     DI void operator()(AccRef acc, const Unit& u, int wr, int wc, int fr, int fq) const {
;     ...
;                 f32x4 o[2]; const float r = ss ? rs_of(ss, row0 + ai * 128 + m * 16) : 1.0f;
; #pragma unroll
;                 for (int n = 0; n < 2; ++n)
; #pragma unroll
;                     for (int j = 0; j < 4; ++j) { const float gt = acc[ai][0][m][n][j] * r, up = acc[ai][1][m][n][j] * r; o[n][j] = gt * sigmoidf_(gt) * up; }
;                 *(u32x4*)(Hd + (size_t)(row0 + ai * 128 + m * 16) * DFF + col0) = pack8(o[0], o[1]);
	s_nop 1
	v_mov_b32_e32 v34, v240
	s_nop 0
	v_mov_b32_e32 v32, v28
	v_mov_b32_e32 v28, v30
	v_mov_b32_e32 v30, v24
	v_mov_b32_e32 v24, v26
	v_mov_b32_e32 v33, v20
	v_mov_b32_e32 v20, v29
	v_mov_b32_e32 v29, v22
	v_mov_b32_e32 v22, v31
	v_mov_b32_e32 v31, v16
	v_mov_b32_e32 v16, v25
	v_mov_b32_e32 v25, v18
	v_mov_b32_e32 v18, v27
	v_fmamk_f32 v26, v34, 0x3a000000, v153
	v_mul_f32_e32 v27, 0x4f800000, v26
	v_cmp_gt_f32_e32 vcc, s63, v26
	s_nop 1
	v_cndmask_b32_e32 v34, v26, v27, vcc
	v_sqrt_f32_e32 v35, v34
	v_add_u32_e32 v26, 0xa0, v144
	v_mad_i64_i32 v[26:27], s[0:1], v26, s64, v[122:123]
	v_add_u32_e32 v36, -1, v35
	v_add_u32_e32 v37, 1, v35
	v_fma_f32 v38, -v36, v35, v34
	v_fma_f32 v39, -v37, v35, v34
	v_cmp_ge_f32_e64 s[8:9], 0, v38
	v_lshl_add_u64 v[26:27], v[26:27], 0, v[120:121]
	s_nop 0
	v_cndmask_b32_e64 v35, v35, v36, s[8:9]
	v_cmp_lt_f32_e64 s[8:9], 0, v39
	s_nop 1
	v_cndmask_b32_e64 v35, v35, v37, s[8:9]
	v_mul_f32_e32 v36, 0x37800000, v35
	v_cndmask_b32_e32 v35, v35, v36, vcc
	v_cmp_class_f32_e32 vcc, v34, v154
	s_nop 1
	v_cndmask_b32_e32 v34, v35, v34, vcc
	v_div_scale_f32 v35, s[0:1], v34, v34, 1.0
	v_rcp_f32_e32 v36, v35
	v_div_scale_f32 v37, vcc, 1.0, v34, 1.0
	v_fma_f32 v38, -v35, v36, 1.0
	v_fmac_f32_e32 v36, v38, v36
	v_mul_f32_e32 v38, v37, v36
	v_fma_f32 v39, -v35, v38, v37
	v_fmac_f32_e32 v38, v39, v36
	v_fma_f32 v35, -v35, v38, v37
	v_div_fmas_f32 v35, v35, v36, v38
	v_div_fixup_f32 v34, v35, v34, 1.0
	v_pk_mul_f32 v[18:19], v[18:19], v[34:35] op_sel_hi:[1,0]
	v_pk_mul_f32 v[32:33], v[32:33], v[34:35] op_sel_hi:[1,0]
	v_pk_mul_f32 v[20:21], v[20:21], v[34:35] op_sel_hi:[1,0]
	v_pk_mul_f32 v[28:29], v[28:29], v[34:35] op_sel_hi:[1,0]
	v_pk_mul_f32 v[22:23], v[22:23], v[34:35] op_sel_hi:[1,0]
	v_pk_mul_f32 v[30:31], v[30:31], v[34:35] op_sel_hi:[1,0]
	v_pk_mul_f32 v[16:17], v[16:17], v[34:35] op_sel_hi:[1,0]
	v_pk_mul_f32 v[24:25], v[24:25], v[34:35] op_sel_hi:[1,0]
	v_mul_f32_e32 v41, 0xbfb8aa3b, v19
	v_mul_f32_e32 v34, 0xbfb8aa3b, v33
	v_mul_f32_e32 v35, 0xbfb8aa3b, v21
	v_mul_f32_e32 v36, 0xbfb8aa3b, v29
	v_mul_f32_e32 v37, 0xbfb8aa3b, v23
	v_mul_f32_e32 v38, 0xbfb8aa3b, v31
	v_mul_f32_e32 v39, 0xbfb8aa3b, v17
	v_mul_f32_e32 v40, 0xbfb8aa3b, v25
	v_exp_f32_e32 v41, v41
	v_exp_f32_e32 v34, v34
	v_exp_f32_e32 v35, v35
	v_exp_f32_e32 v36, v36
	v_exp_f32_e32 v37, v37
	v_exp_f32_e32 v38, v38
	v_exp_f32_e32 v39, v39
	v_exp_f32_e32 v40, v40
	v_add_f32_e32 v41, 1.0, v41
	v_add_f32_e32 v34, 1.0, v34
	v_add_f32_e32 v35, 1.0, v35
	v_add_f32_e32 v36, 1.0, v36
	v_add_f32_e32 v37, 1.0, v37
	v_add_f32_e32 v38, 1.0, v38
	v_add_f32_e32 v39, 1.0, v39
	v_add_f32_e32 v40, 1.0, v40
	v_rcp_f32_e32 v41, v41
	v_rcp_f32_e32 v34, v34
	v_rcp_f32_e32 v35, v35
	v_rcp_f32_e32 v36, v36
	v_rcp_f32_e32 v37, v37
	v_rcp_f32_e32 v38, v38
	v_rcp_f32_e32 v39, v39
	v_rcp_f32_e32 v40, v40
	v_mul_f32_e32 v19, v19, v41
	v_mul_f32_e32 v33, v33, v34
	v_mul_f32_e32 v21, v21, v35
	v_mul_f32_e32 v29, v29, v36
	v_mul_f32_e32 v23, v23, v37
	v_mul_f32_e32 v31, v31, v38
	v_mul_f32_e32 v17, v17, v39
	v_mul_f32_e32 v25, v25, v40
	v_mul_f32_e32 v19, v18, v19
	v_mul_f32_e32 v32, v32, v33
	v_mul_f32_e32 v20, v20, v21
	v_mul_f32_e32 v21, v28, v29
	v_mul_f32_e32 v22, v22, v23
	v_mul_f32_e32 v23, v30, v31
	v_mul_f32_e32 v28, v16, v17
	v_mul_f32_e32 v24, v24, v25
	v_cvt_pk_bf16_f32 v16, v32, v20
	v_cvt_pk_bf16_f32 v17, v21, v22
	v_cvt_pk_bf16_f32 v18, v23, v28
	v_cvt_pk_bf16_f32 v19, v24, v19
	global_store_dwordx4 v[26:27], v[16:19], off
	s_waitcnt vmcnt(7)
	s_nop 1
	v_mov_b32_e32 v18, v241
	s_nop 0
	v_mov_b32_e32 v16, v12
	v_mov_b32_e32 v12, v14
	v_mov_b32_e32 v14, v8
	v_mov_b32_e32 v8, v10
	v_mov_b32_e32 v17, v4
	v_mov_b32_e32 v4, v13
	v_mov_b32_e32 v13, v6
	v_mov_b32_e32 v6, v15
	v_mov_b32_e32 v15, v0
	v_mov_b32_e32 v0, v9
	v_mov_b32_e32 v9, v2
	v_mov_b32_e32 v2, v11
	v_fmamk_f32 v10, v18, 0x3a000000, v153
	v_mul_f32_e32 v11, 0x4f800000, v10
	v_cmp_gt_f32_e32 vcc, s63, v10
	s_nop 1
	v_cndmask_b32_e32 v18, v10, v11, vcc
	v_sqrt_f32_e32 v19, v18
	v_add_u32_e32 v10, 0xb0, v144
	v_mad_i64_i32 v[10:11], s[0:1], v10, s64, v[122:123]
	v_add_u32_e32 v20, -1, v19
	v_add_u32_e32 v21, 1, v19
	v_fma_f32 v22, -v20, v19, v18
	v_fma_f32 v23, -v21, v19, v18
	v_cmp_ge_f32_e64 s[8:9], 0, v22
	v_lshl_add_u64 v[10:11], v[10:11], 0, v[120:121]
	s_nop 0
	v_cndmask_b32_e64 v19, v19, v20, s[8:9]
	v_cmp_lt_f32_e64 s[8:9], 0, v23
	s_nop 1
	v_cndmask_b32_e64 v19, v19, v21, s[8:9]
	v_mul_f32_e32 v20, 0x37800000, v19
	v_cndmask_b32_e32 v19, v19, v20, vcc
	v_cmp_class_f32_e32 vcc, v18, v154
	s_nop 1
	v_cndmask_b32_e32 v18, v19, v18, vcc
	v_div_scale_f32 v19, s[0:1], v18, v18, 1.0
	v_rcp_f32_e32 v20, v19
	v_div_scale_f32 v21, vcc, 1.0, v18, 1.0
	v_fma_f32 v22, -v19, v20, 1.0
	v_fmac_f32_e32 v20, v22, v20
	v_mul_f32_e32 v22, v21, v20
	v_fma_f32 v23, -v19, v22, v21
	v_fmac_f32_e32 v22, v23, v20
	v_fma_f32 v19, -v19, v22, v21
	v_div_fmas_f32 v19, v19, v20, v22
	v_div_fixup_f32 v18, v19, v18, 1.0
	v_pk_mul_f32 v[2:3], v[2:3], v[18:19] op_sel_hi:[1,0]
	v_pk_mul_f32 v[16:17], v[16:17], v[18:19] op_sel_hi:[1,0]
	v_pk_mul_f32 v[4:5], v[4:5], v[18:19] op_sel_hi:[1,0]
	v_pk_mul_f32 v[12:13], v[12:13], v[18:19] op_sel_hi:[1,0]
	v_pk_mul_f32 v[6:7], v[6:7], v[18:19] op_sel_hi:[1,0]
	v_pk_mul_f32 v[14:15], v[14:15], v[18:19] op_sel_hi:[1,0]
	v_pk_mul_f32 v[0:1], v[0:1], v[18:19] op_sel_hi:[1,0]
	v_pk_mul_f32 v[8:9], v[8:9], v[18:19] op_sel_hi:[1,0]
	v_mul_f32_e32 v25, 0xbfb8aa3b, v3
	v_mul_f32_e32 v18, 0xbfb8aa3b, v17
	v_mul_f32_e32 v19, 0xbfb8aa3b, v5
	v_mul_f32_e32 v20, 0xbfb8aa3b, v13
	v_mul_f32_e32 v21, 0xbfb8aa3b, v7
	v_mul_f32_e32 v22, 0xbfb8aa3b, v15
	v_mul_f32_e32 v23, 0xbfb8aa3b, v1
	v_mul_f32_e32 v24, 0xbfb8aa3b, v9
	v_exp_f32_e32 v25, v25
	v_exp_f32_e32 v18, v18
	v_exp_f32_e32 v19, v19
	v_exp_f32_e32 v20, v20
	v_exp_f32_e32 v21, v21
	v_exp_f32_e32 v22, v22
	v_exp_f32_e32 v23, v23
	v_exp_f32_e32 v24, v24
	v_add_f32_e32 v25, 1.0, v25
	v_add_f32_e32 v18, 1.0, v18
	v_add_f32_e32 v19, 1.0, v19
	v_add_f32_e32 v20, 1.0, v20
	v_add_f32_e32 v21, 1.0, v21
	v_add_f32_e32 v22, 1.0, v22
	v_add_f32_e32 v23, 1.0, v23
	v_add_f32_e32 v24, 1.0, v24
	v_rcp_f32_e32 v25, v25
	v_rcp_f32_e32 v18, v18
	v_rcp_f32_e32 v19, v19
	v_rcp_f32_e32 v20, v20
	v_rcp_f32_e32 v21, v21
	v_rcp_f32_e32 v22, v22
	v_rcp_f32_e32 v23, v23
	v_rcp_f32_e32 v24, v24
	v_mul_f32_e32 v3, v3, v25
	v_mul_f32_e32 v17, v17, v18
	v_mul_f32_e32 v5, v5, v19
	v_mul_f32_e32 v13, v13, v20
	v_mul_f32_e32 v7, v7, v21
	v_mul_f32_e32 v15, v15, v22
	v_mul_f32_e32 v1, v1, v23
	v_mul_f32_e32 v9, v9, v24
	v_mul_f32_e32 v3, v2, v3
	s_mov_b64 vcc, s[6:7]
	v_mul_f32_e32 v16, v16, v17
	v_mul_f32_e32 v4, v4, v5
	v_mul_f32_e32 v5, v12, v13
	v_mul_f32_e32 v6, v6, v7
	v_mul_f32_e32 v7, v14, v15
	v_mul_f32_e32 v12, v0, v1
	v_mul_f32_e32 v8, v8, v9
	v_cvt_pk_bf16_f32 v0, v16, v4
	v_cvt_pk_bf16_f32 v1, v5, v6
	v_cvt_pk_bf16_f32 v2, v7, v12
	v_cvt_pk_bf16_f32 v3, v8, v3
	global_store_dwordx4 v[10:11], v[0:3], off
	s_cbranch_vccz .LBB0_1661
	s_waitcnt vmcnt(0)
	s_cmpk_gt_u32 s3, 0xff
	s_cbranch_scc1 .LBB0_1672
	s_barrier

; #define PG8_STAGE(bufoff, gbase, voff) do { _Pragma("unroll") for (int _i = 0; _i < 2; ++_i) \
;         __builtin_amdgcn_global_load_lds((const unsigned*)((const char*)(gbase) + (voff)[_i]), (LAS unsigned*)(lds + (bufoff) + ldsw + _i * 8192), 16, 0, 0); } while (0)
; #define PG8_LDA(dst, b, h) do { _Pragma("unroll") for (int m = 0; m < 4; ++m) _Pragma("unroll") for (int k = 0; k < 2; ++k) dst[m][k] = *(const LAS bf16x8*)(lds + PG8_SA(b, h) + aoff + m * 2048 + k * 1024); } while (0)
; #define PG8_LDB(dst, b, h) do { _Pragma("unroll") for (int n = 0; n < 2; ++n) _Pragma("unroll") for (int k = 0; k < 2; ++k) dst[n][k] = *(const LAS bf16x8*)(lds + PG8_SB(b, h) + boff + n * 2048 + k * 1024); } while (0)
; #define PG8_MMA(ai, bj, At, Bt) do { __builtin_amdgcn_s_setprio(1); _Pragma("unroll") for (int m = 0; m < 4; ++m) _Pragma("unroll") for (int n = 0; n < 2; ++n) _Pragma("unroll") for (int k = 0; k < 2; ++k) \
;         acc[ai][bj][m][n] = __builtin_amdgcn_mfma_f32_16x16x32_bf16(Bt[n][k], At[m][k], acc[ai][bj][m][n], 0, 0, 0); __builtin_amdgcn_s_setprio(0); } while (0)
; #define PG8_WAIT_L(n) asm volatile("s_waitcnt lgkmcnt(" #n ")" ::: "memory")
; #define PG8_BAR __builtin_amdgcn_s_barrier()
; #define PG8_SCHED __builtin_amdgcn_sched_barrier(0)
; template <class Epi, class Sched>
; DI void gemm_phase(LAS unsigned char* lds, const Gemm g, const Sched& S, const Epi& E) {
;     ...
;             PG8_LDB(B0, 0, 0); PG8_SCHED; PG8_LDA(At, 0, 0); PG8_STAGE(PG8_SA(1, 1), a1 + hstep, voffA);
;             PG8_WAIT_L(8); PG8_BAR; PG8_WAIT_L(0); PG8_MMA(0, 0, At, B0); PG8_BAR; PG8_SCHED;
;             PG8_LDB(B1, 0, 1); PG8_STAGE(PG8_SB(0, 0), b2, voffB);
;             PG8_BAR; PG8_WAIT_L(0); PG8_MMA(0, 1, At, B1); PG8_BAR;
;             PG8_LDA(At, 0, 1); PG8_STAGE(PG8_SA(0, 0), a2, voffA);
;             PG8_BAR; PG8_WAIT_L(0); PG8_MMA(1, 0, At, B0); PG8_BAR; PG8_SCHED;
.LBB0_1746:
	ds_read_b128 v[144:147], v155
	ds_read_b128 v[160:163], v155 offset:1024
	ds_read_b128 v[164:167], v155 offset:2048
	ds_read_b128 v[168:171], v155 offset:3072
	s_add_u32 s0, s38, 0xffea0080
	s_addc_u32 s1, s39, -1
	s_cmpk_eq_i32 s68, 0x54
	s_cselect_b32 s43, s9, s1
	s_cselect_b32 s42, s8, s0
	s_cselect_b32 s41, s11, s67
	s_cselect_b32 s40, s10, s35
	v_lshl_add_u64 v[202:203], s[38:39], 0, v[136:137]
	s_add_i32 m0, s52, 0xc000
	ds_read_b128 v[172:175], v156
	ds_read_b128 v[176:179], v156 offset:1024
	ds_read_b128 v[180:183], v156 offset:2048
	ds_read_b128 v[188:191], v156 offset:3072
	ds_read_b128 v[206:209], v156 offset:4096
	ds_read_b128 v[210:213], v156 offset:5120
	ds_read_b128 v[214:217], v156 offset:6144
	ds_read_b128 v[218:221], v156 offset:7168
	global_load_lds_dwordx4 v[202:203], off
	v_lshl_add_u64 v[202:203], s[38:39], 0, v[138:139]
	s_add_i32 m0, s52, 0xe000
	s_nop 0
	global_load_lds_dwordx4 v[202:203], off
	s_waitcnt lgkmcnt(8)
	s_barrier
	s_waitcnt lgkmcnt(0)
	s_setprio 1
	s_waitcnt lgkmcnt(0)
	v_mfma_f32_16x16x32_bf16 v[124:127], v[144:147], v[172:175], v[124:127]
	v_mfma_f32_16x16x32_bf16 v[120:123], v[164:167], v[172:175], v[120:123]
	v_mfma_f32_16x16x32_bf16 v[108:111], v[144:147], v[180:183], v[108:111]
	v_mfma_f32_16x16x32_bf16 v[104:107], v[164:167], v[180:183], v[104:107]
	v_mfma_f32_16x16x32_bf16 v[92:95], v[144:147], v[206:209], v[92:95]
	v_mfma_f32_16x16x32_bf16 v[88:91], v[164:167], v[206:209], v[88:91]
	v_mfma_f32_16x16x32_bf16 v[76:79], v[144:147], v[214:217], v[76:79]
	v_mfma_f32_16x16x32_bf16 v[72:75], v[164:167], v[214:217], v[72:75]
	v_mfma_f32_16x16x32_bf16 v[124:127], v[160:163], v[176:179], v[124:127]
	v_mfma_f32_16x16x32_bf16 v[120:123], v[168:171], v[176:179], v[120:123]
	v_mfma_f32_16x16x32_bf16 v[108:111], v[160:163], v[188:191], v[108:111]
	v_mfma_f32_16x16x32_bf16 v[104:107], v[168:171], v[188:191], v[104:107]
	v_mfma_f32_16x16x32_bf16 v[92:95], v[160:163], v[210:213], v[92:95]
	v_mfma_f32_16x16x32_bf16 v[88:91], v[168:171], v[210:213], v[88:91]
	v_mfma_f32_16x16x32_bf16 v[76:79], v[160:163], v[218:221], v[76:79]
	v_mfma_f32_16x16x32_bf16 v[72:75], v[168:171], v[218:221], v[72:75]
	s_setprio 0
	s_barrier
	s_add_i32 s0, s61, s51
	v_lshl_add_u64 v[202:203], s[40:41], 0, v[130:131]
	s_mov_b32 m0, s0
	ds_read_b128 v[222:225], v157
	ds_read_b128 v[226:229], v157 offset:1024
	ds_read_b128 v[230:233], v157 offset:2048
	ds_read_b128 v[234:237], v157 offset:3072
	global_load_lds_dwordx4 v[202:203], off
	v_lshl_add_u64 v[238:239], s[40:41], 0, v[134:135]
	s_add_i32 m0, s0, 0x2000
	s_nop 0
	global_load_lds_dwordx4 v[238:239], off
	s_barrier
	s_waitcnt lgkmcnt(0)
	s_setprio 1
	s_waitcnt lgkmcnt(0)
	v_mfma_f32_16x16x32_bf16 v[116:119], v[222:225], v[172:175], v[116:119]
	v_mfma_f32_16x16x32_bf16 v[112:115], v[230:233], v[172:175], v[112:115]
	v_mfma_f32_16x16x32_bf16 v[100:103], v[222:225], v[180:183], v[100:103]
	v_mfma_f32_16x16x32_bf16 v[96:99], v[230:233], v[180:183], v[96:99]
	v_mfma_f32_16x16x32_bf16 v[84:87], v[222:225], v[206:209], v[84:87]
	v_mfma_f32_16x16x32_bf16 v[80:83], v[230:233], v[206:209], v[80:83]
	v_mfma_f32_16x16x32_bf16 v[68:71], v[222:225], v[214:217], v[68:71]
	v_mfma_f32_16x16x32_bf16 v[64:67], v[230:233], v[214:217], v[64:67]
	v_mfma_f32_16x16x32_bf16 v[116:119], v[226:229], v[176:179], v[116:119]
	v_mfma_f32_16x16x32_bf16 v[112:115], v[234:237], v[176:179], v[112:115]
	v_mfma_f32_16x16x32_bf16 v[100:103], v[226:229], v[188:191], v[100:103]
	v_mfma_f32_16x16x32_bf16 v[96:99], v[234:237], v[188:191], v[96:99]
	v_mfma_f32_16x16x32_bf16 v[84:87], v[226:229], v[210:213], v[84:87]
	v_mfma_f32_16x16x32_bf16 v[80:83], v[234:237], v[210:213], v[80:83]
	v_mfma_f32_16x16x32_bf16 v[68:71], v[226:229], v[218:221], v[68:71]
	v_mfma_f32_16x16x32_bf16 v[64:67], v[234:237], v[218:221], v[64:67]
	s_setprio 0
	s_mov_b32 m0, s52
	v_lshl_add_u64 v[240:241], s[42:43], 0, v[128:129]
	s_barrier
	ds_read_b128 v[172:175], v156 offset:16384
	ds_read_b128 v[176:179], v156 offset:17408
	ds_read_b128 v[180:183], v156 offset:18432
	ds_read_b128 v[188:191], v156 offset:19456
	ds_read_b128 v[206:209], v156 offset:20480
	ds_read_b128 v[210:213], v156 offset:21504
	ds_read_b128 v[214:217], v156 offset:22528
	ds_read_b128 v[218:221], v156 offset:23552
	global_load_lds_dwordx4 v[240:241], off
	v_lshl_add_u64 v[242:243], s[42:43], 0, v[132:133]
	s_mov_b32 m0, s53
	s_nop 0
	global_load_lds_dwordx4 v[242:243], off
	s_barrier
	s_waitcnt lgkmcnt(0)
	s_setprio 1
	s_waitcnt lgkmcnt(0)
	v_mfma_f32_16x16x32_bf16 v[60:63], v[144:147], v[172:175], v[60:63]
	v_mfma_f32_16x16x32_bf16 v[56:59], v[164:167], v[172:175], v[56:59]
	v_mfma_f32_16x16x32_bf16 v[44:47], v[144:147], v[180:183], v[44:47]
	v_mfma_f32_16x16x32_bf16 v[40:43], v[164:167], v[180:183], v[40:43]
	v_mfma_f32_16x16x32_bf16 v[28:31], v[144:147], v[206:209], v[28:31]
	v_mfma_f32_16x16x32_bf16 v[24:27], v[164:167], v[206:209], v[24:27]
	v_mfma_f32_16x16x32_bf16 v[12:15], v[144:147], v[214:217], v[12:15]
	v_mfma_f32_16x16x32_bf16 v[8:11], v[164:167], v[214:217], v[8:11]
	v_mfma_f32_16x16x32_bf16 v[60:63], v[160:163], v[176:179], v[60:63]
	v_mfma_f32_16x16x32_bf16 v[56:59], v[168:171], v[176:179], v[56:59]
	v_mfma_f32_16x16x32_bf16 v[44:47], v[160:163], v[188:191], v[44:47]
	v_mfma_f32_16x16x32_bf16 v[40:43], v[168:171], v[188:191], v[40:43]
	v_mfma_f32_16x16x32_bf16 v[28:31], v[160:163], v[210:213], v[28:31]
	v_mfma_f32_16x16x32_bf16 v[24:27], v[168:171], v[210:213], v[24:27]
	v_mfma_f32_16x16x32_bf16 v[12:15], v[160:163], v[218:221], v[12:15]
	v_mfma_f32_16x16x32_bf16 v[8:11], v[168:171], v[218:221], v[8:11]
	s_setprio 0
	s_barrier
; #define PG8_STAGE(bufoff, gbase, voff) do { _Pragma("unroll") for (int _i = 0; _i < 2; ++_i) \
;         __builtin_amdgcn_global_load_lds((const unsigned*)((const char*)(gbase) + (voff)[_i]), (LAS unsigned*)(lds + (bufoff) + ldsw + _i * 8192), 16, 0, 0); } while (0)
; #define PG8_LDA(dst, b, h) do { _Pragma("unroll") for (int m = 0; m < 4; ++m) _Pragma("unroll") for (int k = 0; k < 2; ++k) dst[m][k] = *(const LAS bf16x8*)(lds + PG8_SA(b, h) + aoff + m * 2048 + k * 1024); } while (0)
; #define PG8_LDB(dst, b, h) do { _Pragma("unroll") for (int n = 0; n < 2; ++n) _Pragma("unroll") for (int k = 0; k < 2; ++k) dst[n][k] = *(const LAS bf16x8*)(lds + PG8_SB(b, h) + boff + n * 2048 + k * 1024); } while (0)
; #define PG8_MMA(ai, bj, At, Bt) do { __builtin_amdgcn_s_setprio(1); _Pragma("unroll") for (int m = 0; m < 4; ++m) _Pragma("unroll") for (int n = 0; n < 2; ++n) _Pragma("unroll") for (int k = 0; k < 2; ++k) \
;         acc[ai][bj][m][n] = __builtin_amdgcn_mfma_f32_16x16x32_bf16(Bt[n][k], At[m][k], acc[ai][bj][m][n], 0, 0, 0); __builtin_amdgcn_s_setprio(0); } while (0)
; #define PG8_WAIT_V(n) asm volatile("s_waitcnt vmcnt(" #n ")" ::: "memory")
; #define PG8_WAIT_L(n) asm volatile("s_waitcnt lgkmcnt(" #n ")" ::: "memory")
; #define PG8_BAR __builtin_amdgcn_s_barrier()
; #define PG8_SCHED __builtin_amdgcn_sched_barrier(0)
; template <class Epi, class Sched>
; DI void gemm_phase(LAS unsigned char* lds, const Gemm g, const Sched& S, const Epi& E) {
;     ...
;             PG8_STAGE(PG8_SB(0, 1), b2 + hstep, voffB);
;             PG8_WAIT_V(6); PG8_BAR; PG8_MMA(1, 1, At, B1); PG8_BAR;
;             PG8_LDB(B0, 1, 0); PG8_SCHED; PG8_LDA(At, 1, 0); PG8_STAGE(PG8_SA(0, 1), a2 + hstep, voffA);
;             PG8_WAIT_L(8); PG8_BAR; PG8_WAIT_L(0); PG8_MMA(0, 0, At, B0); PG8_BAR; PG8_SCHED;
;             PG8_LDB(B1, 1, 1); PG8_STAGE(PG8_SB(1, 0), b3, voffB);
;             PG8_BAR; PG8_WAIT_L(0); PG8_MMA(0, 1, At, B1); PG8_BAR;
;             PG8_LDA(At, 1, 1); PG8_STAGE(PG8_SA(1, 0), a3, voffA);
	s_add_u32 s0, s40, 0x160000
	s_addc_u32 s1, s41, 0
	s_add_i32 s4, s62, s51
	v_lshl_add_u64 v[144:145], s[0:1], 0, v[130:131]
	s_mov_b32 m0, s4
	s_nop 0
	global_load_lds_dwordx4 v[144:145], off
	v_lshl_add_u64 v[144:145], s[0:1], 0, v[134:135]
	s_add_i32 m0, s4, 0x2000
	s_nop 0
	global_load_lds_dwordx4 v[144:145], off
	s_waitcnt vmcnt(6)
	s_barrier
	s_setprio 1
	v_mfma_f32_16x16x32_bf16 v[52:55], v[222:225], v[172:175], v[52:55]
	v_mfma_f32_16x16x32_bf16 v[48:51], v[230:233], v[172:175], v[48:51]
	v_mfma_f32_16x16x32_bf16 v[36:39], v[222:225], v[180:183], v[36:39]
	v_mfma_f32_16x16x32_bf16 v[32:35], v[230:233], v[180:183], v[32:35]
	v_mfma_f32_16x16x32_bf16 v[20:23], v[222:225], v[206:209], v[20:23]
	v_mfma_f32_16x16x32_bf16 v[16:19], v[230:233], v[206:209], v[16:19]
	v_mfma_f32_16x16x32_bf16 v[4:7], v[222:225], v[214:217], v[4:7]
	v_mfma_f32_16x16x32_bf16 v[0:3], v[230:233], v[214:217], v[0:3]
	v_mfma_f32_16x16x32_bf16 v[52:55], v[226:229], v[176:179], v[52:55]
	v_mfma_f32_16x16x32_bf16 v[48:51], v[234:237], v[176:179], v[48:51]
	v_mfma_f32_16x16x32_bf16 v[36:39], v[226:229], v[188:191], v[36:39]
	v_mfma_f32_16x16x32_bf16 v[32:35], v[234:237], v[188:191], v[32:35]
	v_mfma_f32_16x16x32_bf16 v[20:23], v[226:229], v[210:213], v[20:23]
	v_mfma_f32_16x16x32_bf16 v[16:19], v[234:237], v[210:213], v[16:19]
	v_mfma_f32_16x16x32_bf16 v[4:7], v[226:229], v[218:221], v[4:7]
	v_mfma_f32_16x16x32_bf16 v[0:3], v[234:237], v[218:221], v[0:3]
	s_setprio 0
	s_add_i32 s4, 0, 0x18000
	v_add_u32_e32 v159, s4, v154
	s_barrier
	ds_read_b128 v[144:147], v159
	ds_read_b128 v[160:163], v159 offset:1024
	ds_read_b128 v[164:167], v159 offset:2048
	ds_read_b128 v[168:171], v159 offset:3072
	s_add_u32 s0, s42, 0x160000
	s_addc_u32 s1, s43, 0
	s_mov_b32 m0, s54
	v_lshl_add_u64 v[222:223], s[0:1], 0, v[128:129]
	ds_read_b128 v[172:175], v156 offset:32768
	ds_read_b128 v[176:179], v156 offset:33792
	ds_read_b128 v[180:183], v156 offset:34816
	ds_read_b128 v[188:191], v156 offset:35840
	ds_read_b128 v[206:209], v156 offset:36864
	ds_read_b128 v[210:213], v156 offset:37888
	ds_read_b128 v[214:217], v156 offset:38912
	ds_read_b128 v[218:221], v156 offset:39936
	global_load_lds_dwordx4 v[222:223], off
	v_lshl_add_u64 v[222:223], s[0:1], 0, v[132:133]
	s_mov_b32 m0, s55
	s_nop 0
	global_load_lds_dwordx4 v[222:223], off
	s_waitcnt lgkmcnt(8)
	s_barrier
	s_waitcnt lgkmcnt(0)
	s_setprio 1
	s_waitcnt lgkmcnt(0)
	v_mfma_f32_16x16x32_bf16 v[124:127], v[144:147], v[172:175], v[124:127]
	v_mfma_f32_16x16x32_bf16 v[120:123], v[164:167], v[172:175], v[120:123]
	v_mfma_f32_16x16x32_bf16 v[108:111], v[144:147], v[180:183], v[108:111]
	v_mfma_f32_16x16x32_bf16 v[104:107], v[164:167], v[180:183], v[104:107]
	v_mfma_f32_16x16x32_bf16 v[92:95], v[144:147], v[206:209], v[92:95]
	v_mfma_f32_16x16x32_bf16 v[88:91], v[164:167], v[206:209], v[88:91]
	v_mfma_f32_16x16x32_bf16 v[76:79], v[144:147], v[214:217], v[76:79]
	v_mfma_f32_16x16x32_bf16 v[72:75], v[164:167], v[214:217], v[72:75]
	v_mfma_f32_16x16x32_bf16 v[124:127], v[160:163], v[176:179], v[124:127]
	v_mfma_f32_16x16x32_bf16 v[120:123], v[168:171], v[176:179], v[120:123]
	v_mfma_f32_16x16x32_bf16 v[108:111], v[160:163], v[188:191], v[108:111]
	v_mfma_f32_16x16x32_bf16 v[104:107], v[168:171], v[188:191], v[104:107]
	v_mfma_f32_16x16x32_bf16 v[92:95], v[160:163], v[210:213], v[92:95]
	v_mfma_f32_16x16x32_bf16 v[88:91], v[168:171], v[210:213], v[88:91]
	v_mfma_f32_16x16x32_bf16 v[76:79], v[160:163], v[218:221], v[76:79]
	v_mfma_f32_16x16x32_bf16 v[72:75], v[168:171], v[218:221], v[72:75]
	s_setprio 0
	s_barrier
	s_add_i32 s5, 0, 0x1c000
	s_add_i32 s0, s4, s51
	v_add_u32_e32 v159, s5, v154
	v_lshl_add_u64 v[202:203], v[202:203], 0, s[36:37]
	s_mov_b32 m0, s0
	ds_read_b128 v[222:225], v159
	ds_read_b128 v[226:229], v159 offset:1024
	ds_read_b128 v[230:233], v159 offset:2048
	ds_read_b128 v[234:237], v159 offset:3072
	global_load_lds_dwordx4 v[202:203], off
	v_lshl_add_u64 v[202:203], v[238:239], 0, s[36:37]
	s_add_i32 m0, s0, 0x2000
	s_nop 0
	global_load_lds_dwordx4 v[202:203], off
	s_barrier
	s_waitcnt lgkmcnt(0)
	s_setprio 1
	s_waitcnt lgkmcnt(0)
	v_mfma_f32_16x16x32_bf16 v[116:119], v[222:225], v[172:175], v[116:119]
	v_mfma_f32_16x16x32_bf16 v[112:115], v[230:233], v[172:175], v[112:115]
	v_mfma_f32_16x16x32_bf16 v[100:103], v[222:225], v[180:183], v[100:103]
	v_mfma_f32_16x16x32_bf16 v[96:99], v[230:233], v[180:183], v[96:99]
	v_mfma_f32_16x16x32_bf16 v[84:87], v[222:225], v[206:209], v[84:87]
	v_mfma_f32_16x16x32_bf16 v[80:83], v[230:233], v[206:209], v[80:83]
	v_mfma_f32_16x16x32_bf16 v[68:71], v[222:225], v[214:217], v[68:71]
	v_mfma_f32_16x16x32_bf16 v[64:67], v[230:233], v[214:217], v[64:67]
	v_mfma_f32_16x16x32_bf16 v[116:119], v[226:229], v[176:179], v[116:119]
	v_mfma_f32_16x16x32_bf16 v[112:115], v[234:237], v[176:179], v[112:115]
	v_mfma_f32_16x16x32_bf16 v[100:103], v[226:229], v[188:191], v[100:103]
	v_mfma_f32_16x16x32_bf16 v[96:99], v[234:237], v[188:191], v[96:99]
	v_mfma_f32_16x16x32_bf16 v[84:87], v[226:229], v[210:213], v[84:87]
	v_mfma_f32_16x16x32_bf16 v[80:83], v[234:237], v[210:213], v[80:83]
	v_mfma_f32_16x16x32_bf16 v[68:71], v[226:229], v[218:221], v[68:71]
	v_mfma_f32_16x16x32_bf16 v[64:67], v[234:237], v[218:221], v[64:67]
	s_setprio 0
	s_mov_b32 m0, s59
	v_lshl_add_u64 v[202:203], v[240:241], 0, s[36:37]
	s_barrier
	ds_read_b128 v[172:175], v156 offset:49152
	ds_read_b128 v[176:179], v156 offset:50176
	ds_read_b128 v[180:183], v156 offset:51200
	ds_read_b128 v[188:191], v156 offset:52224
	ds_read_b128 v[206:209], v156 offset:53248
	ds_read_b128 v[210:213], v156 offset:54272
	ds_read_b128 v[214:217], v156 offset:55296
	ds_read_b128 v[218:221], v156 offset:56320
	global_load_lds_dwordx4 v[202:203], off
	v_lshl_add_u64 v[202:203], v[242:243], 0, s[36:37]
	s_mov_b32 m0, s60
	s_nop 0
	global_load_lds_dwordx4 v[202:203], off
	s_barrier
; DI float bf_lo(unsigned u) { return __uint_as_float(u << 16); }
; DI float bf_hi(unsigned u) { return __uint_as_float(u & 0xffff0000u); }
; DI u32x4 pack8(f32x4 a, f32x4 b) { u32x4 w; w.x = cvt_pk_bf16(a[0], a[1]); w.y = cvt_pk_bf16(a[2], a[3]); w.z = cvt_pk_bf16(b[0], b[1]); w.w = cvt_pk_bf16(b[2], b[3]); return w; }
; #define PG8_STAGE(bufoff, gbase, voff) do { _Pragma("unroll") for (int _i = 0; _i < 2; ++_i) \
;         __builtin_amdgcn_global_load_lds((const unsigned*)((const char*)(gbase) + (voff)[_i]), (LAS unsigned*)(lds + (bufoff) + ldsw + _i * 8192), 16, 0, 0); } while (0)
; #define PG8_MMA(ai, bj, At, Bt) do { __builtin_amdgcn_s_setprio(1); _Pragma("unroll") for (int m = 0; m < 4; ++m) _Pragma("unroll") for (int n = 0; n < 2; ++n) _Pragma("unroll") for (int k = 0; k < 2; ++k) \
;         acc[ai][bj][m][n] = __builtin_amdgcn_mfma_f32_16x16x32_bf16(Bt[n][k], At[m][k], acc[ai][bj][m][n], 0, 0, 0); __builtin_amdgcn_s_setprio(0); } while (0)
; #define PG8_WAIT_V(n) asm volatile("s_waitcnt vmcnt(" #n ")" ::: "memory")
; #define PG8_WAIT_L(n) asm volatile("s_waitcnt lgkmcnt(" #n ")" ::: "memory")
; template <class Epi, class Sched>
; DI void gemm_phase(LAS unsigned char* lds, const Gemm g, const Sched& S, const Epi& E) {
;     ...
;             PG8_BAR; PG8_WAIT_L(0); PG8_MMA(1, 0, At, B0); PG8_BAR; PG8_SCHED;
;             PG8_STAGE(PG8_SB(1, 1), b3 + hstep, voffB);
;             PG8_WAIT_V(6); PG8_BAR; PG8_MMA(1, 1, At, B1); PG8_BAR;
;         }
;     DI void operator()(AccRef acc, const Unit& u, int wr, int wc, int fr, int fq) const {
;     ...
;             for (int m = 0; m < 4; ++m) { const int row = u.pm * 256 + ai * 128 + wr * 64 + m * 16 + fr; const size_t off = (size_t)row * DM + col0; float q = 0.f;
; #pragma unroll
;                 for (int bj = 0; bj < 2; ++bj) {
;                     f32x4 b0, b1;
;                     if (F32BASE) { b0 = *(const f32x4*)(bp + off + bj * 128); b1 = *(const f32x4*)(bp + off + bj * 128 + 4); }
;                     else { const u32x4 uv = *(const u32x4*)(Ui + off + bj * 128); b0 = (f32x4){bf_lo(uv.x), bf_hi(uv.x), bf_lo(uv.y), bf_hi(uv.y)}; b1 = (f32x4){bf_lo(uv.z), bf_hi(uv.z), bf_lo(uv.w), bf_hi(uv.w)}; }
;                     const u32x4 w = pack8(b0 + acc[ai][bj][m][0] * (0.5f * S2), b1 + acc[ai][bj][m][1] * (0.5f * S2));
;                     *(u32x4*)(Uo + (size_t)row * ldo + col0 + bj * 128) = w;
	s_waitcnt lgkmcnt(0)
	s_setprio 1
	s_waitcnt lgkmcnt(0)
	v_mfma_f32_16x16x32_bf16 v[60:63], v[144:147], v[172:175], v[60:63]
	v_mfma_f32_16x16x32_bf16 v[56:59], v[164:167], v[172:175], v[56:59]
	v_mfma_f32_16x16x32_bf16 v[44:47], v[144:147], v[180:183], v[44:47]
	v_mfma_f32_16x16x32_bf16 v[40:43], v[164:167], v[180:183], v[40:43]
	v_mfma_f32_16x16x32_bf16 v[28:31], v[144:147], v[206:209], v[28:31]
	v_mfma_f32_16x16x32_bf16 v[24:27], v[164:167], v[206:209], v[24:27]
	v_mfma_f32_16x16x32_bf16 v[12:15], v[144:147], v[214:217], v[12:15]
	v_mfma_f32_16x16x32_bf16 v[8:11], v[164:167], v[214:217], v[8:11]
	v_mfma_f32_16x16x32_bf16 v[60:63], v[160:163], v[176:179], v[60:63]
	v_mfma_f32_16x16x32_bf16 v[56:59], v[168:171], v[176:179], v[56:59]
	v_mfma_f32_16x16x32_bf16 v[44:47], v[160:163], v[188:191], v[44:47]
	v_mfma_f32_16x16x32_bf16 v[40:43], v[168:171], v[188:191], v[40:43]
	v_mfma_f32_16x16x32_bf16 v[28:31], v[160:163], v[210:213], v[28:31]
	v_mfma_f32_16x16x32_bf16 v[24:27], v[168:171], v[210:213], v[24:27]
	v_mfma_f32_16x16x32_bf16 v[12:15], v[160:163], v[218:221], v[12:15]
	v_mfma_f32_16x16x32_bf16 v[8:11], v[168:171], v[218:221], v[8:11]
	s_setprio 0
	s_barrier
	s_add_u32 s0, s40, 0x160080
	s_addc_u32 s1, s41, 0
	s_add_i32 s4, s5, s51
	v_lshl_add_u64 v[144:145], s[0:1], 0, v[130:131]
	s_mov_b32 m0, s4
	s_nop 0
	global_load_lds_dwordx4 v[144:145], off
	v_lshl_add_u64 v[144:145], s[0:1], 0, v[134:135]
	s_add_i32 m0, s4, 0x2000
	s_nop 0
	global_load_lds_dwordx4 v[144:145], off
	s_waitcnt vmcnt(6)
	s_barrier
	s_setprio 1
	v_mfma_f32_16x16x32_bf16 v[52:55], v[222:225], v[172:175], v[52:55]
	v_mfma_f32_16x16x32_bf16 v[48:51], v[230:233], v[172:175], v[48:51]
	v_mfma_f32_16x16x32_bf16 v[36:39], v[222:225], v[180:183], v[36:39]
	v_mfma_f32_16x16x32_bf16 v[32:35], v[230:233], v[180:183], v[32:35]
	v_mfma_f32_16x16x32_bf16 v[20:23], v[222:225], v[206:209], v[20:23]
	v_mfma_f32_16x16x32_bf16 v[16:19], v[230:233], v[206:209], v[16:19]
	v_mfma_f32_16x16x32_bf16 v[4:7], v[222:225], v[214:217], v[4:7]
	v_mfma_f32_16x16x32_bf16 v[0:3], v[230:233], v[214:217], v[0:3]
	v_mfma_f32_16x16x32_bf16 v[52:55], v[226:229], v[176:179], v[52:55]
	v_mfma_f32_16x16x32_bf16 v[48:51], v[234:237], v[176:179], v[48:51]
	v_mfma_f32_16x16x32_bf16 v[36:39], v[226:229], v[188:191], v[36:39]
	v_mfma_f32_16x16x32_bf16 v[32:35], v[234:237], v[188:191], v[32:35]
	v_mfma_f32_16x16x32_bf16 v[20:23], v[226:229], v[210:213], v[20:23]
	v_mfma_f32_16x16x32_bf16 v[16:19], v[234:237], v[210:213], v[16:19]
	v_mfma_f32_16x16x32_bf16 v[4:7], v[226:229], v[218:221], v[4:7]
	v_mfma_f32_16x16x32_bf16 v[0:3], v[234:237], v[218:221], v[0:3]
	s_setprio 0
	s_add_i32 s68, s68, 2
	s_add_u32 s38, s38, 0x100
	s_addc_u32 s39, s39, 0
	s_add_u32 s35, s35, 0x100
	s_addc_u32 s67, s67, 0
	s_cmpk_gt_u32 s68, 0x55
	s_barrier
	s_cbranch_scc0 .LBB0_1746
	s_lshl_b32 s0, s16, 8
	v_mov_b32_e32 v145, v194
	v_mov_b32_e32 v159, v192
	s_or_b32 s0, s0, s58
	s_lshl_b32 s38, s16, 2
	v_lshl_add_u32 v144, v159, 3, s0
	s_lshl_b32 s0, s34, 8
	s_add_i32 s0, s0, s57
	v_add_u32_e32 v146, s0, v145
	v_ashrrev_i32_e32 v147, 31, v146
	v_ashrrev_i32_e32 v145, 31, v144
	v_lshlrev_b64 v[160:161], 12, v[146:147]
	v_lshl_add_u64 v[160:161], s[18:19], 0, v[160:161]
	v_lshlrev_b64 v[144:145], 1, v[144:145]
	v_lshl_add_u64 v[164:165], v[160:161], 0, v[144:145]
	v_mov_b64_e32 v[182:183], v[164:165]
	s_mov_b32 s43, 0
	global_load_dwordx4 v[170:173], v[182:183], off
	global_load_dwordx4 v[174:177], v[182:183], off offset:256
	s_mov_b32 s42, 0x10000
	v_lshl_add_u64 v[182:183], v[182:183], 0, s[42:43]
	global_load_dwordx4 v[178:181], v[182:183], off
	global_load_dwordx4 v[188:191], v[182:183], off offset:256
	s_mov_b32 s42, 0x10000
	v_lshl_add_u64 v[182:183], v[182:183], 0, s[42:43]
	global_load_dwordx4 v[206:209], v[182:183], off
	global_load_dwordx4 v[210:213], v[182:183], off offset:256
	s_mov_b32 s42, 0x10000
	v_lshl_add_u64 v[182:183], v[182:183], 0, s[42:43]
	global_load_dwordx4 v[214:217], v[182:183], off
	global_load_dwordx4 v[218:221], v[182:183], off offset:256
	s_mov_b32 s42, 0x50000
	v_lshl_add_u64 v[182:183], v[182:183], 0, s[42:43]
	global_load_dwordx4 v[222:225], v[182:183], off
	global_load_dwordx4 v[226:229], v[182:183], off offset:256
	s_mov_b32 s42, 0x10000
	v_lshl_add_u64 v[182:183], v[182:183], 0, s[42:43]
	global_load_dwordx4 v[230:233], v[182:183], off
	global_load_dwordx4 v[234:237], v[182:183], off offset:256
	s_mov_b32 s42, 0x10000
	v_lshl_add_u64 v[182:183], v[182:183], 0, s[42:43]
	global_load_dwordx4 v[238:241], v[182:183], off
	v_mov_b64_e32 v[202:203], v[182:183]
	s_mov_b32 s42, 0x10000
	v_lshl_add_u64 v[202:203], v[202:203], 0, s[42:43]
	global_load_dword v201, v[202:203], off
	global_load_dword v201, v[202:203], off offset:256
	s_waitcnt vmcnt(14)
	v_mov_b64_e32 v[160:161], v[170:171]
	v_mov_b64_e32 v[162:163], v[172:173]
	global_load_dwordx4 v[170:173], v[182:183], off offset:256
	s_ashr_i32 s39, s38, 31
	v_lshlrev_b32_e32 v166, 16, v160
	v_and_b32_e32 v167, 0xffff0000, v160
	v_lshlrev_b32_e32 v160, 16, v161
	v_and_b32_e32 v161, 0xffff0000, v161
	v_lshlrev_b32_e32 v168, 16, v162
	v_and_b32_e32 v169, 0xffff0000, v162
	v_lshlrev_b32_e32 v162, 16, v163
	v_and_b32_e32 v163, 0xffff0000, v163
	v_pk_fma_f32 v[126:127], v[126:127], 0.5, v[160:161] op_sel_hi:[1,0,1]
	v_pk_fma_f32 v[124:125], v[124:125], 0.5, v[166:167] op_sel_hi:[1,0,1]
	v_pk_fma_f32 v[160:161], v[122:123], 0.5, v[162:163] op_sel_hi:[1,0,1]
	v_pk_fma_f32 v[120:121], v[120:121], 0.5, v[168:169] op_sel_hi:[1,0,1]
	v_cvt_pk_bf16_f32 v122, v124, v125
	v_cvt_pk_bf16_f32 v123, v126, v127
	v_and_b32_e32 v127, 64, v158
	v_cvt_pk_bf16_f32 v124, v120, v121
	v_cvt_pk_bf16_f32 v125, v160, v161
	s_waitcnt vmcnt(14)
; DI float bf_lo(unsigned u) { return __uint_as_float(u << 16); }
; DI float bf_hi(unsigned u) { return __uint_as_float(u & 0xffff0000u); }
; DI u32x4 pack8(f32x4 a, f32x4 b) { u32x4 w; w.x = cvt_pk_bf16(a[0], a[1]); w.y = cvt_pk_bf16(a[2], a[3]); w.z = cvt_pk_bf16(b[0], b[1]); w.w = cvt_pk_bf16(b[2], b[3]); return w; }
;     DI void operator()(AccRef acc, const Unit& u, int wr, int wc, int fr, int fq) const {
;     ...
;             for (int m = 0; m < 4; ++m) { const int row = u.pm * 256 + ai * 128 + wr * 64 + m * 16 + fr; const size_t off = (size_t)row * DM + col0; float q = 0.f;
; #pragma unroll
;                 for (int bj = 0; bj < 2; ++bj) {
;                     f32x4 b0, b1;
;                     if (F32BASE) { b0 = *(const f32x4*)(bp + off + bj * 128); b1 = *(const f32x4*)(bp + off + bj * 128 + 4); }
;                     else { const u32x4 uv = *(const u32x4*)(Ui + off + bj * 128); b0 = (f32x4){bf_lo(uv.x), bf_hi(uv.x), bf_lo(uv.y), bf_hi(uv.y)}; b1 = (f32x4){bf_lo(uv.z), bf_hi(uv.z), bf_lo(uv.w), bf_hi(uv.w)}; }
;                     const u32x4 w = pack8(b0 + acc[ai][bj][m][0] * (0.5f * S2), b1 + acc[ai][bj][m][1] * (0.5f * S2));
;                     *(u32x4*)(Uo + (size_t)row * ldo + col0 + bj * 128) = w;
;                     const float r0 = bf_lo(w.x), r1 = bf_hi(w.x), r2 = bf_lo(w.y), r3 = bf_hi(w.y), r4 = bf_lo(w.z), r5 = bf_hi(w.z), r6 = bf_lo(w.w), r7 = bf_hi(w.w);
;                     q += (r0 * r0 + r1 * r1) + (r2 * r2 + r3 * r3) + (r4 * r4 + r5 * r5) + (r6 * r6 + r7 * r7); }
;                 q += __shfl_xor(q, 16); q += __shfl_xor(q, 32); if (fq == 0) ssp[(size_t)row * 32 + u.pn * 4 + wc] = q; }
	v_mov_b64_e32 v[160:161], v[174:175]
	v_mov_b64_e32 v[162:163], v[176:177]
	s_mov_b32 s42, 0x10000
	v_lshl_add_u64 v[182:183], v[182:183], 0, s[42:43]
	global_load_dwordx4 v[174:177], v[182:183], off
	v_xor_b32_e32 v126, 16, v158
	v_add_u32_e32 v164, 64, v127
	v_mov_b64_e32 v[120:121], s[28:29]
	v_cmp_lt_i32_e32 vcc, v126, v164
	v_lshlrev_b32_e32 v166, 16, v124
	v_lshlrev_b32_e32 v167, 16, v125
	v_cndmask_b32_e32 v165, v158, v126, vcc
	v_mad_i64_i32 v[126:127], s[0:1], v146, s63, v[120:121]
	v_lshl_add_u64 v[126:127], v[126:127], 0, v[144:145]
	v_lshlrev_b32_e32 v120, 2, v165
	global_store_dwordx4 v[126:127], v[122:125], off
	v_lshlrev_b32_e32 v121, 16, v122
	v_lshlrev_b32_e32 v165, 16, v123
	v_and_b32_e32 v122, 0xffff0000, v122
	v_and_b32_e32 v123, 0xffff0000, v123
	v_and_b32_e32 v124, 0xffff0000, v124
	v_mul_f32_e32 v122, v122, v122
	v_mul_f32_e32 v123, v123, v123
	v_and_b32_e32 v125, 0xffff0000, v125
	v_mul_f32_e32 v124, v124, v124
	v_fmac_f32_e32 v122, v121, v121
	v_fmac_f32_e32 v123, v165, v165
	v_mul_f32_e32 v125, v125, v125
	v_fmac_f32_e32 v124, v166, v166
	v_add_f32_e32 v121, v122, v123
	v_fmac_f32_e32 v125, v167, v167
	v_add_f32_e32 v121, v121, v124
	v_add_f32_e32 v121, v121, v125
	v_lshlrev_b32_e32 v122, 16, v160
	v_and_b32_e32 v123, 0xffff0000, v160
	v_lshlrev_b32_e32 v124, 16, v161
	v_and_b32_e32 v125, 0xffff0000, v161
	v_lshlrev_b32_e32 v160, 16, v162
	v_and_b32_e32 v161, 0xffff0000, v162
	v_lshlrev_b32_e32 v162, 16, v163
	v_and_b32_e32 v163, 0xffff0000, v163
	v_pk_fma_f32 v[118:119], v[118:119], 0.5, v[124:125] op_sel_hi:[1,0,1]
	v_pk_fma_f32 v[116:117], v[116:117], 0.5, v[122:123] op_sel_hi:[1,0,1]
	v_pk_fma_f32 v[114:115], v[114:115], 0.5, v[162:163] op_sel_hi:[1,0,1]
	v_pk_fma_f32 v[112:113], v[112:113], 0.5, v[160:161] op_sel_hi:[1,0,1]
	v_cvt_pk_bf16_f32 v116, v116, v117
	v_cvt_pk_bf16_f32 v117, v118, v119
	s_nop 0
	v_cvt_pk_bf16_f32 v118, v112, v113
	v_cvt_pk_bf16_f32 v119, v114, v115
	v_and_b32_e32 v113, 0xffff0000, v116
	v_and_b32_e32 v115, 0xffff0000, v117
	v_lshlrev_b32_e32 v112, 16, v116
	v_lshlrev_b32_e32 v114, 16, v117
	v_and_b32_e32 v123, 0xffff0000, v118
	v_mul_f32_e32 v113, v113, v113
	v_mul_f32_e32 v115, v115, v115
	v_lshlrev_b32_e32 v122, 16, v118
	v_and_b32_e32 v125, 0xffff0000, v119
	v_mul_f32_e32 v123, v123, v123
	v_fmac_f32_e32 v113, v112, v112
	v_fmac_f32_e32 v115, v114, v114
	v_lshlrev_b32_e32 v124, 16, v119
	v_mul_f32_e32 v125, v125, v125
	v_fmac_f32_e32 v123, v122, v122
	v_add_f32_e32 v112, v113, v115
	v_fmac_f32_e32 v125, v124, v124
	v_add_f32_e32 v112, v112, v123
	v_add_f32_e32 v112, v112, v125
	v_add_f32_e32 v112, v121, v112
	ds_bpermute_b32 v113, v120, v112
	v_xor_b32_e32 v114, 32, v158
	v_cmp_lt_i32_e32 vcc, v114, v164
	global_store_dwordx4 v[126:127], v[116:119], off offset:256
	s_waitcnt lgkmcnt(0)
	v_add_f32_e32 v112, v112, v113
	v_cndmask_b32_e32 v114, v158, v114, vcc
	v_lshlrev_b32_e32 v114, 2, v114
	ds_bpermute_b32 v113, v114, v112
	v_cmp_eq_u32_e32 vcc, 0, v159
	s_and_saveexec_b64 s[40:41], vcc
	s_cbranch_execz .LBB0_1749
	v_lshlrev_b64 v[116:117], 7, v[146:147]
	v_lshl_add_u64 v[116:117], s[30:31], 0, v[116:117]
	v_lshl_add_u64 v[116:117], s[38:39], 2, v[116:117]
	s_lshl_b32 s16, s56, 2
	v_lshl_add_u64 v[116:117], v[116:117], 0, s[16:17]
	s_waitcnt lgkmcnt(0)
	v_add_f32_e32 v112, v112, v113
	global_store_dword v[116:117], v112, off
.LBB0_1749:
	s_or_b64 exec, exec, s[40:41]
	v_add_u32_e32 v112, 16, v146
	s_waitcnt lgkmcnt(0)
	v_ashrrev_i32_e32 v113, 31, v112
	v_lshlrev_b64 v[116:117], 12, v[112:113]
	v_lshl_add_u64 v[116:117], s[18:19], 0, v[116:117]
	v_lshl_add_u64 v[122:123], v[116:117], 0, v[144:145]
	s_waitcnt vmcnt(16)
	v_mov_b64_e32 v[116:117], v[178:179]
	v_mov_b64_e32 v[118:119], v[180:181]
	global_load_dwordx4 v[178:181], v[182:183], off offset:256
	v_lshlrev_b32_e32 v124, 16, v116
	v_and_b32_e32 v125, 0xffff0000, v116
	v_lshlrev_b32_e32 v116, 16, v117
	v_and_b32_e32 v117, 0xffff0000, v117
	v_lshlrev_b32_e32 v126, 16, v118
	v_and_b32_e32 v127, 0xffff0000, v118
	v_lshlrev_b32_e32 v118, 16, v119
	v_and_b32_e32 v119, 0xffff0000, v119
	v_pk_fma_f32 v[110:111], v[110:111], 0.5, v[116:117] op_sel_hi:[1,0,1]
	v_pk_fma_f32 v[108:109], v[108:109], 0.5, v[124:125] op_sel_hi:[1,0,1]
	v_pk_fma_f32 v[116:117], v[106:107], 0.5, v[118:119] op_sel_hi:[1,0,1]
	v_pk_fma_f32 v[106:107], v[104:105], 0.5, v[126:127] op_sel_hi:[1,0,1]
	v_cvt_pk_bf16_f32 v104, v108, v109
	v_cvt_pk_bf16_f32 v105, v110, v111
	s_nop 0
	v_cvt_pk_bf16_f32 v106, v106, v107
	v_cvt_pk_bf16_f32 v107, v116, v117
	s_waitcnt vmcnt(16)
; DI float bf_lo(unsigned u) { return __uint_as_float(u << 16); }
; DI float bf_hi(unsigned u) { return __uint_as_float(u & 0xffff0000u); }
; DI u32x4 pack8(f32x4 a, f32x4 b) { u32x4 w; w.x = cvt_pk_bf16(a[0], a[1]); w.y = cvt_pk_bf16(a[2], a[3]); w.z = cvt_pk_bf16(b[0], b[1]); w.w = cvt_pk_bf16(b[2], b[3]); return w; }
;     DI void operator()(AccRef acc, const Unit& u, int wr, int wc, int fr, int fq) const {
;     ...
;             for (int m = 0; m < 4; ++m) { const int row = u.pm * 256 + ai * 128 + wr * 64 + m * 16 + fr; const size_t off = (size_t)row * DM + col0; float q = 0.f;
; #pragma unroll
;                 for (int bj = 0; bj < 2; ++bj) {
;                     f32x4 b0, b1;
;                     if (F32BASE) { b0 = *(const f32x4*)(bp + off + bj * 128); b1 = *(const f32x4*)(bp + off + bj * 128 + 4); }
;                     else { const u32x4 uv = *(const u32x4*)(Ui + off + bj * 128); b0 = (f32x4){bf_lo(uv.x), bf_hi(uv.x), bf_lo(uv.y), bf_hi(uv.y)}; b1 = (f32x4){bf_lo(uv.z), bf_hi(uv.z), bf_lo(uv.w), bf_hi(uv.w)}; }
;                     const u32x4 w = pack8(b0 + acc[ai][bj][m][0] * (0.5f * S2), b1 + acc[ai][bj][m][1] * (0.5f * S2));
;                     *(u32x4*)(Uo + (size_t)row * ldo + col0 + bj * 128) = w;
;                     const float r0 = bf_lo(w.x), r1 = bf_hi(w.x), r2 = bf_lo(w.y), r3 = bf_hi(w.y), r4 = bf_lo(w.z), r5 = bf_hi(w.z), r6 = bf_lo(w.w), r7 = bf_hi(w.w);
;                     q += (r0 * r0 + r1 * r1) + (r2 * r2 + r3 * r3) + (r4 * r4 + r5 * r5) + (r6 * r6 + r7 * r7); }
;                 q += __shfl_xor(q, 16); q += __shfl_xor(q, 32); if (fq == 0) ssp[(size_t)row * 32 + u.pn * 4 + wc] = q; }
	v_mov_b64_e32 v[108:109], v[188:189]
	v_mov_b64_e32 v[110:111], v[190:191]
	v_mov_b64_e32 v[116:117], s[28:29]
	v_mad_i64_i32 v[116:117], s[0:1], v112, s63, v[116:117]
	v_lshl_add_u64 v[116:117], v[116:117], 0, v[144:145]
	global_store_dwordx4 v[116:117], v[104:107], off
	v_lshlrev_b32_e32 v115, 16, v104
	v_lshlrev_b32_e32 v118, 16, v105
	v_and_b32_e32 v104, 0xffff0000, v104
	v_and_b32_e32 v105, 0xffff0000, v105
	v_lshlrev_b32_e32 v119, 16, v106
	v_and_b32_e32 v106, 0xffff0000, v106
	v_mul_f32_e32 v104, v104, v104
	v_mul_f32_e32 v105, v105, v105
	v_lshlrev_b32_e32 v121, 16, v107
	v_and_b32_e32 v107, 0xffff0000, v107
	v_mul_f32_e32 v106, v106, v106
	v_fmac_f32_e32 v104, v115, v115
	v_fmac_f32_e32 v105, v118, v118
	v_mul_f32_e32 v107, v107, v107
	v_fmac_f32_e32 v106, v119, v119
	v_add_f32_e32 v104, v104, v105
	v_fmac_f32_e32 v107, v121, v121
	v_add_f32_e32 v104, v104, v106
	v_add_f32_e32 v115, v104, v107
	v_lshlrev_b32_e32 v104, 16, v108
	v_and_b32_e32 v105, 0xffff0000, v108
	v_lshlrev_b32_e32 v106, 16, v109
	v_and_b32_e32 v107, 0xffff0000, v109
	v_lshlrev_b32_e32 v108, 16, v110
	v_and_b32_e32 v109, 0xffff0000, v110
	v_lshlrev_b32_e32 v110, 16, v111
	v_and_b32_e32 v111, 0xffff0000, v111
	v_pk_fma_f32 v[102:103], v[102:103], 0.5, v[106:107] op_sel_hi:[1,0,1]
	v_pk_fma_f32 v[100:101], v[100:101], 0.5, v[104:105] op_sel_hi:[1,0,1]
	v_pk_fma_f32 v[96:97], v[96:97], 0.5, v[108:109] op_sel_hi:[1,0,1]
	v_pk_fma_f32 v[104:105], v[98:99], 0.5, v[110:111] op_sel_hi:[1,0,1]
	v_cvt_pk_bf16_f32 v98, v100, v101
	v_cvt_pk_bf16_f32 v99, v102, v103
	v_cvt_pk_bf16_f32 v100, v96, v97
	s_nop 0
	v_and_b32_e32 v97, 0xffff0000, v98
	v_and_b32_e32 v103, 0xffff0000, v99
	v_cvt_pk_bf16_f32 v101, v104, v105
	v_lshlrev_b32_e32 v96, 16, v98
	v_lshlrev_b32_e32 v102, 16, v99
	v_and_b32_e32 v105, 0xffff0000, v100
	v_mul_f32_e32 v97, v97, v97
	v_mul_f32_e32 v103, v103, v103
	v_lshlrev_b32_e32 v104, 16, v100
	v_and_b32_e32 v107, 0xffff0000, v101
	v_mul_f32_e32 v105, v105, v105
	v_fmac_f32_e32 v97, v96, v96
	v_fmac_f32_e32 v103, v102, v102
	v_lshlrev_b32_e32 v106, 16, v101
	v_mul_f32_e32 v107, v107, v107
	v_fmac_f32_e32 v105, v104, v104
	v_add_f32_e32 v96, v97, v103
	v_add_f32_e32 v96, v96, v105
	v_fmac_f32_e32 v107, v106, v106
	v_add_f32_e32 v96, v96, v107
	v_add_f32_e32 v96, v115, v96
	ds_bpermute_b32 v97, v120, v96
	global_store_dwordx4 v[116:117], v[98:101], off offset:256
	s_waitcnt lgkmcnt(0)
	v_add_f32_e32 v96, v96, v97
	ds_bpermute_b32 v97, v114, v96
	s_and_saveexec_b64 s[40:41], vcc
	s_cbranch_execz .LBB0_1751
	v_lshlrev_b64 v[98:99], 7, v[112:113]
	v_lshl_add_u64 v[98:99], s[30:31], 0, v[98:99]
	v_lshl_add_u64 v[98:99], s[38:39], 2, v[98:99]
	s_lshl_b32 s16, s56, 2
	v_lshl_add_u64 v[98:99], v[98:99], 0, s[16:17]
	s_waitcnt lgkmcnt(0)
	v_add_f32_e32 v96, v96, v97
	global_store_dword v[98:99], v96, off
.LBB0_1751:
	s_or_b64 exec, exec, s[40:41]
	v_add_u32_e32 v96, 32, v146
	s_waitcnt lgkmcnt(0)
	v_ashrrev_i32_e32 v97, 31, v96
	v_lshlrev_b64 v[98:99], 12, v[96:97]
	v_lshl_add_u64 v[98:99], s[18:19], 0, v[98:99]
	v_lshl_add_u64 v[102:103], v[98:99], 0, v[144:145]
	s_waitcnt vmcnt(17)
	v_mov_b64_e32 v[98:99], v[206:207]
	v_mov_b64_e32 v[100:101], v[208:209]
	v_lshlrev_b32_e32 v104, 16, v98
	v_and_b32_e32 v105, 0xffff0000, v98
	v_lshlrev_b32_e32 v98, 16, v99
	v_and_b32_e32 v99, 0xffff0000, v99
	v_lshlrev_b32_e32 v106, 16, v100
	v_and_b32_e32 v107, 0xffff0000, v100
	v_lshlrev_b32_e32 v100, 16, v101
	v_and_b32_e32 v101, 0xffff0000, v101
	v_pk_fma_f32 v[94:95], v[94:95], 0.5, v[98:99] op_sel_hi:[1,0,1]
	v_pk_fma_f32 v[92:93], v[92:93], 0.5, v[104:105] op_sel_hi:[1,0,1]
	v_pk_fma_f32 v[98:99], v[90:91], 0.5, v[100:101] op_sel_hi:[1,0,1]
	v_pk_fma_f32 v[90:91], v[88:89], 0.5, v[106:107] op_sel_hi:[1,0,1]
	v_cvt_pk_bf16_f32 v88, v92, v93
	v_cvt_pk_bf16_f32 v89, v94, v95
	s_nop 0
	v_cvt_pk_bf16_f32 v90, v90, v91
	v_cvt_pk_bf16_f32 v91, v98, v99
	s_waitcnt vmcnt(16)
	v_mov_b64_e32 v[92:93], v[210:211]
	v_mov_b64_e32 v[94:95], v[212:213]
	v_mov_b64_e32 v[98:99], s[28:29]
	v_mad_i64_i32 v[98:99], s[0:1], v96, s63, v[98:99]
	v_lshl_add_u64 v[98:99], v[98:99], 0, v[144:145]
	global_store_dwordx4 v[98:99], v[88:91], off
	v_lshlrev_b32_e32 v100, 16, v88
	v_lshlrev_b32_e32 v101, 16, v89
	v_and_b32_e32 v88, 0xffff0000, v88
	v_and_b32_e32 v89, 0xffff0000, v89
	v_lshlrev_b32_e32 v102, 16, v90
	v_and_b32_e32 v90, 0xffff0000, v90
	v_mul_f32_e32 v88, v88, v88
	v_mul_f32_e32 v89, v89, v89
	v_lshlrev_b32_e32 v103, 16, v91
	v_and_b32_e32 v91, 0xffff0000, v91
	v_mul_f32_e32 v90, v90, v90
	v_fmac_f32_e32 v88, v100, v100
	v_fmac_f32_e32 v89, v101, v101
	v_mul_f32_e32 v91, v91, v91
	v_fmac_f32_e32 v90, v102, v102
	v_add_f32_e32 v88, v88, v89
	v_fmac_f32_e32 v91, v103, v103
	v_add_f32_e32 v88, v88, v90
	v_add_f32_e32 v100, v88, v91
	v_lshlrev_b32_e32 v88, 16, v92
	v_and_b32_e32 v89, 0xffff0000, v92
	v_lshlrev_b32_e32 v90, 16, v93
	v_and_b32_e32 v91, 0xffff0000, v93
	v_lshlrev_b32_e32 v92, 16, v94
	v_and_b32_e32 v93, 0xffff0000, v94
	v_lshlrev_b32_e32 v94, 16, v95
	v_and_b32_e32 v95, 0xffff0000, v95
	v_pk_fma_f32 v[86:87], v[86:87], 0.5, v[90:91] op_sel_hi:[1,0,1]
	v_pk_fma_f32 v[84:85], v[84:85], 0.5, v[88:89] op_sel_hi:[1,0,1]
	v_pk_fma_f32 v[80:81], v[80:81], 0.5, v[92:93] op_sel_hi:[1,0,1]
	v_pk_fma_f32 v[88:89], v[82:83], 0.5, v[94:95] op_sel_hi:[1,0,1]
	v_cvt_pk_bf16_f32 v82, v84, v85
	v_cvt_pk_bf16_f32 v83, v86, v87
	v_cvt_pk_bf16_f32 v84, v80, v81
	s_nop 0
	v_and_b32_e32 v81, 0xffff0000, v82
	v_and_b32_e32 v87, 0xffff0000, v83
	v_cvt_pk_bf16_f32 v85, v88, v89
	v_lshlrev_b32_e32 v80, 16, v82
	v_lshlrev_b32_e32 v86, 16, v83
	v_and_b32_e32 v89, 0xffff0000, v84
	v_mul_f32_e32 v81, v81, v81
	v_mul_f32_e32 v87, v87, v87
	v_lshlrev_b32_e32 v88, 16, v84
	v_and_b32_e32 v91, 0xffff0000, v85
	v_mul_f32_e32 v89, v89, v89
	v_fmac_f32_e32 v81, v80, v80
	v_fmac_f32_e32 v87, v86, v86
	v_lshlrev_b32_e32 v90, 16, v85
	v_mul_f32_e32 v91, v91, v91
	v_fmac_f32_e32 v89, v88, v88
	v_add_f32_e32 v80, v81, v87
	v_add_f32_e32 v80, v80, v89
	v_fmac_f32_e32 v91, v90, v90
	v_add_f32_e32 v80, v80, v91
	v_add_f32_e32 v80, v100, v80
	ds_bpermute_b32 v81, v120, v80
	global_store_dwordx4 v[98:99], v[82:85], off offset:256
	s_waitcnt lgkmcnt(0)
	v_add_f32_e32 v80, v80, v81
	ds_bpermute_b32 v81, v114, v80
	s_and_saveexec_b64 s[40:41], vcc
	s_cbranch_execz .LBB0_1753
	v_lshlrev_b64 v[82:83], 7, v[96:97]
	v_lshl_add_u64 v[82:83], s[30:31], 0, v[82:83]
	v_lshl_add_u64 v[82:83], s[38:39], 2, v[82:83]
	s_lshl_b32 s16, s56, 2
	v_lshl_add_u64 v[82:83], v[82:83], 0, s[16:17]
	s_waitcnt lgkmcnt(0)
	v_add_f32_e32 v80, v80, v81
	global_store_dword v[82:83], v80, off
; DI float bf_lo(unsigned u) { return __uint_as_float(u << 16); }
; DI float bf_hi(unsigned u) { return __uint_as_float(u & 0xffff0000u); }
; DI u32x4 pack8(f32x4 a, f32x4 b) { u32x4 w; w.x = cvt_pk_bf16(a[0], a[1]); w.y = cvt_pk_bf16(a[2], a[3]); w.z = cvt_pk_bf16(b[0], b[1]); w.w = cvt_pk_bf16(b[2], b[3]); return w; }
;     DI void operator()(AccRef acc, const Unit& u, int wr, int wc, int fr, int fq) const {
;     ...
;             for (int m = 0; m < 4; ++m) { const int row = u.pm * 256 + ai * 128 + wr * 64 + m * 16 + fr; const size_t off = (size_t)row * DM + col0; float q = 0.f;
; #pragma unroll
;                 for (int bj = 0; bj < 2; ++bj) {
;                     f32x4 b0, b1;
;                     if (F32BASE) { b0 = *(const f32x4*)(bp + off + bj * 128); b1 = *(const f32x4*)(bp + off + bj * 128 + 4); }
;                     else { const u32x4 uv = *(const u32x4*)(Ui + off + bj * 128); b0 = (f32x4){bf_lo(uv.x), bf_hi(uv.x), bf_lo(uv.y), bf_hi(uv.y)}; b1 = (f32x4){bf_lo(uv.z), bf_hi(uv.z), bf_lo(uv.w), bf_hi(uv.w)}; }
;                     const u32x4 w = pack8(b0 + acc[ai][bj][m][0] * (0.5f * S2), b1 + acc[ai][bj][m][1] * (0.5f * S2));
;                     *(u32x4*)(Uo + (size_t)row * ldo + col0 + bj * 128) = w;
;                     const float r0 = bf_lo(w.x), r1 = bf_hi(w.x), r2 = bf_lo(w.y), r3 = bf_hi(w.y), r4 = bf_lo(w.z), r5 = bf_hi(w.z), r6 = bf_lo(w.w), r7 = bf_hi(w.w);
;                     q += (r0 * r0 + r1 * r1) + (r2 * r2 + r3 * r3) + (r4 * r4 + r5 * r5) + (r6 * r6 + r7 * r7); }
;                 q += __shfl_xor(q, 16); q += __shfl_xor(q, 32); if (fq == 0) ssp[(size_t)row * 32 + u.pn * 4 + wc] = q; }
.LBB0_1753:
	s_or_b64 exec, exec, s[40:41]
	v_add_u32_e32 v80, 48, v146
	s_waitcnt lgkmcnt(0)
	v_ashrrev_i32_e32 v81, 31, v80
	v_lshlrev_b64 v[82:83], 12, v[80:81]
	v_lshl_add_u64 v[82:83], s[18:19], 0, v[82:83]
	v_lshl_add_u64 v[86:87], v[82:83], 0, v[144:145]
	s_waitcnt vmcnt(17)
	v_mov_b64_e32 v[82:83], v[214:215]
	v_mov_b64_e32 v[84:85], v[216:217]
	v_lshlrev_b32_e32 v88, 16, v82
	v_and_b32_e32 v89, 0xffff0000, v82
	v_lshlrev_b32_e32 v82, 16, v83
	v_and_b32_e32 v83, 0xffff0000, v83
	v_lshlrev_b32_e32 v90, 16, v84
	v_and_b32_e32 v91, 0xffff0000, v84
	v_lshlrev_b32_e32 v84, 16, v85
	v_and_b32_e32 v85, 0xffff0000, v85
	v_pk_fma_f32 v[78:79], v[78:79], 0.5, v[82:83] op_sel_hi:[1,0,1]
	v_pk_fma_f32 v[76:77], v[76:77], 0.5, v[88:89] op_sel_hi:[1,0,1]
	v_pk_fma_f32 v[82:83], v[74:75], 0.5, v[84:85] op_sel_hi:[1,0,1]
	v_pk_fma_f32 v[74:75], v[72:73], 0.5, v[90:91] op_sel_hi:[1,0,1]
	v_cvt_pk_bf16_f32 v72, v76, v77
	v_cvt_pk_bf16_f32 v73, v78, v79
	s_nop 0
	v_cvt_pk_bf16_f32 v74, v74, v75
	v_cvt_pk_bf16_f32 v75, v82, v83
	s_waitcnt vmcnt(16)
	v_mov_b64_e32 v[76:77], v[218:219]
	v_mov_b64_e32 v[78:79], v[220:221]
	v_mov_b64_e32 v[82:83], s[28:29]
	v_mad_i64_i32 v[82:83], s[0:1], v80, s63, v[82:83]
	v_lshl_add_u64 v[82:83], v[82:83], 0, v[144:145]
	global_store_dwordx4 v[82:83], v[72:75], off
	v_lshlrev_b32_e32 v84, 16, v72
	v_lshlrev_b32_e32 v85, 16, v73
	v_and_b32_e32 v72, 0xffff0000, v72
	v_and_b32_e32 v73, 0xffff0000, v73
	v_lshlrev_b32_e32 v86, 16, v74
	v_and_b32_e32 v74, 0xffff0000, v74
	v_mul_f32_e32 v72, v72, v72
	v_mul_f32_e32 v73, v73, v73
	v_lshlrev_b32_e32 v87, 16, v75
	v_and_b32_e32 v75, 0xffff0000, v75
	v_mul_f32_e32 v74, v74, v74
	v_fmac_f32_e32 v72, v84, v84
	v_fmac_f32_e32 v73, v85, v85
	v_mul_f32_e32 v75, v75, v75
	v_fmac_f32_e32 v74, v86, v86
	v_add_f32_e32 v72, v72, v73
	v_fmac_f32_e32 v75, v87, v87
	v_add_f32_e32 v72, v72, v74
	v_add_f32_e32 v84, v72, v75
	v_lshlrev_b32_e32 v72, 16, v76
	v_and_b32_e32 v73, 0xffff0000, v76
	v_lshlrev_b32_e32 v74, 16, v77
	v_and_b32_e32 v75, 0xffff0000, v77
	v_lshlrev_b32_e32 v76, 16, v78
	v_and_b32_e32 v77, 0xffff0000, v78
	v_lshlrev_b32_e32 v78, 16, v79
	v_and_b32_e32 v79, 0xffff0000, v79
	v_pk_fma_f32 v[70:71], v[70:71], 0.5, v[74:75] op_sel_hi:[1,0,1]
	v_pk_fma_f32 v[68:69], v[68:69], 0.5, v[72:73] op_sel_hi:[1,0,1]
	v_pk_fma_f32 v[64:65], v[64:65], 0.5, v[76:77] op_sel_hi:[1,0,1]
	v_pk_fma_f32 v[72:73], v[66:67], 0.5, v[78:79] op_sel_hi:[1,0,1]
	v_cvt_pk_bf16_f32 v66, v68, v69
	v_cvt_pk_bf16_f32 v67, v70, v71
	v_cvt_pk_bf16_f32 v68, v64, v65
	s_nop 0
	v_and_b32_e32 v65, 0xffff0000, v66
	v_and_b32_e32 v71, 0xffff0000, v67
	v_cvt_pk_bf16_f32 v69, v72, v73
	v_lshlrev_b32_e32 v64, 16, v66
	v_lshlrev_b32_e32 v70, 16, v67
	v_and_b32_e32 v73, 0xffff0000, v68
	v_mul_f32_e32 v65, v65, v65
	v_mul_f32_e32 v71, v71, v71
	v_lshlrev_b32_e32 v72, 16, v68
	v_and_b32_e32 v75, 0xffff0000, v69
	v_mul_f32_e32 v73, v73, v73
	v_fmac_f32_e32 v65, v64, v64
	v_fmac_f32_e32 v71, v70, v70
	v_lshlrev_b32_e32 v74, 16, v69
	v_mul_f32_e32 v75, v75, v75
	v_fmac_f32_e32 v73, v72, v72
	v_add_f32_e32 v64, v65, v71
	v_add_f32_e32 v64, v64, v73
	v_fmac_f32_e32 v75, v74, v74
	v_add_f32_e32 v64, v64, v75
	v_add_f32_e32 v64, v84, v64
	ds_bpermute_b32 v65, v120, v64
	global_store_dwordx4 v[82:83], v[66:69], off offset:256
	s_waitcnt lgkmcnt(0)
	v_add_f32_e32 v64, v64, v65
	ds_bpermute_b32 v65, v114, v64
	s_and_saveexec_b64 s[40:41], vcc
	s_cbranch_execz .LBB0_1755
	v_lshlrev_b64 v[66:67], 7, v[80:81]
	v_lshl_add_u64 v[66:67], s[30:31], 0, v[66:67]
	v_lshl_add_u64 v[66:67], s[38:39], 2, v[66:67]
	s_lshl_b32 s16, s56, 2
	v_lshl_add_u64 v[66:67], v[66:67], 0, s[16:17]
	s_waitcnt lgkmcnt(0)
	v_add_f32_e32 v64, v64, v65
	global_store_dword v[66:67], v64, off
.LBB0_1755:
	s_or_b64 exec, exec, s[40:41]
	v_add_u32_e32 v64, 0x80, v146
	s_waitcnt lgkmcnt(0)
	v_ashrrev_i32_e32 v65, 31, v64
	v_lshlrev_b64 v[66:67], 12, v[64:65]
	v_lshl_add_u64 v[66:67], s[18:19], 0, v[66:67]
	v_lshl_add_u64 v[70:71], v[66:67], 0, v[144:145]
	s_waitcnt vmcnt(17)
	v_mov_b64_e32 v[66:67], v[222:223]
	v_mov_b64_e32 v[68:69], v[224:225]
	v_lshlrev_b32_e32 v72, 16, v66
	v_and_b32_e32 v73, 0xffff0000, v66
	v_lshlrev_b32_e32 v66, 16, v67
	v_and_b32_e32 v67, 0xffff0000, v67
	v_lshlrev_b32_e32 v74, 16, v68
	v_and_b32_e32 v75, 0xffff0000, v68
	v_lshlrev_b32_e32 v68, 16, v69
	v_and_b32_e32 v69, 0xffff0000, v69
	v_pk_fma_f32 v[62:63], v[62:63], 0.5, v[66:67] op_sel_hi:[1,0,1]
	v_pk_fma_f32 v[60:61], v[60:61], 0.5, v[72:73] op_sel_hi:[1,0,1]
	v_pk_fma_f32 v[66:67], v[58:59], 0.5, v[68:69] op_sel_hi:[1,0,1]
	v_pk_fma_f32 v[58:59], v[56:57], 0.5, v[74:75] op_sel_hi:[1,0,1]
	v_cvt_pk_bf16_f32 v56, v60, v61
	v_cvt_pk_bf16_f32 v57, v62, v63
	s_nop 0
	v_cvt_pk_bf16_f32 v58, v58, v59
	v_cvt_pk_bf16_f32 v59, v66, v67
	s_waitcnt vmcnt(16)
; DI float bf_lo(unsigned u) { return __uint_as_float(u << 16); }
; DI float bf_hi(unsigned u) { return __uint_as_float(u & 0xffff0000u); }
; DI u32x4 pack8(f32x4 a, f32x4 b) { u32x4 w; w.x = cvt_pk_bf16(a[0], a[1]); w.y = cvt_pk_bf16(a[2], a[3]); w.z = cvt_pk_bf16(b[0], b[1]); w.w = cvt_pk_bf16(b[2], b[3]); return w; }
;     DI void operator()(AccRef acc, const Unit& u, int wr, int wc, int fr, int fq) const {
;     ...
;             for (int m = 0; m < 4; ++m) { const int row = u.pm * 256 + ai * 128 + wr * 64 + m * 16 + fr; const size_t off = (size_t)row * DM + col0; float q = 0.f;
; #pragma unroll
;                 for (int bj = 0; bj < 2; ++bj) {
;                     f32x4 b0, b1;
;                     if (F32BASE) { b0 = *(const f32x4*)(bp + off + bj * 128); b1 = *(const f32x4*)(bp + off + bj * 128 + 4); }
;                     else { const u32x4 uv = *(const u32x4*)(Ui + off + bj * 128); b0 = (f32x4){bf_lo(uv.x), bf_hi(uv.x), bf_lo(uv.y), bf_hi(uv.y)}; b1 = (f32x4){bf_lo(uv.z), bf_hi(uv.z), bf_lo(uv.w), bf_hi(uv.w)}; }
;                     const u32x4 w = pack8(b0 + acc[ai][bj][m][0] * (0.5f * S2), b1 + acc[ai][bj][m][1] * (0.5f * S2));
;                     *(u32x4*)(Uo + (size_t)row * ldo + col0 + bj * 128) = w;
;                     const float r0 = bf_lo(w.x), r1 = bf_hi(w.x), r2 = bf_lo(w.y), r3 = bf_hi(w.y), r4 = bf_lo(w.z), r5 = bf_hi(w.z), r6 = bf_lo(w.w), r7 = bf_hi(w.w);
;                     q += (r0 * r0 + r1 * r1) + (r2 * r2 + r3 * r3) + (r4 * r4 + r5 * r5) + (r6 * r6 + r7 * r7); }
;                 q += __shfl_xor(q, 16); q += __shfl_xor(q, 32); if (fq == 0) ssp[(size_t)row * 32 + u.pn * 4 + wc] = q; }
	v_mov_b64_e32 v[60:61], v[226:227]
	v_mov_b64_e32 v[62:63], v[228:229]
	v_mov_b64_e32 v[66:67], s[28:29]
	v_mad_i64_i32 v[66:67], s[0:1], v64, s63, v[66:67]
	v_lshl_add_u64 v[66:67], v[66:67], 0, v[144:145]
	global_store_dwordx4 v[66:67], v[56:59], off
	v_lshlrev_b32_e32 v68, 16, v56
	v_lshlrev_b32_e32 v69, 16, v57
	v_and_b32_e32 v56, 0xffff0000, v56
	v_and_b32_e32 v57, 0xffff0000, v57
	v_lshlrev_b32_e32 v70, 16, v58
	v_and_b32_e32 v58, 0xffff0000, v58
	v_mul_f32_e32 v56, v56, v56
	v_mul_f32_e32 v57, v57, v57
	v_lshlrev_b32_e32 v71, 16, v59
	v_and_b32_e32 v59, 0xffff0000, v59
	v_mul_f32_e32 v58, v58, v58
	v_fmac_f32_e32 v56, v68, v68
	v_fmac_f32_e32 v57, v69, v69
	v_mul_f32_e32 v59, v59, v59
	v_fmac_f32_e32 v58, v70, v70
	v_add_f32_e32 v56, v56, v57
	v_fmac_f32_e32 v59, v71, v71
	v_add_f32_e32 v56, v56, v58
	v_add_f32_e32 v68, v56, v59
	v_lshlrev_b32_e32 v56, 16, v60
	v_and_b32_e32 v57, 0xffff0000, v60
	v_lshlrev_b32_e32 v58, 16, v61
	v_and_b32_e32 v59, 0xffff0000, v61
	v_lshlrev_b32_e32 v60, 16, v62
	v_and_b32_e32 v61, 0xffff0000, v62
	v_lshlrev_b32_e32 v62, 16, v63
	v_and_b32_e32 v63, 0xffff0000, v63
	v_pk_fma_f32 v[54:55], v[54:55], 0.5, v[58:59] op_sel_hi:[1,0,1]
	v_pk_fma_f32 v[52:53], v[52:53], 0.5, v[56:57] op_sel_hi:[1,0,1]
	v_pk_fma_f32 v[48:49], v[48:49], 0.5, v[60:61] op_sel_hi:[1,0,1]
	v_pk_fma_f32 v[56:57], v[50:51], 0.5, v[62:63] op_sel_hi:[1,0,1]
	v_cvt_pk_bf16_f32 v50, v52, v53
	v_cvt_pk_bf16_f32 v51, v54, v55
	v_cvt_pk_bf16_f32 v52, v48, v49
	s_nop 0
	v_and_b32_e32 v49, 0xffff0000, v50
	v_and_b32_e32 v55, 0xffff0000, v51
	v_cvt_pk_bf16_f32 v53, v56, v57
	v_lshlrev_b32_e32 v48, 16, v50
	v_lshlrev_b32_e32 v54, 16, v51
	v_and_b32_e32 v57, 0xffff0000, v52
	v_mul_f32_e32 v49, v49, v49
	v_mul_f32_e32 v55, v55, v55
	v_lshlrev_b32_e32 v56, 16, v52
	v_and_b32_e32 v59, 0xffff0000, v53
	v_mul_f32_e32 v57, v57, v57
	v_fmac_f32_e32 v49, v48, v48
	v_fmac_f32_e32 v55, v54, v54
	v_lshlrev_b32_e32 v58, 16, v53
	v_mul_f32_e32 v59, v59, v59
	v_fmac_f32_e32 v57, v56, v56
	v_add_f32_e32 v48, v49, v55
	v_add_f32_e32 v48, v48, v57
	v_fmac_f32_e32 v59, v58, v58
	v_add_f32_e32 v48, v48, v59
	v_add_f32_e32 v48, v68, v48
	ds_bpermute_b32 v49, v120, v48
	global_store_dwordx4 v[66:67], v[50:53], off offset:256
	s_waitcnt lgkmcnt(0)
	v_add_f32_e32 v48, v48, v49
	ds_bpermute_b32 v49, v114, v48
	s_and_saveexec_b64 s[40:41], vcc
	s_cbranch_execz .LBB0_1757
	v_lshlrev_b64 v[50:51], 7, v[64:65]
	v_lshl_add_u64 v[50:51], s[30:31], 0, v[50:51]
	v_lshl_add_u64 v[50:51], s[38:39], 2, v[50:51]
	s_lshl_b32 s16, s56, 2
	v_lshl_add_u64 v[50:51], v[50:51], 0, s[16:17]
	s_waitcnt lgkmcnt(0)
	v_add_f32_e32 v48, v48, v49
	global_store_dword v[50:51], v48, off
.LBB0_1757:
	s_or_b64 exec, exec, s[40:41]
	v_add_u32_e32 v48, 0x90, v146
	s_waitcnt lgkmcnt(0)
	v_ashrrev_i32_e32 v49, 31, v48
	v_lshlrev_b64 v[50:51], 12, v[48:49]
	v_lshl_add_u64 v[50:51], s[18:19], 0, v[50:51]
	v_lshl_add_u64 v[54:55], v[50:51], 0, v[144:145]
	s_waitcnt vmcnt(17)
	v_mov_b64_e32 v[50:51], v[230:231]
	v_mov_b64_e32 v[52:53], v[232:233]
	v_lshlrev_b32_e32 v56, 16, v50
	v_and_b32_e32 v57, 0xffff0000, v50
	v_lshlrev_b32_e32 v50, 16, v51
	v_and_b32_e32 v51, 0xffff0000, v51
	v_lshlrev_b32_e32 v58, 16, v52
	v_and_b32_e32 v59, 0xffff0000, v52
	v_lshlrev_b32_e32 v52, 16, v53
	v_and_b32_e32 v53, 0xffff0000, v53
	v_pk_fma_f32 v[46:47], v[46:47], 0.5, v[50:51] op_sel_hi:[1,0,1]
	v_pk_fma_f32 v[44:45], v[44:45], 0.5, v[56:57] op_sel_hi:[1,0,1]
	v_pk_fma_f32 v[50:51], v[42:43], 0.5, v[52:53] op_sel_hi:[1,0,1]
	v_pk_fma_f32 v[42:43], v[40:41], 0.5, v[58:59] op_sel_hi:[1,0,1]
	v_cvt_pk_bf16_f32 v40, v44, v45
	v_cvt_pk_bf16_f32 v41, v46, v47
	s_nop 0
	v_cvt_pk_bf16_f32 v42, v42, v43
	v_cvt_pk_bf16_f32 v43, v50, v51
	s_waitcnt vmcnt(16)
	v_mov_b64_e32 v[44:45], v[234:235]
	v_mov_b64_e32 v[46:47], v[236:237]
	v_mov_b64_e32 v[50:51], s[28:29]
	v_mad_i64_i32 v[50:51], s[0:1], v48, s63, v[50:51]
	v_lshl_add_u64 v[50:51], v[50:51], 0, v[144:145]
	global_store_dwordx4 v[50:51], v[40:43], off
	v_lshlrev_b32_e32 v52, 16, v40
	v_lshlrev_b32_e32 v53, 16, v41
	v_and_b32_e32 v40, 0xffff0000, v40
	v_and_b32_e32 v41, 0xffff0000, v41
	v_lshlrev_b32_e32 v54, 16, v42
	v_and_b32_e32 v42, 0xffff0000, v42
	v_mul_f32_e32 v40, v40, v40
	v_mul_f32_e32 v41, v41, v41
	v_lshlrev_b32_e32 v55, 16, v43
	v_and_b32_e32 v43, 0xffff0000, v43
	v_mul_f32_e32 v42, v42, v42
	v_fmac_f32_e32 v40, v52, v52
	v_fmac_f32_e32 v41, v53, v53
	v_mul_f32_e32 v43, v43, v43
	v_fmac_f32_e32 v42, v54, v54
	v_add_f32_e32 v40, v40, v41
	v_fmac_f32_e32 v43, v55, v55
	v_add_f32_e32 v40, v40, v42
	v_add_f32_e32 v52, v40, v43
	v_lshlrev_b32_e32 v40, 16, v44
	v_and_b32_e32 v41, 0xffff0000, v44
	v_lshlrev_b32_e32 v42, 16, v45
	v_and_b32_e32 v43, 0xffff0000, v45
	v_lshlrev_b32_e32 v44, 16, v46
	v_and_b32_e32 v45, 0xffff0000, v46
	v_lshlrev_b32_e32 v46, 16, v47
	v_and_b32_e32 v47, 0xffff0000, v47
	v_pk_fma_f32 v[38:39], v[38:39], 0.5, v[42:43] op_sel_hi:[1,0,1]
	v_pk_fma_f32 v[36:37], v[36:37], 0.5, v[40:41] op_sel_hi:[1,0,1]
	v_pk_fma_f32 v[32:33], v[32:33], 0.5, v[44:45] op_sel_hi:[1,0,1]
	v_pk_fma_f32 v[40:41], v[34:35], 0.5, v[46:47] op_sel_hi:[1,0,1]
	v_cvt_pk_bf16_f32 v34, v36, v37
	v_cvt_pk_bf16_f32 v35, v38, v39
	v_cvt_pk_bf16_f32 v36, v32, v33
	s_nop 0
	v_and_b32_e32 v33, 0xffff0000, v34
	v_and_b32_e32 v39, 0xffff0000, v35
	v_cvt_pk_bf16_f32 v37, v40, v41
	v_lshlrev_b32_e32 v32, 16, v34
	v_lshlrev_b32_e32 v38, 16, v35
	v_and_b32_e32 v41, 0xffff0000, v36
	v_mul_f32_e32 v33, v33, v33
	v_mul_f32_e32 v39, v39, v39
	v_lshlrev_b32_e32 v40, 16, v36
	v_and_b32_e32 v43, 0xffff0000, v37
	v_mul_f32_e32 v41, v41, v41
	v_fmac_f32_e32 v33, v32, v32
	v_fmac_f32_e32 v39, v38, v38
	v_lshlrev_b32_e32 v42, 16, v37
	v_mul_f32_e32 v43, v43, v43
	v_fmac_f32_e32 v41, v40, v40
	v_add_f32_e32 v32, v33, v39
	v_add_f32_e32 v32, v32, v41
	v_fmac_f32_e32 v43, v42, v42
	v_add_f32_e32 v32, v32, v43
	v_add_f32_e32 v32, v52, v32
	ds_bpermute_b32 v33, v120, v32
	global_store_dwordx4 v[50:51], v[34:37], off offset:256
	s_waitcnt lgkmcnt(0)
	v_add_f32_e32 v32, v32, v33
	ds_bpermute_b32 v33, v114, v32
	s_and_saveexec_b64 s[40:41], vcc
	s_cbranch_execz .LBB0_1759
	v_lshlrev_b64 v[34:35], 7, v[48:49]
	v_lshl_add_u64 v[34:35], s[30:31], 0, v[34:35]
	v_lshl_add_u64 v[34:35], s[38:39], 2, v[34:35]
	s_lshl_b32 s16, s56, 2
	v_lshl_add_u64 v[34:35], v[34:35], 0, s[16:17]
	s_waitcnt lgkmcnt(0)
	v_add_f32_e32 v32, v32, v33
	global_store_dword v[34:35], v32, off
; DI float bf_lo(unsigned u) { return __uint_as_float(u << 16); }
; DI float bf_hi(unsigned u) { return __uint_as_float(u & 0xffff0000u); }
; DI u32x4 pack8(f32x4 a, f32x4 b) { u32x4 w; w.x = cvt_pk_bf16(a[0], a[1]); w.y = cvt_pk_bf16(a[2], a[3]); w.z = cvt_pk_bf16(b[0], b[1]); w.w = cvt_pk_bf16(b[2], b[3]); return w; }
;     DI void operator()(AccRef acc, const Unit& u, int wr, int wc, int fr, int fq) const {
;     ...
;             for (int m = 0; m < 4; ++m) { const int row = u.pm * 256 + ai * 128 + wr * 64 + m * 16 + fr; const size_t off = (size_t)row * DM + col0; float q = 0.f;
; #pragma unroll
;                 for (int bj = 0; bj < 2; ++bj) {
;                     f32x4 b0, b1;
;                     if (F32BASE) { b0 = *(const f32x4*)(bp + off + bj * 128); b1 = *(const f32x4*)(bp + off + bj * 128 + 4); }
;                     else { const u32x4 uv = *(const u32x4*)(Ui + off + bj * 128); b0 = (f32x4){bf_lo(uv.x), bf_hi(uv.x), bf_lo(uv.y), bf_hi(uv.y)}; b1 = (f32x4){bf_lo(uv.z), bf_hi(uv.z), bf_lo(uv.w), bf_hi(uv.w)}; }
;                     const u32x4 w = pack8(b0 + acc[ai][bj][m][0] * (0.5f * S2), b1 + acc[ai][bj][m][1] * (0.5f * S2));
;                     *(u32x4*)(Uo + (size_t)row * ldo + col0 + bj * 128) = w;
;                     const float r0 = bf_lo(w.x), r1 = bf_hi(w.x), r2 = bf_lo(w.y), r3 = bf_hi(w.y), r4 = bf_lo(w.z), r5 = bf_hi(w.z), r6 = bf_lo(w.w), r7 = bf_hi(w.w);
;                     q += (r0 * r0 + r1 * r1) + (r2 * r2 + r3 * r3) + (r4 * r4 + r5 * r5) + (r6 * r6 + r7 * r7); }
;                 q += __shfl_xor(q, 16); q += __shfl_xor(q, 32); if (fq == 0) ssp[(size_t)row * 32 + u.pn * 4 + wc] = q; }
.LBB0_1759:
	s_or_b64 exec, exec, s[40:41]
	v_add_u32_e32 v32, 0xa0, v146
	s_waitcnt lgkmcnt(0)
	v_ashrrev_i32_e32 v33, 31, v32
	v_lshlrev_b64 v[34:35], 12, v[32:33]
	v_lshl_add_u64 v[34:35], s[18:19], 0, v[34:35]
	v_lshl_add_u64 v[38:39], v[34:35], 0, v[144:145]
	s_waitcnt vmcnt(17)
	v_mov_b64_e32 v[34:35], v[238:239]
	v_mov_b64_e32 v[36:37], v[240:241]
	v_lshlrev_b32_e32 v40, 16, v34
	v_and_b32_e32 v41, 0xffff0000, v34
	v_lshlrev_b32_e32 v34, 16, v35
	v_and_b32_e32 v35, 0xffff0000, v35
	v_lshlrev_b32_e32 v42, 16, v36
	v_and_b32_e32 v43, 0xffff0000, v36
	v_lshlrev_b32_e32 v36, 16, v37
	v_and_b32_e32 v37, 0xffff0000, v37
	v_pk_fma_f32 v[30:31], v[30:31], 0.5, v[34:35] op_sel_hi:[1,0,1]
	v_pk_fma_f32 v[28:29], v[28:29], 0.5, v[40:41] op_sel_hi:[1,0,1]
	v_pk_fma_f32 v[34:35], v[26:27], 0.5, v[36:37] op_sel_hi:[1,0,1]
	v_pk_fma_f32 v[26:27], v[24:25], 0.5, v[42:43] op_sel_hi:[1,0,1]
	v_cvt_pk_bf16_f32 v24, v28, v29
	v_cvt_pk_bf16_f32 v25, v30, v31
	s_nop 0
	v_cvt_pk_bf16_f32 v26, v26, v27
	v_cvt_pk_bf16_f32 v27, v34, v35
	s_waitcnt vmcnt(14)
	v_mov_b64_e32 v[28:29], v[170:171]
	v_mov_b64_e32 v[30:31], v[172:173]
	v_mov_b64_e32 v[34:35], s[28:29]
	v_mad_i64_i32 v[34:35], s[0:1], v32, s63, v[34:35]
	v_lshl_add_u64 v[34:35], v[34:35], 0, v[144:145]
	global_store_dwordx4 v[34:35], v[24:27], off
	v_lshlrev_b32_e32 v36, 16, v24
	v_lshlrev_b32_e32 v37, 16, v25
	v_and_b32_e32 v24, 0xffff0000, v24
	v_and_b32_e32 v25, 0xffff0000, v25
	v_lshlrev_b32_e32 v38, 16, v26
	v_and_b32_e32 v26, 0xffff0000, v26
	v_mul_f32_e32 v24, v24, v24
	v_mul_f32_e32 v25, v25, v25
	v_lshlrev_b32_e32 v39, 16, v27
	v_and_b32_e32 v27, 0xffff0000, v27
	v_mul_f32_e32 v26, v26, v26
	v_fmac_f32_e32 v24, v36, v36
	v_fmac_f32_e32 v25, v37, v37
	v_mul_f32_e32 v27, v27, v27
	v_fmac_f32_e32 v26, v38, v38
	v_add_f32_e32 v24, v24, v25
	v_fmac_f32_e32 v27, v39, v39
	v_add_f32_e32 v24, v24, v26
	v_add_f32_e32 v36, v24, v27
	v_lshlrev_b32_e32 v24, 16, v28
	v_and_b32_e32 v25, 0xffff0000, v28
	v_lshlrev_b32_e32 v26, 16, v29
	v_and_b32_e32 v27, 0xffff0000, v29
	v_lshlrev_b32_e32 v28, 16, v30
	v_and_b32_e32 v29, 0xffff0000, v30
	v_lshlrev_b32_e32 v30, 16, v31
	v_and_b32_e32 v31, 0xffff0000, v31
	v_pk_fma_f32 v[22:23], v[22:23], 0.5, v[26:27] op_sel_hi:[1,0,1]
	v_pk_fma_f32 v[20:21], v[20:21], 0.5, v[24:25] op_sel_hi:[1,0,1]
	v_pk_fma_f32 v[16:17], v[16:17], 0.5, v[28:29] op_sel_hi:[1,0,1]
	v_pk_fma_f32 v[24:25], v[18:19], 0.5, v[30:31] op_sel_hi:[1,0,1]
	v_cvt_pk_bf16_f32 v18, v20, v21
	v_cvt_pk_bf16_f32 v19, v22, v23
	v_cvt_pk_bf16_f32 v20, v16, v17
	s_nop 0
	v_and_b32_e32 v17, 0xffff0000, v18
	v_and_b32_e32 v23, 0xffff0000, v19
	v_cvt_pk_bf16_f32 v21, v24, v25
	v_lshlrev_b32_e32 v16, 16, v18
	v_lshlrev_b32_e32 v22, 16, v19
	v_and_b32_e32 v25, 0xffff0000, v20
	v_mul_f32_e32 v17, v17, v17
	v_mul_f32_e32 v23, v23, v23
	v_lshlrev_b32_e32 v24, 16, v20
	v_and_b32_e32 v27, 0xffff0000, v21
	v_mul_f32_e32 v25, v25, v25
	v_fmac_f32_e32 v17, v16, v16
	v_fmac_f32_e32 v23, v22, v22
	v_lshlrev_b32_e32 v26, 16, v21
	v_mul_f32_e32 v27, v27, v27
	v_fmac_f32_e32 v25, v24, v24
	v_add_f32_e32 v16, v17, v23
	v_add_f32_e32 v16, v16, v25
	v_fmac_f32_e32 v27, v26, v26
	v_add_f32_e32 v16, v16, v27
	v_add_f32_e32 v16, v36, v16
	ds_bpermute_b32 v17, v120, v16
	global_store_dwordx4 v[34:35], v[18:21], off offset:256
	s_waitcnt lgkmcnt(0)
	v_add_f32_e32 v16, v16, v17
	ds_bpermute_b32 v17, v114, v16
	s_and_saveexec_b64 s[40:41], vcc
	s_cbranch_execz .LBB0_1761
	v_lshlrev_b64 v[18:19], 7, v[32:33]
	v_lshl_add_u64 v[18:19], s[30:31], 0, v[18:19]
	v_lshl_add_u64 v[18:19], s[38:39], 2, v[18:19]
	s_lshl_b32 s16, s56, 2
	v_lshl_add_u64 v[18:19], v[18:19], 0, s[16:17]
	s_waitcnt lgkmcnt(0)
	v_add_f32_e32 v16, v16, v17
	global_store_dword v[18:19], v16, off

; DI float bf_lo(unsigned u) { return __uint_as_float(u << 16); }
; DI float bf_hi(unsigned u) { return __uint_as_float(u & 0xffff0000u); }
; DI float sigmoidf_(float x) { return __builtin_amdgcn_rcpf(1.0f + __builtin_amdgcn_exp2f(-x * LOG2E)); }
; DI u32x4 pack8(f32x4 a, f32x4 b) { u32x4 w; w.x = cvt_pk_bf16(a[0], a[1]); w.y = cvt_pk_bf16(a[2], a[3]); w.z = cvt_pk_bf16(b[0], b[1]); w.w = cvt_pk_bf16(b[2], b[3]); return w; }
; DI float rs_of(const float* ss, int row) { return 1.0f / sqrtf(ss[row] * (1.0f / DM) + EPS); }
;     DI void operator()(AccRef acc, const Unit& u, int wr, int wc, int fr, int fq) const {
;     ...
;             for (int m = 0; m < 4; ++m) { const int row = u.pm * 256 + ai * 128 + wr * 64 + m * 16 + fr; const size_t off = (size_t)row * DM + col0; const float r = rs_of(ss, row);
; #pragma unroll
;                 for (int bj = 0; bj < 2; ++bj) {
;                     const u32x4 ev = *(const u32x4*)(Eb + off + bj * 128), uv = *(const u32x4*)(UPh + (size_t)row * 2304 + col0 + bj * 128);
;                     const f32x4 e0 = {bf_lo(ev.x), bf_hi(ev.x), bf_lo(ev.y), bf_hi(ev.y)}, e1 = {bf_lo(ev.z), bf_hi(ev.z), bf_lo(ev.w), bf_hi(ev.w)};
;                     f32x4 h0 = {bf_lo(uv.x), bf_hi(uv.x), bf_lo(uv.y), bf_hi(uv.y)}, h1 = {bf_lo(uv.z), bf_hi(uv.z), bf_lo(uv.w), bf_hi(uv.w)};
; #pragma unroll
;                     for (int j = 0; j < 4; ++j) { h0[j] += sigmoidf_(acc[ai][bj][m][0][j] * r) * e0[j]; h1[j] += sigmoidf_(acc[ai][bj][m][1][j] * r) * e1[j]; }
;                     *(u32x4*)(Hf + off + bj * 128) = pack8(h0, h1); } }
.LBB0_1908:
	v_mov_b32_e32 v144, v194
	v_mov_b32_e32 v145, v192
	s_mov_b64 s[40:41], s[10:11]
	v_add_u32_e32 v150, s34, v144
	v_ashrrev_i32_e32 v151, 31, v150
	v_lshl_add_u32 v148, v145, 3, s35
	v_lshl_add_u64 v[144:145], v[150:151], 2, s[28:29]
	v_mov_b64_e32 v[242:243], v[144:145]
	v_ashrrev_i32_e32 v149, 31, v148
	v_lshlrev_b64 v[166:167], 11, v[150:151]
	v_lshl_add_u64 v[166:167], v[166:167], 0, v[148:149]
	v_lshlrev_b64 v[172:173], 1, v[166:167]
	v_lshl_add_u64 v[174:175], s[14:15], 0, v[172:173]
	v_mov_b64_e32 v[238:239], v[174:175]
	v_mov_b64_e32 v[144:145], s[16:17]
	v_mad_i64_i32 v[162:163], s[0:1], v150, s65, v[144:145]
	v_lshlrev_b64 v[146:147], 1, v[148:149]
	v_lshl_add_u64 v[170:171], v[162:163], 0, v[146:147]
	v_mov_b64_e32 v[240:241], v[170:171]
	s_mov_b32 s5, 0
	global_load_dword v191, v[242:243], off
	global_load_dwordx4 v[196:199], v[238:239], off
	global_load_dwordx4 v[200:203], v[240:241], off
	global_load_dwordx4 v[206:209], v[238:239], off offset:256
	global_load_dwordx4 v[210:213], v[240:241], off offset:256
	s_mov_b32 s4, 0x40
	v_lshl_add_u64 v[242:243], v[242:243], 0, s[4:5]
	global_load_dword v193, v[242:243], off
	s_mov_b32 s4, 0x10000
	v_lshl_add_u64 v[238:239], v[238:239], 0, s[4:5]
	global_load_dwordx4 v[214:217], v[238:239], off
	s_mov_b32 s4, 0x12000
	v_lshl_add_u64 v[240:241], v[240:241], 0, s[4:5]
	global_load_dwordx4 v[218:221], v[240:241], off
	global_load_dwordx4 v[222:225], v[238:239], off offset:256
	global_load_dwordx4 v[226:229], v[240:241], off offset:256
	s_mov_b32 s4, 0x40
	v_lshl_add_u64 v[242:243], v[242:243], 0, s[4:5]
	global_load_dword v205, v[242:243], off
	s_mov_b32 s4, 0x40
	v_lshl_add_u64 v[242:243], v[242:243], 0, s[4:5]
	global_load_dword v234, v[242:243], off
	s_mov_b32 s4, 0x140
	v_lshl_add_u64 v[242:243], v[242:243], 0, s[4:5]
	global_load_dword v235, v[242:243], off
	s_mov_b32 s4, 0x40
	v_lshl_add_u64 v[242:243], v[242:243], 0, s[4:5]
	global_load_dword v236, v[242:243], off
	s_mov_b32 s4, 0x40
	v_lshl_add_u64 v[242:243], v[242:243], 0, s[4:5]
	global_load_dword v237, v[242:243], off
	s_mov_b32 s4, 0x40
	v_lshl_add_u64 v[242:243], v[242:243], 0, s[4:5]
	global_load_dword v230, v[242:243], off
	s_waitcnt vmcnt(15)
	v_mov_b32_e32 v161, v191
	s_waitcnt vmcnt(14)
	v_mov_b64_e32 v[166:167], v[196:197]
	v_mov_b64_e32 v[168:169], v[198:199]
	s_mov_b32 s4, 0x10000
	v_lshl_add_u64 v[238:239], v[238:239], 0, s[4:5]
	global_load_dwordx4 v[196:199], v[238:239], off
	s_waitcnt vmcnt(14)
	v_mov_b64_e32 v[162:163], v[200:201]
	v_mov_b64_e32 v[164:165], v[202:203]
	s_mov_b32 s4, 0x12000
	v_lshl_add_u64 v[240:241], v[240:241], 0, s[4:5]
	global_load_dwordx4 v[200:203], v[240:241], off
	s_mov_b64 s[38:39], s[36:37]
	v_fmamk_f32 v151, v161, 0x3a000000, v159
	v_mul_f32_e32 v161, 0x4f800000, v151
	v_cmp_gt_f32_e32 vcc, s64, v151
	v_lshlrev_b32_e32 v180, 16, v166
	s_nop 0
	v_cndmask_b32_e32 v151, v151, v161, vcc
	v_sqrt_f32_e32 v161, v151
	v_and_b32_e32 v166, 0xffff0000, v166
	v_lshlrev_b32_e32 v181, 16, v167
	v_and_b32_e32 v167, 0xffff0000, v167
	v_add_u32_e32 v187, -1, v161
	v_add_u32_e32 v188, 1, v161
	v_fma_f32 v189, -v187, v161, v151
	v_fma_f32 v190, -v188, v161, v151
	v_cmp_ge_f32_e64 s[8:9], 0, v189
	v_lshlrev_b32_e32 v176, 16, v162
	v_and_b32_e32 v162, 0xffff0000, v162
	v_cndmask_b32_e64 v161, v161, v187, s[8:9]
	v_cmp_lt_f32_e64 s[8:9], 0, v190
	v_lshlrev_b32_e32 v177, 16, v163
	v_and_b32_e32 v163, 0xffff0000, v163
	v_cndmask_b32_e64 v161, v161, v188, s[8:9]
	v_mul_f32_e32 v187, 0x37800000, v161
	v_cndmask_b32_e32 v161, v161, v187, vcc
	v_cmp_class_f32_e32 vcc, v151, v160
	v_lshlrev_b32_e32 v178, 16, v164
	v_and_b32_e32 v164, 0xffff0000, v164
	v_cndmask_b32_e32 v151, v161, v151, vcc
	v_div_scale_f32 v161, s[0:1], v151, v151, 1.0
	v_rcp_f32_e32 v187, v161
	v_div_scale_f32 v188, vcc, 1.0, v151, 1.0
	v_lshlrev_b32_e32 v182, 16, v168
	v_fma_f32 v189, -v161, v187, 1.0
	v_fmac_f32_e32 v187, v189, v187
	v_mul_f32_e32 v189, v188, v187
	v_fma_f32 v190, -v161, v189, v188
	v_fmac_f32_e32 v189, v190, v187
	v_fma_f32 v161, -v161, v189, v188
	v_div_fmas_f32 v161, v161, v187, v189
	v_div_fixup_f32 v151, v161, v151, 1.0
	v_mul_f32_e32 v125, v125, v151
	v_mul_f32_e32 v127, v127, v151
	v_mul_f32_e32 v124, v124, v151
	v_mul_f32_e32 v120, v120, v151
	v_mul_f32_e32 v121, v121, v151
	v_mul_f32_e32 v126, v126, v151
	v_mul_f32_e32 v125, 0xbfb8aa3b, v125
	v_mul_f32_e32 v127, 0xbfb8aa3b, v127
	v_mul_f32_e32 v122, v122, v151
	v_mul_f32_e32 v123, v123, v151
	v_mul_f32_e32 v124, 0xbfb8aa3b, v124
	v_mul_f32_e32 v120, 0xbfb8aa3b, v120
	v_mul_f32_e32 v121, 0xbfb8aa3b, v121
	v_mul_f32_e32 v126, 0xbfb8aa3b, v126
	v_exp_f32_e32 v125, v125
	v_exp_f32_e32 v127, v127
	v_mul_f32_e32 v122, 0xbfb8aa3b, v122
	v_mul_f32_e32 v123, 0xbfb8aa3b, v123
	v_exp_f32_e32 v124, v124
	v_exp_f32_e32 v120, v120
	v_exp_f32_e32 v121, v121
	v_exp_f32_e32 v126, v126
	v_exp_f32_e32 v122, v122
	v_exp_f32_e32 v123, v123
	v_add_f32_e32 v125, 1.0, v125
	v_add_f32_e32 v127, 1.0, v127
	v_add_f32_e32 v124, 1.0, v124
	v_add_f32_e32 v120, 1.0, v120
	v_add_f32_e32 v121, 1.0, v121
	v_add_f32_e32 v126, 1.0, v126
	v_rcp_f32_e32 v125, v125
	v_rcp_f32_e32 v127, v127
	v_add_f32_e32 v122, 1.0, v122
	v_add_f32_e32 v123, 1.0, v123
	v_rcp_f32_e32 v124, v124
	v_rcp_f32_e32 v120, v120
	v_rcp_f32_e32 v121, v121
	v_rcp_f32_e32 v126, v126
	v_rcp_f32_e32 v122, v122
	v_rcp_f32_e32 v123, v123
	v_and_b32_e32 v168, 0xffff0000, v168
	v_fmac_f32_e32 v162, v125, v166
	v_fmac_f32_e32 v163, v127, v167
	v_lshlrev_b32_e32 v179, 16, v165
	v_and_b32_e32 v165, 0xffff0000, v165
	v_lshlrev_b32_e32 v183, 16, v169
	v_and_b32_e32 v169, 0xffff0000, v169
	v_fmac_f32_e32 v176, v124, v180
	v_fmac_f32_e32 v178, v120, v182
	v_fmac_f32_e32 v164, v121, v168
	v_fmac_f32_e32 v177, v126, v181
	v_cvt_pk_bf16_f32 v120, v176, v162
	v_cvt_pk_bf16_f32 v121, v177, v163
	v_lshl_add_u64 v[162:163], s[18:19], 0, v[172:173]
	v_fmac_f32_e32 v179, v122, v183
	v_fmac_f32_e32 v165, v123, v169
	v_cvt_pk_bf16_f32 v122, v178, v164
	v_cvt_pk_bf16_f32 v123, v179, v165
	global_store_dwordx4 v[162:163], v[120:123], off
	s_waitcnt vmcnt(15)
; DI float bf_lo(unsigned u) { return __uint_as_float(u << 16); }
; DI float bf_hi(unsigned u) { return __uint_as_float(u & 0xffff0000u); }
; DI float sigmoidf_(float x) { return __builtin_amdgcn_rcpf(1.0f + __builtin_amdgcn_exp2f(-x * LOG2E)); }
; DI float rs_of(const float* ss, int row) { return 1.0f / sqrtf(ss[row] * (1.0f / DM) + EPS); }
; DI u32x4 pack8(f32x4 a, f32x4 b) { u32x4 w; w.x = cvt_pk_bf16(a[0], a[1]); w.y = cvt_pk_bf16(a[2], a[3]); w.z = cvt_pk_bf16(b[0], b[1]); w.w = cvt_pk_bf16(b[2], b[3]); return w; }
;     DI void operator()(AccRef acc, const Unit& u, int wr, int wc, int fr, int fq) const {
;     ...
;             for (int m = 0; m < 4; ++m) { const int row = u.pm * 256 + ai * 128 + wr * 64 + m * 16 + fr; const size_t off = (size_t)row * DM + col0; const float r = rs_of(ss, row);
; #pragma unroll
;                 for (int bj = 0; bj < 2; ++bj) {
;                     const u32x4 ev = *(const u32x4*)(Eb + off + bj * 128), uv = *(const u32x4*)(UPh + (size_t)row * 2304 + col0 + bj * 128);
;                     const f32x4 e0 = {bf_lo(ev.x), bf_hi(ev.x), bf_lo(ev.y), bf_hi(ev.y)}, e1 = {bf_lo(ev.z), bf_hi(ev.z), bf_lo(ev.w), bf_hi(ev.w)};
;                     f32x4 h0 = {bf_lo(uv.x), bf_hi(uv.x), bf_lo(uv.y), bf_hi(uv.y)}, h1 = {bf_lo(uv.z), bf_hi(uv.z), bf_lo(uv.w), bf_hi(uv.w)};
; #pragma unroll
;                     for (int j = 0; j < 4; ++j) { h0[j] += sigmoidf_(acc[ai][bj][m][0][j] * r) * e0[j]; h1[j] += sigmoidf_(acc[ai][bj][m][1][j] * r) * e1[j]; }
;                     *(u32x4*)(Hf + off + bj * 128) = pack8(h0, h1); } }
	v_mov_b64_e32 v[124:125], v[206:207]
	v_mov_b64_e32 v[126:127], v[208:209]
	global_load_dwordx4 v[206:209], v[238:239], off offset:256
	v_mul_f32_e32 v116, v116, v151
	s_waitcnt vmcnt(15)
	v_mov_b64_e32 v[120:121], v[210:211]
	v_mov_b64_e32 v[122:123], v[212:213]
	global_load_dwordx4 v[210:213], v[240:241], off offset:256
	v_mul_f32_e32 v112, v112, v151
	v_mul_f32_e32 v117, v117, v151
	v_mul_f32_e32 v113, v113, v151
	v_mul_f32_e32 v118, v118, v151
	v_mul_f32_e32 v114, v114, v151
	v_mul_f32_e32 v119, v119, v151
	v_mul_f32_e32 v115, v115, v151
	v_mul_f32_e32 v116, 0xbfb8aa3b, v116
	v_mul_f32_e32 v112, 0xbfb8aa3b, v112
	v_mul_f32_e32 v117, 0xbfb8aa3b, v117
	v_mul_f32_e32 v113, 0xbfb8aa3b, v113
	v_mul_f32_e32 v118, 0xbfb8aa3b, v118
	v_mul_f32_e32 v114, 0xbfb8aa3b, v114
	v_mul_f32_e32 v119, 0xbfb8aa3b, v119
	v_mul_f32_e32 v115, 0xbfb8aa3b, v115
	v_exp_f32_e32 v116, v116
	v_exp_f32_e32 v112, v112
	v_exp_f32_e32 v117, v117
	v_exp_f32_e32 v113, v113
	v_exp_f32_e32 v118, v118
	v_exp_f32_e32 v114, v114
	v_exp_f32_e32 v119, v119
	v_exp_f32_e32 v115, v115
	v_add_f32_e32 v116, 1.0, v116
	v_add_f32_e32 v112, 1.0, v112
	v_add_f32_e32 v117, 1.0, v117
	v_add_f32_e32 v113, 1.0, v113
	v_add_f32_e32 v118, 1.0, v118
	v_add_f32_e32 v114, 1.0, v114
	v_add_f32_e32 v119, 1.0, v119
	v_add_f32_e32 v115, 1.0, v115
	v_add_u32_e32 v164, 16, v150
	v_rcp_f32_e32 v116, v116
	v_rcp_f32_e32 v112, v112
	v_rcp_f32_e32 v117, v117
	v_rcp_f32_e32 v113, v113
	v_rcp_f32_e32 v118, v118
	v_rcp_f32_e32 v114, v114
	v_rcp_f32_e32 v119, v119
	v_rcp_f32_e32 v115, v115
	v_ashrrev_i32_e32 v165, 31, v164
	v_lshlrev_b64 v[166:167], 11, v[164:165]
	v_lshl_add_u64 v[168:169], v[164:165], 2, s[28:29]
	v_lshl_add_u64 v[166:167], v[166:167], 0, v[148:149]
	v_lshlrev_b64 v[166:167], 1, v[166:167]
	v_lshl_add_u64 v[170:171], s[14:15], 0, v[166:167]
	v_lshlrev_b32_e32 v151, 16, v124
	v_and_b32_e32 v124, 0xffff0000, v124
	v_lshlrev_b32_e32 v161, 16, v125
	v_and_b32_e32 v125, 0xffff0000, v125
	v_lshlrev_b32_e32 v165, 16, v126
	v_and_b32_e32 v126, 0xffff0000, v126
	v_lshlrev_b32_e32 v172, 16, v127
	v_and_b32_e32 v127, 0xffff0000, v127
	v_lshlrev_b32_e32 v173, 16, v120
	v_and_b32_e32 v120, 0xffff0000, v120
	v_lshlrev_b32_e32 v174, 16, v121
	v_and_b32_e32 v121, 0xffff0000, v121
	v_lshlrev_b32_e32 v175, 16, v122
	v_and_b32_e32 v122, 0xffff0000, v122
	v_lshlrev_b32_e32 v176, 16, v123
	v_and_b32_e32 v123, 0xffff0000, v123
	v_fmac_f32_e32 v173, v116, v151
	v_fmac_f32_e32 v175, v112, v165
	v_fmac_f32_e32 v120, v117, v124
	v_fmac_f32_e32 v122, v113, v126
	v_fmac_f32_e32 v174, v118, v161
	v_fmac_f32_e32 v176, v114, v172
	v_fmac_f32_e32 v121, v119, v125
	v_fmac_f32_e32 v123, v115, v127
	v_cvt_pk_bf16_f32 v112, v173, v120
	v_cvt_pk_bf16_f32 v113, v174, v121
	v_cvt_pk_bf16_f32 v114, v175, v122
	v_cvt_pk_bf16_f32 v115, v176, v123
	global_store_dwordx4 v[162:163], v[112:115], off offset:256
	s_waitcnt vmcnt(16)
	v_mov_b32_e32 v122, v193
	s_nop 0
	s_waitcnt vmcnt(15)
	v_mov_b64_e32 v[112:113], v[214:215]
	v_mov_b64_e32 v[114:115], v[216:217]
	s_mov_b32 s4, 0x10000
	v_lshl_add_u64 v[238:239], v[238:239], 0, s[4:5]
	global_load_dwordx4 v[214:217], v[238:239], off
	v_mad_i64_i32 v[116:117], s[0:1], v164, s65, v[144:145]
	v_lshl_add_u64 v[120:121], v[116:117], 0, v[146:147]
	s_waitcnt vmcnt(15)
	v_mov_b64_e32 v[116:117], v[218:219]
	v_mov_b64_e32 v[118:119], v[220:221]
	s_mov_b32 s4, 0x12000
	v_lshl_add_u64 v[240:241], v[240:241], 0, s[4:5]
	global_load_dwordx4 v[218:221], v[240:241], off
	v_fmamk_f32 v122, v122, 0x3a000000, v159
	v_mul_f32_e32 v161, 0x4f800000, v122
	v_cmp_gt_f32_e32 vcc, s64, v122
	v_lshlrev_b32_e32 v123, 16, v112
	v_and_b32_e32 v112, 0xffff0000, v112
	v_cndmask_b32_e32 v122, v122, v161, vcc
	v_sqrt_f32_e32 v161, v122
	v_lshlrev_b32_e32 v124, 16, v113
	v_and_b32_e32 v113, 0xffff0000, v113
	v_lshlrev_b32_e32 v127, 16, v116
	v_add_u32_e32 v164, -1, v161
	v_add_u32_e32 v165, 1, v161
	v_fma_f32 v168, -v164, v161, v122
	v_fma_f32 v169, -v165, v161, v122
	v_cmp_ge_f32_e64 s[8:9], 0, v168
	v_and_b32_e32 v116, 0xffff0000, v116
	v_lshlrev_b32_e32 v151, 16, v117
	v_cndmask_b32_e64 v161, v161, v164, s[8:9]
	v_cmp_lt_f32_e64 s[8:9], 0, v169
	v_and_b32_e32 v117, 0xffff0000, v117
	v_lshlrev_b32_e32 v125, 16, v114
	v_cndmask_b32_e64 v161, v161, v165, s[8:9]
	v_mul_f32_e32 v164, 0x37800000, v161
	v_cndmask_b32_e32 v161, v161, v164, vcc
	v_cmp_class_f32_e32 vcc, v122, v160
	v_and_b32_e32 v114, 0xffff0000, v114
	v_lshlrev_b32_e32 v126, 16, v115
	v_cndmask_b32_e32 v122, v161, v122, vcc
	v_div_scale_f32 v161, s[0:1], v122, v122, 1.0
	v_rcp_f32_e32 v164, v161
	v_div_scale_f32 v165, vcc, 1.0, v122, 1.0
	v_and_b32_e32 v115, 0xffff0000, v115
	v_fma_f32 v168, -v161, v164, 1.0
	v_fmac_f32_e32 v164, v168, v164
	v_mul_f32_e32 v168, v165, v164
	v_fma_f32 v169, -v161, v168, v165
	v_fmac_f32_e32 v168, v169, v164
	v_fma_f32 v161, -v161, v168, v165
	v_div_fmas_f32 v161, v161, v164, v168
	v_div_fixup_f32 v122, v161, v122, 1.0
	v_mul_f32_e32 v109, v109, v122
	v_mul_f32_e32 v111, v111, v122
	v_mul_f32_e32 v108, v108, v122
	v_mul_f32_e32 v104, v104, v122
	v_mul_f32_e32 v105, v105, v122
	v_mul_f32_e32 v110, v110, v122
	v_mul_f32_e32 v106, v106, v122
	v_mul_f32_e32 v107, v107, v122
	v_mul_f32_e32 v109, 0xbfb8aa3b, v109
	v_mul_f32_e32 v111, 0xbfb8aa3b, v111
	v_mul_f32_e32 v108, 0xbfb8aa3b, v108
	v_mul_f32_e32 v104, 0xbfb8aa3b, v104
	v_mul_f32_e32 v105, 0xbfb8aa3b, v105
	v_mul_f32_e32 v110, 0xbfb8aa3b, v110
	v_mul_f32_e32 v106, 0xbfb8aa3b, v106
	v_mul_f32_e32 v107, 0xbfb8aa3b, v107
	v_exp_f32_e32 v109, v109
	v_exp_f32_e32 v111, v111
	v_exp_f32_e32 v108, v108
	v_exp_f32_e32 v104, v104
	v_exp_f32_e32 v105, v105
	v_exp_f32_e32 v110, v110
	v_exp_f32_e32 v106, v106
	v_exp_f32_e32 v107, v107
	v_add_f32_e32 v109, 1.0, v109
	v_add_f32_e32 v111, 1.0, v111
	v_add_f32_e32 v108, 1.0, v108
	v_add_f32_e32 v104, 1.0, v104
	v_add_f32_e32 v105, 1.0, v105
	v_add_f32_e32 v110, 1.0, v110
	v_add_f32_e32 v106, 1.0, v106
	v_add_f32_e32 v107, 1.0, v107
	v_rcp_f32_e32 v109, v109
	v_rcp_f32_e32 v111, v111
	v_rcp_f32_e32 v108, v108
	v_rcp_f32_e32 v104, v104
	v_rcp_f32_e32 v105, v105
	v_rcp_f32_e32 v110, v110
	v_rcp_f32_e32 v106, v106
	v_rcp_f32_e32 v107, v107
	v_lshlrev_b32_e32 v162, 16, v118
	v_and_b32_e32 v118, 0xffff0000, v118
	v_lshlrev_b32_e32 v163, 16, v119
	v_and_b32_e32 v119, 0xffff0000, v119
	v_fmac_f32_e32 v116, v109, v112
	v_fmac_f32_e32 v117, v111, v113
	v_lshl_add_u64 v[112:113], s[18:19], 0, v[166:167]
	v_fmac_f32_e32 v127, v108, v123
	v_fmac_f32_e32 v162, v104, v125
	v_fmac_f32_e32 v118, v105, v114
	v_fmac_f32_e32 v151, v110, v124
	v_fmac_f32_e32 v163, v106, v126
	v_fmac_f32_e32 v119, v107, v115
	v_cvt_pk_bf16_f32 v104, v127, v116
	v_cvt_pk_bf16_f32 v105, v151, v117
	v_cvt_pk_bf16_f32 v106, v162, v118
	v_cvt_pk_bf16_f32 v107, v163, v119
	global_store_dwordx4 v[112:113], v[104:107], off
	s_waitcnt vmcnt(16)
; DI float bf_lo(unsigned u) { return __uint_as_float(u << 16); }
; DI float bf_hi(unsigned u) { return __uint_as_float(u & 0xffff0000u); }
; DI float sigmoidf_(float x) { return __builtin_amdgcn_rcpf(1.0f + __builtin_amdgcn_exp2f(-x * LOG2E)); }
; DI float rs_of(const float* ss, int row) { return 1.0f / sqrtf(ss[row] * (1.0f / DM) + EPS); }
; DI u32x4 pack8(f32x4 a, f32x4 b) { u32x4 w; w.x = cvt_pk_bf16(a[0], a[1]); w.y = cvt_pk_bf16(a[2], a[3]); w.z = cvt_pk_bf16(b[0], b[1]); w.w = cvt_pk_bf16(b[2], b[3]); return w; }
;     DI void operator()(AccRef acc, const Unit& u, int wr, int wc, int fr, int fq) const {
;     ...
;             for (int m = 0; m < 4; ++m) { const int row = u.pm * 256 + ai * 128 + wr * 64 + m * 16 + fr; const size_t off = (size_t)row * DM + col0; const float r = rs_of(ss, row);
; #pragma unroll
;                 for (int bj = 0; bj < 2; ++bj) {
;                     const u32x4 ev = *(const u32x4*)(Eb + off + bj * 128), uv = *(const u32x4*)(UPh + (size_t)row * 2304 + col0 + bj * 128);
;                     const f32x4 e0 = {bf_lo(ev.x), bf_hi(ev.x), bf_lo(ev.y), bf_hi(ev.y)}, e1 = {bf_lo(ev.z), bf_hi(ev.z), bf_lo(ev.w), bf_hi(ev.w)};
;                     f32x4 h0 = {bf_lo(uv.x), bf_hi(uv.x), bf_lo(uv.y), bf_hi(uv.y)}, h1 = {bf_lo(uv.z), bf_hi(uv.z), bf_lo(uv.w), bf_hi(uv.w)};
; #pragma unroll
;                     for (int j = 0; j < 4; ++j) { h0[j] += sigmoidf_(acc[ai][bj][m][0][j] * r) * e0[j]; h1[j] += sigmoidf_(acc[ai][bj][m][1][j] * r) * e1[j]; }
;                     *(u32x4*)(Hf + off + bj * 128) = pack8(h0, h1); } }
	v_mov_b64_e32 v[108:109], v[222:223]
	v_mov_b64_e32 v[110:111], v[224:225]
	global_load_dwordx4 v[222:225], v[238:239], off offset:256
	v_mul_f32_e32 v100, v100, v122
	s_waitcnt vmcnt(16)
	v_mov_b64_e32 v[104:105], v[226:227]
	v_mov_b64_e32 v[106:107], v[228:229]
	global_load_dwordx4 v[226:229], v[240:241], off offset:256
	v_mul_f32_e32 v96, v96, v122
	v_mul_f32_e32 v101, v101, v122
	v_mul_f32_e32 v97, v97, v122
	v_mul_f32_e32 v102, v102, v122
	v_mul_f32_e32 v98, v98, v122
	v_mul_f32_e32 v103, v103, v122
	v_mul_f32_e32 v99, v99, v122
	v_mul_f32_e32 v100, 0xbfb8aa3b, v100
	v_mul_f32_e32 v96, 0xbfb8aa3b, v96
	v_mul_f32_e32 v101, 0xbfb8aa3b, v101
	v_mul_f32_e32 v97, 0xbfb8aa3b, v97
	v_mul_f32_e32 v102, 0xbfb8aa3b, v102
	v_mul_f32_e32 v98, 0xbfb8aa3b, v98
	v_mul_f32_e32 v103, 0xbfb8aa3b, v103
	v_mul_f32_e32 v99, 0xbfb8aa3b, v99
	v_exp_f32_e32 v100, v100
	v_exp_f32_e32 v96, v96
	v_exp_f32_e32 v101, v101
	v_exp_f32_e32 v97, v97
	v_exp_f32_e32 v102, v102
	v_exp_f32_e32 v98, v98
	v_exp_f32_e32 v103, v103
	v_exp_f32_e32 v99, v99
	v_add_f32_e32 v100, 1.0, v100
	v_add_f32_e32 v96, 1.0, v96
	v_add_f32_e32 v101, 1.0, v101
	v_add_f32_e32 v97, 1.0, v97
	v_add_f32_e32 v102, 1.0, v102
	v_add_f32_e32 v98, 1.0, v98
	v_add_f32_e32 v103, 1.0, v103
	v_add_f32_e32 v99, 1.0, v99
	v_add_u32_e32 v114, 32, v150
	v_rcp_f32_e32 v100, v100
	v_rcp_f32_e32 v96, v96
	v_rcp_f32_e32 v101, v101
	v_rcp_f32_e32 v97, v97
	v_rcp_f32_e32 v102, v102
	v_rcp_f32_e32 v98, v98
	v_rcp_f32_e32 v103, v103
	v_rcp_f32_e32 v99, v99
	v_ashrrev_i32_e32 v115, 31, v114
	v_lshlrev_b64 v[116:117], 11, v[114:115]
	v_lshl_add_u64 v[118:119], v[114:115], 2, s[28:29]
	v_lshl_add_u64 v[116:117], v[116:117], 0, v[148:149]
	v_lshlrev_b64 v[116:117], 1, v[116:117]
	v_lshl_add_u64 v[120:121], s[14:15], 0, v[116:117]
	v_lshlrev_b32_e32 v115, 16, v108
	v_and_b32_e32 v108, 0xffff0000, v108
	v_lshlrev_b32_e32 v122, 16, v109
	v_and_b32_e32 v109, 0xffff0000, v109
	v_lshlrev_b32_e32 v123, 16, v110
	v_and_b32_e32 v110, 0xffff0000, v110
	v_lshlrev_b32_e32 v124, 16, v111
	v_and_b32_e32 v111, 0xffff0000, v111
	v_lshlrev_b32_e32 v125, 16, v104
	v_and_b32_e32 v104, 0xffff0000, v104
	v_lshlrev_b32_e32 v126, 16, v105
	v_and_b32_e32 v105, 0xffff0000, v105
	v_lshlrev_b32_e32 v127, 16, v106
	v_and_b32_e32 v106, 0xffff0000, v106
	v_lshlrev_b32_e32 v151, 16, v107
	v_and_b32_e32 v107, 0xffff0000, v107
	v_fmac_f32_e32 v125, v100, v115
	v_fmac_f32_e32 v127, v96, v123
	v_fmac_f32_e32 v104, v101, v108
	v_fmac_f32_e32 v106, v97, v110
	v_fmac_f32_e32 v126, v102, v122
	v_fmac_f32_e32 v151, v98, v124
	v_fmac_f32_e32 v105, v103, v109
	v_fmac_f32_e32 v107, v99, v111
	v_cvt_pk_bf16_f32 v96, v125, v104
	v_cvt_pk_bf16_f32 v97, v126, v105
	v_cvt_pk_bf16_f32 v98, v127, v106
	v_cvt_pk_bf16_f32 v99, v151, v107
	global_store_dwordx4 v[112:113], v[96:99], off offset:256
	s_waitcnt vmcnt(17)
	v_mov_b32_e32 v106, v205
	s_nop 0
	s_waitcnt vmcnt(11)
	v_mov_b64_e32 v[96:97], v[196:197]
	v_mov_b64_e32 v[98:99], v[198:199]
	s_mov_b32 s4, 0x50000
	v_lshl_add_u64 v[238:239], v[238:239], 0, s[4:5]
	global_load_dwordx4 v[196:199], v[238:239], off
	v_mad_i64_i32 v[100:101], s[0:1], v114, s65, v[144:145]
	v_lshl_add_u64 v[104:105], v[100:101], 0, v[146:147]
	s_waitcnt vmcnt(11)
	v_mov_b64_e32 v[100:101], v[200:201]
	v_mov_b64_e32 v[102:103], v[202:203]
	s_mov_b32 s4, 0x5a000
	v_lshl_add_u64 v[240:241], v[240:241], 0, s[4:5]
	global_load_dwordx4 v[200:203], v[240:241], off
	v_fmamk_f32 v106, v106, 0x3a000000, v159
	v_mul_f32_e32 v113, 0x4f800000, v106
	v_cmp_gt_f32_e32 vcc, s64, v106
	v_lshlrev_b32_e32 v107, 16, v96
	v_and_b32_e32 v96, 0xffff0000, v96
	v_cndmask_b32_e32 v106, v106, v113, vcc
	v_sqrt_f32_e32 v113, v106
	v_lshlrev_b32_e32 v108, 16, v97
	v_and_b32_e32 v97, 0xffff0000, v97
	v_lshlrev_b32_e32 v111, 16, v100
	v_add_u32_e32 v118, -1, v113
	v_add_u32_e32 v119, 1, v113
	v_fma_f32 v122, -v118, v113, v106
	v_fma_f32 v123, -v119, v113, v106
	v_cmp_ge_f32_e64 s[8:9], 0, v122
	v_and_b32_e32 v100, 0xffff0000, v100
	v_lshlrev_b32_e32 v112, 16, v101
	v_cndmask_b32_e64 v113, v113, v118, s[8:9]
	v_cmp_lt_f32_e64 s[8:9], 0, v123
	v_and_b32_e32 v101, 0xffff0000, v101
	v_lshlrev_b32_e32 v109, 16, v98
	v_cndmask_b32_e64 v113, v113, v119, s[8:9]
	v_mul_f32_e32 v118, 0x37800000, v113
	v_cndmask_b32_e32 v113, v113, v118, vcc
	v_cmp_class_f32_e32 vcc, v106, v160
	v_and_b32_e32 v98, 0xffff0000, v98
	v_lshlrev_b32_e32 v110, 16, v99
	v_cndmask_b32_e32 v106, v113, v106, vcc
	v_div_scale_f32 v113, s[0:1], v106, v106, 1.0
	v_rcp_f32_e32 v118, v113
	v_div_scale_f32 v119, vcc, 1.0, v106, 1.0
	v_and_b32_e32 v99, 0xffff0000, v99
	v_fma_f32 v122, -v113, v118, 1.0
	v_fmac_f32_e32 v118, v122, v118
	v_mul_f32_e32 v122, v119, v118
	v_fma_f32 v123, -v113, v122, v119
	v_fmac_f32_e32 v122, v123, v118
	v_fma_f32 v113, -v113, v122, v119
	v_div_fmas_f32 v113, v113, v118, v122
	v_div_fixup_f32 v106, v113, v106, 1.0
	v_mul_f32_e32 v93, v93, v106
	v_mul_f32_e32 v95, v95, v106
	v_mul_f32_e32 v92, v92, v106
	v_mul_f32_e32 v88, v88, v106
	v_mul_f32_e32 v89, v89, v106
	v_mul_f32_e32 v94, v94, v106
	v_mul_f32_e32 v90, v90, v106
	v_mul_f32_e32 v91, v91, v106
	v_mul_f32_e32 v93, 0xbfb8aa3b, v93
	v_mul_f32_e32 v95, 0xbfb8aa3b, v95
	v_mul_f32_e32 v92, 0xbfb8aa3b, v92
	v_mul_f32_e32 v88, 0xbfb8aa3b, v88
	v_mul_f32_e32 v89, 0xbfb8aa3b, v89
	v_mul_f32_e32 v94, 0xbfb8aa3b, v94
	v_mul_f32_e32 v90, 0xbfb8aa3b, v90
	v_mul_f32_e32 v91, 0xbfb8aa3b, v91
	v_exp_f32_e32 v93, v93
	v_exp_f32_e32 v95, v95
	v_exp_f32_e32 v92, v92
	v_exp_f32_e32 v88, v88
	v_exp_f32_e32 v89, v89
	v_exp_f32_e32 v94, v94
	v_exp_f32_e32 v90, v90
	v_exp_f32_e32 v91, v91
	v_add_f32_e32 v93, 1.0, v93
	v_add_f32_e32 v95, 1.0, v95
	v_add_f32_e32 v92, 1.0, v92
	v_add_f32_e32 v88, 1.0, v88
	v_add_f32_e32 v89, 1.0, v89
	v_add_f32_e32 v94, 1.0, v94
	v_add_f32_e32 v90, 1.0, v90
	v_add_f32_e32 v91, 1.0, v91
	v_rcp_f32_e32 v93, v93
	v_rcp_f32_e32 v95, v95
	v_rcp_f32_e32 v92, v92
	v_rcp_f32_e32 v88, v88
	v_rcp_f32_e32 v89, v89
	v_rcp_f32_e32 v94, v94
	v_rcp_f32_e32 v90, v90
	v_rcp_f32_e32 v91, v91
	v_lshlrev_b32_e32 v114, 16, v102
	v_and_b32_e32 v102, 0xffff0000, v102
	v_lshlrev_b32_e32 v115, 16, v103
	v_and_b32_e32 v103, 0xffff0000, v103
	v_fmac_f32_e32 v100, v93, v96
	v_fmac_f32_e32 v101, v95, v97
	v_lshl_add_u64 v[96:97], s[18:19], 0, v[116:117]
	v_fmac_f32_e32 v111, v92, v107
	v_fmac_f32_e32 v114, v88, v109
	v_fmac_f32_e32 v102, v89, v98
	v_fmac_f32_e32 v112, v94, v108
	v_fmac_f32_e32 v115, v90, v110
	v_fmac_f32_e32 v103, v91, v99
	v_cvt_pk_bf16_f32 v88, v111, v100
	v_cvt_pk_bf16_f32 v89, v112, v101
	v_cvt_pk_bf16_f32 v90, v114, v102
	v_cvt_pk_bf16_f32 v91, v115, v103
	global_store_dwordx4 v[96:97], v[88:91], off
	s_waitcnt vmcnt(11)
; DI float bf_lo(unsigned u) { return __uint_as_float(u << 16); }
; DI float bf_hi(unsigned u) { return __uint_as_float(u & 0xffff0000u); }
; DI float sigmoidf_(float x) { return __builtin_amdgcn_rcpf(1.0f + __builtin_amdgcn_exp2f(-x * LOG2E)); }
; DI float rs_of(const float* ss, int row) { return 1.0f / sqrtf(ss[row] * (1.0f / DM) + EPS); }
; DI u32x4 pack8(f32x4 a, f32x4 b) { u32x4 w; w.x = cvt_pk_bf16(a[0], a[1]); w.y = cvt_pk_bf16(a[2], a[3]); w.z = cvt_pk_bf16(b[0], b[1]); w.w = cvt_pk_bf16(b[2], b[3]); return w; }
;     DI void operator()(AccRef acc, const Unit& u, int wr, int wc, int fr, int fq) const {
;     ...
;             for (int m = 0; m < 4; ++m) { const int row = u.pm * 256 + ai * 128 + wr * 64 + m * 16 + fr; const size_t off = (size_t)row * DM + col0; const float r = rs_of(ss, row);
; #pragma unroll
;                 for (int bj = 0; bj < 2; ++bj) {
;                     const u32x4 ev = *(const u32x4*)(Eb + off + bj * 128), uv = *(const u32x4*)(UPh + (size_t)row * 2304 + col0 + bj * 128);
;                     const f32x4 e0 = {bf_lo(ev.x), bf_hi(ev.x), bf_lo(ev.y), bf_hi(ev.y)}, e1 = {bf_lo(ev.z), bf_hi(ev.z), bf_lo(ev.w), bf_hi(ev.w)};
;                     f32x4 h0 = {bf_lo(uv.x), bf_hi(uv.x), bf_lo(uv.y), bf_hi(uv.y)}, h1 = {bf_lo(uv.z), bf_hi(uv.z), bf_lo(uv.w), bf_hi(uv.w)};
; #pragma unroll
;                     for (int j = 0; j < 4; ++j) { h0[j] += sigmoidf_(acc[ai][bj][m][0][j] * r) * e0[j]; h1[j] += sigmoidf_(acc[ai][bj][m][1][j] * r) * e1[j]; }
;                     *(u32x4*)(Hf + off + bj * 128) = pack8(h0, h1); } }
	v_mov_b64_e32 v[92:93], v[206:207]
	v_mov_b64_e32 v[94:95], v[208:209]
	global_load_dwordx4 v[206:209], v[238:239], off offset:256
	v_mul_f32_e32 v84, v84, v106
	s_waitcnt vmcnt(11)
	v_mov_b64_e32 v[88:89], v[210:211]
	v_mov_b64_e32 v[90:91], v[212:213]
	global_load_dwordx4 v[210:213], v[240:241], off offset:256
	v_mul_f32_e32 v80, v80, v106
	v_mul_f32_e32 v85, v85, v106
	v_mul_f32_e32 v81, v81, v106
	v_mul_f32_e32 v86, v86, v106
	v_mul_f32_e32 v82, v82, v106
	v_mul_f32_e32 v87, v87, v106
	v_mul_f32_e32 v83, v83, v106
	v_mul_f32_e32 v84, 0xbfb8aa3b, v84
	v_mul_f32_e32 v80, 0xbfb8aa3b, v80
	v_mul_f32_e32 v85, 0xbfb8aa3b, v85
	v_mul_f32_e32 v81, 0xbfb8aa3b, v81
	v_mul_f32_e32 v86, 0xbfb8aa3b, v86
	v_mul_f32_e32 v82, 0xbfb8aa3b, v82
	v_mul_f32_e32 v87, 0xbfb8aa3b, v87
	v_mul_f32_e32 v83, 0xbfb8aa3b, v83
	v_exp_f32_e32 v84, v84
	v_exp_f32_e32 v80, v80
	v_exp_f32_e32 v85, v85
	v_exp_f32_e32 v81, v81
	v_exp_f32_e32 v86, v86
	v_exp_f32_e32 v82, v82
	v_exp_f32_e32 v87, v87
	v_exp_f32_e32 v83, v83
	v_add_f32_e32 v84, 1.0, v84
	v_add_f32_e32 v80, 1.0, v80
	v_add_f32_e32 v85, 1.0, v85
	v_add_f32_e32 v81, 1.0, v81
	v_add_f32_e32 v86, 1.0, v86
	v_add_f32_e32 v82, 1.0, v82
	v_add_f32_e32 v87, 1.0, v87
	v_add_f32_e32 v83, 1.0, v83
	v_add_u32_e32 v98, 48, v150
	v_rcp_f32_e32 v84, v84
	v_rcp_f32_e32 v80, v80
	v_rcp_f32_e32 v85, v85
	v_rcp_f32_e32 v81, v81
	v_rcp_f32_e32 v86, v86
	v_rcp_f32_e32 v82, v82
	v_rcp_f32_e32 v87, v87
	v_rcp_f32_e32 v83, v83
	v_ashrrev_i32_e32 v99, 31, v98
	v_lshlrev_b64 v[100:101], 11, v[98:99]
	v_lshl_add_u64 v[102:103], v[98:99], 2, s[28:29]
	v_lshl_add_u64 v[100:101], v[100:101], 0, v[148:149]
	v_lshlrev_b64 v[100:101], 1, v[100:101]
	v_lshl_add_u64 v[104:105], s[14:15], 0, v[100:101]
	v_lshlrev_b32_e32 v99, 16, v92
	v_and_b32_e32 v92, 0xffff0000, v92
	v_lshlrev_b32_e32 v106, 16, v93
	v_and_b32_e32 v93, 0xffff0000, v93
	v_lshlrev_b32_e32 v107, 16, v94
	v_and_b32_e32 v94, 0xffff0000, v94
	v_lshlrev_b32_e32 v108, 16, v95
	v_and_b32_e32 v95, 0xffff0000, v95
	v_lshlrev_b32_e32 v109, 16, v88
	v_and_b32_e32 v88, 0xffff0000, v88
	v_lshlrev_b32_e32 v110, 16, v89
	v_and_b32_e32 v89, 0xffff0000, v89
	v_lshlrev_b32_e32 v111, 16, v90
	v_and_b32_e32 v90, 0xffff0000, v90
	v_lshlrev_b32_e32 v112, 16, v91
	v_and_b32_e32 v91, 0xffff0000, v91
	v_fmac_f32_e32 v109, v84, v99
	v_fmac_f32_e32 v111, v80, v107
	v_fmac_f32_e32 v88, v85, v92
	v_fmac_f32_e32 v90, v81, v94
	v_fmac_f32_e32 v110, v86, v106
	v_fmac_f32_e32 v112, v82, v108
	v_fmac_f32_e32 v89, v87, v93
	v_fmac_f32_e32 v91, v83, v95
	v_cvt_pk_bf16_f32 v80, v109, v88
	v_cvt_pk_bf16_f32 v81, v110, v89
	v_cvt_pk_bf16_f32 v82, v111, v90
	v_cvt_pk_bf16_f32 v83, v112, v91
	global_store_dwordx4 v[96:97], v[80:83], off offset:256
	s_waitcnt vmcnt(22)
	v_mov_b32_e32 v90, v234
	s_nop 0
	s_waitcnt vmcnt(11)
	v_mov_b64_e32 v[80:81], v[214:215]
	v_mov_b64_e32 v[82:83], v[216:217]
	s_mov_b32 s4, 0x10000
	v_lshl_add_u64 v[238:239], v[238:239], 0, s[4:5]
	global_load_dwordx4 v[214:217], v[238:239], off
	v_mad_i64_i32 v[84:85], s[0:1], v98, s65, v[144:145]
	v_lshl_add_u64 v[88:89], v[84:85], 0, v[146:147]
	s_waitcnt vmcnt(11)
	v_mov_b64_e32 v[84:85], v[218:219]
	v_mov_b64_e32 v[86:87], v[220:221]
	s_mov_b32 s4, 0x12000
	v_lshl_add_u64 v[240:241], v[240:241], 0, s[4:5]
	global_load_dwordx4 v[218:221], v[240:241], off
	v_fmamk_f32 v90, v90, 0x3a000000, v159
	v_mul_f32_e32 v97, 0x4f800000, v90
	v_cmp_gt_f32_e32 vcc, s64, v90
	v_lshlrev_b32_e32 v91, 16, v80
	v_and_b32_e32 v80, 0xffff0000, v80
	v_cndmask_b32_e32 v90, v90, v97, vcc
	v_sqrt_f32_e32 v97, v90
	v_lshlrev_b32_e32 v92, 16, v81
	v_and_b32_e32 v81, 0xffff0000, v81
	v_lshlrev_b32_e32 v95, 16, v84
	v_add_u32_e32 v102, -1, v97
	v_add_u32_e32 v103, 1, v97
	v_fma_f32 v106, -v102, v97, v90
	v_fma_f32 v107, -v103, v97, v90
	v_cmp_ge_f32_e64 s[8:9], 0, v106
	v_and_b32_e32 v84, 0xffff0000, v84
	v_lshlrev_b32_e32 v96, 16, v85
	v_cndmask_b32_e64 v97, v97, v102, s[8:9]
	v_cmp_lt_f32_e64 s[8:9], 0, v107
	v_and_b32_e32 v85, 0xffff0000, v85
	v_lshlrev_b32_e32 v93, 16, v82
	v_cndmask_b32_e64 v97, v97, v103, s[8:9]
	v_mul_f32_e32 v102, 0x37800000, v97
	v_cndmask_b32_e32 v97, v97, v102, vcc
	v_cmp_class_f32_e32 vcc, v90, v160
	v_and_b32_e32 v82, 0xffff0000, v82
	v_lshlrev_b32_e32 v94, 16, v83
	v_cndmask_b32_e32 v90, v97, v90, vcc
	v_div_scale_f32 v97, s[0:1], v90, v90, 1.0
	v_rcp_f32_e32 v102, v97
	v_div_scale_f32 v103, vcc, 1.0, v90, 1.0
	v_and_b32_e32 v83, 0xffff0000, v83
	v_fma_f32 v106, -v97, v102, 1.0
	v_fmac_f32_e32 v102, v106, v102
	v_mul_f32_e32 v106, v103, v102
	v_fma_f32 v107, -v97, v106, v103
	v_fmac_f32_e32 v106, v107, v102
	v_fma_f32 v97, -v97, v106, v103
	v_div_fmas_f32 v97, v97, v102, v106
	v_div_fixup_f32 v90, v97, v90, 1.0
	v_mul_f32_e32 v77, v77, v90
	v_mul_f32_e32 v79, v79, v90
	v_mul_f32_e32 v76, v76, v90
	v_mul_f32_e32 v72, v72, v90
	v_mul_f32_e32 v73, v73, v90
	v_mul_f32_e32 v78, v78, v90
	v_mul_f32_e32 v74, v74, v90
	v_mul_f32_e32 v75, v75, v90
	v_mul_f32_e32 v77, 0xbfb8aa3b, v77
	v_mul_f32_e32 v79, 0xbfb8aa3b, v79
	v_mul_f32_e32 v76, 0xbfb8aa3b, v76
	v_mul_f32_e32 v72, 0xbfb8aa3b, v72
	v_mul_f32_e32 v73, 0xbfb8aa3b, v73
	v_mul_f32_e32 v78, 0xbfb8aa3b, v78
	v_mul_f32_e32 v74, 0xbfb8aa3b, v74
	v_mul_f32_e32 v75, 0xbfb8aa3b, v75
	v_exp_f32_e32 v77, v77
	v_exp_f32_e32 v79, v79
	v_exp_f32_e32 v76, v76
	v_exp_f32_e32 v72, v72
	v_exp_f32_e32 v73, v73
	v_exp_f32_e32 v78, v78
	v_exp_f32_e32 v74, v74
	v_exp_f32_e32 v75, v75
	v_add_f32_e32 v77, 1.0, v77
	v_add_f32_e32 v79, 1.0, v79
	v_add_f32_e32 v76, 1.0, v76
	v_add_f32_e32 v72, 1.0, v72
	v_add_f32_e32 v73, 1.0, v73
	v_add_f32_e32 v78, 1.0, v78
	v_add_f32_e32 v74, 1.0, v74
	v_add_f32_e32 v75, 1.0, v75
	v_rcp_f32_e32 v77, v77
	v_rcp_f32_e32 v79, v79
	v_rcp_f32_e32 v76, v76
	v_rcp_f32_e32 v72, v72
	v_rcp_f32_e32 v73, v73
	v_rcp_f32_e32 v78, v78
	v_rcp_f32_e32 v74, v74
	v_rcp_f32_e32 v75, v75
	v_lshlrev_b32_e32 v98, 16, v86
	v_and_b32_e32 v86, 0xffff0000, v86
	v_lshlrev_b32_e32 v99, 16, v87
	v_and_b32_e32 v87, 0xffff0000, v87
	v_fmac_f32_e32 v84, v77, v80
	v_fmac_f32_e32 v85, v79, v81
	v_lshl_add_u64 v[80:81], s[18:19], 0, v[100:101]
	v_fmac_f32_e32 v95, v76, v91
	v_fmac_f32_e32 v98, v72, v93
	v_fmac_f32_e32 v86, v73, v82
	v_fmac_f32_e32 v96, v78, v92
	v_fmac_f32_e32 v99, v74, v94
	v_fmac_f32_e32 v87, v75, v83
	v_cvt_pk_bf16_f32 v72, v95, v84
	v_cvt_pk_bf16_f32 v73, v96, v85
	v_cvt_pk_bf16_f32 v74, v98, v86
	v_cvt_pk_bf16_f32 v75, v99, v87
	global_store_dwordx4 v[80:81], v[72:75], off
	s_waitcnt vmcnt(11)
; DI float bf_lo(unsigned u) { return __uint_as_float(u << 16); }
; DI float bf_hi(unsigned u) { return __uint_as_float(u & 0xffff0000u); }
; DI float sigmoidf_(float x) { return __builtin_amdgcn_rcpf(1.0f + __builtin_amdgcn_exp2f(-x * LOG2E)); }
; DI float rs_of(const float* ss, int row) { return 1.0f / sqrtf(ss[row] * (1.0f / DM) + EPS); }
; DI u32x4 pack8(f32x4 a, f32x4 b) { u32x4 w; w.x = cvt_pk_bf16(a[0], a[1]); w.y = cvt_pk_bf16(a[2], a[3]); w.z = cvt_pk_bf16(b[0], b[1]); w.w = cvt_pk_bf16(b[2], b[3]); return w; }
;     DI void operator()(AccRef acc, const Unit& u, int wr, int wc, int fr, int fq) const {
;     ...
;             for (int m = 0; m < 4; ++m) { const int row = u.pm * 256 + ai * 128 + wr * 64 + m * 16 + fr; const size_t off = (size_t)row * DM + col0; const float r = rs_of(ss, row);
; #pragma unroll
;                 for (int bj = 0; bj < 2; ++bj) {
;                     const u32x4 ev = *(const u32x4*)(Eb + off + bj * 128), uv = *(const u32x4*)(UPh + (size_t)row * 2304 + col0 + bj * 128);
;                     const f32x4 e0 = {bf_lo(ev.x), bf_hi(ev.x), bf_lo(ev.y), bf_hi(ev.y)}, e1 = {bf_lo(ev.z), bf_hi(ev.z), bf_lo(ev.w), bf_hi(ev.w)};
;                     f32x4 h0 = {bf_lo(uv.x), bf_hi(uv.x), bf_lo(uv.y), bf_hi(uv.y)}, h1 = {bf_lo(uv.z), bf_hi(uv.z), bf_lo(uv.w), bf_hi(uv.w)};
; #pragma unroll
;                     for (int j = 0; j < 4; ++j) { h0[j] += sigmoidf_(acc[ai][bj][m][0][j] * r) * e0[j]; h1[j] += sigmoidf_(acc[ai][bj][m][1][j] * r) * e1[j]; }
;                     *(u32x4*)(Hf + off + bj * 128) = pack8(h0, h1); } }
	v_mov_b64_e32 v[76:77], v[222:223]
	v_mov_b64_e32 v[78:79], v[224:225]
	global_load_dwordx4 v[222:225], v[238:239], off offset:256
	v_mul_f32_e32 v68, v68, v90
	s_waitcnt vmcnt(11)
	v_mov_b64_e32 v[72:73], v[226:227]
	v_mov_b64_e32 v[74:75], v[228:229]
	global_load_dwordx4 v[226:229], v[240:241], off offset:256
	v_mul_f32_e32 v64, v64, v90
	v_mul_f32_e32 v69, v69, v90
	v_mul_f32_e32 v65, v65, v90
	v_mul_f32_e32 v70, v70, v90
	v_mul_f32_e32 v66, v66, v90
	v_mul_f32_e32 v71, v71, v90
	v_mul_f32_e32 v67, v67, v90
	v_mul_f32_e32 v68, 0xbfb8aa3b, v68
	v_mul_f32_e32 v64, 0xbfb8aa3b, v64
	v_mul_f32_e32 v69, 0xbfb8aa3b, v69
	v_mul_f32_e32 v65, 0xbfb8aa3b, v65
	v_mul_f32_e32 v70, 0xbfb8aa3b, v70
	v_mul_f32_e32 v66, 0xbfb8aa3b, v66
	v_mul_f32_e32 v71, 0xbfb8aa3b, v71
	v_mul_f32_e32 v67, 0xbfb8aa3b, v67
	v_exp_f32_e32 v68, v68
	v_exp_f32_e32 v64, v64
	v_exp_f32_e32 v69, v69
	v_exp_f32_e32 v65, v65
	v_exp_f32_e32 v70, v70
	v_exp_f32_e32 v66, v66
	v_exp_f32_e32 v71, v71
	v_exp_f32_e32 v67, v67
	v_add_f32_e32 v68, 1.0, v68
	v_add_f32_e32 v64, 1.0, v64
	v_add_f32_e32 v69, 1.0, v69
	v_add_f32_e32 v65, 1.0, v65
	v_add_f32_e32 v70, 1.0, v70
	v_add_f32_e32 v66, 1.0, v66
	v_add_f32_e32 v71, 1.0, v71
	v_add_f32_e32 v67, 1.0, v67
	v_add_u32_e32 v82, 0x80, v150
	v_rcp_f32_e32 v68, v68
	v_rcp_f32_e32 v64, v64
	v_rcp_f32_e32 v69, v69
	v_rcp_f32_e32 v65, v65
	v_rcp_f32_e32 v70, v70
	v_rcp_f32_e32 v66, v66
	v_rcp_f32_e32 v71, v71
	v_rcp_f32_e32 v67, v67
	v_ashrrev_i32_e32 v83, 31, v82
	v_lshlrev_b64 v[84:85], 11, v[82:83]
	v_lshl_add_u64 v[86:87], v[82:83], 2, s[28:29]
	v_lshl_add_u64 v[84:85], v[84:85], 0, v[148:149]
	v_lshlrev_b64 v[84:85], 1, v[84:85]
	v_lshl_add_u64 v[88:89], s[14:15], 0, v[84:85]
	v_lshlrev_b32_e32 v83, 16, v76
	v_and_b32_e32 v76, 0xffff0000, v76
	v_lshlrev_b32_e32 v90, 16, v77
	v_and_b32_e32 v77, 0xffff0000, v77
	v_lshlrev_b32_e32 v91, 16, v78
	v_and_b32_e32 v78, 0xffff0000, v78
	v_lshlrev_b32_e32 v92, 16, v79
	v_and_b32_e32 v79, 0xffff0000, v79
	v_lshlrev_b32_e32 v93, 16, v72
	v_and_b32_e32 v72, 0xffff0000, v72
	v_lshlrev_b32_e32 v94, 16, v73
	v_and_b32_e32 v73, 0xffff0000, v73
	v_lshlrev_b32_e32 v95, 16, v74
	v_and_b32_e32 v74, 0xffff0000, v74
	v_lshlrev_b32_e32 v96, 16, v75
	v_and_b32_e32 v75, 0xffff0000, v75
	v_fmac_f32_e32 v93, v68, v83
	v_fmac_f32_e32 v95, v64, v91
	v_fmac_f32_e32 v72, v69, v76
	v_fmac_f32_e32 v74, v65, v78
	v_fmac_f32_e32 v94, v70, v90
	v_fmac_f32_e32 v96, v66, v92
	v_fmac_f32_e32 v73, v71, v77
	v_fmac_f32_e32 v75, v67, v79
	v_cvt_pk_bf16_f32 v64, v93, v72
	v_cvt_pk_bf16_f32 v65, v94, v73
	v_cvt_pk_bf16_f32 v66, v95, v74
	v_cvt_pk_bf16_f32 v67, v96, v75
	global_store_dwordx4 v[80:81], v[64:67], off offset:256
	s_waitcnt vmcnt(27)
	v_mov_b32_e32 v74, v235
	s_nop 0
	s_waitcnt vmcnt(11)
	v_mov_b64_e32 v[64:65], v[196:197]
	v_mov_b64_e32 v[66:67], v[198:199]
	s_mov_b32 s4, 0x10000
	v_lshl_add_u64 v[238:239], v[238:239], 0, s[4:5]
	global_load_dwordx4 v[196:199], v[238:239], off
	v_mad_i64_i32 v[68:69], s[0:1], v82, s65, v[144:145]
	v_lshl_add_u64 v[72:73], v[68:69], 0, v[146:147]
	s_waitcnt vmcnt(11)
	v_mov_b64_e32 v[68:69], v[200:201]
	v_mov_b64_e32 v[70:71], v[202:203]
	s_mov_b32 s4, 0x12000
	v_lshl_add_u64 v[240:241], v[240:241], 0, s[4:5]
	global_load_dwordx4 v[200:203], v[240:241], off
	v_fmamk_f32 v74, v74, 0x3a000000, v159
	v_mul_f32_e32 v81, 0x4f800000, v74
	v_cmp_gt_f32_e32 vcc, s64, v74
	v_lshlrev_b32_e32 v75, 16, v64
	v_and_b32_e32 v64, 0xffff0000, v64
	v_cndmask_b32_e32 v74, v74, v81, vcc
	v_sqrt_f32_e32 v81, v74
	v_lshlrev_b32_e32 v76, 16, v65
	v_and_b32_e32 v65, 0xffff0000, v65
	v_lshlrev_b32_e32 v79, 16, v68
	v_add_u32_e32 v86, -1, v81
	v_add_u32_e32 v87, 1, v81
	v_fma_f32 v90, -v86, v81, v74
	v_fma_f32 v91, -v87, v81, v74
	v_cmp_ge_f32_e64 s[8:9], 0, v90
	v_and_b32_e32 v68, 0xffff0000, v68
	v_lshlrev_b32_e32 v80, 16, v69
	v_cndmask_b32_e64 v81, v81, v86, s[8:9]
	v_cmp_lt_f32_e64 s[8:9], 0, v91
	v_and_b32_e32 v69, 0xffff0000, v69
	v_lshlrev_b32_e32 v77, 16, v66
	v_cndmask_b32_e64 v81, v81, v87, s[8:9]
	v_mul_f32_e32 v86, 0x37800000, v81
	v_cndmask_b32_e32 v81, v81, v86, vcc
	v_cmp_class_f32_e32 vcc, v74, v160
	v_and_b32_e32 v66, 0xffff0000, v66
	v_lshlrev_b32_e32 v78, 16, v67
	v_cndmask_b32_e32 v74, v81, v74, vcc
	v_div_scale_f32 v81, s[0:1], v74, v74, 1.0
	v_rcp_f32_e32 v86, v81
	v_div_scale_f32 v87, vcc, 1.0, v74, 1.0
	v_and_b32_e32 v67, 0xffff0000, v67
	v_fma_f32 v90, -v81, v86, 1.0
	v_fmac_f32_e32 v86, v90, v86
	v_mul_f32_e32 v90, v87, v86
	v_fma_f32 v91, -v81, v90, v87
	v_fmac_f32_e32 v90, v91, v86
	v_fma_f32 v81, -v81, v90, v87
	v_div_fmas_f32 v81, v81, v86, v90
	v_div_fixup_f32 v74, v81, v74, 1.0
	v_mul_f32_e32 v61, v61, v74
	v_mul_f32_e32 v63, v63, v74
	v_mul_f32_e32 v60, v60, v74
	v_mul_f32_e32 v56, v56, v74
	v_mul_f32_e32 v57, v57, v74
	v_mul_f32_e32 v62, v62, v74
	v_mul_f32_e32 v58, v58, v74
	v_mul_f32_e32 v59, v59, v74
	v_mul_f32_e32 v61, 0xbfb8aa3b, v61
	v_mul_f32_e32 v63, 0xbfb8aa3b, v63
	v_mul_f32_e32 v60, 0xbfb8aa3b, v60
	v_mul_f32_e32 v56, 0xbfb8aa3b, v56
	v_mul_f32_e32 v57, 0xbfb8aa3b, v57
	v_mul_f32_e32 v62, 0xbfb8aa3b, v62
	v_mul_f32_e32 v58, 0xbfb8aa3b, v58
	v_mul_f32_e32 v59, 0xbfb8aa3b, v59
	v_exp_f32_e32 v61, v61
	v_exp_f32_e32 v63, v63
	v_exp_f32_e32 v60, v60
	v_exp_f32_e32 v56, v56
	v_exp_f32_e32 v57, v57
	v_exp_f32_e32 v62, v62
	v_exp_f32_e32 v58, v58
	v_exp_f32_e32 v59, v59
	v_add_f32_e32 v61, 1.0, v61
	v_add_f32_e32 v63, 1.0, v63
	v_add_f32_e32 v60, 1.0, v60
	v_add_f32_e32 v56, 1.0, v56
	v_add_f32_e32 v57, 1.0, v57
	v_add_f32_e32 v62, 1.0, v62
	v_add_f32_e32 v58, 1.0, v58
	v_add_f32_e32 v59, 1.0, v59
	v_rcp_f32_e32 v61, v61
	v_rcp_f32_e32 v63, v63
	v_rcp_f32_e32 v60, v60
	v_rcp_f32_e32 v56, v56
	v_rcp_f32_e32 v57, v57
	v_rcp_f32_e32 v62, v62
	v_rcp_f32_e32 v58, v58
	v_rcp_f32_e32 v59, v59
	v_lshlrev_b32_e32 v82, 16, v70
	v_and_b32_e32 v70, 0xffff0000, v70
	v_lshlrev_b32_e32 v83, 16, v71
	v_and_b32_e32 v71, 0xffff0000, v71
	v_fmac_f32_e32 v68, v61, v64
	v_fmac_f32_e32 v69, v63, v65
	v_lshl_add_u64 v[64:65], s[18:19], 0, v[84:85]
	v_fmac_f32_e32 v79, v60, v75
	v_fmac_f32_e32 v82, v56, v77
	v_fmac_f32_e32 v70, v57, v66
	v_fmac_f32_e32 v80, v62, v76
	v_fmac_f32_e32 v83, v58, v78
	v_fmac_f32_e32 v71, v59, v67
	v_cvt_pk_bf16_f32 v56, v79, v68
	v_cvt_pk_bf16_f32 v57, v80, v69
	v_cvt_pk_bf16_f32 v58, v82, v70
	v_cvt_pk_bf16_f32 v59, v83, v71
	global_store_dwordx4 v[64:65], v[56:59], off
	s_waitcnt vmcnt(11)
; DI float bf_lo(unsigned u) { return __uint_as_float(u << 16); }
; DI float bf_hi(unsigned u) { return __uint_as_float(u & 0xffff0000u); }
; DI float sigmoidf_(float x) { return __builtin_amdgcn_rcpf(1.0f + __builtin_amdgcn_exp2f(-x * LOG2E)); }
; DI float rs_of(const float* ss, int row) { return 1.0f / sqrtf(ss[row] * (1.0f / DM) + EPS); }
; DI u32x4 pack8(f32x4 a, f32x4 b) { u32x4 w; w.x = cvt_pk_bf16(a[0], a[1]); w.y = cvt_pk_bf16(a[2], a[3]); w.z = cvt_pk_bf16(b[0], b[1]); w.w = cvt_pk_bf16(b[2], b[3]); return w; }
;     DI void operator()(AccRef acc, const Unit& u, int wr, int wc, int fr, int fq) const {
;     ...
;             for (int m = 0; m < 4; ++m) { const int row = u.pm * 256 + ai * 128 + wr * 64 + m * 16 + fr; const size_t off = (size_t)row * DM + col0; const float r = rs_of(ss, row);
; #pragma unroll
;                 for (int bj = 0; bj < 2; ++bj) {
;                     const u32x4 ev = *(const u32x4*)(Eb + off + bj * 128), uv = *(const u32x4*)(UPh + (size_t)row * 2304 + col0 + bj * 128);
;                     const f32x4 e0 = {bf_lo(ev.x), bf_hi(ev.x), bf_lo(ev.y), bf_hi(ev.y)}, e1 = {bf_lo(ev.z), bf_hi(ev.z), bf_lo(ev.w), bf_hi(ev.w)};
;                     f32x4 h0 = {bf_lo(uv.x), bf_hi(uv.x), bf_lo(uv.y), bf_hi(uv.y)}, h1 = {bf_lo(uv.z), bf_hi(uv.z), bf_lo(uv.w), bf_hi(uv.w)};
; #pragma unroll
;                     for (int j = 0; j < 4; ++j) { h0[j] += sigmoidf_(acc[ai][bj][m][0][j] * r) * e0[j]; h1[j] += sigmoidf_(acc[ai][bj][m][1][j] * r) * e1[j]; }
;                     *(u32x4*)(Hf + off + bj * 128) = pack8(h0, h1); } }
	v_mov_b64_e32 v[60:61], v[206:207]
	v_mov_b64_e32 v[62:63], v[208:209]
	global_load_dwordx4 v[206:209], v[238:239], off offset:256
	v_mul_f32_e32 v52, v52, v74
	s_waitcnt vmcnt(11)
	v_mov_b64_e32 v[56:57], v[210:211]
	v_mov_b64_e32 v[58:59], v[212:213]
	global_load_dwordx4 v[210:213], v[240:241], off offset:256
	v_mul_f32_e32 v48, v48, v74
	v_mul_f32_e32 v53, v53, v74
	v_mul_f32_e32 v49, v49, v74
	v_mul_f32_e32 v54, v54, v74
	v_mul_f32_e32 v50, v50, v74
	v_mul_f32_e32 v55, v55, v74
	v_mul_f32_e32 v51, v51, v74
	v_mul_f32_e32 v52, 0xbfb8aa3b, v52
	v_mul_f32_e32 v48, 0xbfb8aa3b, v48
	v_mul_f32_e32 v53, 0xbfb8aa3b, v53
	v_mul_f32_e32 v49, 0xbfb8aa3b, v49
	v_mul_f32_e32 v54, 0xbfb8aa3b, v54
	v_mul_f32_e32 v50, 0xbfb8aa3b, v50
	v_mul_f32_e32 v55, 0xbfb8aa3b, v55
	v_mul_f32_e32 v51, 0xbfb8aa3b, v51
	v_exp_f32_e32 v52, v52
	v_exp_f32_e32 v48, v48
	v_exp_f32_e32 v53, v53
	v_exp_f32_e32 v49, v49
	v_exp_f32_e32 v54, v54
	v_exp_f32_e32 v50, v50
	v_exp_f32_e32 v55, v55
	v_exp_f32_e32 v51, v51
	v_add_f32_e32 v52, 1.0, v52
	v_add_f32_e32 v48, 1.0, v48
	v_add_f32_e32 v53, 1.0, v53
	v_add_f32_e32 v49, 1.0, v49
	v_add_f32_e32 v54, 1.0, v54
	v_add_f32_e32 v50, 1.0, v50
	v_add_f32_e32 v55, 1.0, v55
	v_add_f32_e32 v51, 1.0, v51
	v_add_u32_e32 v66, 0x90, v150
	v_rcp_f32_e32 v52, v52
	v_rcp_f32_e32 v48, v48
	v_rcp_f32_e32 v53, v53
	v_rcp_f32_e32 v49, v49
	v_rcp_f32_e32 v54, v54
	v_rcp_f32_e32 v50, v50
	v_rcp_f32_e32 v55, v55
	v_rcp_f32_e32 v51, v51
	v_ashrrev_i32_e32 v67, 31, v66
	v_lshlrev_b64 v[68:69], 11, v[66:67]
	v_lshl_add_u64 v[70:71], v[66:67], 2, s[28:29]
	v_lshl_add_u64 v[68:69], v[68:69], 0, v[148:149]
	v_lshlrev_b64 v[68:69], 1, v[68:69]
	v_lshl_add_u64 v[72:73], s[14:15], 0, v[68:69]
	v_lshlrev_b32_e32 v67, 16, v60
	v_and_b32_e32 v60, 0xffff0000, v60
	v_lshlrev_b32_e32 v74, 16, v61
	v_and_b32_e32 v61, 0xffff0000, v61
	v_lshlrev_b32_e32 v75, 16, v62
	v_and_b32_e32 v62, 0xffff0000, v62
	v_lshlrev_b32_e32 v76, 16, v63
	v_and_b32_e32 v63, 0xffff0000, v63
	v_lshlrev_b32_e32 v77, 16, v56
	v_and_b32_e32 v56, 0xffff0000, v56
	v_lshlrev_b32_e32 v78, 16, v57
	v_and_b32_e32 v57, 0xffff0000, v57
	v_lshlrev_b32_e32 v79, 16, v58
	v_and_b32_e32 v58, 0xffff0000, v58
	v_lshlrev_b32_e32 v80, 16, v59
	v_and_b32_e32 v59, 0xffff0000, v59
	v_fmac_f32_e32 v77, v52, v67
	v_fmac_f32_e32 v79, v48, v75
	v_fmac_f32_e32 v56, v53, v60
	v_fmac_f32_e32 v58, v49, v62
	v_fmac_f32_e32 v78, v54, v74
	v_fmac_f32_e32 v80, v50, v76
	v_fmac_f32_e32 v57, v55, v61
	v_fmac_f32_e32 v59, v51, v63
	v_cvt_pk_bf16_f32 v48, v77, v56
	v_cvt_pk_bf16_f32 v49, v78, v57
	v_cvt_pk_bf16_f32 v50, v79, v58
	v_cvt_pk_bf16_f32 v51, v80, v59
	global_store_dwordx4 v[64:65], v[48:51], off offset:256
	s_waitcnt vmcnt(32)
	v_mov_b32_e32 v58, v236
	s_nop 0
	s_waitcnt vmcnt(11)
	v_mov_b64_e32 v[48:49], v[214:215]
	v_mov_b64_e32 v[50:51], v[216:217]
	s_mov_b32 s4, 0x10000
	v_lshl_add_u64 v[238:239], v[238:239], 0, s[4:5]
	global_load_dwordx4 v[214:217], v[238:239], off
	v_mad_i64_i32 v[52:53], s[0:1], v66, s65, v[144:145]
	v_lshl_add_u64 v[56:57], v[52:53], 0, v[146:147]
	s_waitcnt vmcnt(11)
	v_mov_b64_e32 v[52:53], v[218:219]
	v_mov_b64_e32 v[54:55], v[220:221]
	s_mov_b32 s4, 0x12000
	v_lshl_add_u64 v[240:241], v[240:241], 0, s[4:5]
	global_load_dwordx4 v[218:221], v[240:241], off
	v_fmamk_f32 v58, v58, 0x3a000000, v159
	v_mul_f32_e32 v65, 0x4f800000, v58
	v_cmp_gt_f32_e32 vcc, s64, v58
	v_lshlrev_b32_e32 v59, 16, v48
	v_and_b32_e32 v48, 0xffff0000, v48
	v_cndmask_b32_e32 v58, v58, v65, vcc
	v_sqrt_f32_e32 v65, v58
	v_lshlrev_b32_e32 v60, 16, v49
	v_and_b32_e32 v49, 0xffff0000, v49
	v_lshlrev_b32_e32 v63, 16, v52
	v_add_u32_e32 v70, -1, v65
	v_add_u32_e32 v71, 1, v65
	v_fma_f32 v74, -v70, v65, v58
	v_fma_f32 v75, -v71, v65, v58
	v_cmp_ge_f32_e64 s[8:9], 0, v74
	v_and_b32_e32 v52, 0xffff0000, v52
	v_lshlrev_b32_e32 v64, 16, v53
	v_cndmask_b32_e64 v65, v65, v70, s[8:9]
	v_cmp_lt_f32_e64 s[8:9], 0, v75
	v_and_b32_e32 v53, 0xffff0000, v53
	v_lshlrev_b32_e32 v61, 16, v50
	v_cndmask_b32_e64 v65, v65, v71, s[8:9]
	v_mul_f32_e32 v70, 0x37800000, v65
	v_cndmask_b32_e32 v65, v65, v70, vcc
	v_cmp_class_f32_e32 vcc, v58, v160
	v_and_b32_e32 v50, 0xffff0000, v50
	v_lshlrev_b32_e32 v62, 16, v51
	v_cndmask_b32_e32 v58, v65, v58, vcc
	v_div_scale_f32 v65, s[0:1], v58, v58, 1.0
	v_rcp_f32_e32 v70, v65
	v_div_scale_f32 v71, vcc, 1.0, v58, 1.0
	v_and_b32_e32 v51, 0xffff0000, v51
	v_fma_f32 v74, -v65, v70, 1.0
	v_fmac_f32_e32 v70, v74, v70
	v_mul_f32_e32 v74, v71, v70
	v_fma_f32 v75, -v65, v74, v71
	v_fmac_f32_e32 v74, v75, v70
	v_fma_f32 v65, -v65, v74, v71
	v_div_fmas_f32 v65, v65, v70, v74
	v_div_fixup_f32 v58, v65, v58, 1.0
	v_mul_f32_e32 v45, v45, v58
	v_mul_f32_e32 v47, v47, v58
	v_mul_f32_e32 v44, v44, v58
	v_mul_f32_e32 v40, v40, v58
	v_mul_f32_e32 v41, v41, v58
	v_mul_f32_e32 v46, v46, v58
	v_mul_f32_e32 v42, v42, v58
	v_mul_f32_e32 v43, v43, v58
	v_mul_f32_e32 v45, 0xbfb8aa3b, v45
	v_mul_f32_e32 v47, 0xbfb8aa3b, v47
	v_mul_f32_e32 v44, 0xbfb8aa3b, v44
	v_mul_f32_e32 v40, 0xbfb8aa3b, v40
	v_mul_f32_e32 v41, 0xbfb8aa3b, v41
	v_mul_f32_e32 v46, 0xbfb8aa3b, v46
	v_mul_f32_e32 v42, 0xbfb8aa3b, v42
	v_mul_f32_e32 v43, 0xbfb8aa3b, v43
	v_exp_f32_e32 v45, v45
	v_exp_f32_e32 v47, v47
	v_exp_f32_e32 v44, v44
	v_exp_f32_e32 v40, v40
	v_exp_f32_e32 v41, v41
	v_exp_f32_e32 v46, v46
	v_exp_f32_e32 v42, v42
	v_exp_f32_e32 v43, v43
	v_add_f32_e32 v45, 1.0, v45
	v_add_f32_e32 v47, 1.0, v47
	v_add_f32_e32 v44, 1.0, v44
	v_add_f32_e32 v40, 1.0, v40
	v_add_f32_e32 v41, 1.0, v41
	v_add_f32_e32 v46, 1.0, v46
	v_add_f32_e32 v42, 1.0, v42
	v_add_f32_e32 v43, 1.0, v43
	v_rcp_f32_e32 v45, v45
	v_rcp_f32_e32 v47, v47
	v_rcp_f32_e32 v44, v44
	v_rcp_f32_e32 v40, v40
	v_rcp_f32_e32 v41, v41
	v_rcp_f32_e32 v46, v46
	v_rcp_f32_e32 v42, v42
	v_rcp_f32_e32 v43, v43
	v_lshlrev_b32_e32 v66, 16, v54
	v_and_b32_e32 v54, 0xffff0000, v54
	v_lshlrev_b32_e32 v67, 16, v55
	v_and_b32_e32 v55, 0xffff0000, v55
	v_fmac_f32_e32 v52, v45, v48
	v_fmac_f32_e32 v53, v47, v49
	v_lshl_add_u64 v[48:49], s[18:19], 0, v[68:69]
	v_fmac_f32_e32 v63, v44, v59
	v_fmac_f32_e32 v66, v40, v61
	v_fmac_f32_e32 v54, v41, v50
	v_fmac_f32_e32 v64, v46, v60
	v_fmac_f32_e32 v67, v42, v62
	v_fmac_f32_e32 v55, v43, v51
	v_cvt_pk_bf16_f32 v40, v63, v52
	v_cvt_pk_bf16_f32 v41, v64, v53
	v_cvt_pk_bf16_f32 v42, v66, v54
	v_cvt_pk_bf16_f32 v43, v67, v55
	global_store_dwordx4 v[48:49], v[40:43], off
	s_waitcnt vmcnt(11)
; DI float bf_lo(unsigned u) { return __uint_as_float(u << 16); }
; DI float bf_hi(unsigned u) { return __uint_as_float(u & 0xffff0000u); }
; DI float sigmoidf_(float x) { return __builtin_amdgcn_rcpf(1.0f + __builtin_amdgcn_exp2f(-x * LOG2E)); }
; DI float rs_of(const float* ss, int row) { return 1.0f / sqrtf(ss[row] * (1.0f / DM) + EPS); }
; DI u32x4 pack8(f32x4 a, f32x4 b) { u32x4 w; w.x = cvt_pk_bf16(a[0], a[1]); w.y = cvt_pk_bf16(a[2], a[3]); w.z = cvt_pk_bf16(b[0], b[1]); w.w = cvt_pk_bf16(b[2], b[3]); return w; }
;     DI void operator()(AccRef acc, const Unit& u, int wr, int wc, int fr, int fq) const {
;     ...
;             for (int m = 0; m < 4; ++m) { const int row = u.pm * 256 + ai * 128 + wr * 64 + m * 16 + fr; const size_t off = (size_t)row * DM + col0; const float r = rs_of(ss, row);
; #pragma unroll
;                 for (int bj = 0; bj < 2; ++bj) {
;                     const u32x4 ev = *(const u32x4*)(Eb + off + bj * 128), uv = *(const u32x4*)(UPh + (size_t)row * 2304 + col0 + bj * 128);
;                     const f32x4 e0 = {bf_lo(ev.x), bf_hi(ev.x), bf_lo(ev.y), bf_hi(ev.y)}, e1 = {bf_lo(ev.z), bf_hi(ev.z), bf_lo(ev.w), bf_hi(ev.w)};
;                     f32x4 h0 = {bf_lo(uv.x), bf_hi(uv.x), bf_lo(uv.y), bf_hi(uv.y)}, h1 = {bf_lo(uv.z), bf_hi(uv.z), bf_lo(uv.w), bf_hi(uv.w)};
; #pragma unroll
;                     for (int j = 0; j < 4; ++j) { h0[j] += sigmoidf_(acc[ai][bj][m][0][j] * r) * e0[j]; h1[j] += sigmoidf_(acc[ai][bj][m][1][j] * r) * e1[j]; }
;                     *(u32x4*)(Hf + off + bj * 128) = pack8(h0, h1); } }
	v_mov_b64_e32 v[44:45], v[222:223]
	v_mov_b64_e32 v[46:47], v[224:225]
	global_load_dwordx4 v[222:225], v[238:239], off offset:256
	v_mul_f32_e32 v36, v36, v58
	s_waitcnt vmcnt(11)
	v_mov_b64_e32 v[40:41], v[226:227]
	v_mov_b64_e32 v[42:43], v[228:229]
	global_load_dwordx4 v[226:229], v[240:241], off offset:256
	v_mul_f32_e32 v32, v32, v58
	v_mul_f32_e32 v37, v37, v58
	v_mul_f32_e32 v33, v33, v58
	v_mul_f32_e32 v38, v38, v58
	v_mul_f32_e32 v34, v34, v58
	v_mul_f32_e32 v39, v39, v58
	v_mul_f32_e32 v35, v35, v58
	v_mul_f32_e32 v36, 0xbfb8aa3b, v36
	v_mul_f32_e32 v32, 0xbfb8aa3b, v32
	v_mul_f32_e32 v37, 0xbfb8aa3b, v37
	v_mul_f32_e32 v33, 0xbfb8aa3b, v33
	v_mul_f32_e32 v38, 0xbfb8aa3b, v38
	v_mul_f32_e32 v34, 0xbfb8aa3b, v34
	v_mul_f32_e32 v39, 0xbfb8aa3b, v39
	v_mul_f32_e32 v35, 0xbfb8aa3b, v35
	v_exp_f32_e32 v36, v36
	v_exp_f32_e32 v32, v32
	v_exp_f32_e32 v37, v37
	v_exp_f32_e32 v33, v33
	v_exp_f32_e32 v38, v38
	v_exp_f32_e32 v34, v34
	v_exp_f32_e32 v39, v39
	v_exp_f32_e32 v35, v35
	v_add_f32_e32 v36, 1.0, v36
	v_add_f32_e32 v32, 1.0, v32
	v_add_f32_e32 v37, 1.0, v37
	v_add_f32_e32 v33, 1.0, v33
	v_add_f32_e32 v38, 1.0, v38
	v_add_f32_e32 v34, 1.0, v34
	v_add_f32_e32 v39, 1.0, v39
	v_add_f32_e32 v35, 1.0, v35
	v_add_u32_e32 v50, 0xa0, v150
	v_rcp_f32_e32 v36, v36
	v_rcp_f32_e32 v32, v32
	v_rcp_f32_e32 v37, v37
	v_rcp_f32_e32 v33, v33
	v_rcp_f32_e32 v38, v38
	v_rcp_f32_e32 v34, v34
	v_rcp_f32_e32 v39, v39
	v_rcp_f32_e32 v35, v35
	v_ashrrev_i32_e32 v51, 31, v50
	v_lshlrev_b64 v[52:53], 11, v[50:51]
	v_lshl_add_u64 v[54:55], v[50:51], 2, s[28:29]
	v_lshl_add_u64 v[52:53], v[52:53], 0, v[148:149]
	v_lshlrev_b64 v[52:53], 1, v[52:53]
	v_lshl_add_u64 v[56:57], s[14:15], 0, v[52:53]
	v_lshlrev_b32_e32 v51, 16, v44
	v_and_b32_e32 v44, 0xffff0000, v44
	v_lshlrev_b32_e32 v58, 16, v45
	v_and_b32_e32 v45, 0xffff0000, v45
	v_lshlrev_b32_e32 v59, 16, v46
	v_and_b32_e32 v46, 0xffff0000, v46
	v_lshlrev_b32_e32 v60, 16, v47
	v_and_b32_e32 v47, 0xffff0000, v47
	v_lshlrev_b32_e32 v61, 16, v40
	v_and_b32_e32 v40, 0xffff0000, v40
	v_lshlrev_b32_e32 v62, 16, v41
	v_and_b32_e32 v41, 0xffff0000, v41
	v_lshlrev_b32_e32 v63, 16, v42
	v_and_b32_e32 v42, 0xffff0000, v42
	v_lshlrev_b32_e32 v64, 16, v43
	v_and_b32_e32 v43, 0xffff0000, v43
	v_fmac_f32_e32 v61, v36, v51
	v_fmac_f32_e32 v63, v32, v59
	v_fmac_f32_e32 v40, v37, v44
	v_fmac_f32_e32 v42, v33, v46
	v_fmac_f32_e32 v62, v38, v58
	v_fmac_f32_e32 v64, v34, v60
	v_fmac_f32_e32 v41, v39, v45
	v_fmac_f32_e32 v43, v35, v47
	v_cvt_pk_bf16_f32 v32, v61, v40
	v_cvt_pk_bf16_f32 v33, v62, v41
	v_cvt_pk_bf16_f32 v34, v63, v42
	v_cvt_pk_bf16_f32 v35, v64, v43
	global_store_dwordx4 v[48:49], v[32:35], off offset:256
	s_waitcnt vmcnt(37)
	v_mov_b32_e32 v42, v237
	s_nop 0
	s_waitcnt vmcnt(11)
	v_mov_b64_e32 v[32:33], v[196:197]
	v_mov_b64_e32 v[34:35], v[198:199]
	v_mad_i64_i32 v[36:37], s[0:1], v50, s65, v[144:145]
	v_lshl_add_u64 v[40:41], v[36:37], 0, v[146:147]
	s_waitcnt vmcnt(10)
	v_mov_b64_e32 v[36:37], v[200:201]
	v_mov_b64_e32 v[38:39], v[202:203]
	v_fmamk_f32 v42, v42, 0x3a000000, v159
	v_mul_f32_e32 v49, 0x4f800000, v42
	v_cmp_gt_f32_e32 vcc, s64, v42
	v_lshlrev_b32_e32 v43, 16, v32
	v_and_b32_e32 v32, 0xffff0000, v32
	v_cndmask_b32_e32 v42, v42, v49, vcc
	v_sqrt_f32_e32 v49, v42
	v_lshlrev_b32_e32 v44, 16, v33
	v_and_b32_e32 v33, 0xffff0000, v33
	v_lshlrev_b32_e32 v47, 16, v36
	v_add_u32_e32 v54, -1, v49
	v_add_u32_e32 v55, 1, v49
	v_fma_f32 v58, -v54, v49, v42
	v_fma_f32 v59, -v55, v49, v42
	v_cmp_ge_f32_e64 s[8:9], 0, v58
	v_and_b32_e32 v36, 0xffff0000, v36
	v_lshlrev_b32_e32 v48, 16, v37
	v_cndmask_b32_e64 v49, v49, v54, s[8:9]
	v_cmp_lt_f32_e64 s[8:9], 0, v59
	v_and_b32_e32 v37, 0xffff0000, v37
	v_lshlrev_b32_e32 v45, 16, v34
	v_cndmask_b32_e64 v49, v49, v55, s[8:9]
	v_mul_f32_e32 v54, 0x37800000, v49
	v_cndmask_b32_e32 v49, v49, v54, vcc
	v_cmp_class_f32_e32 vcc, v42, v160
	v_and_b32_e32 v34, 0xffff0000, v34
	v_lshlrev_b32_e32 v46, 16, v35
	v_cndmask_b32_e32 v42, v49, v42, vcc
	v_div_scale_f32 v49, s[0:1], v42, v42, 1.0
	v_rcp_f32_e32 v54, v49
	v_div_scale_f32 v55, vcc, 1.0, v42, 1.0
	v_and_b32_e32 v35, 0xffff0000, v35
	v_fma_f32 v58, -v49, v54, 1.0
	v_fmac_f32_e32 v54, v58, v54
	v_mul_f32_e32 v58, v55, v54
	v_fma_f32 v59, -v49, v58, v55
	v_fmac_f32_e32 v58, v59, v54
	v_fma_f32 v49, -v49, v58, v55
	v_div_fmas_f32 v49, v49, v54, v58
	v_div_fixup_f32 v42, v49, v42, 1.0
	v_mul_f32_e32 v29, v29, v42
	v_mul_f32_e32 v31, v31, v42
	v_mul_f32_e32 v28, v28, v42
	v_mul_f32_e32 v24, v24, v42
	v_mul_f32_e32 v25, v25, v42
	v_mul_f32_e32 v30, v30, v42
	v_mul_f32_e32 v26, v26, v42
	v_mul_f32_e32 v27, v27, v42
	v_mul_f32_e32 v29, 0xbfb8aa3b, v29
	v_mul_f32_e32 v31, 0xbfb8aa3b, v31
	v_mul_f32_e32 v28, 0xbfb8aa3b, v28
	v_mul_f32_e32 v24, 0xbfb8aa3b, v24
	v_mul_f32_e32 v25, 0xbfb8aa3b, v25
	v_mul_f32_e32 v30, 0xbfb8aa3b, v30
	v_mul_f32_e32 v26, 0xbfb8aa3b, v26
	v_mul_f32_e32 v27, 0xbfb8aa3b, v27
	v_exp_f32_e32 v29, v29
	v_exp_f32_e32 v31, v31
	v_exp_f32_e32 v28, v28
	v_exp_f32_e32 v24, v24
	v_exp_f32_e32 v25, v25
	v_exp_f32_e32 v30, v30
	v_exp_f32_e32 v26, v26
	v_exp_f32_e32 v27, v27
	v_add_f32_e32 v29, 1.0, v29
	v_add_f32_e32 v31, 1.0, v31
	v_add_f32_e32 v28, 1.0, v28
	v_add_f32_e32 v24, 1.0, v24
	v_add_f32_e32 v25, 1.0, v25
	v_add_f32_e32 v30, 1.0, v30
	v_add_f32_e32 v26, 1.0, v26
	v_add_f32_e32 v27, 1.0, v27
	v_rcp_f32_e32 v29, v29
	v_rcp_f32_e32 v31, v31
	v_rcp_f32_e32 v28, v28
	v_rcp_f32_e32 v24, v24
	v_rcp_f32_e32 v25, v25
	v_rcp_f32_e32 v30, v30
	v_rcp_f32_e32 v26, v26
	v_rcp_f32_e32 v27, v27
	v_lshlrev_b32_e32 v50, 16, v38
	v_and_b32_e32 v38, 0xffff0000, v38
	v_lshlrev_b32_e32 v51, 16, v39
	v_and_b32_e32 v39, 0xffff0000, v39
	v_fmac_f32_e32 v36, v29, v32
	v_fmac_f32_e32 v37, v31, v33
	v_lshl_add_u64 v[32:33], s[18:19], 0, v[52:53]
	v_fmac_f32_e32 v47, v28, v43
	v_fmac_f32_e32 v50, v24, v45
	v_fmac_f32_e32 v38, v25, v34
	v_fmac_f32_e32 v48, v30, v44
	v_fmac_f32_e32 v51, v26, v46
	v_fmac_f32_e32 v39, v27, v35
	v_cvt_pk_bf16_f32 v24, v47, v36
	v_cvt_pk_bf16_f32 v25, v48, v37
	v_cvt_pk_bf16_f32 v26, v50, v38
	v_cvt_pk_bf16_f32 v27, v51, v39
	global_store_dwordx4 v[32:33], v[24:27], off
	s_waitcnt vmcnt(9)
; DI float bf_lo(unsigned u) { return __uint_as_float(u << 16); }
; DI float bf_hi(unsigned u) { return __uint_as_float(u & 0xffff0000u); }
; DI float sigmoidf_(float x) { return __builtin_amdgcn_rcpf(1.0f + __builtin_amdgcn_exp2f(-x * LOG2E)); }
; DI float rs_of(const float* ss, int row) { return 1.0f / sqrtf(ss[row] * (1.0f / DM) + EPS); }
; DI u32x4 pack8(f32x4 a, f32x4 b) { u32x4 w; w.x = cvt_pk_bf16(a[0], a[1]); w.y = cvt_pk_bf16(a[2], a[3]); w.z = cvt_pk_bf16(b[0], b[1]); w.w = cvt_pk_bf16(b[2], b[3]); return w; }
;     DI void operator()(AccRef acc, const Unit& u, int wr, int wc, int fr, int fq) const {
;     ...
;             for (int m = 0; m < 4; ++m) { const int row = u.pm * 256 + ai * 128 + wr * 64 + m * 16 + fr; const size_t off = (size_t)row * DM + col0; const float r = rs_of(ss, row);
; #pragma unroll
;                 for (int bj = 0; bj < 2; ++bj) {
;                     const u32x4 ev = *(const u32x4*)(Eb + off + bj * 128), uv = *(const u32x4*)(UPh + (size_t)row * 2304 + col0 + bj * 128);
;                     const f32x4 e0 = {bf_lo(ev.x), bf_hi(ev.x), bf_lo(ev.y), bf_hi(ev.y)}, e1 = {bf_lo(ev.z), bf_hi(ev.z), bf_lo(ev.w), bf_hi(ev.w)};
;                     f32x4 h0 = {bf_lo(uv.x), bf_hi(uv.x), bf_lo(uv.y), bf_hi(uv.y)}, h1 = {bf_lo(uv.z), bf_hi(uv.z), bf_lo(uv.w), bf_hi(uv.w)};
; #pragma unroll
;                     for (int j = 0; j < 4; ++j) { h0[j] += sigmoidf_(acc[ai][bj][m][0][j] * r) * e0[j]; h1[j] += sigmoidf_(acc[ai][bj][m][1][j] * r) * e1[j]; }
;                     *(u32x4*)(Hf + off + bj * 128) = pack8(h0, h1); } }
	v_mov_b64_e32 v[28:29], v[206:207]
	v_mov_b64_e32 v[30:31], v[208:209]
	v_mul_f32_e32 v20, v20, v42
	s_waitcnt vmcnt(8)
	v_mov_b64_e32 v[24:25], v[210:211]
	v_mov_b64_e32 v[26:27], v[212:213]
	v_mul_f32_e32 v16, v16, v42
	v_mul_f32_e32 v21, v21, v42
	v_mul_f32_e32 v17, v17, v42
	v_mul_f32_e32 v22, v22, v42
	v_mul_f32_e32 v18, v18, v42
	v_mul_f32_e32 v23, v23, v42
	v_mul_f32_e32 v19, v19, v42
	v_mul_f32_e32 v20, 0xbfb8aa3b, v20
	v_mul_f32_e32 v16, 0xbfb8aa3b, v16
	v_mul_f32_e32 v21, 0xbfb8aa3b, v21
	v_mul_f32_e32 v17, 0xbfb8aa3b, v17
	v_mul_f32_e32 v22, 0xbfb8aa3b, v22
	v_mul_f32_e32 v18, 0xbfb8aa3b, v18
	v_mul_f32_e32 v23, 0xbfb8aa3b, v23
	v_mul_f32_e32 v19, 0xbfb8aa3b, v19
	v_exp_f32_e32 v20, v20
	v_exp_f32_e32 v16, v16
	v_exp_f32_e32 v21, v21
	v_exp_f32_e32 v17, v17
	v_exp_f32_e32 v22, v22
	v_exp_f32_e32 v18, v18
	v_exp_f32_e32 v23, v23
	v_exp_f32_e32 v19, v19
	v_add_f32_e32 v20, 1.0, v20
	v_add_f32_e32 v16, 1.0, v16
	v_add_f32_e32 v21, 1.0, v21
	v_add_f32_e32 v17, 1.0, v17
	v_add_f32_e32 v22, 1.0, v22
	v_add_f32_e32 v18, 1.0, v18
	v_add_f32_e32 v23, 1.0, v23
	v_add_f32_e32 v19, 1.0, v19
	v_add_u32_e32 v34, 0xb0, v150
	v_rcp_f32_e32 v20, v20
	v_rcp_f32_e32 v16, v16
	v_rcp_f32_e32 v21, v21
	v_rcp_f32_e32 v17, v17
	v_rcp_f32_e32 v22, v22
	v_rcp_f32_e32 v18, v18
	v_rcp_f32_e32 v23, v23
	v_rcp_f32_e32 v19, v19
	v_ashrrev_i32_e32 v35, 31, v34
	v_lshlrev_b64 v[36:37], 11, v[34:35]
	v_lshl_add_u64 v[38:39], v[34:35], 2, s[28:29]
	v_lshl_add_u64 v[36:37], v[36:37], 0, v[148:149]
	v_lshlrev_b64 v[36:37], 1, v[36:37]
	v_lshl_add_u64 v[40:41], s[14:15], 0, v[36:37]
	v_lshlrev_b32_e32 v35, 16, v28
	v_and_b32_e32 v28, 0xffff0000, v28
	v_lshlrev_b32_e32 v42, 16, v29
	v_and_b32_e32 v29, 0xffff0000, v29
	v_lshlrev_b32_e32 v43, 16, v30
	v_and_b32_e32 v30, 0xffff0000, v30
	v_lshlrev_b32_e32 v44, 16, v31
	v_and_b32_e32 v31, 0xffff0000, v31
	v_lshlrev_b32_e32 v45, 16, v24
	v_and_b32_e32 v24, 0xffff0000, v24
	v_lshlrev_b32_e32 v46, 16, v25
	v_and_b32_e32 v25, 0xffff0000, v25
	v_lshlrev_b32_e32 v47, 16, v26
	v_and_b32_e32 v26, 0xffff0000, v26
	v_lshlrev_b32_e32 v48, 16, v27
	v_and_b32_e32 v27, 0xffff0000, v27
	v_fmac_f32_e32 v45, v20, v35
	v_fmac_f32_e32 v47, v16, v43
	v_fmac_f32_e32 v24, v21, v28
	v_fmac_f32_e32 v26, v17, v30
	v_fmac_f32_e32 v46, v22, v42
	v_fmac_f32_e32 v48, v18, v44
	v_fmac_f32_e32 v25, v23, v29
	v_fmac_f32_e32 v27, v19, v31
	v_cvt_pk_bf16_f32 v16, v45, v24
	v_cvt_pk_bf16_f32 v17, v46, v25
	v_cvt_pk_bf16_f32 v18, v47, v26
	v_cvt_pk_bf16_f32 v19, v48, v27
	global_store_dwordx4 v[32:33], v[16:19], off offset:256
	s_waitcnt vmcnt(38)
	v_mov_b32_e32 v26, v230
	s_nop 0
	s_waitcnt vmcnt(7)
	v_mov_b64_e32 v[16:17], v[214:215]
	v_mov_b64_e32 v[18:19], v[216:217]
	v_mad_i64_i32 v[20:21], s[0:1], v34, s65, v[144:145]
	v_lshl_add_u64 v[24:25], v[20:21], 0, v[146:147]
	s_waitcnt vmcnt(6)
; DI float bf_lo(unsigned u) { return __uint_as_float(u << 16); }
; DI float bf_hi(unsigned u) { return __uint_as_float(u & 0xffff0000u); }
; DI float sigmoidf_(float x) { return __builtin_amdgcn_rcpf(1.0f + __builtin_amdgcn_exp2f(-x * LOG2E)); }
; DI float rs_of(const float* ss, int row) { return 1.0f / sqrtf(ss[row] * (1.0f / DM) + EPS); }
; DI u32x4 pack8(f32x4 a, f32x4 b) { u32x4 w; w.x = cvt_pk_bf16(a[0], a[1]); w.y = cvt_pk_bf16(a[2], a[3]); w.z = cvt_pk_bf16(b[0], b[1]); w.w = cvt_pk_bf16(b[2], b[3]); return w; }
;     DI void operator()(AccRef acc, const Unit& u, int wr, int wc, int fr, int fq) const {
;     ...
;             for (int m = 0; m < 4; ++m) { const int row = u.pm * 256 + ai * 128 + wr * 64 + m * 16 + fr; const size_t off = (size_t)row * DM + col0; const float r = rs_of(ss, row);
; #pragma unroll
;                 for (int bj = 0; bj < 2; ++bj) {
;                     const u32x4 ev = *(const u32x4*)(Eb + off + bj * 128), uv = *(const u32x4*)(UPh + (size_t)row * 2304 + col0 + bj * 128);
;                     const f32x4 e0 = {bf_lo(ev.x), bf_hi(ev.x), bf_lo(ev.y), bf_hi(ev.y)}, e1 = {bf_lo(ev.z), bf_hi(ev.z), bf_lo(ev.w), bf_hi(ev.w)};
;                     f32x4 h0 = {bf_lo(uv.x), bf_hi(uv.x), bf_lo(uv.y), bf_hi(uv.y)}, h1 = {bf_lo(uv.z), bf_hi(uv.z), bf_lo(uv.w), bf_hi(uv.w)};
; #pragma unroll
;                     for (int j = 0; j < 4; ++j) { h0[j] += sigmoidf_(acc[ai][bj][m][0][j] * r) * e0[j]; h1[j] += sigmoidf_(acc[ai][bj][m][1][j] * r) * e1[j]; }
;                     *(u32x4*)(Hf + off + bj * 128) = pack8(h0, h1); } }
	v_mov_b64_e32 v[20:21], v[218:219]
	v_mov_b64_e32 v[22:23], v[220:221]
	v_fmamk_f32 v26, v26, 0x3a000000, v159
	v_mul_f32_e32 v33, 0x4f800000, v26
	v_cmp_gt_f32_e32 vcc, s64, v26
	v_lshlrev_b32_e32 v27, 16, v16
	v_and_b32_e32 v16, 0xffff0000, v16
	v_cndmask_b32_e32 v26, v26, v33, vcc
	v_sqrt_f32_e32 v33, v26
	v_lshlrev_b32_e32 v28, 16, v17
	v_and_b32_e32 v17, 0xffff0000, v17
	v_lshlrev_b32_e32 v31, 16, v20
	v_add_u32_e32 v38, -1, v33
	v_add_u32_e32 v39, 1, v33
	v_fma_f32 v42, -v38, v33, v26
	v_fma_f32 v43, -v39, v33, v26
	v_cmp_ge_f32_e64 s[8:9], 0, v42
	v_and_b32_e32 v20, 0xffff0000, v20
	v_lshlrev_b32_e32 v32, 16, v21
	v_cndmask_b32_e64 v33, v33, v38, s[8:9]
	v_cmp_lt_f32_e64 s[8:9], 0, v43
	v_and_b32_e32 v21, 0xffff0000, v21
	v_lshlrev_b32_e32 v29, 16, v18
	v_cndmask_b32_e64 v33, v33, v39, s[8:9]
	v_mul_f32_e32 v38, 0x37800000, v33
	v_cndmask_b32_e32 v33, v33, v38, vcc
	v_cmp_class_f32_e32 vcc, v26, v160
	v_and_b32_e32 v18, 0xffff0000, v18
	v_lshlrev_b32_e32 v30, 16, v19
	v_cndmask_b32_e32 v26, v33, v26, vcc
	v_div_scale_f32 v33, s[0:1], v26, v26, 1.0
	v_rcp_f32_e32 v38, v33
	v_div_scale_f32 v39, vcc, 1.0, v26, 1.0
	v_and_b32_e32 v19, 0xffff0000, v19
	v_fma_f32 v42, -v33, v38, 1.0
	v_fmac_f32_e32 v38, v42, v38
	v_mul_f32_e32 v42, v39, v38
	v_fma_f32 v43, -v33, v42, v39
	v_fmac_f32_e32 v42, v43, v38
	v_fma_f32 v33, -v33, v42, v39
	v_div_fmas_f32 v33, v33, v38, v42
	v_div_fixup_f32 v26, v33, v26, 1.0
	v_mul_f32_e32 v13, v13, v26
	v_mul_f32_e32 v15, v15, v26
	v_mul_f32_e32 v12, v12, v26
	v_mul_f32_e32 v8, v8, v26
	v_mul_f32_e32 v9, v9, v26
	v_mul_f32_e32 v14, v14, v26
	v_mul_f32_e32 v10, v10, v26
	v_mul_f32_e32 v11, v11, v26
	v_mul_f32_e32 v13, 0xbfb8aa3b, v13
	v_mul_f32_e32 v15, 0xbfb8aa3b, v15
	v_mul_f32_e32 v12, 0xbfb8aa3b, v12
	v_mul_f32_e32 v8, 0xbfb8aa3b, v8
	v_mul_f32_e32 v9, 0xbfb8aa3b, v9
	v_mul_f32_e32 v14, 0xbfb8aa3b, v14
	v_mul_f32_e32 v10, 0xbfb8aa3b, v10
	v_mul_f32_e32 v11, 0xbfb8aa3b, v11
	v_exp_f32_e32 v13, v13
	v_exp_f32_e32 v15, v15
	v_exp_f32_e32 v12, v12
	v_exp_f32_e32 v8, v8
	v_exp_f32_e32 v9, v9
	v_exp_f32_e32 v14, v14
	v_exp_f32_e32 v10, v10
	v_exp_f32_e32 v11, v11
	v_add_f32_e32 v13, 1.0, v13
	v_add_f32_e32 v15, 1.0, v15
	v_add_f32_e32 v12, 1.0, v12
	v_add_f32_e32 v8, 1.0, v8
	v_add_f32_e32 v9, 1.0, v9
	v_add_f32_e32 v14, 1.0, v14
	v_add_f32_e32 v10, 1.0, v10
	v_add_f32_e32 v11, 1.0, v11
	v_rcp_f32_e32 v13, v13
	v_rcp_f32_e32 v15, v15
	v_rcp_f32_e32 v12, v12
	v_rcp_f32_e32 v8, v8
	v_rcp_f32_e32 v9, v9
	v_rcp_f32_e32 v14, v14
	v_rcp_f32_e32 v10, v10
	v_rcp_f32_e32 v11, v11
	v_lshlrev_b32_e32 v34, 16, v22
	v_and_b32_e32 v22, 0xffff0000, v22
	v_lshlrev_b32_e32 v35, 16, v23
	v_and_b32_e32 v23, 0xffff0000, v23
	v_fmac_f32_e32 v20, v13, v16
	v_fmac_f32_e32 v21, v15, v17
	v_lshl_add_u64 v[16:17], s[18:19], 0, v[36:37]
	v_fmac_f32_e32 v31, v12, v27
	v_fmac_f32_e32 v34, v8, v29
	v_fmac_f32_e32 v22, v9, v18
	v_fmac_f32_e32 v32, v14, v28
	v_fmac_f32_e32 v35, v10, v30
	v_fmac_f32_e32 v23, v11, v19
	v_cvt_pk_bf16_f32 v8, v31, v20
	v_cvt_pk_bf16_f32 v9, v32, v21
	v_cvt_pk_bf16_f32 v10, v34, v22
	v_cvt_pk_bf16_f32 v11, v35, v23
	global_store_dwordx4 v[16:17], v[8:11], off
	s_waitcnt vmcnt(5)
	v_mov_b64_e32 v[12:13], v[222:223]
	v_mov_b64_e32 v[14:15], v[224:225]
	v_mul_f32_e32 v4, v4, v26
	s_waitcnt vmcnt(4)
	v_mov_b64_e32 v[8:9], v[226:227]
	v_mov_b64_e32 v[10:11], v[228:229]
	v_mul_f32_e32 v0, v0, v26
	v_mul_f32_e32 v5, v5, v26
	v_mul_f32_e32 v1, v1, v26
	v_mul_f32_e32 v6, v6, v26
	v_mul_f32_e32 v2, v2, v26
	v_mul_f32_e32 v7, v7, v26
	v_mul_f32_e32 v3, v3, v26
	v_mul_f32_e32 v4, 0xbfb8aa3b, v4
	v_mul_f32_e32 v0, 0xbfb8aa3b, v0
	v_mul_f32_e32 v5, 0xbfb8aa3b, v5
	v_mul_f32_e32 v1, 0xbfb8aa3b, v1
	v_mul_f32_e32 v6, 0xbfb8aa3b, v6
	v_mul_f32_e32 v2, 0xbfb8aa3b, v2
	v_mul_f32_e32 v7, 0xbfb8aa3b, v7
	v_mul_f32_e32 v3, 0xbfb8aa3b, v3
	v_exp_f32_e32 v4, v4
	v_exp_f32_e32 v0, v0
	v_exp_f32_e32 v5, v5
	v_exp_f32_e32 v1, v1
	v_exp_f32_e32 v6, v6
	v_exp_f32_e32 v2, v2
	v_exp_f32_e32 v7, v7
	v_exp_f32_e32 v3, v3
	v_add_f32_e32 v4, 1.0, v4
	v_add_f32_e32 v0, 1.0, v0
	v_add_f32_e32 v5, 1.0, v5
	v_add_f32_e32 v1, 1.0, v1
	v_add_f32_e32 v6, 1.0, v6
	v_add_f32_e32 v2, 1.0, v2
	v_add_f32_e32 v7, 1.0, v7
	v_add_f32_e32 v3, 1.0, v3
	v_rcp_f32_e32 v4, v4
	v_rcp_f32_e32 v0, v0
	v_rcp_f32_e32 v5, v5
	v_rcp_f32_e32 v1, v1
	v_rcp_f32_e32 v6, v6
	v_rcp_f32_e32 v2, v2
	v_rcp_f32_e32 v7, v7
	v_rcp_f32_e32 v3, v3
	s_and_b64 vcc, exec, s[6:7]
	s_mov_b32 s1, s66
	s_mov_b32 s0, s67
	v_lshlrev_b32_e32 v18, 16, v12
	v_and_b32_e32 v12, 0xffff0000, v12
	v_lshlrev_b32_e32 v19, 16, v13
	v_and_b32_e32 v13, 0xffff0000, v13
	v_lshlrev_b32_e32 v20, 16, v14
	v_and_b32_e32 v14, 0xffff0000, v14
	v_lshlrev_b32_e32 v21, 16, v15
	v_and_b32_e32 v15, 0xffff0000, v15
	v_lshlrev_b32_e32 v22, 16, v8
	v_and_b32_e32 v8, 0xffff0000, v8
	v_lshlrev_b32_e32 v23, 16, v9
	v_and_b32_e32 v9, 0xffff0000, v9
	v_lshlrev_b32_e32 v24, 16, v10
	v_and_b32_e32 v10, 0xffff0000, v10
	v_lshlrev_b32_e32 v25, 16, v11
	v_and_b32_e32 v11, 0xffff0000, v11
	v_fmac_f32_e32 v22, v4, v18
	v_fmac_f32_e32 v24, v0, v20
	v_fmac_f32_e32 v8, v5, v12
	v_fmac_f32_e32 v10, v1, v14
	v_fmac_f32_e32 v23, v6, v19
	v_fmac_f32_e32 v25, v2, v21
	v_fmac_f32_e32 v9, v7, v13
	v_fmac_f32_e32 v11, v3, v15
	v_cvt_pk_bf16_f32 v0, v22, v8
	v_cvt_pk_bf16_f32 v1, v23, v9
	v_cvt_pk_bf16_f32 v2, v24, v10
	v_cvt_pk_bf16_f32 v3, v25, v11
	global_store_dwordx4 v[16:17], v[0:3], off offset:256
	s_cbranch_vccnz .LBB0_1923
